# opt23 back-edge rotation (7.11): loop-back barrier is the K loop head; counter/exit test/branch run before it; exit path keeps its conditional barrier copy; on v062
# speedup vs baseline: 1.0018x; 1.0018x over previous
.Lmy_nobar2_2:
	ds_read_b128 v[152:155], v157
	ds_read_b128 v[160:163], v157 offset:1024
	ds_read_b128 v[164:167], v157 offset:2048
	ds_read_b128 v[168:171], v157 offset:3072
	ds_read_b128 v[172:175], v158
	ds_read_b128 v[176:179], v158 offset:1024
	ds_read_b128 v[180:183], v158 offset:2048
	ds_read_b128 v[184:187], v158 offset:3072
	s_add_u32 s34, s50, 0xfffc0080
	s_addc_u32 s35, s51, -1
	s_cmp_eq_u32 s86, 12
	s_cselect_b32 s55, s7, s35
	s_cselect_b32 s54, s8, s34
	s_cselect_b32 s53, s12, s41
	s_cselect_b32 s52, s13, s29
	v_lshl_add_u64 v[220:221], s[50:51], 0, v[144:145]
	s_add_i32 m0, s63, 0xc000
	ds_read_b128 v[188:191], v159
	ds_read_b128 v[192:195], v159 offset:1024
	ds_read_b128 v[196:199], v159 offset:2048
	ds_read_b128 v[200:203], v159 offset:3072
	ds_read_b128 v[204:207], v159 offset:4096
	ds_read_b128 v[208:211], v159 offset:5120
	ds_read_b128 v[212:215], v159 offset:6144
	ds_read_b128 v[216:219], v159 offset:7168
	global_load_lds_dwordx4 v[220:221], off
	v_lshl_add_u64 v[220:221], s[50:51], 0, v[146:147]
	s_add_i32 m0, s63, 0xe000
	s_nop 0
	global_load_lds_dwordx4 v[220:221], off
	s_waitcnt vmcnt(8)
	s_waitcnt lgkmcnt(0)
	s_barrier
	s_setprio 1
	s_waitcnt lgkmcnt(0)
	v_mfma_f32_16x16x32_bf16 v[124:127], v[152:155], v[188:191], 0
	v_mfma_f32_16x16x32_bf16 v[120:123], v[164:167], v[188:191], 0
	v_mfma_f32_16x16x32_bf16 v[108:111], v[152:155], v[196:199], 0
	v_mfma_f32_16x16x32_bf16 v[104:107], v[164:167], v[196:199], 0
	v_mfma_f32_16x16x32_bf16 v[92:95], v[152:155], v[204:207], 0
	v_mfma_f32_16x16x32_bf16 v[88:91], v[164:167], v[204:207], 0
	v_mfma_f32_16x16x32_bf16 v[76:79], v[152:155], v[212:215], 0
	v_mfma_f32_16x16x32_bf16 v[72:75], v[164:167], v[212:215], 0
	v_mfma_f32_16x16x32_bf16 v[124:127], v[160:163], v[192:195], v[124:127]
	v_mfma_f32_16x16x32_bf16 v[120:123], v[168:171], v[192:195], v[120:123]
	v_mfma_f32_16x16x32_bf16 v[108:111], v[160:163], v[200:203], v[108:111]
	v_mfma_f32_16x16x32_bf16 v[104:107], v[168:171], v[200:203], v[104:107]
	v_mfma_f32_16x16x32_bf16 v[92:95], v[160:163], v[208:211], v[92:95]
	v_mfma_f32_16x16x32_bf16 v[88:91], v[168:171], v[208:211], v[88:91]
	v_mfma_f32_16x16x32_bf16 v[76:79], v[160:163], v[216:219], v[76:79]
	v_mfma_f32_16x16x32_bf16 v[72:75], v[168:171], v[216:219], v[72:75]
	s_setprio 0
	s_setprio 1
	v_mfma_f32_16x16x32_bf16 v[116:119], v[172:175], v[188:191], 0
	v_mfma_f32_16x16x32_bf16 v[112:115], v[180:183], v[188:191], 0
	v_mfma_f32_16x16x32_bf16 v[100:103], v[172:175], v[196:199], 0
	v_mfma_f32_16x16x32_bf16 v[96:99], v[180:183], v[196:199], 0
	v_mfma_f32_16x16x32_bf16 v[84:87], v[172:175], v[204:207], 0
	v_mfma_f32_16x16x32_bf16 v[80:83], v[180:183], v[204:207], 0
	v_mfma_f32_16x16x32_bf16 v[68:71], v[172:175], v[212:215], 0
	v_mfma_f32_16x16x32_bf16 v[64:67], v[180:183], v[212:215], 0
	v_mfma_f32_16x16x32_bf16 v[116:119], v[176:179], v[192:195], v[116:119]
	v_mfma_f32_16x16x32_bf16 v[112:115], v[184:187], v[192:195], v[112:115]
	v_mfma_f32_16x16x32_bf16 v[100:103], v[176:179], v[200:203], v[100:103]
	v_mfma_f32_16x16x32_bf16 v[96:99], v[184:187], v[200:203], v[96:99]
	v_mfma_f32_16x16x32_bf16 v[84:87], v[176:179], v[208:211], v[84:87]
	v_mfma_f32_16x16x32_bf16 v[80:83], v[184:187], v[208:211], v[80:83]
	v_mfma_f32_16x16x32_bf16 v[68:71], v[176:179], v[216:219], v[68:71]
	v_mfma_f32_16x16x32_bf16 v[64:67], v[184:187], v[216:219], v[64:67]
	s_setprio 0
	s_barrier
	s_add_i32 s34, s82, s58
	v_lshl_add_u64 v[220:221], s[52:53], 0, v[136:137]
	s_mov_b32 m0, s34
	ds_read_b128 v[188:191], v159 offset:16384
	ds_read_b128 v[192:195], v159 offset:17408
	ds_read_b128 v[196:199], v159 offset:18432
	ds_read_b128 v[200:203], v159 offset:19456
	ds_read_b128 v[204:207], v159 offset:20480
	ds_read_b128 v[208:211], v159 offset:21504
	ds_read_b128 v[212:215], v159 offset:22528
	ds_read_b128 v[216:219], v159 offset:23552
	global_load_lds_dwordx4 v[220:221], off
	s_add_i32 m0, s34, 0x2000
	s_add_u32 s34, s52, 0x40000
	v_lshl_add_u64 v[222:223], s[52:53], 0, v[140:141]
	s_addc_u32 s35, s53, 0
	s_add_i32 s87, s83, s58
	global_load_lds_dwordx4 v[222:223], off
	v_lshl_add_u64 v[224:225], s[34:35], 0, v[136:137]
	s_mov_b32 m0, s87
	v_lshl_add_u64 v[226:227], s[54:55], 0, v[138:139]
	global_load_lds_dwordx4 v[224:225], off
	v_lshl_add_u64 v[224:225], s[34:35], 0, v[140:141]
	s_add_i32 m0, s87, 0x2000
	s_nop 0
	global_load_lds_dwordx4 v[224:225], off
	v_lshl_add_u64 v[224:225], s[54:55], 0, v[134:135]
	s_mov_b32 m0, s63
	s_nop 0
	global_load_lds_dwordx4 v[224:225], off
	s_mov_b32 m0, s64
	s_nop 0
	global_load_lds_dwordx4 v[226:227], off
	s_waitcnt vmcnt(8)
	s_waitcnt lgkmcnt(0)
	s_barrier
	s_setprio 1
	s_waitcnt lgkmcnt(0)
	v_mfma_f32_16x16x32_bf16 v[60:63], v[152:155], v[188:191], 0
	v_mfma_f32_16x16x32_bf16 v[56:59], v[164:167], v[188:191], 0
	v_mfma_f32_16x16x32_bf16 v[44:47], v[152:155], v[196:199], 0
	v_mfma_f32_16x16x32_bf16 v[40:43], v[164:167], v[196:199], 0
	v_mfma_f32_16x16x32_bf16 v[28:31], v[152:155], v[204:207], 0
	v_mfma_f32_16x16x32_bf16 v[24:27], v[164:167], v[204:207], 0
	v_mfma_f32_16x16x32_bf16 v[12:15], v[152:155], v[212:215], 0
	v_mfma_f32_16x16x32_bf16 v[8:11], v[164:167], v[212:215], 0
	v_mfma_f32_16x16x32_bf16 v[60:63], v[160:163], v[192:195], v[60:63]
	v_mfma_f32_16x16x32_bf16 v[56:59], v[168:171], v[192:195], v[56:59]
	v_mfma_f32_16x16x32_bf16 v[44:47], v[160:163], v[200:203], v[44:47]
	v_mfma_f32_16x16x32_bf16 v[40:43], v[168:171], v[200:203], v[40:43]
	v_mfma_f32_16x16x32_bf16 v[28:31], v[160:163], v[208:211], v[28:31]
	v_mfma_f32_16x16x32_bf16 v[24:27], v[168:171], v[208:211], v[24:27]
	v_mfma_f32_16x16x32_bf16 v[12:15], v[160:163], v[216:219], v[12:15]
	v_mfma_f32_16x16x32_bf16 v[8:11], v[168:171], v[216:219], v[8:11]
	s_setprio 0
	s_setprio 1
	v_mfma_f32_16x16x32_bf16 v[52:55], v[172:175], v[188:191], 0
	v_mfma_f32_16x16x32_bf16 v[48:51], v[180:183], v[188:191], 0
	v_mfma_f32_16x16x32_bf16 v[36:39], v[172:175], v[196:199], 0
	v_mfma_f32_16x16x32_bf16 v[32:35], v[180:183], v[196:199], 0
	v_mfma_f32_16x16x32_bf16 v[20:23], v[172:175], v[204:207], 0
	v_mfma_f32_16x16x32_bf16 v[16:19], v[180:183], v[204:207], 0
	v_mfma_f32_16x16x32_bf16 v[4:7], v[172:175], v[212:215], 0
	v_mfma_f32_16x16x32_bf16 v[0:3], v[180:183], v[212:215], 0
	v_mfma_f32_16x16x32_bf16 v[52:55], v[176:179], v[192:195], v[52:55]
	v_mfma_f32_16x16x32_bf16 v[48:51], v[184:187], v[192:195], v[48:51]
	v_mfma_f32_16x16x32_bf16 v[36:39], v[176:179], v[200:203], v[36:39]
	v_mfma_f32_16x16x32_bf16 v[32:35], v[184:187], v[200:203], v[32:35]
	v_mfma_f32_16x16x32_bf16 v[20:23], v[176:179], v[208:211], v[20:23]
	v_mfma_f32_16x16x32_bf16 v[16:19], v[184:187], v[208:211], v[16:19]
	v_mfma_f32_16x16x32_bf16 v[4:7], v[176:179], v[216:219], v[4:7]
	v_mfma_f32_16x16x32_bf16 v[0:3], v[184:187], v[216:219], v[0:3]
	s_setprio 0
	s_barrier
	s_add_i32 s87, 0, 0x18000
	v_add_u32_e32 v142, s87, v133
	s_add_i32 s88, 0, 0x1c000
	ds_read_b128 v[152:155], v142
	ds_read_b128 v[160:163], v142 offset:1024
	ds_read_b128 v[164:167], v142 offset:2048
	ds_read_b128 v[168:171], v142 offset:3072
	v_add_u32_e32 v142, s88, v133
	ds_read_b128 v[172:175], v142
	ds_read_b128 v[176:179], v142 offset:1024
	ds_read_b128 v[180:183], v142 offset:2048
	ds_read_b128 v[184:187], v142 offset:3072
	s_add_u32 s34, s54, 0x40000
	s_addc_u32 s35, s55, 0
	s_mov_b32 m0, s65
	v_lshl_add_u64 v[228:229], s[34:35], 0, v[134:135]
	ds_read_b128 v[188:191], v159 offset:32768
	ds_read_b128 v[192:195], v159 offset:33792
	ds_read_b128 v[196:199], v159 offset:34816
	ds_read_b128 v[200:203], v159 offset:35840
	ds_read_b128 v[204:207], v159 offset:36864
	ds_read_b128 v[208:211], v159 offset:37888
	ds_read_b128 v[212:215], v159 offset:38912
	ds_read_b128 v[216:219], v159 offset:39936
	global_load_lds_dwordx4 v[228:229], off
	v_lshl_add_u64 v[228:229], s[34:35], 0, v[138:139]
	s_mov_b32 m0, s66
	s_nop 0
	global_load_lds_dwordx4 v[228:229], off
	s_waitcnt vmcnt(8)
	s_waitcnt lgkmcnt(0)
	s_barrier
	s_setprio 1
	s_waitcnt lgkmcnt(0)
	v_mfma_f32_16x16x32_bf16 v[124:127], v[152:155], v[188:191], v[124:127]
	v_mfma_f32_16x16x32_bf16 v[120:123], v[164:167], v[188:191], v[120:123]
	v_mfma_f32_16x16x32_bf16 v[108:111], v[152:155], v[196:199], v[108:111]
	v_mfma_f32_16x16x32_bf16 v[104:107], v[164:167], v[196:199], v[104:107]
	v_mfma_f32_16x16x32_bf16 v[92:95], v[152:155], v[204:207], v[92:95]
	v_mfma_f32_16x16x32_bf16 v[88:91], v[164:167], v[204:207], v[88:91]
	v_mfma_f32_16x16x32_bf16 v[76:79], v[152:155], v[212:215], v[76:79]
	v_mfma_f32_16x16x32_bf16 v[72:75], v[164:167], v[212:215], v[72:75]
	v_mfma_f32_16x16x32_bf16 v[124:127], v[160:163], v[192:195], v[124:127]
	v_mfma_f32_16x16x32_bf16 v[120:123], v[168:171], v[192:195], v[120:123]
	v_mfma_f32_16x16x32_bf16 v[108:111], v[160:163], v[200:203], v[108:111]
	v_mfma_f32_16x16x32_bf16 v[104:107], v[168:171], v[200:203], v[104:107]
	v_mfma_f32_16x16x32_bf16 v[92:95], v[160:163], v[208:211], v[92:95]
	v_mfma_f32_16x16x32_bf16 v[88:91], v[168:171], v[208:211], v[88:91]
	v_mfma_f32_16x16x32_bf16 v[76:79], v[160:163], v[216:219], v[76:79]
	v_mfma_f32_16x16x32_bf16 v[72:75], v[168:171], v[216:219], v[72:75]
	s_setprio 0
	s_setprio 1
	v_mfma_f32_16x16x32_bf16 v[116:119], v[172:175], v[188:191], v[116:119]
	v_mfma_f32_16x16x32_bf16 v[112:115], v[180:183], v[188:191], v[112:115]
	v_mfma_f32_16x16x32_bf16 v[100:103], v[172:175], v[196:199], v[100:103]
	v_mfma_f32_16x16x32_bf16 v[96:99], v[180:183], v[196:199], v[96:99]
	v_mfma_f32_16x16x32_bf16 v[84:87], v[172:175], v[204:207], v[84:87]
	v_mfma_f32_16x16x32_bf16 v[80:83], v[180:183], v[204:207], v[80:83]
	v_mfma_f32_16x16x32_bf16 v[68:71], v[172:175], v[212:215], v[68:71]
	v_mfma_f32_16x16x32_bf16 v[64:67], v[180:183], v[212:215], v[64:67]
	v_mfma_f32_16x16x32_bf16 v[116:119], v[176:179], v[192:195], v[116:119]
	v_mfma_f32_16x16x32_bf16 v[112:115], v[184:187], v[192:195], v[112:115]
	v_mfma_f32_16x16x32_bf16 v[100:103], v[176:179], v[200:203], v[100:103]
	v_mfma_f32_16x16x32_bf16 v[96:99], v[184:187], v[200:203], v[96:99]
	v_mfma_f32_16x16x32_bf16 v[84:87], v[176:179], v[208:211], v[84:87]
	v_mfma_f32_16x16x32_bf16 v[80:83], v[184:187], v[208:211], v[80:83]
	v_mfma_f32_16x16x32_bf16 v[68:71], v[176:179], v[216:219], v[68:71]
	v_mfma_f32_16x16x32_bf16 v[64:67], v[184:187], v[216:219], v[64:67]
	s_setprio 0
	s_barrier
	s_add_i32 s34, s87, s58
	v_lshl_add_u64 v[220:221], v[220:221], 0, s[22:23]
	s_mov_b32 m0, s34
	ds_read_b128 v[188:191], v159 offset:49152
	ds_read_b128 v[192:195], v159 offset:50176
	ds_read_b128 v[196:199], v159 offset:51200
	ds_read_b128 v[200:203], v159 offset:52224
	ds_read_b128 v[204:207], v159 offset:53248
	ds_read_b128 v[208:211], v159 offset:54272
	ds_read_b128 v[212:215], v159 offset:55296
	ds_read_b128 v[216:219], v159 offset:56320
	global_load_lds_dwordx4 v[220:221], off
	s_add_i32 m0, s34, 0x2000
	s_add_u32 s34, s52, 0x40080
	v_lshl_add_u64 v[220:221], v[222:223], 0, s[22:23]
	s_addc_u32 s35, s53, 0
	s_add_i32 s52, s88, s58
	global_load_lds_dwordx4 v[220:221], off
	v_lshl_add_u64 v[220:221], s[34:35], 0, v[136:137]
	s_mov_b32 m0, s52
	s_nop 0
	global_load_lds_dwordx4 v[220:221], off
	v_lshl_add_u64 v[220:221], s[34:35], 0, v[140:141]
	s_add_i32 m0, s52, 0x2000
	s_nop 0
	global_load_lds_dwordx4 v[220:221], off
	v_lshl_add_u64 v[220:221], v[224:225], 0, s[22:23]
	s_mov_b32 m0, s79
	s_nop 0
	global_load_lds_dwordx4 v[220:221], off
	v_lshl_add_u64 v[220:221], v[226:227], 0, s[22:23]
	s_mov_b32 m0, s81
	s_nop 0
	global_load_lds_dwordx4 v[220:221], off
	s_waitcnt vmcnt(8)
	s_waitcnt lgkmcnt(0)
	s_barrier
	s_add_u32 s50, s50, 0x100
	s_addc_u32 s51, s51, 0
	s_add_u32 s29, s29, 0x100
	s_addc_u32 s41, s41, 0
	s_setprio 1
	s_waitcnt lgkmcnt(0)
	v_mfma_f32_16x16x32_bf16 v[60:63], v[152:155], v[188:191], v[60:63]
	v_mfma_f32_16x16x32_bf16 v[56:59], v[164:167], v[188:191], v[56:59]
	v_mfma_f32_16x16x32_bf16 v[44:47], v[152:155], v[196:199], v[44:47]
	v_mfma_f32_16x16x32_bf16 v[40:43], v[164:167], v[196:199], v[40:43]
	v_mfma_f32_16x16x32_bf16 v[28:31], v[152:155], v[204:207], v[28:31]
	v_mfma_f32_16x16x32_bf16 v[24:27], v[164:167], v[204:207], v[24:27]
	v_mfma_f32_16x16x32_bf16 v[12:15], v[152:155], v[212:215], v[12:15]
	v_mfma_f32_16x16x32_bf16 v[8:11], v[164:167], v[212:215], v[8:11]
	v_mfma_f32_16x16x32_bf16 v[60:63], v[160:163], v[192:195], v[60:63]
	v_mfma_f32_16x16x32_bf16 v[56:59], v[168:171], v[192:195], v[56:59]
	v_mfma_f32_16x16x32_bf16 v[44:47], v[160:163], v[200:203], v[44:47]
	v_mfma_f32_16x16x32_bf16 v[40:43], v[168:171], v[200:203], v[40:43]
	v_mfma_f32_16x16x32_bf16 v[28:31], v[160:163], v[208:211], v[28:31]
	v_mfma_f32_16x16x32_bf16 v[24:27], v[168:171], v[208:211], v[24:27]
	v_mfma_f32_16x16x32_bf16 v[12:15], v[160:163], v[216:219], v[12:15]
	v_mfma_f32_16x16x32_bf16 v[8:11], v[168:171], v[216:219], v[8:11]
	s_setprio 0
	s_setprio 1
	v_mfma_f32_16x16x32_bf16 v[52:55], v[172:175], v[188:191], v[52:55]
	v_mfma_f32_16x16x32_bf16 v[48:51], v[180:183], v[188:191], v[48:51]
	v_mfma_f32_16x16x32_bf16 v[36:39], v[172:175], v[196:199], v[36:39]
	v_mfma_f32_16x16x32_bf16 v[32:35], v[180:183], v[196:199], v[32:35]
	v_mfma_f32_16x16x32_bf16 v[20:23], v[172:175], v[204:207], v[20:23]
	v_mfma_f32_16x16x32_bf16 v[16:19], v[180:183], v[204:207], v[16:19]
	v_mfma_f32_16x16x32_bf16 v[4:7], v[172:175], v[212:215], v[4:7]
	v_mfma_f32_16x16x32_bf16 v[0:3], v[180:183], v[212:215], v[0:3]
	v_mfma_f32_16x16x32_bf16 v[52:55], v[176:179], v[192:195], v[52:55]
	v_mfma_f32_16x16x32_bf16 v[48:51], v[184:187], v[192:195], v[48:51]
	v_mfma_f32_16x16x32_bf16 v[36:39], v[176:179], v[200:203], v[36:39]
	v_mfma_f32_16x16x32_bf16 v[32:35], v[184:187], v[200:203], v[32:35]
	v_mfma_f32_16x16x32_bf16 v[20:23], v[176:179], v[208:211], v[20:23]
	v_mfma_f32_16x16x32_bf16 v[16:19], v[184:187], v[208:211], v[16:19]
	v_mfma_f32_16x16x32_bf16 v[4:7], v[176:179], v[216:219], v[4:7]
	v_mfma_f32_16x16x32_bf16 v[0:3], v[184:187], v[216:219], v[0:3]
	s_setprio 0
	s_add_i32 s86, s86, 2
.LBB0_211:
	s_barrier
	ds_read_b128 v[152:155], v157
	ds_read_b128 v[160:163], v157 offset:1024
	ds_read_b128 v[164:167], v157 offset:2048
	ds_read_b128 v[168:171], v157 offset:3072
	ds_read_b128 v[172:175], v158
	ds_read_b128 v[176:179], v158 offset:1024
	ds_read_b128 v[180:183], v158 offset:2048
	ds_read_b128 v[184:187], v158 offset:3072
	s_add_u32 s34, s50, 0xfffc0080
	s_addc_u32 s35, s51, -1
	s_cmp_eq_u32 s86, 12
	s_cselect_b32 s55, s7, s35
	s_cselect_b32 s54, s8, s34
	s_cselect_b32 s53, s12, s41
	s_cselect_b32 s52, s13, s29
	v_lshl_add_u64 v[220:221], s[50:51], 0, v[144:145]
	s_add_i32 m0, s63, 0xc000
	ds_read_b128 v[188:191], v159
	ds_read_b128 v[192:195], v159 offset:1024
	ds_read_b128 v[196:199], v159 offset:2048
	ds_read_b128 v[200:203], v159 offset:3072
	ds_read_b128 v[204:207], v159 offset:4096
	ds_read_b128 v[208:211], v159 offset:5120
	ds_read_b128 v[212:215], v159 offset:6144
	ds_read_b128 v[216:219], v159 offset:7168
	global_load_lds_dwordx4 v[220:221], off
	v_lshl_add_u64 v[220:221], s[50:51], 0, v[146:147]
	s_add_i32 m0, s63, 0xe000
	s_nop 0
	global_load_lds_dwordx4 v[220:221], off
	s_waitcnt vmcnt(8)
	s_waitcnt lgkmcnt(0)
	s_barrier
	s_setprio 1
	s_waitcnt lgkmcnt(0)
	v_mfma_f32_16x16x32_bf16 v[124:127], v[152:155], v[188:191], v[124:127]
	v_mfma_f32_16x16x32_bf16 v[120:123], v[164:167], v[188:191], v[120:123]
	v_mfma_f32_16x16x32_bf16 v[108:111], v[152:155], v[196:199], v[108:111]
	v_mfma_f32_16x16x32_bf16 v[104:107], v[164:167], v[196:199], v[104:107]
	v_mfma_f32_16x16x32_bf16 v[92:95], v[152:155], v[204:207], v[92:95]
	v_mfma_f32_16x16x32_bf16 v[88:91], v[164:167], v[204:207], v[88:91]
	v_mfma_f32_16x16x32_bf16 v[76:79], v[152:155], v[212:215], v[76:79]
	v_mfma_f32_16x16x32_bf16 v[72:75], v[164:167], v[212:215], v[72:75]
	v_mfma_f32_16x16x32_bf16 v[124:127], v[160:163], v[192:195], v[124:127]
	v_mfma_f32_16x16x32_bf16 v[120:123], v[168:171], v[192:195], v[120:123]
	v_mfma_f32_16x16x32_bf16 v[108:111], v[160:163], v[200:203], v[108:111]
	v_mfma_f32_16x16x32_bf16 v[104:107], v[168:171], v[200:203], v[104:107]
	v_mfma_f32_16x16x32_bf16 v[92:95], v[160:163], v[208:211], v[92:95]
	v_mfma_f32_16x16x32_bf16 v[88:91], v[168:171], v[208:211], v[88:91]
	v_mfma_f32_16x16x32_bf16 v[76:79], v[160:163], v[216:219], v[76:79]
	v_mfma_f32_16x16x32_bf16 v[72:75], v[168:171], v[216:219], v[72:75]
	s_setprio 0
	s_setprio 1
	v_mfma_f32_16x16x32_bf16 v[116:119], v[172:175], v[188:191], v[116:119]
	v_mfma_f32_16x16x32_bf16 v[112:115], v[180:183], v[188:191], v[112:115]
	v_mfma_f32_16x16x32_bf16 v[100:103], v[172:175], v[196:199], v[100:103]
	v_mfma_f32_16x16x32_bf16 v[96:99], v[180:183], v[196:199], v[96:99]
	v_mfma_f32_16x16x32_bf16 v[84:87], v[172:175], v[204:207], v[84:87]
	v_mfma_f32_16x16x32_bf16 v[80:83], v[180:183], v[204:207], v[80:83]
	v_mfma_f32_16x16x32_bf16 v[68:71], v[172:175], v[212:215], v[68:71]
	v_mfma_f32_16x16x32_bf16 v[64:67], v[180:183], v[212:215], v[64:67]
	v_mfma_f32_16x16x32_bf16 v[116:119], v[176:179], v[192:195], v[116:119]
	v_mfma_f32_16x16x32_bf16 v[112:115], v[184:187], v[192:195], v[112:115]
	v_mfma_f32_16x16x32_bf16 v[100:103], v[176:179], v[200:203], v[100:103]
	v_mfma_f32_16x16x32_bf16 v[96:99], v[184:187], v[200:203], v[96:99]
	v_mfma_f32_16x16x32_bf16 v[84:87], v[176:179], v[208:211], v[84:87]
	v_mfma_f32_16x16x32_bf16 v[80:83], v[184:187], v[208:211], v[80:83]
	v_mfma_f32_16x16x32_bf16 v[68:71], v[176:179], v[216:219], v[68:71]
	v_mfma_f32_16x16x32_bf16 v[64:67], v[184:187], v[216:219], v[64:67]
	s_setprio 0
	s_barrier
	s_add_i32 s34, s82, s58
	v_lshl_add_u64 v[220:221], s[52:53], 0, v[136:137]
	s_mov_b32 m0, s34
	ds_read_b128 v[188:191], v159 offset:16384
	ds_read_b128 v[192:195], v159 offset:17408
	ds_read_b128 v[196:199], v159 offset:18432
	ds_read_b128 v[200:203], v159 offset:19456
	ds_read_b128 v[204:207], v159 offset:20480
	ds_read_b128 v[208:211], v159 offset:21504
	ds_read_b128 v[212:215], v159 offset:22528
	ds_read_b128 v[216:219], v159 offset:23552
	global_load_lds_dwordx4 v[220:221], off
	s_add_i32 m0, s34, 0x2000
	s_add_u32 s34, s52, 0x40000
	v_lshl_add_u64 v[222:223], s[52:53], 0, v[140:141]
	s_addc_u32 s35, s53, 0
	s_add_i32 s87, s83, s58
	global_load_lds_dwordx4 v[222:223], off
	v_lshl_add_u64 v[224:225], s[34:35], 0, v[136:137]
	s_mov_b32 m0, s87
	v_lshl_add_u64 v[226:227], s[54:55], 0, v[138:139]
	global_load_lds_dwordx4 v[224:225], off
	v_lshl_add_u64 v[224:225], s[34:35], 0, v[140:141]
	s_add_i32 m0, s87, 0x2000
	s_nop 0
	global_load_lds_dwordx4 v[224:225], off
	v_lshl_add_u64 v[224:225], s[54:55], 0, v[134:135]
	s_mov_b32 m0, s63
	s_nop 0
	global_load_lds_dwordx4 v[224:225], off
	s_mov_b32 m0, s64
	s_nop 0
	global_load_lds_dwordx4 v[226:227], off
	s_waitcnt vmcnt(8)
	s_waitcnt lgkmcnt(0)
	s_barrier
	s_setprio 1
	s_waitcnt lgkmcnt(0)
	v_mfma_f32_16x16x32_bf16 v[60:63], v[152:155], v[188:191], v[60:63]
	v_mfma_f32_16x16x32_bf16 v[56:59], v[164:167], v[188:191], v[56:59]
	v_mfma_f32_16x16x32_bf16 v[44:47], v[152:155], v[196:199], v[44:47]
	v_mfma_f32_16x16x32_bf16 v[40:43], v[164:167], v[196:199], v[40:43]
	v_mfma_f32_16x16x32_bf16 v[28:31], v[152:155], v[204:207], v[28:31]
	v_mfma_f32_16x16x32_bf16 v[24:27], v[164:167], v[204:207], v[24:27]
	v_mfma_f32_16x16x32_bf16 v[12:15], v[152:155], v[212:215], v[12:15]
	v_mfma_f32_16x16x32_bf16 v[8:11], v[164:167], v[212:215], v[8:11]
	v_mfma_f32_16x16x32_bf16 v[60:63], v[160:163], v[192:195], v[60:63]
	v_mfma_f32_16x16x32_bf16 v[56:59], v[168:171], v[192:195], v[56:59]
	v_mfma_f32_16x16x32_bf16 v[44:47], v[160:163], v[200:203], v[44:47]
	v_mfma_f32_16x16x32_bf16 v[40:43], v[168:171], v[200:203], v[40:43]
	v_mfma_f32_16x16x32_bf16 v[28:31], v[160:163], v[208:211], v[28:31]
	v_mfma_f32_16x16x32_bf16 v[24:27], v[168:171], v[208:211], v[24:27]
	v_mfma_f32_16x16x32_bf16 v[12:15], v[160:163], v[216:219], v[12:15]
	v_mfma_f32_16x16x32_bf16 v[8:11], v[168:171], v[216:219], v[8:11]
	s_setprio 0
	s_setprio 1
	v_mfma_f32_16x16x32_bf16 v[52:55], v[172:175], v[188:191], v[52:55]
	v_mfma_f32_16x16x32_bf16 v[48:51], v[180:183], v[188:191], v[48:51]
	v_mfma_f32_16x16x32_bf16 v[36:39], v[172:175], v[196:199], v[36:39]
	v_mfma_f32_16x16x32_bf16 v[32:35], v[180:183], v[196:199], v[32:35]
	v_mfma_f32_16x16x32_bf16 v[20:23], v[172:175], v[204:207], v[20:23]
	v_mfma_f32_16x16x32_bf16 v[16:19], v[180:183], v[204:207], v[16:19]
	v_mfma_f32_16x16x32_bf16 v[4:7], v[172:175], v[212:215], v[4:7]
	v_mfma_f32_16x16x32_bf16 v[0:3], v[180:183], v[212:215], v[0:3]
	v_mfma_f32_16x16x32_bf16 v[52:55], v[176:179], v[192:195], v[52:55]
	v_mfma_f32_16x16x32_bf16 v[48:51], v[184:187], v[192:195], v[48:51]
	v_mfma_f32_16x16x32_bf16 v[36:39], v[176:179], v[200:203], v[36:39]
	v_mfma_f32_16x16x32_bf16 v[32:35], v[184:187], v[200:203], v[32:35]
	v_mfma_f32_16x16x32_bf16 v[20:23], v[176:179], v[208:211], v[20:23]
	v_mfma_f32_16x16x32_bf16 v[16:19], v[184:187], v[208:211], v[16:19]
	v_mfma_f32_16x16x32_bf16 v[4:7], v[176:179], v[216:219], v[4:7]
	v_mfma_f32_16x16x32_bf16 v[0:3], v[184:187], v[216:219], v[0:3]
	s_setprio 0
	s_barrier
	s_add_i32 s87, 0, 0x18000
	v_add_u32_e32 v142, s87, v133
	s_add_i32 s88, 0, 0x1c000
	ds_read_b128 v[152:155], v142
	ds_read_b128 v[160:163], v142 offset:1024
	ds_read_b128 v[164:167], v142 offset:2048
	ds_read_b128 v[168:171], v142 offset:3072
	v_add_u32_e32 v142, s88, v133
	ds_read_b128 v[172:175], v142
	ds_read_b128 v[176:179], v142 offset:1024
	ds_read_b128 v[180:183], v142 offset:2048
	ds_read_b128 v[184:187], v142 offset:3072
	s_add_u32 s34, s54, 0x40000
	s_addc_u32 s35, s55, 0
	s_mov_b32 m0, s65
	v_lshl_add_u64 v[228:229], s[34:35], 0, v[134:135]
	ds_read_b128 v[188:191], v159 offset:32768
	ds_read_b128 v[192:195], v159 offset:33792
	ds_read_b128 v[196:199], v159 offset:34816
	ds_read_b128 v[200:203], v159 offset:35840
	ds_read_b128 v[204:207], v159 offset:36864
	ds_read_b128 v[208:211], v159 offset:37888
	ds_read_b128 v[212:215], v159 offset:38912
	ds_read_b128 v[216:219], v159 offset:39936
	global_load_lds_dwordx4 v[228:229], off
	v_lshl_add_u64 v[228:229], s[34:35], 0, v[138:139]
	s_mov_b32 m0, s66
	s_nop 0
	global_load_lds_dwordx4 v[228:229], off
	s_waitcnt vmcnt(8)
	s_waitcnt lgkmcnt(0)
	s_barrier
	s_setprio 1
	s_waitcnt lgkmcnt(0)
	v_mfma_f32_16x16x32_bf16 v[124:127], v[152:155], v[188:191], v[124:127]
	v_mfma_f32_16x16x32_bf16 v[120:123], v[164:167], v[188:191], v[120:123]
	v_mfma_f32_16x16x32_bf16 v[108:111], v[152:155], v[196:199], v[108:111]
	v_mfma_f32_16x16x32_bf16 v[104:107], v[164:167], v[196:199], v[104:107]
	v_mfma_f32_16x16x32_bf16 v[92:95], v[152:155], v[204:207], v[92:95]
	v_mfma_f32_16x16x32_bf16 v[88:91], v[164:167], v[204:207], v[88:91]
	v_mfma_f32_16x16x32_bf16 v[76:79], v[152:155], v[212:215], v[76:79]
	v_mfma_f32_16x16x32_bf16 v[72:75], v[164:167], v[212:215], v[72:75]
	v_mfma_f32_16x16x32_bf16 v[124:127], v[160:163], v[192:195], v[124:127]
	v_mfma_f32_16x16x32_bf16 v[120:123], v[168:171], v[192:195], v[120:123]
	v_mfma_f32_16x16x32_bf16 v[108:111], v[160:163], v[200:203], v[108:111]
	v_mfma_f32_16x16x32_bf16 v[104:107], v[168:171], v[200:203], v[104:107]
	v_mfma_f32_16x16x32_bf16 v[92:95], v[160:163], v[208:211], v[92:95]
	v_mfma_f32_16x16x32_bf16 v[88:91], v[168:171], v[208:211], v[88:91]
	v_mfma_f32_16x16x32_bf16 v[76:79], v[160:163], v[216:219], v[76:79]
	v_mfma_f32_16x16x32_bf16 v[72:75], v[168:171], v[216:219], v[72:75]
	s_setprio 0
	s_setprio 1
	v_mfma_f32_16x16x32_bf16 v[116:119], v[172:175], v[188:191], v[116:119]
	v_mfma_f32_16x16x32_bf16 v[112:115], v[180:183], v[188:191], v[112:115]
	v_mfma_f32_16x16x32_bf16 v[100:103], v[172:175], v[196:199], v[100:103]
	v_mfma_f32_16x16x32_bf16 v[96:99], v[180:183], v[196:199], v[96:99]
	v_mfma_f32_16x16x32_bf16 v[84:87], v[172:175], v[204:207], v[84:87]
	v_mfma_f32_16x16x32_bf16 v[80:83], v[180:183], v[204:207], v[80:83]
	v_mfma_f32_16x16x32_bf16 v[68:71], v[172:175], v[212:215], v[68:71]
	v_mfma_f32_16x16x32_bf16 v[64:67], v[180:183], v[212:215], v[64:67]
	v_mfma_f32_16x16x32_bf16 v[116:119], v[176:179], v[192:195], v[116:119]
	v_mfma_f32_16x16x32_bf16 v[112:115], v[184:187], v[192:195], v[112:115]
	v_mfma_f32_16x16x32_bf16 v[100:103], v[176:179], v[200:203], v[100:103]
	v_mfma_f32_16x16x32_bf16 v[96:99], v[184:187], v[200:203], v[96:99]
	v_mfma_f32_16x16x32_bf16 v[84:87], v[176:179], v[208:211], v[84:87]
	v_mfma_f32_16x16x32_bf16 v[80:83], v[184:187], v[208:211], v[80:83]
	v_mfma_f32_16x16x32_bf16 v[68:71], v[176:179], v[216:219], v[68:71]
	v_mfma_f32_16x16x32_bf16 v[64:67], v[184:187], v[216:219], v[64:67]
	s_setprio 0
	s_barrier
	s_add_i32 s34, s87, s58
	v_lshl_add_u64 v[220:221], v[220:221], 0, s[22:23]
	s_mov_b32 m0, s34
	ds_read_b128 v[188:191], v159 offset:49152
	ds_read_b128 v[192:195], v159 offset:50176
	ds_read_b128 v[196:199], v159 offset:51200
	ds_read_b128 v[200:203], v159 offset:52224
	ds_read_b128 v[204:207], v159 offset:53248
	ds_read_b128 v[208:211], v159 offset:54272
	ds_read_b128 v[212:215], v159 offset:55296
	ds_read_b128 v[216:219], v159 offset:56320
	global_load_lds_dwordx4 v[220:221], off
	s_add_i32 m0, s34, 0x2000
	s_add_u32 s34, s52, 0x40080
	v_lshl_add_u64 v[220:221], v[222:223], 0, s[22:23]
	s_addc_u32 s35, s53, 0
	s_add_i32 s52, s88, s58
	global_load_lds_dwordx4 v[220:221], off
	v_lshl_add_u64 v[220:221], s[34:35], 0, v[136:137]
	s_mov_b32 m0, s52
	s_nop 0
	global_load_lds_dwordx4 v[220:221], off
	v_lshl_add_u64 v[220:221], s[34:35], 0, v[140:141]
	s_add_i32 m0, s52, 0x2000
	s_nop 0
	global_load_lds_dwordx4 v[220:221], off
	v_lshl_add_u64 v[220:221], v[224:225], 0, s[22:23]
	s_mov_b32 m0, s79
	s_nop 0
	global_load_lds_dwordx4 v[220:221], off
	v_lshl_add_u64 v[220:221], v[226:227], 0, s[22:23]
	s_mov_b32 m0, s81
	s_nop 0
	global_load_lds_dwordx4 v[220:221], off
	s_waitcnt vmcnt(8)
	s_waitcnt lgkmcnt(0)
	s_barrier
	s_add_u32 s50, s50, 0x100
	s_addc_u32 s51, s51, 0
	s_add_u32 s29, s29, 0x100
	s_addc_u32 s41, s41, 0
	s_setprio 1
	s_waitcnt lgkmcnt(0)
	v_mfma_f32_16x16x32_bf16 v[60:63], v[152:155], v[188:191], v[60:63]
	v_mfma_f32_16x16x32_bf16 v[56:59], v[164:167], v[188:191], v[56:59]
	v_mfma_f32_16x16x32_bf16 v[44:47], v[152:155], v[196:199], v[44:47]
	v_mfma_f32_16x16x32_bf16 v[40:43], v[164:167], v[196:199], v[40:43]
	v_mfma_f32_16x16x32_bf16 v[28:31], v[152:155], v[204:207], v[28:31]
	v_mfma_f32_16x16x32_bf16 v[24:27], v[164:167], v[204:207], v[24:27]
	v_mfma_f32_16x16x32_bf16 v[12:15], v[152:155], v[212:215], v[12:15]
	v_mfma_f32_16x16x32_bf16 v[8:11], v[164:167], v[212:215], v[8:11]
	v_mfma_f32_16x16x32_bf16 v[60:63], v[160:163], v[192:195], v[60:63]
	v_mfma_f32_16x16x32_bf16 v[56:59], v[168:171], v[192:195], v[56:59]
	v_mfma_f32_16x16x32_bf16 v[44:47], v[160:163], v[200:203], v[44:47]
	v_mfma_f32_16x16x32_bf16 v[40:43], v[168:171], v[200:203], v[40:43]
	v_mfma_f32_16x16x32_bf16 v[28:31], v[160:163], v[208:211], v[28:31]
	v_mfma_f32_16x16x32_bf16 v[24:27], v[168:171], v[208:211], v[24:27]
	v_mfma_f32_16x16x32_bf16 v[12:15], v[160:163], v[216:219], v[12:15]
	v_mfma_f32_16x16x32_bf16 v[8:11], v[168:171], v[216:219], v[8:11]
	s_setprio 0
	s_setprio 1
	v_mfma_f32_16x16x32_bf16 v[52:55], v[172:175], v[188:191], v[52:55]
	v_mfma_f32_16x16x32_bf16 v[48:51], v[180:183], v[188:191], v[48:51]
	v_mfma_f32_16x16x32_bf16 v[36:39], v[172:175], v[196:199], v[36:39]
	v_mfma_f32_16x16x32_bf16 v[32:35], v[180:183], v[196:199], v[32:35]
	v_mfma_f32_16x16x32_bf16 v[20:23], v[172:175], v[204:207], v[20:23]
	v_mfma_f32_16x16x32_bf16 v[16:19], v[180:183], v[204:207], v[16:19]
	v_mfma_f32_16x16x32_bf16 v[4:7], v[172:175], v[212:215], v[4:7]
	v_mfma_f32_16x16x32_bf16 v[0:3], v[180:183], v[212:215], v[0:3]
	v_mfma_f32_16x16x32_bf16 v[52:55], v[176:179], v[192:195], v[52:55]
	v_mfma_f32_16x16x32_bf16 v[48:51], v[184:187], v[192:195], v[48:51]
	v_mfma_f32_16x16x32_bf16 v[36:39], v[176:179], v[200:203], v[36:39]
	v_mfma_f32_16x16x32_bf16 v[32:35], v[184:187], v[200:203], v[32:35]
	v_mfma_f32_16x16x32_bf16 v[20:23], v[176:179], v[208:211], v[20:23]
	v_mfma_f32_16x16x32_bf16 v[16:19], v[184:187], v[208:211], v[16:19]
	v_mfma_f32_16x16x32_bf16 v[4:7], v[176:179], v[216:219], v[4:7]
	v_mfma_f32_16x16x32_bf16 v[0:3], v[184:187], v[216:219], v[0:3]
	s_setprio 0
	s_add_i32 s86, s86, 2
	s_cmp_gt_u32 s86, 13
	s_cbranch_scc0 .LBB0_211
	s_sub_i32 s100, s86, 2
	s_cmp_eq_u32 s100, s98
	s_cbranch_scc1 .Lmy_nobar_2
	s_barrier
.Lmy_nobar_2:
	s_and_b64 vcc, exec, s[26:27]
	s_cbranch_vccz .LBB0_214
	s_nop 0

.Lmy_nobar2_4:
	ds_read_b128 v[148:151], v154
	ds_read_b128 v[160:163], v154 offset:1024
	ds_read_b128 v[164:167], v154 offset:2048
	ds_read_b128 v[168:171], v154 offset:3072
	ds_read_b128 v[172:175], v155
	ds_read_b128 v[176:179], v155 offset:1024
	ds_read_b128 v[180:183], v155 offset:2048
	ds_read_b128 v[184:187], v155 offset:3072
	s_add_u32 s34, s50, 0xfffc0080
	s_addc_u32 s35, s51, -1
	s_cmp_eq_u32 s85, 12
	s_cselect_b32 s55, s12, s35
	s_cselect_b32 s54, s13, s34
	s_cselect_b32 s53, s27, s77
	s_cselect_b32 s52, s29, s49
	v_lshl_add_u64 v[220:221], s[50:51], 0, v[140:141]
	s_add_i32 m0, s58, 0xc000
	ds_read_b128 v[188:191], v157
	ds_read_b128 v[192:195], v157 offset:1024
	ds_read_b128 v[196:199], v157 offset:2048
	ds_read_b128 v[200:203], v157 offset:3072
	ds_read_b128 v[204:207], v157 offset:4096
	ds_read_b128 v[208:211], v157 offset:5120
	ds_read_b128 v[212:215], v157 offset:6144
	ds_read_b128 v[216:219], v157 offset:7168
	global_load_lds_dwordx4 v[220:221], off
	v_lshl_add_u64 v[220:221], s[50:51], 0, v[142:143]
	s_add_i32 m0, s58, 0xe000
	s_nop 0
	global_load_lds_dwordx4 v[220:221], off
	s_waitcnt vmcnt(8)
	s_waitcnt lgkmcnt(0)
	s_barrier
	s_setprio 1
	s_waitcnt lgkmcnt(0)
	v_mfma_f32_16x16x32_bf16 v[124:127], v[148:151], v[188:191], 0
	v_mfma_f32_16x16x32_bf16 v[120:123], v[164:167], v[188:191], 0
	v_mfma_f32_16x16x32_bf16 v[108:111], v[148:151], v[196:199], 0
	v_mfma_f32_16x16x32_bf16 v[104:107], v[164:167], v[196:199], 0
	v_mfma_f32_16x16x32_bf16 v[92:95], v[148:151], v[204:207], 0
	v_mfma_f32_16x16x32_bf16 v[88:91], v[164:167], v[204:207], 0
	v_mfma_f32_16x16x32_bf16 v[76:79], v[148:151], v[212:215], 0
	v_mfma_f32_16x16x32_bf16 v[72:75], v[164:167], v[212:215], 0
	v_mfma_f32_16x16x32_bf16 v[124:127], v[160:163], v[192:195], v[124:127]
	v_mfma_f32_16x16x32_bf16 v[120:123], v[168:171], v[192:195], v[120:123]
	v_mfma_f32_16x16x32_bf16 v[108:111], v[160:163], v[200:203], v[108:111]
	v_mfma_f32_16x16x32_bf16 v[104:107], v[168:171], v[200:203], v[104:107]
	v_mfma_f32_16x16x32_bf16 v[92:95], v[160:163], v[208:211], v[92:95]
	v_mfma_f32_16x16x32_bf16 v[88:91], v[168:171], v[208:211], v[88:91]
	v_mfma_f32_16x16x32_bf16 v[76:79], v[160:163], v[216:219], v[76:79]
	v_mfma_f32_16x16x32_bf16 v[72:75], v[168:171], v[216:219], v[72:75]
	s_setprio 0
	s_setprio 1
	v_mfma_f32_16x16x32_bf16 v[116:119], v[172:175], v[188:191], 0
	v_mfma_f32_16x16x32_bf16 v[112:115], v[180:183], v[188:191], 0
	v_mfma_f32_16x16x32_bf16 v[100:103], v[172:175], v[196:199], 0
	v_mfma_f32_16x16x32_bf16 v[96:99], v[180:183], v[196:199], 0
	v_mfma_f32_16x16x32_bf16 v[84:87], v[172:175], v[204:207], 0
	v_mfma_f32_16x16x32_bf16 v[80:83], v[180:183], v[204:207], 0
	v_mfma_f32_16x16x32_bf16 v[68:71], v[172:175], v[212:215], 0
	v_mfma_f32_16x16x32_bf16 v[64:67], v[180:183], v[212:215], 0
	v_mfma_f32_16x16x32_bf16 v[116:119], v[176:179], v[192:195], v[116:119]
	v_mfma_f32_16x16x32_bf16 v[112:115], v[184:187], v[192:195], v[112:115]
	v_mfma_f32_16x16x32_bf16 v[100:103], v[176:179], v[200:203], v[100:103]
	v_mfma_f32_16x16x32_bf16 v[96:99], v[184:187], v[200:203], v[96:99]
	v_mfma_f32_16x16x32_bf16 v[84:87], v[176:179], v[208:211], v[84:87]
	v_mfma_f32_16x16x32_bf16 v[80:83], v[184:187], v[208:211], v[80:83]
	v_mfma_f32_16x16x32_bf16 v[68:71], v[176:179], v[216:219], v[68:71]
	v_mfma_f32_16x16x32_bf16 v[64:67], v[184:187], v[216:219], v[64:67]
	s_setprio 0
	s_barrier
	s_add_i32 s34, s82, s57
	v_lshl_add_u64 v[220:221], s[52:53], 0, v[134:135]
	s_mov_b32 m0, s34
	ds_read_b128 v[188:191], v157 offset:16384
	ds_read_b128 v[192:195], v157 offset:17408
	ds_read_b128 v[196:199], v157 offset:18432
	ds_read_b128 v[200:203], v157 offset:19456
	ds_read_b128 v[204:207], v157 offset:20480
	ds_read_b128 v[208:211], v157 offset:21504
	ds_read_b128 v[212:215], v157 offset:22528
	ds_read_b128 v[216:219], v157 offset:23552
	global_load_lds_dwordx4 v[220:221], off
	s_add_i32 m0, s34, 0x2000
	s_add_u32 s34, s52, 0x40000
	v_lshl_add_u64 v[222:223], s[52:53], 0, v[138:139]
	s_addc_u32 s35, s53, 0
	s_add_i32 s86, s83, s57
	global_load_lds_dwordx4 v[222:223], off
	v_lshl_add_u64 v[224:225], s[34:35], 0, v[134:135]
	s_mov_b32 m0, s86
	v_lshl_add_u64 v[226:227], s[54:55], 0, v[136:137]
	global_load_lds_dwordx4 v[224:225], off
	v_lshl_add_u64 v[224:225], s[34:35], 0, v[138:139]
	s_add_i32 m0, s86, 0x2000
	s_nop 0
	global_load_lds_dwordx4 v[224:225], off
	v_lshl_add_u64 v[224:225], s[54:55], 0, v[132:133]
	s_mov_b32 m0, s58
	s_nop 0
	global_load_lds_dwordx4 v[224:225], off
	s_mov_b32 m0, s59
	s_nop 0
	global_load_lds_dwordx4 v[226:227], off
	s_waitcnt vmcnt(8)
	s_waitcnt lgkmcnt(0)
	s_barrier
	s_setprio 1
	s_waitcnt lgkmcnt(0)
	v_mfma_f32_16x16x32_bf16 v[60:63], v[148:151], v[188:191], 0
	v_mfma_f32_16x16x32_bf16 v[56:59], v[164:167], v[188:191], 0
	v_mfma_f32_16x16x32_bf16 v[44:47], v[148:151], v[196:199], 0
	v_mfma_f32_16x16x32_bf16 v[40:43], v[164:167], v[196:199], 0
	v_mfma_f32_16x16x32_bf16 v[28:31], v[148:151], v[204:207], 0
	v_mfma_f32_16x16x32_bf16 v[24:27], v[164:167], v[204:207], 0
	v_mfma_f32_16x16x32_bf16 v[12:15], v[148:151], v[212:215], 0
	v_mfma_f32_16x16x32_bf16 v[8:11], v[164:167], v[212:215], 0
	v_mfma_f32_16x16x32_bf16 v[60:63], v[160:163], v[192:195], v[60:63]
	v_mfma_f32_16x16x32_bf16 v[56:59], v[168:171], v[192:195], v[56:59]
	v_mfma_f32_16x16x32_bf16 v[44:47], v[160:163], v[200:203], v[44:47]
	v_mfma_f32_16x16x32_bf16 v[40:43], v[168:171], v[200:203], v[40:43]
	v_mfma_f32_16x16x32_bf16 v[28:31], v[160:163], v[208:211], v[28:31]
	v_mfma_f32_16x16x32_bf16 v[24:27], v[168:171], v[208:211], v[24:27]
	v_mfma_f32_16x16x32_bf16 v[12:15], v[160:163], v[216:219], v[12:15]
	v_mfma_f32_16x16x32_bf16 v[8:11], v[168:171], v[216:219], v[8:11]
	s_setprio 0
	s_setprio 1
	v_mfma_f32_16x16x32_bf16 v[52:55], v[172:175], v[188:191], 0
	v_mfma_f32_16x16x32_bf16 v[48:51], v[180:183], v[188:191], 0
	v_mfma_f32_16x16x32_bf16 v[36:39], v[172:175], v[196:199], 0
	v_mfma_f32_16x16x32_bf16 v[32:35], v[180:183], v[196:199], 0
	v_mfma_f32_16x16x32_bf16 v[20:23], v[172:175], v[204:207], 0
	v_mfma_f32_16x16x32_bf16 v[16:19], v[180:183], v[204:207], 0
	v_mfma_f32_16x16x32_bf16 v[4:7], v[172:175], v[212:215], 0
	v_mfma_f32_16x16x32_bf16 v[0:3], v[180:183], v[212:215], 0
	v_mfma_f32_16x16x32_bf16 v[52:55], v[176:179], v[192:195], v[52:55]
	v_mfma_f32_16x16x32_bf16 v[48:51], v[184:187], v[192:195], v[48:51]
	v_mfma_f32_16x16x32_bf16 v[36:39], v[176:179], v[200:203], v[36:39]
	v_mfma_f32_16x16x32_bf16 v[32:35], v[184:187], v[200:203], v[32:35]
	v_mfma_f32_16x16x32_bf16 v[20:23], v[176:179], v[208:211], v[20:23]
	v_mfma_f32_16x16x32_bf16 v[16:19], v[184:187], v[208:211], v[16:19]
	v_mfma_f32_16x16x32_bf16 v[4:7], v[176:179], v[216:219], v[4:7]
	v_mfma_f32_16x16x32_bf16 v[0:3], v[184:187], v[216:219], v[0:3]
	s_setprio 0
	s_barrier
	s_add_i32 s86, 0, 0x18000
	v_add_u32_e32 v159, s86, v152
	s_add_i32 s87, 0, 0x1c000
	ds_read_b128 v[148:151], v159
	ds_read_b128 v[160:163], v159 offset:1024
	ds_read_b128 v[164:167], v159 offset:2048
	ds_read_b128 v[168:171], v159 offset:3072
	v_add_u32_e32 v159, s87, v152
	ds_read_b128 v[172:175], v159
	ds_read_b128 v[176:179], v159 offset:1024
	ds_read_b128 v[180:183], v159 offset:2048
	ds_read_b128 v[184:187], v159 offset:3072
	s_add_u32 s34, s54, 0x40000
	s_addc_u32 s35, s55, 0
	s_mov_b32 m0, s62
	v_lshl_add_u64 v[228:229], s[34:35], 0, v[132:133]
	ds_read_b128 v[188:191], v157 offset:32768
	ds_read_b128 v[192:195], v157 offset:33792
	ds_read_b128 v[196:199], v157 offset:34816
	ds_read_b128 v[200:203], v157 offset:35840
	ds_read_b128 v[204:207], v157 offset:36864
	ds_read_b128 v[208:211], v157 offset:37888
	ds_read_b128 v[212:215], v157 offset:38912
	ds_read_b128 v[216:219], v157 offset:39936
	global_load_lds_dwordx4 v[228:229], off
	v_lshl_add_u64 v[228:229], s[34:35], 0, v[136:137]
	s_mov_b32 m0, s63
	s_nop 0
	global_load_lds_dwordx4 v[228:229], off
	s_waitcnt vmcnt(8)
	s_waitcnt lgkmcnt(0)
	s_barrier
	s_setprio 1
	s_waitcnt lgkmcnt(0)
	v_mfma_f32_16x16x32_bf16 v[124:127], v[148:151], v[188:191], v[124:127]
	v_mfma_f32_16x16x32_bf16 v[120:123], v[164:167], v[188:191], v[120:123]
	v_mfma_f32_16x16x32_bf16 v[108:111], v[148:151], v[196:199], v[108:111]
	v_mfma_f32_16x16x32_bf16 v[104:107], v[164:167], v[196:199], v[104:107]
	v_mfma_f32_16x16x32_bf16 v[92:95], v[148:151], v[204:207], v[92:95]
	v_mfma_f32_16x16x32_bf16 v[88:91], v[164:167], v[204:207], v[88:91]
	v_mfma_f32_16x16x32_bf16 v[76:79], v[148:151], v[212:215], v[76:79]
	v_mfma_f32_16x16x32_bf16 v[72:75], v[164:167], v[212:215], v[72:75]
	v_mfma_f32_16x16x32_bf16 v[124:127], v[160:163], v[192:195], v[124:127]
	v_mfma_f32_16x16x32_bf16 v[120:123], v[168:171], v[192:195], v[120:123]
	v_mfma_f32_16x16x32_bf16 v[108:111], v[160:163], v[200:203], v[108:111]
	v_mfma_f32_16x16x32_bf16 v[104:107], v[168:171], v[200:203], v[104:107]
	v_mfma_f32_16x16x32_bf16 v[92:95], v[160:163], v[208:211], v[92:95]
	v_mfma_f32_16x16x32_bf16 v[88:91], v[168:171], v[208:211], v[88:91]
	v_mfma_f32_16x16x32_bf16 v[76:79], v[160:163], v[216:219], v[76:79]
	v_mfma_f32_16x16x32_bf16 v[72:75], v[168:171], v[216:219], v[72:75]
	s_setprio 0
	s_setprio 1
	v_mfma_f32_16x16x32_bf16 v[116:119], v[172:175], v[188:191], v[116:119]
	v_mfma_f32_16x16x32_bf16 v[112:115], v[180:183], v[188:191], v[112:115]
	v_mfma_f32_16x16x32_bf16 v[100:103], v[172:175], v[196:199], v[100:103]
	v_mfma_f32_16x16x32_bf16 v[96:99], v[180:183], v[196:199], v[96:99]
	v_mfma_f32_16x16x32_bf16 v[84:87], v[172:175], v[204:207], v[84:87]
	v_mfma_f32_16x16x32_bf16 v[80:83], v[180:183], v[204:207], v[80:83]
	v_mfma_f32_16x16x32_bf16 v[68:71], v[172:175], v[212:215], v[68:71]
	v_mfma_f32_16x16x32_bf16 v[64:67], v[180:183], v[212:215], v[64:67]
	v_mfma_f32_16x16x32_bf16 v[116:119], v[176:179], v[192:195], v[116:119]
	v_mfma_f32_16x16x32_bf16 v[112:115], v[184:187], v[192:195], v[112:115]
	v_mfma_f32_16x16x32_bf16 v[100:103], v[176:179], v[200:203], v[100:103]
	v_mfma_f32_16x16x32_bf16 v[96:99], v[184:187], v[200:203], v[96:99]
	v_mfma_f32_16x16x32_bf16 v[84:87], v[176:179], v[208:211], v[84:87]
	v_mfma_f32_16x16x32_bf16 v[80:83], v[184:187], v[208:211], v[80:83]
	v_mfma_f32_16x16x32_bf16 v[68:71], v[176:179], v[216:219], v[68:71]
	v_mfma_f32_16x16x32_bf16 v[64:67], v[184:187], v[216:219], v[64:67]
	s_setprio 0
	s_barrier
	s_add_i32 s34, s86, s57
	v_lshl_add_u64 v[220:221], v[220:221], 0, s[10:11]
	s_mov_b32 m0, s34
	ds_read_b128 v[188:191], v157 offset:49152
	ds_read_b128 v[192:195], v157 offset:50176
	ds_read_b128 v[196:199], v157 offset:51200
	ds_read_b128 v[200:203], v157 offset:52224
	ds_read_b128 v[204:207], v157 offset:53248
	ds_read_b128 v[208:211], v157 offset:54272
	ds_read_b128 v[212:215], v157 offset:55296
	ds_read_b128 v[216:219], v157 offset:56320
	global_load_lds_dwordx4 v[220:221], off
	s_add_i32 m0, s34, 0x2000
	s_add_u32 s34, s52, 0x40080
	v_lshl_add_u64 v[220:221], v[222:223], 0, s[10:11]
	s_addc_u32 s35, s53, 0
	s_add_i32 s52, s87, s57
	global_load_lds_dwordx4 v[220:221], off
	v_lshl_add_u64 v[220:221], s[34:35], 0, v[134:135]
	s_mov_b32 m0, s52
	s_nop 0
	global_load_lds_dwordx4 v[220:221], off
	v_lshl_add_u64 v[220:221], s[34:35], 0, v[138:139]
	s_add_i32 m0, s52, 0x2000
	s_nop 0
	global_load_lds_dwordx4 v[220:221], off
	v_lshl_add_u64 v[220:221], v[224:225], 0, s[10:11]
	s_mov_b32 m0, s65
	s_nop 0
	global_load_lds_dwordx4 v[220:221], off
	v_lshl_add_u64 v[220:221], v[226:227], 0, s[10:11]
	s_mov_b32 m0, s66
	s_nop 0
	global_load_lds_dwordx4 v[220:221], off
	s_waitcnt vmcnt(8)
	s_waitcnt lgkmcnt(0)
	s_barrier
	s_add_u32 s50, s50, 0x100
	s_addc_u32 s51, s51, 0
	s_add_u32 s49, s49, 0x100
	s_addc_u32 s77, s77, 0
	s_setprio 1
	s_waitcnt lgkmcnt(0)
	v_mfma_f32_16x16x32_bf16 v[60:63], v[148:151], v[188:191], v[60:63]
	v_mfma_f32_16x16x32_bf16 v[56:59], v[164:167], v[188:191], v[56:59]
	v_mfma_f32_16x16x32_bf16 v[44:47], v[148:151], v[196:199], v[44:47]
	v_mfma_f32_16x16x32_bf16 v[40:43], v[164:167], v[196:199], v[40:43]
	v_mfma_f32_16x16x32_bf16 v[28:31], v[148:151], v[204:207], v[28:31]
	v_mfma_f32_16x16x32_bf16 v[24:27], v[164:167], v[204:207], v[24:27]
	v_mfma_f32_16x16x32_bf16 v[12:15], v[148:151], v[212:215], v[12:15]
	v_mfma_f32_16x16x32_bf16 v[8:11], v[164:167], v[212:215], v[8:11]
	v_mfma_f32_16x16x32_bf16 v[60:63], v[160:163], v[192:195], v[60:63]
	v_mfma_f32_16x16x32_bf16 v[56:59], v[168:171], v[192:195], v[56:59]
	v_mfma_f32_16x16x32_bf16 v[44:47], v[160:163], v[200:203], v[44:47]
	v_mfma_f32_16x16x32_bf16 v[40:43], v[168:171], v[200:203], v[40:43]
	v_mfma_f32_16x16x32_bf16 v[28:31], v[160:163], v[208:211], v[28:31]
	v_mfma_f32_16x16x32_bf16 v[24:27], v[168:171], v[208:211], v[24:27]
	v_mfma_f32_16x16x32_bf16 v[12:15], v[160:163], v[216:219], v[12:15]
	v_mfma_f32_16x16x32_bf16 v[8:11], v[168:171], v[216:219], v[8:11]
	s_setprio 0
	s_setprio 1
	v_mfma_f32_16x16x32_bf16 v[52:55], v[172:175], v[188:191], v[52:55]
	v_mfma_f32_16x16x32_bf16 v[48:51], v[180:183], v[188:191], v[48:51]
	v_mfma_f32_16x16x32_bf16 v[36:39], v[172:175], v[196:199], v[36:39]
	v_mfma_f32_16x16x32_bf16 v[32:35], v[180:183], v[196:199], v[32:35]
	v_mfma_f32_16x16x32_bf16 v[20:23], v[172:175], v[204:207], v[20:23]
	v_mfma_f32_16x16x32_bf16 v[16:19], v[180:183], v[204:207], v[16:19]
	v_mfma_f32_16x16x32_bf16 v[4:7], v[172:175], v[212:215], v[4:7]
	v_mfma_f32_16x16x32_bf16 v[0:3], v[180:183], v[212:215], v[0:3]
	v_mfma_f32_16x16x32_bf16 v[52:55], v[176:179], v[192:195], v[52:55]
	v_mfma_f32_16x16x32_bf16 v[48:51], v[184:187], v[192:195], v[48:51]
	v_mfma_f32_16x16x32_bf16 v[36:39], v[176:179], v[200:203], v[36:39]
	v_mfma_f32_16x16x32_bf16 v[32:35], v[184:187], v[200:203], v[32:35]
	v_mfma_f32_16x16x32_bf16 v[20:23], v[176:179], v[208:211], v[20:23]
	v_mfma_f32_16x16x32_bf16 v[16:19], v[184:187], v[208:211], v[16:19]
	v_mfma_f32_16x16x32_bf16 v[4:7], v[176:179], v[216:219], v[4:7]
	v_mfma_f32_16x16x32_bf16 v[0:3], v[184:187], v[216:219], v[0:3]
	s_setprio 0
	s_add_i32 s85, s85, 2
.LBB0_386:
	s_barrier
	ds_read_b128 v[148:151], v154
	ds_read_b128 v[160:163], v154 offset:1024
	ds_read_b128 v[164:167], v154 offset:2048
	ds_read_b128 v[168:171], v154 offset:3072
	ds_read_b128 v[172:175], v155
	ds_read_b128 v[176:179], v155 offset:1024
	ds_read_b128 v[180:183], v155 offset:2048
	ds_read_b128 v[184:187], v155 offset:3072
	s_add_u32 s34, s50, 0xfffc0080
	s_addc_u32 s35, s51, -1
	s_cmp_eq_u32 s85, 12
	s_cselect_b32 s55, s12, s35
	s_cselect_b32 s54, s13, s34
	s_cselect_b32 s53, s27, s77
	s_cselect_b32 s52, s29, s49
	v_lshl_add_u64 v[220:221], s[50:51], 0, v[140:141]
	s_add_i32 m0, s58, 0xc000
	ds_read_b128 v[188:191], v157
	ds_read_b128 v[192:195], v157 offset:1024
	ds_read_b128 v[196:199], v157 offset:2048
	ds_read_b128 v[200:203], v157 offset:3072
	ds_read_b128 v[204:207], v157 offset:4096
	ds_read_b128 v[208:211], v157 offset:5120
	ds_read_b128 v[212:215], v157 offset:6144
	ds_read_b128 v[216:219], v157 offset:7168
	global_load_lds_dwordx4 v[220:221], off
	v_lshl_add_u64 v[220:221], s[50:51], 0, v[142:143]
	s_add_i32 m0, s58, 0xe000
	s_nop 0
	global_load_lds_dwordx4 v[220:221], off
	s_waitcnt vmcnt(8)
	s_waitcnt lgkmcnt(0)
	s_barrier
	s_setprio 1
	s_waitcnt lgkmcnt(0)
	v_mfma_f32_16x16x32_bf16 v[124:127], v[148:151], v[188:191], v[124:127]
	v_mfma_f32_16x16x32_bf16 v[120:123], v[164:167], v[188:191], v[120:123]
	v_mfma_f32_16x16x32_bf16 v[108:111], v[148:151], v[196:199], v[108:111]
	v_mfma_f32_16x16x32_bf16 v[104:107], v[164:167], v[196:199], v[104:107]
	v_mfma_f32_16x16x32_bf16 v[92:95], v[148:151], v[204:207], v[92:95]
	v_mfma_f32_16x16x32_bf16 v[88:91], v[164:167], v[204:207], v[88:91]
	v_mfma_f32_16x16x32_bf16 v[76:79], v[148:151], v[212:215], v[76:79]
	v_mfma_f32_16x16x32_bf16 v[72:75], v[164:167], v[212:215], v[72:75]
	v_mfma_f32_16x16x32_bf16 v[124:127], v[160:163], v[192:195], v[124:127]
	v_mfma_f32_16x16x32_bf16 v[120:123], v[168:171], v[192:195], v[120:123]
	v_mfma_f32_16x16x32_bf16 v[108:111], v[160:163], v[200:203], v[108:111]
	v_mfma_f32_16x16x32_bf16 v[104:107], v[168:171], v[200:203], v[104:107]
	v_mfma_f32_16x16x32_bf16 v[92:95], v[160:163], v[208:211], v[92:95]
	v_mfma_f32_16x16x32_bf16 v[88:91], v[168:171], v[208:211], v[88:91]
	v_mfma_f32_16x16x32_bf16 v[76:79], v[160:163], v[216:219], v[76:79]
	v_mfma_f32_16x16x32_bf16 v[72:75], v[168:171], v[216:219], v[72:75]
	s_setprio 0
	s_setprio 1
	v_mfma_f32_16x16x32_bf16 v[116:119], v[172:175], v[188:191], v[116:119]
	v_mfma_f32_16x16x32_bf16 v[112:115], v[180:183], v[188:191], v[112:115]
	v_mfma_f32_16x16x32_bf16 v[100:103], v[172:175], v[196:199], v[100:103]
	v_mfma_f32_16x16x32_bf16 v[96:99], v[180:183], v[196:199], v[96:99]
	v_mfma_f32_16x16x32_bf16 v[84:87], v[172:175], v[204:207], v[84:87]
	v_mfma_f32_16x16x32_bf16 v[80:83], v[180:183], v[204:207], v[80:83]
	v_mfma_f32_16x16x32_bf16 v[68:71], v[172:175], v[212:215], v[68:71]
	v_mfma_f32_16x16x32_bf16 v[64:67], v[180:183], v[212:215], v[64:67]
	v_mfma_f32_16x16x32_bf16 v[116:119], v[176:179], v[192:195], v[116:119]
	v_mfma_f32_16x16x32_bf16 v[112:115], v[184:187], v[192:195], v[112:115]
	v_mfma_f32_16x16x32_bf16 v[100:103], v[176:179], v[200:203], v[100:103]
	v_mfma_f32_16x16x32_bf16 v[96:99], v[184:187], v[200:203], v[96:99]
	v_mfma_f32_16x16x32_bf16 v[84:87], v[176:179], v[208:211], v[84:87]
	v_mfma_f32_16x16x32_bf16 v[80:83], v[184:187], v[208:211], v[80:83]
	v_mfma_f32_16x16x32_bf16 v[68:71], v[176:179], v[216:219], v[68:71]
	v_mfma_f32_16x16x32_bf16 v[64:67], v[184:187], v[216:219], v[64:67]
	s_setprio 0
	s_barrier
	s_add_i32 s34, s82, s57
	v_lshl_add_u64 v[220:221], s[52:53], 0, v[134:135]
	s_mov_b32 m0, s34
	ds_read_b128 v[188:191], v157 offset:16384
	ds_read_b128 v[192:195], v157 offset:17408
	ds_read_b128 v[196:199], v157 offset:18432
	ds_read_b128 v[200:203], v157 offset:19456
	ds_read_b128 v[204:207], v157 offset:20480
	ds_read_b128 v[208:211], v157 offset:21504
	ds_read_b128 v[212:215], v157 offset:22528
	ds_read_b128 v[216:219], v157 offset:23552
	global_load_lds_dwordx4 v[220:221], off
	s_add_i32 m0, s34, 0x2000
	s_add_u32 s34, s52, 0x40000
	v_lshl_add_u64 v[222:223], s[52:53], 0, v[138:139]
	s_addc_u32 s35, s53, 0
	s_add_i32 s86, s83, s57
	global_load_lds_dwordx4 v[222:223], off
	v_lshl_add_u64 v[224:225], s[34:35], 0, v[134:135]
	s_mov_b32 m0, s86
	v_lshl_add_u64 v[226:227], s[54:55], 0, v[136:137]
	global_load_lds_dwordx4 v[224:225], off
	v_lshl_add_u64 v[224:225], s[34:35], 0, v[138:139]
	s_add_i32 m0, s86, 0x2000
	s_nop 0
	global_load_lds_dwordx4 v[224:225], off
	v_lshl_add_u64 v[224:225], s[54:55], 0, v[132:133]
	s_mov_b32 m0, s58
	s_nop 0
	global_load_lds_dwordx4 v[224:225], off
	s_mov_b32 m0, s59
	s_nop 0
	global_load_lds_dwordx4 v[226:227], off
	s_waitcnt vmcnt(8)
	s_waitcnt lgkmcnt(0)
	s_barrier
	s_setprio 1
	s_waitcnt lgkmcnt(0)
	v_mfma_f32_16x16x32_bf16 v[60:63], v[148:151], v[188:191], v[60:63]
	v_mfma_f32_16x16x32_bf16 v[56:59], v[164:167], v[188:191], v[56:59]
	v_mfma_f32_16x16x32_bf16 v[44:47], v[148:151], v[196:199], v[44:47]
	v_mfma_f32_16x16x32_bf16 v[40:43], v[164:167], v[196:199], v[40:43]
	v_mfma_f32_16x16x32_bf16 v[28:31], v[148:151], v[204:207], v[28:31]
	v_mfma_f32_16x16x32_bf16 v[24:27], v[164:167], v[204:207], v[24:27]
	v_mfma_f32_16x16x32_bf16 v[12:15], v[148:151], v[212:215], v[12:15]
	v_mfma_f32_16x16x32_bf16 v[8:11], v[164:167], v[212:215], v[8:11]
	v_mfma_f32_16x16x32_bf16 v[60:63], v[160:163], v[192:195], v[60:63]
	v_mfma_f32_16x16x32_bf16 v[56:59], v[168:171], v[192:195], v[56:59]
	v_mfma_f32_16x16x32_bf16 v[44:47], v[160:163], v[200:203], v[44:47]
	v_mfma_f32_16x16x32_bf16 v[40:43], v[168:171], v[200:203], v[40:43]
	v_mfma_f32_16x16x32_bf16 v[28:31], v[160:163], v[208:211], v[28:31]
	v_mfma_f32_16x16x32_bf16 v[24:27], v[168:171], v[208:211], v[24:27]
	v_mfma_f32_16x16x32_bf16 v[12:15], v[160:163], v[216:219], v[12:15]
	v_mfma_f32_16x16x32_bf16 v[8:11], v[168:171], v[216:219], v[8:11]
	s_setprio 0
	s_setprio 1
	v_mfma_f32_16x16x32_bf16 v[52:55], v[172:175], v[188:191], v[52:55]
	v_mfma_f32_16x16x32_bf16 v[48:51], v[180:183], v[188:191], v[48:51]
	v_mfma_f32_16x16x32_bf16 v[36:39], v[172:175], v[196:199], v[36:39]
	v_mfma_f32_16x16x32_bf16 v[32:35], v[180:183], v[196:199], v[32:35]
	v_mfma_f32_16x16x32_bf16 v[20:23], v[172:175], v[204:207], v[20:23]
	v_mfma_f32_16x16x32_bf16 v[16:19], v[180:183], v[204:207], v[16:19]
	v_mfma_f32_16x16x32_bf16 v[4:7], v[172:175], v[212:215], v[4:7]
	v_mfma_f32_16x16x32_bf16 v[0:3], v[180:183], v[212:215], v[0:3]
	v_mfma_f32_16x16x32_bf16 v[52:55], v[176:179], v[192:195], v[52:55]
	v_mfma_f32_16x16x32_bf16 v[48:51], v[184:187], v[192:195], v[48:51]
	v_mfma_f32_16x16x32_bf16 v[36:39], v[176:179], v[200:203], v[36:39]
	v_mfma_f32_16x16x32_bf16 v[32:35], v[184:187], v[200:203], v[32:35]
	v_mfma_f32_16x16x32_bf16 v[20:23], v[176:179], v[208:211], v[20:23]
	v_mfma_f32_16x16x32_bf16 v[16:19], v[184:187], v[208:211], v[16:19]
	v_mfma_f32_16x16x32_bf16 v[4:7], v[176:179], v[216:219], v[4:7]
	v_mfma_f32_16x16x32_bf16 v[0:3], v[184:187], v[216:219], v[0:3]
	s_setprio 0
	s_barrier
	s_add_i32 s86, 0, 0x18000
	v_add_u32_e32 v159, s86, v152
	s_add_i32 s87, 0, 0x1c000
	ds_read_b128 v[148:151], v159
	ds_read_b128 v[160:163], v159 offset:1024
	ds_read_b128 v[164:167], v159 offset:2048
	ds_read_b128 v[168:171], v159 offset:3072
	v_add_u32_e32 v159, s87, v152
	ds_read_b128 v[172:175], v159
	ds_read_b128 v[176:179], v159 offset:1024
	ds_read_b128 v[180:183], v159 offset:2048
	ds_read_b128 v[184:187], v159 offset:3072
	s_add_u32 s34, s54, 0x40000
	s_addc_u32 s35, s55, 0
	s_mov_b32 m0, s62
	v_lshl_add_u64 v[228:229], s[34:35], 0, v[132:133]
	ds_read_b128 v[188:191], v157 offset:32768
	ds_read_b128 v[192:195], v157 offset:33792
	ds_read_b128 v[196:199], v157 offset:34816
	ds_read_b128 v[200:203], v157 offset:35840
	ds_read_b128 v[204:207], v157 offset:36864
	ds_read_b128 v[208:211], v157 offset:37888
	ds_read_b128 v[212:215], v157 offset:38912
	ds_read_b128 v[216:219], v157 offset:39936
	global_load_lds_dwordx4 v[228:229], off
	v_lshl_add_u64 v[228:229], s[34:35], 0, v[136:137]
	s_mov_b32 m0, s63
	s_nop 0
	global_load_lds_dwordx4 v[228:229], off
	s_waitcnt vmcnt(8)
	s_waitcnt lgkmcnt(0)
	s_barrier
	s_setprio 1
	s_waitcnt lgkmcnt(0)
	v_mfma_f32_16x16x32_bf16 v[124:127], v[148:151], v[188:191], v[124:127]
	v_mfma_f32_16x16x32_bf16 v[120:123], v[164:167], v[188:191], v[120:123]
	v_mfma_f32_16x16x32_bf16 v[108:111], v[148:151], v[196:199], v[108:111]
	v_mfma_f32_16x16x32_bf16 v[104:107], v[164:167], v[196:199], v[104:107]
	v_mfma_f32_16x16x32_bf16 v[92:95], v[148:151], v[204:207], v[92:95]
	v_mfma_f32_16x16x32_bf16 v[88:91], v[164:167], v[204:207], v[88:91]
	v_mfma_f32_16x16x32_bf16 v[76:79], v[148:151], v[212:215], v[76:79]
	v_mfma_f32_16x16x32_bf16 v[72:75], v[164:167], v[212:215], v[72:75]
	v_mfma_f32_16x16x32_bf16 v[124:127], v[160:163], v[192:195], v[124:127]
	v_mfma_f32_16x16x32_bf16 v[120:123], v[168:171], v[192:195], v[120:123]
	v_mfma_f32_16x16x32_bf16 v[108:111], v[160:163], v[200:203], v[108:111]
	v_mfma_f32_16x16x32_bf16 v[104:107], v[168:171], v[200:203], v[104:107]
	v_mfma_f32_16x16x32_bf16 v[92:95], v[160:163], v[208:211], v[92:95]
	v_mfma_f32_16x16x32_bf16 v[88:91], v[168:171], v[208:211], v[88:91]
	v_mfma_f32_16x16x32_bf16 v[76:79], v[160:163], v[216:219], v[76:79]
	v_mfma_f32_16x16x32_bf16 v[72:75], v[168:171], v[216:219], v[72:75]
	s_setprio 0
	s_setprio 1
	v_mfma_f32_16x16x32_bf16 v[116:119], v[172:175], v[188:191], v[116:119]
	v_mfma_f32_16x16x32_bf16 v[112:115], v[180:183], v[188:191], v[112:115]
	v_mfma_f32_16x16x32_bf16 v[100:103], v[172:175], v[196:199], v[100:103]
	v_mfma_f32_16x16x32_bf16 v[96:99], v[180:183], v[196:199], v[96:99]
	v_mfma_f32_16x16x32_bf16 v[84:87], v[172:175], v[204:207], v[84:87]
	v_mfma_f32_16x16x32_bf16 v[80:83], v[180:183], v[204:207], v[80:83]
	v_mfma_f32_16x16x32_bf16 v[68:71], v[172:175], v[212:215], v[68:71]
	v_mfma_f32_16x16x32_bf16 v[64:67], v[180:183], v[212:215], v[64:67]
	v_mfma_f32_16x16x32_bf16 v[116:119], v[176:179], v[192:195], v[116:119]
	v_mfma_f32_16x16x32_bf16 v[112:115], v[184:187], v[192:195], v[112:115]
	v_mfma_f32_16x16x32_bf16 v[100:103], v[176:179], v[200:203], v[100:103]
	v_mfma_f32_16x16x32_bf16 v[96:99], v[184:187], v[200:203], v[96:99]
	v_mfma_f32_16x16x32_bf16 v[84:87], v[176:179], v[208:211], v[84:87]
	v_mfma_f32_16x16x32_bf16 v[80:83], v[184:187], v[208:211], v[80:83]
	v_mfma_f32_16x16x32_bf16 v[68:71], v[176:179], v[216:219], v[68:71]
	v_mfma_f32_16x16x32_bf16 v[64:67], v[184:187], v[216:219], v[64:67]
	s_setprio 0
	s_barrier
	s_add_i32 s34, s86, s57
	v_lshl_add_u64 v[220:221], v[220:221], 0, s[10:11]
	s_mov_b32 m0, s34
	ds_read_b128 v[188:191], v157 offset:49152
	ds_read_b128 v[192:195], v157 offset:50176
	ds_read_b128 v[196:199], v157 offset:51200
	ds_read_b128 v[200:203], v157 offset:52224
	ds_read_b128 v[204:207], v157 offset:53248
	ds_read_b128 v[208:211], v157 offset:54272
	ds_read_b128 v[212:215], v157 offset:55296
	ds_read_b128 v[216:219], v157 offset:56320
	global_load_lds_dwordx4 v[220:221], off
	s_add_i32 m0, s34, 0x2000
	s_add_u32 s34, s52, 0x40080
	v_lshl_add_u64 v[220:221], v[222:223], 0, s[10:11]
	s_addc_u32 s35, s53, 0
	s_add_i32 s52, s87, s57
	global_load_lds_dwordx4 v[220:221], off
	v_lshl_add_u64 v[220:221], s[34:35], 0, v[134:135]
	s_mov_b32 m0, s52
	s_nop 0
	global_load_lds_dwordx4 v[220:221], off
	v_lshl_add_u64 v[220:221], s[34:35], 0, v[138:139]
	s_add_i32 m0, s52, 0x2000
	s_nop 0
	global_load_lds_dwordx4 v[220:221], off
	v_lshl_add_u64 v[220:221], v[224:225], 0, s[10:11]
	s_mov_b32 m0, s65
	s_nop 0
	global_load_lds_dwordx4 v[220:221], off
	v_lshl_add_u64 v[220:221], v[226:227], 0, s[10:11]
	s_mov_b32 m0, s66
	s_nop 0
	global_load_lds_dwordx4 v[220:221], off
	s_waitcnt vmcnt(8)
	s_waitcnt lgkmcnt(0)
	s_barrier
	s_add_u32 s50, s50, 0x100
	s_addc_u32 s51, s51, 0
	s_add_u32 s49, s49, 0x100
	s_addc_u32 s77, s77, 0
	s_setprio 1
	s_waitcnt lgkmcnt(0)
	v_mfma_f32_16x16x32_bf16 v[60:63], v[148:151], v[188:191], v[60:63]
	v_mfma_f32_16x16x32_bf16 v[56:59], v[164:167], v[188:191], v[56:59]
	v_mfma_f32_16x16x32_bf16 v[44:47], v[148:151], v[196:199], v[44:47]
	v_mfma_f32_16x16x32_bf16 v[40:43], v[164:167], v[196:199], v[40:43]
	v_mfma_f32_16x16x32_bf16 v[28:31], v[148:151], v[204:207], v[28:31]
	v_mfma_f32_16x16x32_bf16 v[24:27], v[164:167], v[204:207], v[24:27]
	v_mfma_f32_16x16x32_bf16 v[12:15], v[148:151], v[212:215], v[12:15]
	v_mfma_f32_16x16x32_bf16 v[8:11], v[164:167], v[212:215], v[8:11]
	v_mfma_f32_16x16x32_bf16 v[60:63], v[160:163], v[192:195], v[60:63]
	v_mfma_f32_16x16x32_bf16 v[56:59], v[168:171], v[192:195], v[56:59]
	v_mfma_f32_16x16x32_bf16 v[44:47], v[160:163], v[200:203], v[44:47]
	v_mfma_f32_16x16x32_bf16 v[40:43], v[168:171], v[200:203], v[40:43]
	v_mfma_f32_16x16x32_bf16 v[28:31], v[160:163], v[208:211], v[28:31]
	v_mfma_f32_16x16x32_bf16 v[24:27], v[168:171], v[208:211], v[24:27]
	v_mfma_f32_16x16x32_bf16 v[12:15], v[160:163], v[216:219], v[12:15]
	v_mfma_f32_16x16x32_bf16 v[8:11], v[168:171], v[216:219], v[8:11]
	s_setprio 0
	s_setprio 1
	v_mfma_f32_16x16x32_bf16 v[52:55], v[172:175], v[188:191], v[52:55]
	v_mfma_f32_16x16x32_bf16 v[48:51], v[180:183], v[188:191], v[48:51]
	v_mfma_f32_16x16x32_bf16 v[36:39], v[172:175], v[196:199], v[36:39]
	v_mfma_f32_16x16x32_bf16 v[32:35], v[180:183], v[196:199], v[32:35]
	v_mfma_f32_16x16x32_bf16 v[20:23], v[172:175], v[204:207], v[20:23]
	v_mfma_f32_16x16x32_bf16 v[16:19], v[180:183], v[204:207], v[16:19]
	v_mfma_f32_16x16x32_bf16 v[4:7], v[172:175], v[212:215], v[4:7]
	v_mfma_f32_16x16x32_bf16 v[0:3], v[180:183], v[212:215], v[0:3]
	v_mfma_f32_16x16x32_bf16 v[52:55], v[176:179], v[192:195], v[52:55]
	v_mfma_f32_16x16x32_bf16 v[48:51], v[184:187], v[192:195], v[48:51]
	v_mfma_f32_16x16x32_bf16 v[36:39], v[176:179], v[200:203], v[36:39]
	v_mfma_f32_16x16x32_bf16 v[32:35], v[184:187], v[200:203], v[32:35]
	v_mfma_f32_16x16x32_bf16 v[20:23], v[176:179], v[208:211], v[20:23]
	v_mfma_f32_16x16x32_bf16 v[16:19], v[184:187], v[208:211], v[16:19]
	v_mfma_f32_16x16x32_bf16 v[4:7], v[176:179], v[216:219], v[4:7]
	v_mfma_f32_16x16x32_bf16 v[0:3], v[184:187], v[216:219], v[0:3]
	s_setprio 0
	s_add_i32 s85, s85, 2
	s_cmp_gt_u32 s85, 13
	s_cbranch_scc0 .LBB0_386
	s_sub_i32 s100, s85, 2
	s_cmp_eq_u32 s100, s98
	s_cbranch_scc1 .Lmy_nobar_4
	s_barrier
.Lmy_nobar_4:
	s_and_b64 vcc, exec, s[22:23]
	s_cbranch_vccz .LBB0_389
	s_nop 0

.Lmy_nobar2_5:
	ds_read_b128 v[148:151], v155
	ds_read_b128 v[160:163], v155 offset:1024
	ds_read_b128 v[164:167], v155 offset:2048
	ds_read_b128 v[168:171], v155 offset:3072
	ds_read_b128 v[172:175], v157
	ds_read_b128 v[176:179], v157 offset:1024
	ds_read_b128 v[180:183], v157 offset:2048
	ds_read_b128 v[184:187], v157 offset:3072
	s_add_u32 s34, s42, 0xfffc0080
	s_addc_u32 s35, s43, -1
	s_cmp_eq_u32 s85, 12
	s_cselect_b32 s51, s23, s35
	s_cselect_b32 s50, s81, s34
	s_cselect_b32 s49, s11, s84
	s_cselect_b32 s48, s82, s83
	v_lshl_add_u64 v[220:221], s[42:43], 0, v[140:141]
	s_add_i32 m0, s41, 0xc000
	ds_read_b128 v[188:191], v158
	ds_read_b128 v[192:195], v158 offset:1024
	ds_read_b128 v[196:199], v158 offset:2048
	ds_read_b128 v[200:203], v158 offset:3072
	ds_read_b128 v[204:207], v158 offset:4096
	ds_read_b128 v[208:211], v158 offset:5120
	ds_read_b128 v[212:215], v158 offset:6144
	ds_read_b128 v[216:219], v158 offset:7168
	global_load_lds_dwordx4 v[220:221], off
	v_lshl_add_u64 v[220:221], s[42:43], 0, v[142:143]
	s_add_i32 m0, s41, 0xe000
	s_nop 0
	global_load_lds_dwordx4 v[220:221], off
	s_waitcnt vmcnt(8)
	s_waitcnt lgkmcnt(0)
	s_barrier
	s_setprio 1
	s_waitcnt lgkmcnt(0)
	v_mfma_f32_16x16x32_bf16 v[124:127], v[148:151], v[188:191], 0
	v_mfma_f32_16x16x32_bf16 v[120:123], v[164:167], v[188:191], 0
	v_mfma_f32_16x16x32_bf16 v[108:111], v[148:151], v[196:199], 0
	v_mfma_f32_16x16x32_bf16 v[104:107], v[164:167], v[196:199], 0
	v_mfma_f32_16x16x32_bf16 v[92:95], v[148:151], v[204:207], 0
	v_mfma_f32_16x16x32_bf16 v[88:91], v[164:167], v[204:207], 0
	v_mfma_f32_16x16x32_bf16 v[76:79], v[148:151], v[212:215], 0
	v_mfma_f32_16x16x32_bf16 v[72:75], v[164:167], v[212:215], 0
	v_mfma_f32_16x16x32_bf16 v[124:127], v[160:163], v[192:195], v[124:127]
	v_mfma_f32_16x16x32_bf16 v[120:123], v[168:171], v[192:195], v[120:123]
	v_mfma_f32_16x16x32_bf16 v[108:111], v[160:163], v[200:203], v[108:111]
	v_mfma_f32_16x16x32_bf16 v[104:107], v[168:171], v[200:203], v[104:107]
	v_mfma_f32_16x16x32_bf16 v[92:95], v[160:163], v[208:211], v[92:95]
	v_mfma_f32_16x16x32_bf16 v[88:91], v[168:171], v[208:211], v[88:91]
	v_mfma_f32_16x16x32_bf16 v[76:79], v[160:163], v[216:219], v[76:79]
	v_mfma_f32_16x16x32_bf16 v[72:75], v[168:171], v[216:219], v[72:75]
	s_setprio 0
	s_setprio 1
	v_mfma_f32_16x16x32_bf16 v[116:119], v[172:175], v[188:191], 0
	v_mfma_f32_16x16x32_bf16 v[112:115], v[180:183], v[188:191], 0
	v_mfma_f32_16x16x32_bf16 v[100:103], v[172:175], v[196:199], 0
	v_mfma_f32_16x16x32_bf16 v[96:99], v[180:183], v[196:199], 0
	v_mfma_f32_16x16x32_bf16 v[84:87], v[172:175], v[204:207], 0
	v_mfma_f32_16x16x32_bf16 v[80:83], v[180:183], v[204:207], 0
	v_mfma_f32_16x16x32_bf16 v[68:71], v[172:175], v[212:215], 0
	v_mfma_f32_16x16x32_bf16 v[64:67], v[180:183], v[212:215], 0
	v_mfma_f32_16x16x32_bf16 v[116:119], v[176:179], v[192:195], v[116:119]
	v_mfma_f32_16x16x32_bf16 v[112:115], v[184:187], v[192:195], v[112:115]
	v_mfma_f32_16x16x32_bf16 v[100:103], v[176:179], v[200:203], v[100:103]
	v_mfma_f32_16x16x32_bf16 v[96:99], v[184:187], v[200:203], v[96:99]
	v_mfma_f32_16x16x32_bf16 v[84:87], v[176:179], v[208:211], v[84:87]
	v_mfma_f32_16x16x32_bf16 v[80:83], v[184:187], v[208:211], v[80:83]
	v_mfma_f32_16x16x32_bf16 v[68:71], v[176:179], v[216:219], v[68:71]
	v_mfma_f32_16x16x32_bf16 v[64:67], v[184:187], v[216:219], v[64:67]
	s_setprio 0
	s_barrier
	s_add_i32 s34, s65, s54
	v_lshl_add_u64 v[220:221], s[48:49], 0, v[136:137]
	s_mov_b32 m0, s34
	ds_read_b128 v[188:191], v158 offset:16384
	ds_read_b128 v[192:195], v158 offset:17408
	ds_read_b128 v[196:199], v158 offset:18432
	ds_read_b128 v[200:203], v158 offset:19456
	ds_read_b128 v[204:207], v158 offset:20480
	ds_read_b128 v[208:211], v158 offset:21504
	ds_read_b128 v[212:215], v158 offset:22528
	ds_read_b128 v[216:219], v158 offset:23552
	global_load_lds_dwordx4 v[220:221], off
	s_add_i32 m0, s34, 0x2000
	s_add_u32 s34, s48, 0x40000
	v_lshl_add_u64 v[222:223], s[48:49], 0, v[132:133]
	s_addc_u32 s35, s49, 0
	s_add_i32 s86, s66, s54
	global_load_lds_dwordx4 v[222:223], off
	v_lshl_add_u64 v[224:225], s[34:35], 0, v[136:137]
	s_mov_b32 m0, s86
	v_lshl_add_u64 v[226:227], s[50:51], 0, v[134:135]
	global_load_lds_dwordx4 v[224:225], off
	v_lshl_add_u64 v[224:225], s[34:35], 0, v[132:133]
	s_add_i32 m0, s86, 0x2000
	s_nop 0
	global_load_lds_dwordx4 v[224:225], off
	v_lshl_add_u64 v[224:225], s[50:51], 0, v[138:139]
	s_mov_b32 m0, s41
	s_nop 0
	global_load_lds_dwordx4 v[224:225], off
	s_mov_b32 m0, s58
	s_nop 0
	global_load_lds_dwordx4 v[226:227], off
	s_waitcnt vmcnt(8)
	s_waitcnt lgkmcnt(0)
	s_barrier
	s_setprio 1
	s_waitcnt lgkmcnt(0)
	v_mfma_f32_16x16x32_bf16 v[60:63], v[148:151], v[188:191], 0
	v_mfma_f32_16x16x32_bf16 v[56:59], v[164:167], v[188:191], 0
	v_mfma_f32_16x16x32_bf16 v[44:47], v[148:151], v[196:199], 0
	v_mfma_f32_16x16x32_bf16 v[40:43], v[164:167], v[196:199], 0
	v_mfma_f32_16x16x32_bf16 v[28:31], v[148:151], v[204:207], 0
	v_mfma_f32_16x16x32_bf16 v[24:27], v[164:167], v[204:207], 0
	v_mfma_f32_16x16x32_bf16 v[12:15], v[148:151], v[212:215], 0
	v_mfma_f32_16x16x32_bf16 v[8:11], v[164:167], v[212:215], 0
	v_mfma_f32_16x16x32_bf16 v[60:63], v[160:163], v[192:195], v[60:63]
	v_mfma_f32_16x16x32_bf16 v[56:59], v[168:171], v[192:195], v[56:59]
	v_mfma_f32_16x16x32_bf16 v[44:47], v[160:163], v[200:203], v[44:47]
	v_mfma_f32_16x16x32_bf16 v[40:43], v[168:171], v[200:203], v[40:43]
	v_mfma_f32_16x16x32_bf16 v[28:31], v[160:163], v[208:211], v[28:31]
	v_mfma_f32_16x16x32_bf16 v[24:27], v[168:171], v[208:211], v[24:27]
	v_mfma_f32_16x16x32_bf16 v[12:15], v[160:163], v[216:219], v[12:15]
	v_mfma_f32_16x16x32_bf16 v[8:11], v[168:171], v[216:219], v[8:11]
	s_setprio 0
	s_setprio 1
	v_mfma_f32_16x16x32_bf16 v[52:55], v[172:175], v[188:191], 0
	v_mfma_f32_16x16x32_bf16 v[48:51], v[180:183], v[188:191], 0
	v_mfma_f32_16x16x32_bf16 v[36:39], v[172:175], v[196:199], 0
	v_mfma_f32_16x16x32_bf16 v[32:35], v[180:183], v[196:199], 0
	v_mfma_f32_16x16x32_bf16 v[20:23], v[172:175], v[204:207], 0
	v_mfma_f32_16x16x32_bf16 v[16:19], v[180:183], v[204:207], 0
	v_mfma_f32_16x16x32_bf16 v[4:7], v[172:175], v[212:215], 0
	v_mfma_f32_16x16x32_bf16 v[0:3], v[180:183], v[212:215], 0
	v_mfma_f32_16x16x32_bf16 v[52:55], v[176:179], v[192:195], v[52:55]
	v_mfma_f32_16x16x32_bf16 v[48:51], v[184:187], v[192:195], v[48:51]
	v_mfma_f32_16x16x32_bf16 v[36:39], v[176:179], v[200:203], v[36:39]
	v_mfma_f32_16x16x32_bf16 v[32:35], v[184:187], v[200:203], v[32:35]
	v_mfma_f32_16x16x32_bf16 v[20:23], v[176:179], v[208:211], v[20:23]
	v_mfma_f32_16x16x32_bf16 v[16:19], v[184:187], v[208:211], v[16:19]
	v_mfma_f32_16x16x32_bf16 v[4:7], v[176:179], v[216:219], v[4:7]
	v_mfma_f32_16x16x32_bf16 v[0:3], v[184:187], v[216:219], v[0:3]
	s_setprio 0
	s_barrier
	s_add_i32 s86, 0, 0x18000
	v_add_u32_e32 v159, s86, v152
	s_add_i32 s87, 0, 0x1c000
	ds_read_b128 v[148:151], v159
	ds_read_b128 v[160:163], v159 offset:1024
	ds_read_b128 v[164:167], v159 offset:2048
	ds_read_b128 v[168:171], v159 offset:3072
	v_add_u32_e32 v159, s87, v152
	ds_read_b128 v[172:175], v159
	ds_read_b128 v[176:179], v159 offset:1024
	ds_read_b128 v[180:183], v159 offset:2048
	ds_read_b128 v[184:187], v159 offset:3072
	s_add_u32 s34, s50, 0x40000
	s_addc_u32 s35, s51, 0
	s_mov_b32 m0, s59
	v_lshl_add_u64 v[228:229], s[34:35], 0, v[138:139]
	ds_read_b128 v[188:191], v158 offset:32768
	ds_read_b128 v[192:195], v158 offset:33792
	ds_read_b128 v[196:199], v158 offset:34816
	ds_read_b128 v[200:203], v158 offset:35840
	ds_read_b128 v[204:207], v158 offset:36864
	ds_read_b128 v[208:211], v158 offset:37888
	ds_read_b128 v[212:215], v158 offset:38912
	ds_read_b128 v[216:219], v158 offset:39936
	global_load_lds_dwordx4 v[228:229], off
	v_lshl_add_u64 v[228:229], s[34:35], 0, v[134:135]
	s_mov_b32 m0, s62
	s_nop 0
	global_load_lds_dwordx4 v[228:229], off
	s_waitcnt vmcnt(8)
	s_waitcnt lgkmcnt(0)
	s_barrier
	s_setprio 1
	s_waitcnt lgkmcnt(0)
	v_mfma_f32_16x16x32_bf16 v[124:127], v[148:151], v[188:191], v[124:127]
	v_mfma_f32_16x16x32_bf16 v[120:123], v[164:167], v[188:191], v[120:123]
	v_mfma_f32_16x16x32_bf16 v[108:111], v[148:151], v[196:199], v[108:111]
	v_mfma_f32_16x16x32_bf16 v[104:107], v[164:167], v[196:199], v[104:107]
	v_mfma_f32_16x16x32_bf16 v[92:95], v[148:151], v[204:207], v[92:95]
	v_mfma_f32_16x16x32_bf16 v[88:91], v[164:167], v[204:207], v[88:91]
	v_mfma_f32_16x16x32_bf16 v[76:79], v[148:151], v[212:215], v[76:79]
	v_mfma_f32_16x16x32_bf16 v[72:75], v[164:167], v[212:215], v[72:75]
	v_mfma_f32_16x16x32_bf16 v[124:127], v[160:163], v[192:195], v[124:127]
	v_mfma_f32_16x16x32_bf16 v[120:123], v[168:171], v[192:195], v[120:123]
	v_mfma_f32_16x16x32_bf16 v[108:111], v[160:163], v[200:203], v[108:111]
	v_mfma_f32_16x16x32_bf16 v[104:107], v[168:171], v[200:203], v[104:107]
	v_mfma_f32_16x16x32_bf16 v[92:95], v[160:163], v[208:211], v[92:95]
	v_mfma_f32_16x16x32_bf16 v[88:91], v[168:171], v[208:211], v[88:91]
	v_mfma_f32_16x16x32_bf16 v[76:79], v[160:163], v[216:219], v[76:79]
	v_mfma_f32_16x16x32_bf16 v[72:75], v[168:171], v[216:219], v[72:75]
	s_setprio 0
	s_setprio 1
	v_mfma_f32_16x16x32_bf16 v[116:119], v[172:175], v[188:191], v[116:119]
	v_mfma_f32_16x16x32_bf16 v[112:115], v[180:183], v[188:191], v[112:115]
	v_mfma_f32_16x16x32_bf16 v[100:103], v[172:175], v[196:199], v[100:103]
	v_mfma_f32_16x16x32_bf16 v[96:99], v[180:183], v[196:199], v[96:99]
	v_mfma_f32_16x16x32_bf16 v[84:87], v[172:175], v[204:207], v[84:87]
	v_mfma_f32_16x16x32_bf16 v[80:83], v[180:183], v[204:207], v[80:83]
	v_mfma_f32_16x16x32_bf16 v[68:71], v[172:175], v[212:215], v[68:71]
	v_mfma_f32_16x16x32_bf16 v[64:67], v[180:183], v[212:215], v[64:67]
	v_mfma_f32_16x16x32_bf16 v[116:119], v[176:179], v[192:195], v[116:119]
	v_mfma_f32_16x16x32_bf16 v[112:115], v[184:187], v[192:195], v[112:115]
	v_mfma_f32_16x16x32_bf16 v[100:103], v[176:179], v[200:203], v[100:103]
	v_mfma_f32_16x16x32_bf16 v[96:99], v[184:187], v[200:203], v[96:99]
	v_mfma_f32_16x16x32_bf16 v[84:87], v[176:179], v[208:211], v[84:87]
	v_mfma_f32_16x16x32_bf16 v[80:83], v[184:187], v[208:211], v[80:83]
	v_mfma_f32_16x16x32_bf16 v[68:71], v[176:179], v[216:219], v[68:71]
	v_mfma_f32_16x16x32_bf16 v[64:67], v[184:187], v[216:219], v[64:67]
	s_setprio 0
	s_barrier
	s_add_i32 s34, s86, s54
	v_lshl_add_u64 v[220:221], v[220:221], 0, s[6:7]
	s_mov_b32 m0, s34
	ds_read_b128 v[188:191], v158 offset:49152
	ds_read_b128 v[192:195], v158 offset:50176
	ds_read_b128 v[196:199], v158 offset:51200
	ds_read_b128 v[200:203], v158 offset:52224
	ds_read_b128 v[204:207], v158 offset:53248
	ds_read_b128 v[208:211], v158 offset:54272
	ds_read_b128 v[212:215], v158 offset:55296
	ds_read_b128 v[216:219], v158 offset:56320
	global_load_lds_dwordx4 v[220:221], off
	s_add_i32 m0, s34, 0x2000
	s_add_u32 s34, s48, 0x40080
	v_lshl_add_u64 v[220:221], v[222:223], 0, s[6:7]
	s_addc_u32 s35, s49, 0
	s_add_i32 s48, s87, s54
	global_load_lds_dwordx4 v[220:221], off
	v_lshl_add_u64 v[220:221], s[34:35], 0, v[136:137]
	s_mov_b32 m0, s48
	s_nop 0
	global_load_lds_dwordx4 v[220:221], off
	v_lshl_add_u64 v[220:221], s[34:35], 0, v[132:133]
	s_add_i32 m0, s48, 0x2000
	s_nop 0
	global_load_lds_dwordx4 v[220:221], off
	v_lshl_add_u64 v[220:221], v[224:225], 0, s[6:7]
	s_mov_b32 m0, s63
	s_nop 0
	global_load_lds_dwordx4 v[220:221], off
	v_lshl_add_u64 v[220:221], v[226:227], 0, s[6:7]
	s_mov_b32 m0, s64
	s_nop 0
	global_load_lds_dwordx4 v[220:221], off
	s_waitcnt vmcnt(8)
	s_waitcnt lgkmcnt(0)
	s_barrier
	s_add_u32 s42, s42, 0x100
	s_addc_u32 s43, s43, 0
	s_add_u32 s83, s83, 0x100
	s_addc_u32 s84, s84, 0
	s_setprio 1
	s_waitcnt lgkmcnt(0)
	v_mfma_f32_16x16x32_bf16 v[60:63], v[148:151], v[188:191], v[60:63]
	v_mfma_f32_16x16x32_bf16 v[56:59], v[164:167], v[188:191], v[56:59]
	v_mfma_f32_16x16x32_bf16 v[44:47], v[148:151], v[196:199], v[44:47]
	v_mfma_f32_16x16x32_bf16 v[40:43], v[164:167], v[196:199], v[40:43]
	v_mfma_f32_16x16x32_bf16 v[28:31], v[148:151], v[204:207], v[28:31]
	v_mfma_f32_16x16x32_bf16 v[24:27], v[164:167], v[204:207], v[24:27]
	v_mfma_f32_16x16x32_bf16 v[12:15], v[148:151], v[212:215], v[12:15]
	v_mfma_f32_16x16x32_bf16 v[8:11], v[164:167], v[212:215], v[8:11]
	v_mfma_f32_16x16x32_bf16 v[60:63], v[160:163], v[192:195], v[60:63]
	v_mfma_f32_16x16x32_bf16 v[56:59], v[168:171], v[192:195], v[56:59]
	v_mfma_f32_16x16x32_bf16 v[44:47], v[160:163], v[200:203], v[44:47]
	v_mfma_f32_16x16x32_bf16 v[40:43], v[168:171], v[200:203], v[40:43]
	v_mfma_f32_16x16x32_bf16 v[28:31], v[160:163], v[208:211], v[28:31]
	v_mfma_f32_16x16x32_bf16 v[24:27], v[168:171], v[208:211], v[24:27]
	v_mfma_f32_16x16x32_bf16 v[12:15], v[160:163], v[216:219], v[12:15]
	v_mfma_f32_16x16x32_bf16 v[8:11], v[168:171], v[216:219], v[8:11]
	s_setprio 0
	s_setprio 1
	v_mfma_f32_16x16x32_bf16 v[52:55], v[172:175], v[188:191], v[52:55]
	v_mfma_f32_16x16x32_bf16 v[48:51], v[180:183], v[188:191], v[48:51]
	v_mfma_f32_16x16x32_bf16 v[36:39], v[172:175], v[196:199], v[36:39]
	v_mfma_f32_16x16x32_bf16 v[32:35], v[180:183], v[196:199], v[32:35]
	v_mfma_f32_16x16x32_bf16 v[20:23], v[172:175], v[204:207], v[20:23]
	v_mfma_f32_16x16x32_bf16 v[16:19], v[180:183], v[204:207], v[16:19]
	v_mfma_f32_16x16x32_bf16 v[4:7], v[172:175], v[212:215], v[4:7]
	v_mfma_f32_16x16x32_bf16 v[0:3], v[180:183], v[212:215], v[0:3]
	v_mfma_f32_16x16x32_bf16 v[52:55], v[176:179], v[192:195], v[52:55]
	v_mfma_f32_16x16x32_bf16 v[48:51], v[184:187], v[192:195], v[48:51]
	v_mfma_f32_16x16x32_bf16 v[36:39], v[176:179], v[200:203], v[36:39]
	v_mfma_f32_16x16x32_bf16 v[32:35], v[184:187], v[200:203], v[32:35]
	v_mfma_f32_16x16x32_bf16 v[20:23], v[176:179], v[208:211], v[20:23]
	v_mfma_f32_16x16x32_bf16 v[16:19], v[184:187], v[208:211], v[16:19]
	v_mfma_f32_16x16x32_bf16 v[4:7], v[176:179], v[216:219], v[4:7]
	v_mfma_f32_16x16x32_bf16 v[0:3], v[184:187], v[216:219], v[0:3]
	s_setprio 0
	s_add_i32 s85, s85, 2
.LBB0_476:
	s_barrier
	ds_read_b128 v[148:151], v155
	ds_read_b128 v[160:163], v155 offset:1024
	ds_read_b128 v[164:167], v155 offset:2048
	ds_read_b128 v[168:171], v155 offset:3072
	ds_read_b128 v[172:175], v157
	ds_read_b128 v[176:179], v157 offset:1024
	ds_read_b128 v[180:183], v157 offset:2048
	ds_read_b128 v[184:187], v157 offset:3072
	s_add_u32 s34, s42, 0xfffc0080
	s_addc_u32 s35, s43, -1
	s_cmp_eq_u32 s85, 12
	s_cselect_b32 s51, s23, s35
	s_cselect_b32 s50, s81, s34
	s_cselect_b32 s49, s11, s84
	s_cselect_b32 s48, s82, s83
	v_lshl_add_u64 v[220:221], s[42:43], 0, v[140:141]
	s_add_i32 m0, s41, 0xc000
	ds_read_b128 v[188:191], v158
	ds_read_b128 v[192:195], v158 offset:1024
	ds_read_b128 v[196:199], v158 offset:2048
	ds_read_b128 v[200:203], v158 offset:3072
	ds_read_b128 v[204:207], v158 offset:4096
	ds_read_b128 v[208:211], v158 offset:5120
	ds_read_b128 v[212:215], v158 offset:6144
	ds_read_b128 v[216:219], v158 offset:7168
	global_load_lds_dwordx4 v[220:221], off
	v_lshl_add_u64 v[220:221], s[42:43], 0, v[142:143]
	s_add_i32 m0, s41, 0xe000
	s_nop 0
	global_load_lds_dwordx4 v[220:221], off
	s_waitcnt vmcnt(8)
	s_waitcnt lgkmcnt(0)
	s_barrier
	s_setprio 1
	s_waitcnt lgkmcnt(0)
	v_mfma_f32_16x16x32_bf16 v[124:127], v[148:151], v[188:191], v[124:127]
	v_mfma_f32_16x16x32_bf16 v[120:123], v[164:167], v[188:191], v[120:123]
	v_mfma_f32_16x16x32_bf16 v[108:111], v[148:151], v[196:199], v[108:111]
	v_mfma_f32_16x16x32_bf16 v[104:107], v[164:167], v[196:199], v[104:107]
	v_mfma_f32_16x16x32_bf16 v[92:95], v[148:151], v[204:207], v[92:95]
	v_mfma_f32_16x16x32_bf16 v[88:91], v[164:167], v[204:207], v[88:91]
	v_mfma_f32_16x16x32_bf16 v[76:79], v[148:151], v[212:215], v[76:79]
	v_mfma_f32_16x16x32_bf16 v[72:75], v[164:167], v[212:215], v[72:75]
	v_mfma_f32_16x16x32_bf16 v[124:127], v[160:163], v[192:195], v[124:127]
	v_mfma_f32_16x16x32_bf16 v[120:123], v[168:171], v[192:195], v[120:123]
	v_mfma_f32_16x16x32_bf16 v[108:111], v[160:163], v[200:203], v[108:111]
	v_mfma_f32_16x16x32_bf16 v[104:107], v[168:171], v[200:203], v[104:107]
	v_mfma_f32_16x16x32_bf16 v[92:95], v[160:163], v[208:211], v[92:95]
	v_mfma_f32_16x16x32_bf16 v[88:91], v[168:171], v[208:211], v[88:91]
	v_mfma_f32_16x16x32_bf16 v[76:79], v[160:163], v[216:219], v[76:79]
	v_mfma_f32_16x16x32_bf16 v[72:75], v[168:171], v[216:219], v[72:75]
	s_setprio 0
	s_setprio 1
	v_mfma_f32_16x16x32_bf16 v[116:119], v[172:175], v[188:191], v[116:119]
	v_mfma_f32_16x16x32_bf16 v[112:115], v[180:183], v[188:191], v[112:115]
	v_mfma_f32_16x16x32_bf16 v[100:103], v[172:175], v[196:199], v[100:103]
	v_mfma_f32_16x16x32_bf16 v[96:99], v[180:183], v[196:199], v[96:99]
	v_mfma_f32_16x16x32_bf16 v[84:87], v[172:175], v[204:207], v[84:87]
	v_mfma_f32_16x16x32_bf16 v[80:83], v[180:183], v[204:207], v[80:83]
	v_mfma_f32_16x16x32_bf16 v[68:71], v[172:175], v[212:215], v[68:71]
	v_mfma_f32_16x16x32_bf16 v[64:67], v[180:183], v[212:215], v[64:67]
	v_mfma_f32_16x16x32_bf16 v[116:119], v[176:179], v[192:195], v[116:119]
	v_mfma_f32_16x16x32_bf16 v[112:115], v[184:187], v[192:195], v[112:115]
	v_mfma_f32_16x16x32_bf16 v[100:103], v[176:179], v[200:203], v[100:103]
	v_mfma_f32_16x16x32_bf16 v[96:99], v[184:187], v[200:203], v[96:99]
	v_mfma_f32_16x16x32_bf16 v[84:87], v[176:179], v[208:211], v[84:87]
	v_mfma_f32_16x16x32_bf16 v[80:83], v[184:187], v[208:211], v[80:83]
	v_mfma_f32_16x16x32_bf16 v[68:71], v[176:179], v[216:219], v[68:71]
	v_mfma_f32_16x16x32_bf16 v[64:67], v[184:187], v[216:219], v[64:67]
	s_setprio 0
	s_barrier
	s_add_i32 s34, s65, s54
	v_lshl_add_u64 v[220:221], s[48:49], 0, v[136:137]
	s_mov_b32 m0, s34
	ds_read_b128 v[188:191], v158 offset:16384
	ds_read_b128 v[192:195], v158 offset:17408
	ds_read_b128 v[196:199], v158 offset:18432
	ds_read_b128 v[200:203], v158 offset:19456
	ds_read_b128 v[204:207], v158 offset:20480
	ds_read_b128 v[208:211], v158 offset:21504
	ds_read_b128 v[212:215], v158 offset:22528
	ds_read_b128 v[216:219], v158 offset:23552
	global_load_lds_dwordx4 v[220:221], off
	s_add_i32 m0, s34, 0x2000
	s_add_u32 s34, s48, 0x40000
	v_lshl_add_u64 v[222:223], s[48:49], 0, v[132:133]
	s_addc_u32 s35, s49, 0
	s_add_i32 s86, s66, s54
	global_load_lds_dwordx4 v[222:223], off
	v_lshl_add_u64 v[224:225], s[34:35], 0, v[136:137]
	s_mov_b32 m0, s86
	v_lshl_add_u64 v[226:227], s[50:51], 0, v[134:135]
	global_load_lds_dwordx4 v[224:225], off
	v_lshl_add_u64 v[224:225], s[34:35], 0, v[132:133]
	s_add_i32 m0, s86, 0x2000
	s_nop 0
	global_load_lds_dwordx4 v[224:225], off
	v_lshl_add_u64 v[224:225], s[50:51], 0, v[138:139]
	s_mov_b32 m0, s41
	s_nop 0
	global_load_lds_dwordx4 v[224:225], off
	s_mov_b32 m0, s58
	s_nop 0
	global_load_lds_dwordx4 v[226:227], off
	s_waitcnt vmcnt(8)
	s_waitcnt lgkmcnt(0)
	s_barrier
	s_setprio 1
	s_waitcnt lgkmcnt(0)
	v_mfma_f32_16x16x32_bf16 v[60:63], v[148:151], v[188:191], v[60:63]
	v_mfma_f32_16x16x32_bf16 v[56:59], v[164:167], v[188:191], v[56:59]
	v_mfma_f32_16x16x32_bf16 v[44:47], v[148:151], v[196:199], v[44:47]
	v_mfma_f32_16x16x32_bf16 v[40:43], v[164:167], v[196:199], v[40:43]
	v_mfma_f32_16x16x32_bf16 v[28:31], v[148:151], v[204:207], v[28:31]
	v_mfma_f32_16x16x32_bf16 v[24:27], v[164:167], v[204:207], v[24:27]
	v_mfma_f32_16x16x32_bf16 v[12:15], v[148:151], v[212:215], v[12:15]
	v_mfma_f32_16x16x32_bf16 v[8:11], v[164:167], v[212:215], v[8:11]
	v_mfma_f32_16x16x32_bf16 v[60:63], v[160:163], v[192:195], v[60:63]
	v_mfma_f32_16x16x32_bf16 v[56:59], v[168:171], v[192:195], v[56:59]
	v_mfma_f32_16x16x32_bf16 v[44:47], v[160:163], v[200:203], v[44:47]
	v_mfma_f32_16x16x32_bf16 v[40:43], v[168:171], v[200:203], v[40:43]
	v_mfma_f32_16x16x32_bf16 v[28:31], v[160:163], v[208:211], v[28:31]
	v_mfma_f32_16x16x32_bf16 v[24:27], v[168:171], v[208:211], v[24:27]
	v_mfma_f32_16x16x32_bf16 v[12:15], v[160:163], v[216:219], v[12:15]
	v_mfma_f32_16x16x32_bf16 v[8:11], v[168:171], v[216:219], v[8:11]
	s_setprio 0
	s_setprio 1
	v_mfma_f32_16x16x32_bf16 v[52:55], v[172:175], v[188:191], v[52:55]
	v_mfma_f32_16x16x32_bf16 v[48:51], v[180:183], v[188:191], v[48:51]
	v_mfma_f32_16x16x32_bf16 v[36:39], v[172:175], v[196:199], v[36:39]
	v_mfma_f32_16x16x32_bf16 v[32:35], v[180:183], v[196:199], v[32:35]
	v_mfma_f32_16x16x32_bf16 v[20:23], v[172:175], v[204:207], v[20:23]
	v_mfma_f32_16x16x32_bf16 v[16:19], v[180:183], v[204:207], v[16:19]
	v_mfma_f32_16x16x32_bf16 v[4:7], v[172:175], v[212:215], v[4:7]
	v_mfma_f32_16x16x32_bf16 v[0:3], v[180:183], v[212:215], v[0:3]
	v_mfma_f32_16x16x32_bf16 v[52:55], v[176:179], v[192:195], v[52:55]
	v_mfma_f32_16x16x32_bf16 v[48:51], v[184:187], v[192:195], v[48:51]
	v_mfma_f32_16x16x32_bf16 v[36:39], v[176:179], v[200:203], v[36:39]
	v_mfma_f32_16x16x32_bf16 v[32:35], v[184:187], v[200:203], v[32:35]
	v_mfma_f32_16x16x32_bf16 v[20:23], v[176:179], v[208:211], v[20:23]
	v_mfma_f32_16x16x32_bf16 v[16:19], v[184:187], v[208:211], v[16:19]
	v_mfma_f32_16x16x32_bf16 v[4:7], v[176:179], v[216:219], v[4:7]
	v_mfma_f32_16x16x32_bf16 v[0:3], v[184:187], v[216:219], v[0:3]
	s_setprio 0
	s_barrier
	s_add_i32 s86, 0, 0x18000
	v_add_u32_e32 v159, s86, v152
	s_add_i32 s87, 0, 0x1c000
	ds_read_b128 v[148:151], v159
	ds_read_b128 v[160:163], v159 offset:1024
	ds_read_b128 v[164:167], v159 offset:2048
	ds_read_b128 v[168:171], v159 offset:3072
	v_add_u32_e32 v159, s87, v152
	ds_read_b128 v[172:175], v159
	ds_read_b128 v[176:179], v159 offset:1024
	ds_read_b128 v[180:183], v159 offset:2048
	ds_read_b128 v[184:187], v159 offset:3072
	s_add_u32 s34, s50, 0x40000
	s_addc_u32 s35, s51, 0
	s_mov_b32 m0, s59
	v_lshl_add_u64 v[228:229], s[34:35], 0, v[138:139]
	ds_read_b128 v[188:191], v158 offset:32768
	ds_read_b128 v[192:195], v158 offset:33792
	ds_read_b128 v[196:199], v158 offset:34816
	ds_read_b128 v[200:203], v158 offset:35840
	ds_read_b128 v[204:207], v158 offset:36864
	ds_read_b128 v[208:211], v158 offset:37888
	ds_read_b128 v[212:215], v158 offset:38912
	ds_read_b128 v[216:219], v158 offset:39936
	global_load_lds_dwordx4 v[228:229], off
	v_lshl_add_u64 v[228:229], s[34:35], 0, v[134:135]
	s_mov_b32 m0, s62
	s_nop 0
	global_load_lds_dwordx4 v[228:229], off
	s_waitcnt vmcnt(8)
	s_waitcnt lgkmcnt(0)
	s_barrier
	s_setprio 1
	s_waitcnt lgkmcnt(0)
	v_mfma_f32_16x16x32_bf16 v[124:127], v[148:151], v[188:191], v[124:127]
	v_mfma_f32_16x16x32_bf16 v[120:123], v[164:167], v[188:191], v[120:123]
	v_mfma_f32_16x16x32_bf16 v[108:111], v[148:151], v[196:199], v[108:111]
	v_mfma_f32_16x16x32_bf16 v[104:107], v[164:167], v[196:199], v[104:107]
	v_mfma_f32_16x16x32_bf16 v[92:95], v[148:151], v[204:207], v[92:95]
	v_mfma_f32_16x16x32_bf16 v[88:91], v[164:167], v[204:207], v[88:91]
	v_mfma_f32_16x16x32_bf16 v[76:79], v[148:151], v[212:215], v[76:79]
	v_mfma_f32_16x16x32_bf16 v[72:75], v[164:167], v[212:215], v[72:75]
	v_mfma_f32_16x16x32_bf16 v[124:127], v[160:163], v[192:195], v[124:127]
	v_mfma_f32_16x16x32_bf16 v[120:123], v[168:171], v[192:195], v[120:123]
	v_mfma_f32_16x16x32_bf16 v[108:111], v[160:163], v[200:203], v[108:111]
	v_mfma_f32_16x16x32_bf16 v[104:107], v[168:171], v[200:203], v[104:107]
	v_mfma_f32_16x16x32_bf16 v[92:95], v[160:163], v[208:211], v[92:95]
	v_mfma_f32_16x16x32_bf16 v[88:91], v[168:171], v[208:211], v[88:91]
	v_mfma_f32_16x16x32_bf16 v[76:79], v[160:163], v[216:219], v[76:79]
	v_mfma_f32_16x16x32_bf16 v[72:75], v[168:171], v[216:219], v[72:75]
	s_setprio 0
	s_setprio 1
	v_mfma_f32_16x16x32_bf16 v[116:119], v[172:175], v[188:191], v[116:119]
	v_mfma_f32_16x16x32_bf16 v[112:115], v[180:183], v[188:191], v[112:115]
	v_mfma_f32_16x16x32_bf16 v[100:103], v[172:175], v[196:199], v[100:103]
	v_mfma_f32_16x16x32_bf16 v[96:99], v[180:183], v[196:199], v[96:99]
	v_mfma_f32_16x16x32_bf16 v[84:87], v[172:175], v[204:207], v[84:87]
	v_mfma_f32_16x16x32_bf16 v[80:83], v[180:183], v[204:207], v[80:83]
	v_mfma_f32_16x16x32_bf16 v[68:71], v[172:175], v[212:215], v[68:71]
	v_mfma_f32_16x16x32_bf16 v[64:67], v[180:183], v[212:215], v[64:67]
	v_mfma_f32_16x16x32_bf16 v[116:119], v[176:179], v[192:195], v[116:119]
	v_mfma_f32_16x16x32_bf16 v[112:115], v[184:187], v[192:195], v[112:115]
	v_mfma_f32_16x16x32_bf16 v[100:103], v[176:179], v[200:203], v[100:103]
	v_mfma_f32_16x16x32_bf16 v[96:99], v[184:187], v[200:203], v[96:99]
	v_mfma_f32_16x16x32_bf16 v[84:87], v[176:179], v[208:211], v[84:87]
	v_mfma_f32_16x16x32_bf16 v[80:83], v[184:187], v[208:211], v[80:83]
	v_mfma_f32_16x16x32_bf16 v[68:71], v[176:179], v[216:219], v[68:71]
	v_mfma_f32_16x16x32_bf16 v[64:67], v[184:187], v[216:219], v[64:67]
	s_setprio 0
	s_barrier
	s_add_i32 s34, s86, s54
	v_lshl_add_u64 v[220:221], v[220:221], 0, s[6:7]
	s_mov_b32 m0, s34
	ds_read_b128 v[188:191], v158 offset:49152
	ds_read_b128 v[192:195], v158 offset:50176
	ds_read_b128 v[196:199], v158 offset:51200
	ds_read_b128 v[200:203], v158 offset:52224
	ds_read_b128 v[204:207], v158 offset:53248
	ds_read_b128 v[208:211], v158 offset:54272
	ds_read_b128 v[212:215], v158 offset:55296
	ds_read_b128 v[216:219], v158 offset:56320
	global_load_lds_dwordx4 v[220:221], off
	s_add_i32 m0, s34, 0x2000
	s_add_u32 s34, s48, 0x40080
	v_lshl_add_u64 v[220:221], v[222:223], 0, s[6:7]
	s_addc_u32 s35, s49, 0
	s_add_i32 s48, s87, s54
	global_load_lds_dwordx4 v[220:221], off
	v_lshl_add_u64 v[220:221], s[34:35], 0, v[136:137]
	s_mov_b32 m0, s48
	s_nop 0
	global_load_lds_dwordx4 v[220:221], off
	v_lshl_add_u64 v[220:221], s[34:35], 0, v[132:133]
	s_add_i32 m0, s48, 0x2000
	s_nop 0
	global_load_lds_dwordx4 v[220:221], off
	v_lshl_add_u64 v[220:221], v[224:225], 0, s[6:7]
	s_mov_b32 m0, s63
	s_nop 0
	global_load_lds_dwordx4 v[220:221], off
	v_lshl_add_u64 v[220:221], v[226:227], 0, s[6:7]
	s_mov_b32 m0, s64
	s_nop 0
	global_load_lds_dwordx4 v[220:221], off
	s_waitcnt vmcnt(8)
	s_waitcnt lgkmcnt(0)
	s_barrier
	s_add_u32 s42, s42, 0x100
	s_addc_u32 s43, s43, 0
	s_add_u32 s83, s83, 0x100
	s_addc_u32 s84, s84, 0
	s_setprio 1
	s_waitcnt lgkmcnt(0)
	v_mfma_f32_16x16x32_bf16 v[60:63], v[148:151], v[188:191], v[60:63]
	v_mfma_f32_16x16x32_bf16 v[56:59], v[164:167], v[188:191], v[56:59]
	v_mfma_f32_16x16x32_bf16 v[44:47], v[148:151], v[196:199], v[44:47]
	v_mfma_f32_16x16x32_bf16 v[40:43], v[164:167], v[196:199], v[40:43]
	v_mfma_f32_16x16x32_bf16 v[28:31], v[148:151], v[204:207], v[28:31]
	v_mfma_f32_16x16x32_bf16 v[24:27], v[164:167], v[204:207], v[24:27]
	v_mfma_f32_16x16x32_bf16 v[12:15], v[148:151], v[212:215], v[12:15]
	v_mfma_f32_16x16x32_bf16 v[8:11], v[164:167], v[212:215], v[8:11]
	v_mfma_f32_16x16x32_bf16 v[60:63], v[160:163], v[192:195], v[60:63]
	v_mfma_f32_16x16x32_bf16 v[56:59], v[168:171], v[192:195], v[56:59]
	v_mfma_f32_16x16x32_bf16 v[44:47], v[160:163], v[200:203], v[44:47]
	v_mfma_f32_16x16x32_bf16 v[40:43], v[168:171], v[200:203], v[40:43]
	v_mfma_f32_16x16x32_bf16 v[28:31], v[160:163], v[208:211], v[28:31]
	v_mfma_f32_16x16x32_bf16 v[24:27], v[168:171], v[208:211], v[24:27]
	v_mfma_f32_16x16x32_bf16 v[12:15], v[160:163], v[216:219], v[12:15]
	v_mfma_f32_16x16x32_bf16 v[8:11], v[168:171], v[216:219], v[8:11]
	s_setprio 0
	s_setprio 1
	v_mfma_f32_16x16x32_bf16 v[52:55], v[172:175], v[188:191], v[52:55]
	v_mfma_f32_16x16x32_bf16 v[48:51], v[180:183], v[188:191], v[48:51]
	v_mfma_f32_16x16x32_bf16 v[36:39], v[172:175], v[196:199], v[36:39]
	v_mfma_f32_16x16x32_bf16 v[32:35], v[180:183], v[196:199], v[32:35]
	v_mfma_f32_16x16x32_bf16 v[20:23], v[172:175], v[204:207], v[20:23]
	v_mfma_f32_16x16x32_bf16 v[16:19], v[180:183], v[204:207], v[16:19]
	v_mfma_f32_16x16x32_bf16 v[4:7], v[172:175], v[212:215], v[4:7]
	v_mfma_f32_16x16x32_bf16 v[0:3], v[180:183], v[212:215], v[0:3]
	v_mfma_f32_16x16x32_bf16 v[52:55], v[176:179], v[192:195], v[52:55]
	v_mfma_f32_16x16x32_bf16 v[48:51], v[184:187], v[192:195], v[48:51]
	v_mfma_f32_16x16x32_bf16 v[36:39], v[176:179], v[200:203], v[36:39]
	v_mfma_f32_16x16x32_bf16 v[32:35], v[184:187], v[200:203], v[32:35]
	v_mfma_f32_16x16x32_bf16 v[20:23], v[176:179], v[208:211], v[20:23]
	v_mfma_f32_16x16x32_bf16 v[16:19], v[184:187], v[208:211], v[16:19]
	v_mfma_f32_16x16x32_bf16 v[4:7], v[176:179], v[216:219], v[4:7]
	v_mfma_f32_16x16x32_bf16 v[0:3], v[184:187], v[216:219], v[0:3]
	s_setprio 0
	s_add_i32 s85, s85, 2
	s_cmp_gt_u32 s85, 13
	s_cbranch_scc0 .LBB0_476
	s_sub_i32 s100, s85, 2
	s_cmp_eq_u32 s100, s98
	s_cbranch_scc1 .Lmy_nobar_5
	s_barrier
.Lmy_nobar_5:
	s_and_b64 vcc, exec, s[8:9]
	s_cbranch_vccz .LBB0_479
	s_nop 0

.Lmy_nobar2_6:
	ds_read_b128 v[148:151], v154
	ds_read_b128 v[160:163], v154 offset:1024
	ds_read_b128 v[164:167], v154 offset:2048
	ds_read_b128 v[168:171], v154 offset:3072
	ds_read_b128 v[172:175], v155
	ds_read_b128 v[176:179], v155 offset:1024
	ds_read_b128 v[180:183], v155 offset:2048
	ds_read_b128 v[184:187], v155 offset:3072
	s_add_u32 s34, s40, 0xfff50080
	s_addc_u32 s35, s41, -1
	s_cmp_eq_u32 s81, 40
	s_cselect_b32 s49, s1, s35
	s_cselect_b32 s48, s0, s34
	s_cselect_b32 s43, s29, s77
	s_cselect_b32 s42, s28, s13
	v_lshl_add_u64 v[220:221], s[40:41], 0, v[140:141]
	s_add_i32 m0, s52, 0xc000
	ds_read_b128 v[188:191], v157
	ds_read_b128 v[192:195], v157 offset:1024
	ds_read_b128 v[196:199], v157 offset:2048
	ds_read_b128 v[200:203], v157 offset:3072
	ds_read_b128 v[204:207], v157 offset:4096
	ds_read_b128 v[208:211], v157 offset:5120
	ds_read_b128 v[212:215], v157 offset:6144
	ds_read_b128 v[216:219], v157 offset:7168
	global_load_lds_dwordx4 v[220:221], off
	v_lshl_add_u64 v[220:221], s[40:41], 0, v[142:143]
	s_add_i32 m0, s52, 0xe000
	s_nop 0
	global_load_lds_dwordx4 v[220:221], off
	s_waitcnt vmcnt(8)
	s_waitcnt lgkmcnt(0)
	s_barrier
	s_setprio 1
	s_waitcnt lgkmcnt(0)
	v_mfma_f32_16x16x32_bf16 v[124:127], v[148:151], v[188:191], 0
	v_mfma_f32_16x16x32_bf16 v[120:123], v[164:167], v[188:191], 0
	v_mfma_f32_16x16x32_bf16 v[108:111], v[148:151], v[196:199], 0
	v_mfma_f32_16x16x32_bf16 v[104:107], v[164:167], v[196:199], 0
	v_mfma_f32_16x16x32_bf16 v[92:95], v[148:151], v[204:207], 0
	v_mfma_f32_16x16x32_bf16 v[88:91], v[164:167], v[204:207], 0
	v_mfma_f32_16x16x32_bf16 v[76:79], v[148:151], v[212:215], 0
	v_mfma_f32_16x16x32_bf16 v[72:75], v[164:167], v[212:215], 0
	v_mfma_f32_16x16x32_bf16 v[124:127], v[160:163], v[192:195], v[124:127]
	v_mfma_f32_16x16x32_bf16 v[120:123], v[168:171], v[192:195], v[120:123]
	v_mfma_f32_16x16x32_bf16 v[108:111], v[160:163], v[200:203], v[108:111]
	v_mfma_f32_16x16x32_bf16 v[104:107], v[168:171], v[200:203], v[104:107]
	v_mfma_f32_16x16x32_bf16 v[92:95], v[160:163], v[208:211], v[92:95]
	v_mfma_f32_16x16x32_bf16 v[88:91], v[168:171], v[208:211], v[88:91]
	v_mfma_f32_16x16x32_bf16 v[76:79], v[160:163], v[216:219], v[76:79]
	v_mfma_f32_16x16x32_bf16 v[72:75], v[168:171], v[216:219], v[72:75]
	s_setprio 0
	s_setprio 1
	v_mfma_f32_16x16x32_bf16 v[116:119], v[172:175], v[188:191], 0
	v_mfma_f32_16x16x32_bf16 v[112:115], v[180:183], v[188:191], 0
	v_mfma_f32_16x16x32_bf16 v[100:103], v[172:175], v[196:199], 0
	v_mfma_f32_16x16x32_bf16 v[96:99], v[180:183], v[196:199], 0
	v_mfma_f32_16x16x32_bf16 v[84:87], v[172:175], v[204:207], 0
	v_mfma_f32_16x16x32_bf16 v[80:83], v[180:183], v[204:207], 0
	v_mfma_f32_16x16x32_bf16 v[68:71], v[172:175], v[212:215], 0
	v_mfma_f32_16x16x32_bf16 v[64:67], v[180:183], v[212:215], 0
	v_mfma_f32_16x16x32_bf16 v[116:119], v[176:179], v[192:195], v[116:119]
	v_mfma_f32_16x16x32_bf16 v[112:115], v[184:187], v[192:195], v[112:115]
	v_mfma_f32_16x16x32_bf16 v[100:103], v[176:179], v[200:203], v[100:103]
	v_mfma_f32_16x16x32_bf16 v[96:99], v[184:187], v[200:203], v[96:99]
	v_mfma_f32_16x16x32_bf16 v[84:87], v[176:179], v[208:211], v[84:87]
	v_mfma_f32_16x16x32_bf16 v[80:83], v[184:187], v[208:211], v[80:83]
	v_mfma_f32_16x16x32_bf16 v[68:71], v[176:179], v[216:219], v[68:71]
	v_mfma_f32_16x16x32_bf16 v[64:67], v[184:187], v[216:219], v[64:67]
	s_setprio 0
	s_barrier
	s_add_i32 s34, s64, s51
	v_lshl_add_u64 v[220:221], s[42:43], 0, v[134:135]
	s_mov_b32 m0, s34
	ds_read_b128 v[188:191], v157 offset:16384
	ds_read_b128 v[192:195], v157 offset:17408
	ds_read_b128 v[196:199], v157 offset:18432
	ds_read_b128 v[200:203], v157 offset:19456
	ds_read_b128 v[204:207], v157 offset:20480
	ds_read_b128 v[208:211], v157 offset:21504
	ds_read_b128 v[212:215], v157 offset:22528
	ds_read_b128 v[216:219], v157 offset:23552
	global_load_lds_dwordx4 v[220:221], off
	s_add_i32 m0, s34, 0x2000
	s_add_u32 s34, s42, 0xb0000
	v_lshl_add_u64 v[222:223], s[42:43], 0, v[138:139]
	s_addc_u32 s35, s43, 0
	s_add_i32 s82, s65, s51
	global_load_lds_dwordx4 v[222:223], off
	v_lshl_add_u64 v[224:225], s[34:35], 0, v[134:135]
	s_mov_b32 m0, s82
	v_lshl_add_u64 v[226:227], s[48:49], 0, v[136:137]
	global_load_lds_dwordx4 v[224:225], off
	v_lshl_add_u64 v[224:225], s[34:35], 0, v[138:139]
	s_add_i32 m0, s82, 0x2000
	s_nop 0
	global_load_lds_dwordx4 v[224:225], off
	v_lshl_add_u64 v[224:225], s[48:49], 0, v[132:133]
	s_mov_b32 m0, s52
	s_nop 0
	global_load_lds_dwordx4 v[224:225], off
	s_mov_b32 m0, s53
	s_nop 0
	global_load_lds_dwordx4 v[226:227], off
	s_waitcnt vmcnt(8)
	s_waitcnt lgkmcnt(0)
	s_barrier
	s_setprio 1
	s_waitcnt lgkmcnt(0)
	v_mfma_f32_16x16x32_bf16 v[60:63], v[148:151], v[188:191], 0
	v_mfma_f32_16x16x32_bf16 v[56:59], v[164:167], v[188:191], 0
	v_mfma_f32_16x16x32_bf16 v[44:47], v[148:151], v[196:199], 0
	v_mfma_f32_16x16x32_bf16 v[40:43], v[164:167], v[196:199], 0
	v_mfma_f32_16x16x32_bf16 v[28:31], v[148:151], v[204:207], 0
	v_mfma_f32_16x16x32_bf16 v[24:27], v[164:167], v[204:207], 0
	v_mfma_f32_16x16x32_bf16 v[12:15], v[148:151], v[212:215], 0
	v_mfma_f32_16x16x32_bf16 v[8:11], v[164:167], v[212:215], 0
	v_mfma_f32_16x16x32_bf16 v[60:63], v[160:163], v[192:195], v[60:63]
	v_mfma_f32_16x16x32_bf16 v[56:59], v[168:171], v[192:195], v[56:59]
	v_mfma_f32_16x16x32_bf16 v[44:47], v[160:163], v[200:203], v[44:47]
	v_mfma_f32_16x16x32_bf16 v[40:43], v[168:171], v[200:203], v[40:43]
	v_mfma_f32_16x16x32_bf16 v[28:31], v[160:163], v[208:211], v[28:31]
	v_mfma_f32_16x16x32_bf16 v[24:27], v[168:171], v[208:211], v[24:27]
	v_mfma_f32_16x16x32_bf16 v[12:15], v[160:163], v[216:219], v[12:15]
	v_mfma_f32_16x16x32_bf16 v[8:11], v[168:171], v[216:219], v[8:11]
	s_setprio 0
	s_setprio 1
	v_mfma_f32_16x16x32_bf16 v[52:55], v[172:175], v[188:191], 0
	v_mfma_f32_16x16x32_bf16 v[48:51], v[180:183], v[188:191], 0
	v_mfma_f32_16x16x32_bf16 v[36:39], v[172:175], v[196:199], 0
	v_mfma_f32_16x16x32_bf16 v[32:35], v[180:183], v[196:199], 0
	v_mfma_f32_16x16x32_bf16 v[20:23], v[172:175], v[204:207], 0
	v_mfma_f32_16x16x32_bf16 v[16:19], v[180:183], v[204:207], 0
	v_mfma_f32_16x16x32_bf16 v[4:7], v[172:175], v[212:215], 0
	v_mfma_f32_16x16x32_bf16 v[0:3], v[180:183], v[212:215], 0
	v_mfma_f32_16x16x32_bf16 v[52:55], v[176:179], v[192:195], v[52:55]
	v_mfma_f32_16x16x32_bf16 v[48:51], v[184:187], v[192:195], v[48:51]
	v_mfma_f32_16x16x32_bf16 v[36:39], v[176:179], v[200:203], v[36:39]
	v_mfma_f32_16x16x32_bf16 v[32:35], v[184:187], v[200:203], v[32:35]
	v_mfma_f32_16x16x32_bf16 v[20:23], v[176:179], v[208:211], v[20:23]
	v_mfma_f32_16x16x32_bf16 v[16:19], v[184:187], v[208:211], v[16:19]
	v_mfma_f32_16x16x32_bf16 v[4:7], v[176:179], v[216:219], v[4:7]
	v_mfma_f32_16x16x32_bf16 v[0:3], v[184:187], v[216:219], v[0:3]
	s_setprio 0
	s_barrier
	s_add_i32 s82, 0, 0x18000
	v_add_u32_e32 v159, s82, v152
	s_add_i32 s83, 0, 0x1c000
	ds_read_b128 v[148:151], v159
	ds_read_b128 v[160:163], v159 offset:1024
	ds_read_b128 v[164:167], v159 offset:2048
	ds_read_b128 v[168:171], v159 offset:3072
	v_add_u32_e32 v159, s83, v152
	ds_read_b128 v[172:175], v159
	ds_read_b128 v[176:179], v159 offset:1024
	ds_read_b128 v[180:183], v159 offset:2048
	ds_read_b128 v[184:187], v159 offset:3072
	s_add_u32 s34, s48, 0xb0000
	s_addc_u32 s35, s49, 0
	s_mov_b32 m0, s54
	v_lshl_add_u64 v[228:229], s[34:35], 0, v[132:133]
	ds_read_b128 v[188:191], v157 offset:32768
	ds_read_b128 v[192:195], v157 offset:33792
	ds_read_b128 v[196:199], v157 offset:34816
	ds_read_b128 v[200:203], v157 offset:35840
	ds_read_b128 v[204:207], v157 offset:36864
	ds_read_b128 v[208:211], v157 offset:37888
	ds_read_b128 v[212:215], v157 offset:38912
	ds_read_b128 v[216:219], v157 offset:39936
	global_load_lds_dwordx4 v[228:229], off
	v_lshl_add_u64 v[228:229], s[34:35], 0, v[136:137]
	s_mov_b32 m0, s55
	s_nop 0
	global_load_lds_dwordx4 v[228:229], off
	s_waitcnt vmcnt(8)
	s_waitcnt lgkmcnt(0)
	s_barrier
	s_setprio 1
	s_waitcnt lgkmcnt(0)
	v_mfma_f32_16x16x32_bf16 v[124:127], v[148:151], v[188:191], v[124:127]
	v_mfma_f32_16x16x32_bf16 v[120:123], v[164:167], v[188:191], v[120:123]
	v_mfma_f32_16x16x32_bf16 v[108:111], v[148:151], v[196:199], v[108:111]
	v_mfma_f32_16x16x32_bf16 v[104:107], v[164:167], v[196:199], v[104:107]
	v_mfma_f32_16x16x32_bf16 v[92:95], v[148:151], v[204:207], v[92:95]
	v_mfma_f32_16x16x32_bf16 v[88:91], v[164:167], v[204:207], v[88:91]
	v_mfma_f32_16x16x32_bf16 v[76:79], v[148:151], v[212:215], v[76:79]
	v_mfma_f32_16x16x32_bf16 v[72:75], v[164:167], v[212:215], v[72:75]
	v_mfma_f32_16x16x32_bf16 v[124:127], v[160:163], v[192:195], v[124:127]
	v_mfma_f32_16x16x32_bf16 v[120:123], v[168:171], v[192:195], v[120:123]
	v_mfma_f32_16x16x32_bf16 v[108:111], v[160:163], v[200:203], v[108:111]
	v_mfma_f32_16x16x32_bf16 v[104:107], v[168:171], v[200:203], v[104:107]
	v_mfma_f32_16x16x32_bf16 v[92:95], v[160:163], v[208:211], v[92:95]
	v_mfma_f32_16x16x32_bf16 v[88:91], v[168:171], v[208:211], v[88:91]
	v_mfma_f32_16x16x32_bf16 v[76:79], v[160:163], v[216:219], v[76:79]
	v_mfma_f32_16x16x32_bf16 v[72:75], v[168:171], v[216:219], v[72:75]
	s_setprio 0
	s_setprio 1
	v_mfma_f32_16x16x32_bf16 v[116:119], v[172:175], v[188:191], v[116:119]
	v_mfma_f32_16x16x32_bf16 v[112:115], v[180:183], v[188:191], v[112:115]
	v_mfma_f32_16x16x32_bf16 v[100:103], v[172:175], v[196:199], v[100:103]
	v_mfma_f32_16x16x32_bf16 v[96:99], v[180:183], v[196:199], v[96:99]
	v_mfma_f32_16x16x32_bf16 v[84:87], v[172:175], v[204:207], v[84:87]
	v_mfma_f32_16x16x32_bf16 v[80:83], v[180:183], v[204:207], v[80:83]
	v_mfma_f32_16x16x32_bf16 v[68:71], v[172:175], v[212:215], v[68:71]
	v_mfma_f32_16x16x32_bf16 v[64:67], v[180:183], v[212:215], v[64:67]
	v_mfma_f32_16x16x32_bf16 v[116:119], v[176:179], v[192:195], v[116:119]
	v_mfma_f32_16x16x32_bf16 v[112:115], v[184:187], v[192:195], v[112:115]
	v_mfma_f32_16x16x32_bf16 v[100:103], v[176:179], v[200:203], v[100:103]
	v_mfma_f32_16x16x32_bf16 v[96:99], v[184:187], v[200:203], v[96:99]
	v_mfma_f32_16x16x32_bf16 v[84:87], v[176:179], v[208:211], v[84:87]
	v_mfma_f32_16x16x32_bf16 v[80:83], v[184:187], v[208:211], v[80:83]
	v_mfma_f32_16x16x32_bf16 v[68:71], v[176:179], v[216:219], v[68:71]
	v_mfma_f32_16x16x32_bf16 v[64:67], v[184:187], v[216:219], v[64:67]
	s_setprio 0
	s_barrier
	s_add_i32 s34, s82, s51
	v_lshl_add_u64 v[220:221], v[220:221], 0, s[22:23]
	s_mov_b32 m0, s34
	ds_read_b128 v[188:191], v157 offset:49152
	ds_read_b128 v[192:195], v157 offset:50176
	ds_read_b128 v[196:199], v157 offset:51200
	ds_read_b128 v[200:203], v157 offset:52224
	ds_read_b128 v[204:207], v157 offset:53248
	ds_read_b128 v[208:211], v157 offset:54272
	ds_read_b128 v[212:215], v157 offset:55296
	ds_read_b128 v[216:219], v157 offset:56320
	global_load_lds_dwordx4 v[220:221], off
	s_add_i32 m0, s34, 0x2000
	s_add_u32 s34, s42, 0xb0080
	v_lshl_add_u64 v[220:221], v[222:223], 0, s[22:23]
	s_addc_u32 s35, s43, 0
	s_add_i32 s42, s83, s51
	global_load_lds_dwordx4 v[220:221], off
	v_lshl_add_u64 v[220:221], s[34:35], 0, v[134:135]
	s_mov_b32 m0, s42
	s_nop 0
	global_load_lds_dwordx4 v[220:221], off
	v_lshl_add_u64 v[220:221], s[34:35], 0, v[138:139]
	s_add_i32 m0, s42, 0x2000
	s_nop 0
	global_load_lds_dwordx4 v[220:221], off
	v_lshl_add_u64 v[220:221], v[224:225], 0, s[22:23]
	s_mov_b32 m0, s57
	s_nop 0
	global_load_lds_dwordx4 v[220:221], off
	v_lshl_add_u64 v[220:221], v[226:227], 0, s[22:23]
	s_mov_b32 m0, s58
	s_nop 0
	global_load_lds_dwordx4 v[220:221], off
	s_waitcnt vmcnt(8)
	s_waitcnt lgkmcnt(0)
	s_barrier
	s_add_u32 s40, s40, 0x100
	s_addc_u32 s41, s41, 0
	s_add_u32 s13, s13, 0x100
	s_addc_u32 s77, s77, 0
	s_setprio 1
	s_waitcnt lgkmcnt(0)
	v_mfma_f32_16x16x32_bf16 v[60:63], v[148:151], v[188:191], v[60:63]
	v_mfma_f32_16x16x32_bf16 v[56:59], v[164:167], v[188:191], v[56:59]
	v_mfma_f32_16x16x32_bf16 v[44:47], v[148:151], v[196:199], v[44:47]
	v_mfma_f32_16x16x32_bf16 v[40:43], v[164:167], v[196:199], v[40:43]
	v_mfma_f32_16x16x32_bf16 v[28:31], v[148:151], v[204:207], v[28:31]
	v_mfma_f32_16x16x32_bf16 v[24:27], v[164:167], v[204:207], v[24:27]
	v_mfma_f32_16x16x32_bf16 v[12:15], v[148:151], v[212:215], v[12:15]
	v_mfma_f32_16x16x32_bf16 v[8:11], v[164:167], v[212:215], v[8:11]
	v_mfma_f32_16x16x32_bf16 v[60:63], v[160:163], v[192:195], v[60:63]
	v_mfma_f32_16x16x32_bf16 v[56:59], v[168:171], v[192:195], v[56:59]
	v_mfma_f32_16x16x32_bf16 v[44:47], v[160:163], v[200:203], v[44:47]
	v_mfma_f32_16x16x32_bf16 v[40:43], v[168:171], v[200:203], v[40:43]
	v_mfma_f32_16x16x32_bf16 v[28:31], v[160:163], v[208:211], v[28:31]
	v_mfma_f32_16x16x32_bf16 v[24:27], v[168:171], v[208:211], v[24:27]
	v_mfma_f32_16x16x32_bf16 v[12:15], v[160:163], v[216:219], v[12:15]
	v_mfma_f32_16x16x32_bf16 v[8:11], v[168:171], v[216:219], v[8:11]
	s_setprio 0
	s_setprio 1
	v_mfma_f32_16x16x32_bf16 v[52:55], v[172:175], v[188:191], v[52:55]
	v_mfma_f32_16x16x32_bf16 v[48:51], v[180:183], v[188:191], v[48:51]
	v_mfma_f32_16x16x32_bf16 v[36:39], v[172:175], v[196:199], v[36:39]
	v_mfma_f32_16x16x32_bf16 v[32:35], v[180:183], v[196:199], v[32:35]
	v_mfma_f32_16x16x32_bf16 v[20:23], v[172:175], v[204:207], v[20:23]
	v_mfma_f32_16x16x32_bf16 v[16:19], v[180:183], v[204:207], v[16:19]
	v_mfma_f32_16x16x32_bf16 v[4:7], v[172:175], v[212:215], v[4:7]
	v_mfma_f32_16x16x32_bf16 v[0:3], v[180:183], v[212:215], v[0:3]
	v_mfma_f32_16x16x32_bf16 v[52:55], v[176:179], v[192:195], v[52:55]
	v_mfma_f32_16x16x32_bf16 v[48:51], v[184:187], v[192:195], v[48:51]
	v_mfma_f32_16x16x32_bf16 v[36:39], v[176:179], v[200:203], v[36:39]
	v_mfma_f32_16x16x32_bf16 v[32:35], v[184:187], v[200:203], v[32:35]
	v_mfma_f32_16x16x32_bf16 v[20:23], v[176:179], v[208:211], v[20:23]
	v_mfma_f32_16x16x32_bf16 v[16:19], v[184:187], v[208:211], v[16:19]
	v_mfma_f32_16x16x32_bf16 v[4:7], v[176:179], v[216:219], v[4:7]
	v_mfma_f32_16x16x32_bf16 v[0:3], v[184:187], v[216:219], v[0:3]
	s_setprio 0
	s_add_i32 s81, s81, 2
.LBB0_562:
	s_barrier
	ds_read_b128 v[148:151], v154
	ds_read_b128 v[160:163], v154 offset:1024
	ds_read_b128 v[164:167], v154 offset:2048
	ds_read_b128 v[168:171], v154 offset:3072
	ds_read_b128 v[172:175], v155
	ds_read_b128 v[176:179], v155 offset:1024
	ds_read_b128 v[180:183], v155 offset:2048
	ds_read_b128 v[184:187], v155 offset:3072
	s_add_u32 s34, s40, 0xfff50080
	s_addc_u32 s35, s41, -1
	s_cmp_eq_u32 s81, 40
	s_cselect_b32 s49, s1, s35
	s_cselect_b32 s48, s0, s34
	s_cselect_b32 s43, s29, s77
	s_cselect_b32 s42, s28, s13
	v_lshl_add_u64 v[220:221], s[40:41], 0, v[140:141]
	s_add_i32 m0, s52, 0xc000
	ds_read_b128 v[188:191], v157
	ds_read_b128 v[192:195], v157 offset:1024
	ds_read_b128 v[196:199], v157 offset:2048
	ds_read_b128 v[200:203], v157 offset:3072
	ds_read_b128 v[204:207], v157 offset:4096
	ds_read_b128 v[208:211], v157 offset:5120
	ds_read_b128 v[212:215], v157 offset:6144
	ds_read_b128 v[216:219], v157 offset:7168
	global_load_lds_dwordx4 v[220:221], off
	v_lshl_add_u64 v[220:221], s[40:41], 0, v[142:143]
	s_add_i32 m0, s52, 0xe000
	s_nop 0
	global_load_lds_dwordx4 v[220:221], off
	s_waitcnt vmcnt(8)
	s_waitcnt lgkmcnt(0)
	s_barrier
	s_setprio 1
	s_waitcnt lgkmcnt(0)
	v_mfma_f32_16x16x32_bf16 v[124:127], v[148:151], v[188:191], v[124:127]
	v_mfma_f32_16x16x32_bf16 v[120:123], v[164:167], v[188:191], v[120:123]
	v_mfma_f32_16x16x32_bf16 v[108:111], v[148:151], v[196:199], v[108:111]
	v_mfma_f32_16x16x32_bf16 v[104:107], v[164:167], v[196:199], v[104:107]
	v_mfma_f32_16x16x32_bf16 v[92:95], v[148:151], v[204:207], v[92:95]
	v_mfma_f32_16x16x32_bf16 v[88:91], v[164:167], v[204:207], v[88:91]
	v_mfma_f32_16x16x32_bf16 v[76:79], v[148:151], v[212:215], v[76:79]
	v_mfma_f32_16x16x32_bf16 v[72:75], v[164:167], v[212:215], v[72:75]
	v_mfma_f32_16x16x32_bf16 v[124:127], v[160:163], v[192:195], v[124:127]
	v_mfma_f32_16x16x32_bf16 v[120:123], v[168:171], v[192:195], v[120:123]
	v_mfma_f32_16x16x32_bf16 v[108:111], v[160:163], v[200:203], v[108:111]
	v_mfma_f32_16x16x32_bf16 v[104:107], v[168:171], v[200:203], v[104:107]
	v_mfma_f32_16x16x32_bf16 v[92:95], v[160:163], v[208:211], v[92:95]
	v_mfma_f32_16x16x32_bf16 v[88:91], v[168:171], v[208:211], v[88:91]
	v_mfma_f32_16x16x32_bf16 v[76:79], v[160:163], v[216:219], v[76:79]
	v_mfma_f32_16x16x32_bf16 v[72:75], v[168:171], v[216:219], v[72:75]
	s_setprio 0
	s_setprio 1
	v_mfma_f32_16x16x32_bf16 v[116:119], v[172:175], v[188:191], v[116:119]
	v_mfma_f32_16x16x32_bf16 v[112:115], v[180:183], v[188:191], v[112:115]
	v_mfma_f32_16x16x32_bf16 v[100:103], v[172:175], v[196:199], v[100:103]
	v_mfma_f32_16x16x32_bf16 v[96:99], v[180:183], v[196:199], v[96:99]
	v_mfma_f32_16x16x32_bf16 v[84:87], v[172:175], v[204:207], v[84:87]
	v_mfma_f32_16x16x32_bf16 v[80:83], v[180:183], v[204:207], v[80:83]
	v_mfma_f32_16x16x32_bf16 v[68:71], v[172:175], v[212:215], v[68:71]
	v_mfma_f32_16x16x32_bf16 v[64:67], v[180:183], v[212:215], v[64:67]
	v_mfma_f32_16x16x32_bf16 v[116:119], v[176:179], v[192:195], v[116:119]
	v_mfma_f32_16x16x32_bf16 v[112:115], v[184:187], v[192:195], v[112:115]
	v_mfma_f32_16x16x32_bf16 v[100:103], v[176:179], v[200:203], v[100:103]
	v_mfma_f32_16x16x32_bf16 v[96:99], v[184:187], v[200:203], v[96:99]
	v_mfma_f32_16x16x32_bf16 v[84:87], v[176:179], v[208:211], v[84:87]
	v_mfma_f32_16x16x32_bf16 v[80:83], v[184:187], v[208:211], v[80:83]
	v_mfma_f32_16x16x32_bf16 v[68:71], v[176:179], v[216:219], v[68:71]
	v_mfma_f32_16x16x32_bf16 v[64:67], v[184:187], v[216:219], v[64:67]
	s_setprio 0
	s_barrier
	s_add_i32 s34, s64, s51
	v_lshl_add_u64 v[220:221], s[42:43], 0, v[134:135]
	s_mov_b32 m0, s34
	ds_read_b128 v[188:191], v157 offset:16384
	ds_read_b128 v[192:195], v157 offset:17408
	ds_read_b128 v[196:199], v157 offset:18432
	ds_read_b128 v[200:203], v157 offset:19456
	ds_read_b128 v[204:207], v157 offset:20480
	ds_read_b128 v[208:211], v157 offset:21504
	ds_read_b128 v[212:215], v157 offset:22528
	ds_read_b128 v[216:219], v157 offset:23552
	global_load_lds_dwordx4 v[220:221], off
	s_add_i32 m0, s34, 0x2000
	s_add_u32 s34, s42, 0xb0000
	v_lshl_add_u64 v[222:223], s[42:43], 0, v[138:139]
	s_addc_u32 s35, s43, 0
	s_add_i32 s82, s65, s51
	global_load_lds_dwordx4 v[222:223], off
	v_lshl_add_u64 v[224:225], s[34:35], 0, v[134:135]
	s_mov_b32 m0, s82
	v_lshl_add_u64 v[226:227], s[48:49], 0, v[136:137]
	global_load_lds_dwordx4 v[224:225], off
	v_lshl_add_u64 v[224:225], s[34:35], 0, v[138:139]
	s_add_i32 m0, s82, 0x2000
	s_nop 0
	global_load_lds_dwordx4 v[224:225], off
	v_lshl_add_u64 v[224:225], s[48:49], 0, v[132:133]
	s_mov_b32 m0, s52
	s_nop 0
	global_load_lds_dwordx4 v[224:225], off
	s_mov_b32 m0, s53
	s_nop 0
	global_load_lds_dwordx4 v[226:227], off
	s_waitcnt vmcnt(8)
	s_waitcnt lgkmcnt(0)
	s_barrier
	s_setprio 1
	s_waitcnt lgkmcnt(0)
	v_mfma_f32_16x16x32_bf16 v[60:63], v[148:151], v[188:191], v[60:63]
	v_mfma_f32_16x16x32_bf16 v[56:59], v[164:167], v[188:191], v[56:59]
	v_mfma_f32_16x16x32_bf16 v[44:47], v[148:151], v[196:199], v[44:47]
	v_mfma_f32_16x16x32_bf16 v[40:43], v[164:167], v[196:199], v[40:43]
	v_mfma_f32_16x16x32_bf16 v[28:31], v[148:151], v[204:207], v[28:31]
	v_mfma_f32_16x16x32_bf16 v[24:27], v[164:167], v[204:207], v[24:27]
	v_mfma_f32_16x16x32_bf16 v[12:15], v[148:151], v[212:215], v[12:15]
	v_mfma_f32_16x16x32_bf16 v[8:11], v[164:167], v[212:215], v[8:11]
	v_mfma_f32_16x16x32_bf16 v[60:63], v[160:163], v[192:195], v[60:63]
	v_mfma_f32_16x16x32_bf16 v[56:59], v[168:171], v[192:195], v[56:59]
	v_mfma_f32_16x16x32_bf16 v[44:47], v[160:163], v[200:203], v[44:47]
	v_mfma_f32_16x16x32_bf16 v[40:43], v[168:171], v[200:203], v[40:43]
	v_mfma_f32_16x16x32_bf16 v[28:31], v[160:163], v[208:211], v[28:31]
	v_mfma_f32_16x16x32_bf16 v[24:27], v[168:171], v[208:211], v[24:27]
	v_mfma_f32_16x16x32_bf16 v[12:15], v[160:163], v[216:219], v[12:15]
	v_mfma_f32_16x16x32_bf16 v[8:11], v[168:171], v[216:219], v[8:11]
	s_setprio 0
	s_setprio 1
	v_mfma_f32_16x16x32_bf16 v[52:55], v[172:175], v[188:191], v[52:55]
	v_mfma_f32_16x16x32_bf16 v[48:51], v[180:183], v[188:191], v[48:51]
	v_mfma_f32_16x16x32_bf16 v[36:39], v[172:175], v[196:199], v[36:39]
	v_mfma_f32_16x16x32_bf16 v[32:35], v[180:183], v[196:199], v[32:35]
	v_mfma_f32_16x16x32_bf16 v[20:23], v[172:175], v[204:207], v[20:23]
	v_mfma_f32_16x16x32_bf16 v[16:19], v[180:183], v[204:207], v[16:19]
	v_mfma_f32_16x16x32_bf16 v[4:7], v[172:175], v[212:215], v[4:7]
	v_mfma_f32_16x16x32_bf16 v[0:3], v[180:183], v[212:215], v[0:3]
	v_mfma_f32_16x16x32_bf16 v[52:55], v[176:179], v[192:195], v[52:55]
	v_mfma_f32_16x16x32_bf16 v[48:51], v[184:187], v[192:195], v[48:51]
	v_mfma_f32_16x16x32_bf16 v[36:39], v[176:179], v[200:203], v[36:39]
	v_mfma_f32_16x16x32_bf16 v[32:35], v[184:187], v[200:203], v[32:35]
	v_mfma_f32_16x16x32_bf16 v[20:23], v[176:179], v[208:211], v[20:23]
	v_mfma_f32_16x16x32_bf16 v[16:19], v[184:187], v[208:211], v[16:19]
	v_mfma_f32_16x16x32_bf16 v[4:7], v[176:179], v[216:219], v[4:7]
	v_mfma_f32_16x16x32_bf16 v[0:3], v[184:187], v[216:219], v[0:3]
	s_setprio 0
	s_barrier
	s_add_i32 s82, 0, 0x18000
	v_add_u32_e32 v159, s82, v152
	s_add_i32 s83, 0, 0x1c000
	ds_read_b128 v[148:151], v159
	ds_read_b128 v[160:163], v159 offset:1024
	ds_read_b128 v[164:167], v159 offset:2048
	ds_read_b128 v[168:171], v159 offset:3072
	v_add_u32_e32 v159, s83, v152
	ds_read_b128 v[172:175], v159
	ds_read_b128 v[176:179], v159 offset:1024
	ds_read_b128 v[180:183], v159 offset:2048
	ds_read_b128 v[184:187], v159 offset:3072
	s_add_u32 s34, s48, 0xb0000
	s_addc_u32 s35, s49, 0
	s_mov_b32 m0, s54
	v_lshl_add_u64 v[228:229], s[34:35], 0, v[132:133]
	ds_read_b128 v[188:191], v157 offset:32768
	ds_read_b128 v[192:195], v157 offset:33792
	ds_read_b128 v[196:199], v157 offset:34816
	ds_read_b128 v[200:203], v157 offset:35840
	ds_read_b128 v[204:207], v157 offset:36864
	ds_read_b128 v[208:211], v157 offset:37888
	ds_read_b128 v[212:215], v157 offset:38912
	ds_read_b128 v[216:219], v157 offset:39936
	global_load_lds_dwordx4 v[228:229], off
	v_lshl_add_u64 v[228:229], s[34:35], 0, v[136:137]
	s_mov_b32 m0, s55
	s_nop 0
	global_load_lds_dwordx4 v[228:229], off
	s_waitcnt vmcnt(8)
	s_waitcnt lgkmcnt(0)
	s_barrier
	s_setprio 1
	s_waitcnt lgkmcnt(0)
	v_mfma_f32_16x16x32_bf16 v[124:127], v[148:151], v[188:191], v[124:127]
	v_mfma_f32_16x16x32_bf16 v[120:123], v[164:167], v[188:191], v[120:123]
	v_mfma_f32_16x16x32_bf16 v[108:111], v[148:151], v[196:199], v[108:111]
	v_mfma_f32_16x16x32_bf16 v[104:107], v[164:167], v[196:199], v[104:107]
	v_mfma_f32_16x16x32_bf16 v[92:95], v[148:151], v[204:207], v[92:95]
	v_mfma_f32_16x16x32_bf16 v[88:91], v[164:167], v[204:207], v[88:91]
	v_mfma_f32_16x16x32_bf16 v[76:79], v[148:151], v[212:215], v[76:79]
	v_mfma_f32_16x16x32_bf16 v[72:75], v[164:167], v[212:215], v[72:75]
	v_mfma_f32_16x16x32_bf16 v[124:127], v[160:163], v[192:195], v[124:127]
	v_mfma_f32_16x16x32_bf16 v[120:123], v[168:171], v[192:195], v[120:123]
	v_mfma_f32_16x16x32_bf16 v[108:111], v[160:163], v[200:203], v[108:111]
	v_mfma_f32_16x16x32_bf16 v[104:107], v[168:171], v[200:203], v[104:107]
	v_mfma_f32_16x16x32_bf16 v[92:95], v[160:163], v[208:211], v[92:95]
	v_mfma_f32_16x16x32_bf16 v[88:91], v[168:171], v[208:211], v[88:91]
	v_mfma_f32_16x16x32_bf16 v[76:79], v[160:163], v[216:219], v[76:79]
	v_mfma_f32_16x16x32_bf16 v[72:75], v[168:171], v[216:219], v[72:75]
	s_setprio 0
	s_setprio 1
	v_mfma_f32_16x16x32_bf16 v[116:119], v[172:175], v[188:191], v[116:119]
	v_mfma_f32_16x16x32_bf16 v[112:115], v[180:183], v[188:191], v[112:115]
	v_mfma_f32_16x16x32_bf16 v[100:103], v[172:175], v[196:199], v[100:103]
	v_mfma_f32_16x16x32_bf16 v[96:99], v[180:183], v[196:199], v[96:99]
	v_mfma_f32_16x16x32_bf16 v[84:87], v[172:175], v[204:207], v[84:87]
	v_mfma_f32_16x16x32_bf16 v[80:83], v[180:183], v[204:207], v[80:83]
	v_mfma_f32_16x16x32_bf16 v[68:71], v[172:175], v[212:215], v[68:71]
	v_mfma_f32_16x16x32_bf16 v[64:67], v[180:183], v[212:215], v[64:67]
	v_mfma_f32_16x16x32_bf16 v[116:119], v[176:179], v[192:195], v[116:119]
	v_mfma_f32_16x16x32_bf16 v[112:115], v[184:187], v[192:195], v[112:115]
	v_mfma_f32_16x16x32_bf16 v[100:103], v[176:179], v[200:203], v[100:103]
	v_mfma_f32_16x16x32_bf16 v[96:99], v[184:187], v[200:203], v[96:99]
	v_mfma_f32_16x16x32_bf16 v[84:87], v[176:179], v[208:211], v[84:87]
	v_mfma_f32_16x16x32_bf16 v[80:83], v[184:187], v[208:211], v[80:83]
	v_mfma_f32_16x16x32_bf16 v[68:71], v[176:179], v[216:219], v[68:71]
	v_mfma_f32_16x16x32_bf16 v[64:67], v[184:187], v[216:219], v[64:67]
	s_setprio 0
	s_barrier
	s_add_i32 s34, s82, s51
	v_lshl_add_u64 v[220:221], v[220:221], 0, s[22:23]
	s_mov_b32 m0, s34
	ds_read_b128 v[188:191], v157 offset:49152
	ds_read_b128 v[192:195], v157 offset:50176
	ds_read_b128 v[196:199], v157 offset:51200
	ds_read_b128 v[200:203], v157 offset:52224
	ds_read_b128 v[204:207], v157 offset:53248
	ds_read_b128 v[208:211], v157 offset:54272
	ds_read_b128 v[212:215], v157 offset:55296
	ds_read_b128 v[216:219], v157 offset:56320
	global_load_lds_dwordx4 v[220:221], off
	s_add_i32 m0, s34, 0x2000
	s_add_u32 s34, s42, 0xb0080
	v_lshl_add_u64 v[220:221], v[222:223], 0, s[22:23]
	s_addc_u32 s35, s43, 0
	s_add_i32 s42, s83, s51
	global_load_lds_dwordx4 v[220:221], off
	v_lshl_add_u64 v[220:221], s[34:35], 0, v[134:135]
	s_mov_b32 m0, s42
	s_nop 0
	global_load_lds_dwordx4 v[220:221], off
	v_lshl_add_u64 v[220:221], s[34:35], 0, v[138:139]
	s_add_i32 m0, s42, 0x2000
	s_nop 0
	global_load_lds_dwordx4 v[220:221], off
	v_lshl_add_u64 v[220:221], v[224:225], 0, s[22:23]
	s_mov_b32 m0, s57
	s_nop 0
	global_load_lds_dwordx4 v[220:221], off
	v_lshl_add_u64 v[220:221], v[226:227], 0, s[22:23]
	s_mov_b32 m0, s58
	s_nop 0
	global_load_lds_dwordx4 v[220:221], off
	s_waitcnt vmcnt(8)
	s_waitcnt lgkmcnt(0)
	s_barrier
	s_add_u32 s40, s40, 0x100
	s_addc_u32 s41, s41, 0
	s_add_u32 s13, s13, 0x100
	s_addc_u32 s77, s77, 0
	s_setprio 1
	s_waitcnt lgkmcnt(0)
	v_mfma_f32_16x16x32_bf16 v[60:63], v[148:151], v[188:191], v[60:63]
	v_mfma_f32_16x16x32_bf16 v[56:59], v[164:167], v[188:191], v[56:59]
	v_mfma_f32_16x16x32_bf16 v[44:47], v[148:151], v[196:199], v[44:47]
	v_mfma_f32_16x16x32_bf16 v[40:43], v[164:167], v[196:199], v[40:43]
	v_mfma_f32_16x16x32_bf16 v[28:31], v[148:151], v[204:207], v[28:31]
	v_mfma_f32_16x16x32_bf16 v[24:27], v[164:167], v[204:207], v[24:27]
	v_mfma_f32_16x16x32_bf16 v[12:15], v[148:151], v[212:215], v[12:15]
	v_mfma_f32_16x16x32_bf16 v[8:11], v[164:167], v[212:215], v[8:11]
	v_mfma_f32_16x16x32_bf16 v[60:63], v[160:163], v[192:195], v[60:63]
	v_mfma_f32_16x16x32_bf16 v[56:59], v[168:171], v[192:195], v[56:59]
	v_mfma_f32_16x16x32_bf16 v[44:47], v[160:163], v[200:203], v[44:47]
	v_mfma_f32_16x16x32_bf16 v[40:43], v[168:171], v[200:203], v[40:43]
	v_mfma_f32_16x16x32_bf16 v[28:31], v[160:163], v[208:211], v[28:31]
	v_mfma_f32_16x16x32_bf16 v[24:27], v[168:171], v[208:211], v[24:27]
	v_mfma_f32_16x16x32_bf16 v[12:15], v[160:163], v[216:219], v[12:15]
	v_mfma_f32_16x16x32_bf16 v[8:11], v[168:171], v[216:219], v[8:11]
	s_setprio 0
	s_setprio 1
	v_mfma_f32_16x16x32_bf16 v[52:55], v[172:175], v[188:191], v[52:55]
	v_mfma_f32_16x16x32_bf16 v[48:51], v[180:183], v[188:191], v[48:51]
	v_mfma_f32_16x16x32_bf16 v[36:39], v[172:175], v[196:199], v[36:39]
	v_mfma_f32_16x16x32_bf16 v[32:35], v[180:183], v[196:199], v[32:35]
	v_mfma_f32_16x16x32_bf16 v[20:23], v[172:175], v[204:207], v[20:23]
	v_mfma_f32_16x16x32_bf16 v[16:19], v[180:183], v[204:207], v[16:19]
	v_mfma_f32_16x16x32_bf16 v[4:7], v[172:175], v[212:215], v[4:7]
	v_mfma_f32_16x16x32_bf16 v[0:3], v[180:183], v[212:215], v[0:3]
	v_mfma_f32_16x16x32_bf16 v[52:55], v[176:179], v[192:195], v[52:55]
	v_mfma_f32_16x16x32_bf16 v[48:51], v[184:187], v[192:195], v[48:51]
	v_mfma_f32_16x16x32_bf16 v[36:39], v[176:179], v[200:203], v[36:39]
	v_mfma_f32_16x16x32_bf16 v[32:35], v[184:187], v[200:203], v[32:35]
	v_mfma_f32_16x16x32_bf16 v[20:23], v[176:179], v[208:211], v[20:23]
	v_mfma_f32_16x16x32_bf16 v[16:19], v[184:187], v[208:211], v[16:19]
	v_mfma_f32_16x16x32_bf16 v[4:7], v[176:179], v[216:219], v[4:7]
	v_mfma_f32_16x16x32_bf16 v[0:3], v[184:187], v[216:219], v[0:3]
	s_setprio 0
	s_add_i32 s81, s81, 2
	s_cmp_gt_u32 s81, 41
	s_cbranch_scc0 .LBB0_562
	s_sub_i32 s100, s81, 2
	s_cmp_eq_u32 s100, s98
	s_cbranch_scc1 .Lmy_nobar_6
	s_barrier

.Lmy_nobar2_7:
	ds_read_b128 v[148:151], v160
	ds_read_b128 v[152:155], v160 offset:1024
	ds_read_b128 v[164:167], v160 offset:2048
	ds_read_b128 v[168:171], v160 offset:3072
	ds_read_b128 v[172:175], v161
	ds_read_b128 v[176:179], v161 offset:1024
	ds_read_b128 v[180:183], v161 offset:2048
	ds_read_b128 v[184:187], v161 offset:3072
	s_add_u32 s34, s52, 0xfffc0080
	s_addc_u32 s35, s53, -1
	s_cmp_eq_u32 s77, 12
	s_cselect_b32 s57, s9, s35
	s_cselect_b32 s56, s10, s34
	s_cselect_b32 s55, s12, s43
	s_cselect_b32 s54, s13, s41
	v_lshl_add_u64 v[220:221], s[52:53], 0, v[140:141]
	s_add_i32 m0, s65, 0xc000
	ds_read_b128 v[188:191], v162
	ds_read_b128 v[192:195], v162 offset:1024
	ds_read_b128 v[196:199], v162 offset:2048
	ds_read_b128 v[200:203], v162 offset:3072
	ds_read_b128 v[204:207], v162 offset:4096
	ds_read_b128 v[208:211], v162 offset:5120
	ds_read_b128 v[212:215], v162 offset:6144
	ds_read_b128 v[216:219], v162 offset:7168
	global_load_lds_dwordx4 v[220:221], off
	v_lshl_add_u64 v[220:221], s[52:53], 0, v[142:143]
	s_add_i32 m0, s65, 0xe000
	s_nop 0
	global_load_lds_dwordx4 v[220:221], off
	s_waitcnt vmcnt(8)
	s_waitcnt lgkmcnt(0)
	s_barrier
	s_setprio 1
	s_waitcnt lgkmcnt(0)
	v_mfma_f32_16x16x32_bf16 v[124:127], v[148:151], v[188:191], 0
	v_mfma_f32_16x16x32_bf16 v[120:123], v[164:167], v[188:191], 0
	v_mfma_f32_16x16x32_bf16 v[108:111], v[148:151], v[196:199], 0
	v_mfma_f32_16x16x32_bf16 v[104:107], v[164:167], v[196:199], 0
	v_mfma_f32_16x16x32_bf16 v[92:95], v[148:151], v[204:207], 0
	v_mfma_f32_16x16x32_bf16 v[88:91], v[164:167], v[204:207], 0
	v_mfma_f32_16x16x32_bf16 v[76:79], v[148:151], v[212:215], 0
	v_mfma_f32_16x16x32_bf16 v[72:75], v[164:167], v[212:215], 0
	v_mfma_f32_16x16x32_bf16 v[124:127], v[152:155], v[192:195], v[124:127]
	v_mfma_f32_16x16x32_bf16 v[120:123], v[168:171], v[192:195], v[120:123]
	v_mfma_f32_16x16x32_bf16 v[108:111], v[152:155], v[200:203], v[108:111]
	v_mfma_f32_16x16x32_bf16 v[104:107], v[168:171], v[200:203], v[104:107]
	v_mfma_f32_16x16x32_bf16 v[92:95], v[152:155], v[208:211], v[92:95]
	v_mfma_f32_16x16x32_bf16 v[88:91], v[168:171], v[208:211], v[88:91]
	v_mfma_f32_16x16x32_bf16 v[76:79], v[152:155], v[216:219], v[76:79]
	v_mfma_f32_16x16x32_bf16 v[72:75], v[168:171], v[216:219], v[72:75]
	s_setprio 0
	s_setprio 1
	v_mfma_f32_16x16x32_bf16 v[116:119], v[172:175], v[188:191], 0
	v_mfma_f32_16x16x32_bf16 v[112:115], v[180:183], v[188:191], 0
	v_mfma_f32_16x16x32_bf16 v[100:103], v[172:175], v[196:199], 0
	v_mfma_f32_16x16x32_bf16 v[96:99], v[180:183], v[196:199], 0
	v_mfma_f32_16x16x32_bf16 v[84:87], v[172:175], v[204:207], 0
	v_mfma_f32_16x16x32_bf16 v[80:83], v[180:183], v[204:207], 0
	v_mfma_f32_16x16x32_bf16 v[68:71], v[172:175], v[212:215], 0
	v_mfma_f32_16x16x32_bf16 v[64:67], v[180:183], v[212:215], 0
	v_mfma_f32_16x16x32_bf16 v[116:119], v[176:179], v[192:195], v[116:119]
	v_mfma_f32_16x16x32_bf16 v[112:115], v[184:187], v[192:195], v[112:115]
	v_mfma_f32_16x16x32_bf16 v[100:103], v[176:179], v[200:203], v[100:103]
	v_mfma_f32_16x16x32_bf16 v[96:99], v[184:187], v[200:203], v[96:99]
	v_mfma_f32_16x16x32_bf16 v[84:87], v[176:179], v[208:211], v[84:87]
	v_mfma_f32_16x16x32_bf16 v[80:83], v[184:187], v[208:211], v[80:83]
	v_mfma_f32_16x16x32_bf16 v[68:71], v[176:179], v[216:219], v[68:71]
	v_mfma_f32_16x16x32_bf16 v[64:67], v[184:187], v[216:219], v[64:67]
	s_setprio 0
	s_barrier
	s_add_i32 s34, s88, s62
	v_lshl_add_u64 v[220:221], s[54:55], 0, v[134:135]
	s_mov_b32 m0, s34
	ds_read_b128 v[188:191], v162 offset:16384
	ds_read_b128 v[192:195], v162 offset:17408
	ds_read_b128 v[196:199], v162 offset:18432
	ds_read_b128 v[200:203], v162 offset:19456
	ds_read_b128 v[204:207], v162 offset:20480
	ds_read_b128 v[208:211], v162 offset:21504
	ds_read_b128 v[212:215], v162 offset:22528
	ds_read_b128 v[216:219], v162 offset:23552
	global_load_lds_dwordx4 v[220:221], off
	s_add_i32 m0, s34, 0x2000
	s_add_u32 s34, s54, 0x40000
	v_lshl_add_u64 v[222:223], s[54:55], 0, v[138:139]
	s_addc_u32 s35, s55, 0
	s_add_i32 s90, s89, s62
	global_load_lds_dwordx4 v[222:223], off
	v_lshl_add_u64 v[224:225], s[34:35], 0, v[134:135]
	s_mov_b32 m0, s90
	v_lshl_add_u64 v[226:227], s[56:57], 0, v[136:137]
	global_load_lds_dwordx4 v[224:225], off
	v_lshl_add_u64 v[224:225], s[34:35], 0, v[138:139]
	s_add_i32 m0, s90, 0x2000
	s_nop 0
	global_load_lds_dwordx4 v[224:225], off
	v_lshl_add_u64 v[224:225], s[56:57], 0, v[132:133]
	s_mov_b32 m0, s65
	s_nop 0
	global_load_lds_dwordx4 v[224:225], off
	s_mov_b32 m0, s66
	s_nop 0
	global_load_lds_dwordx4 v[226:227], off
	s_waitcnt vmcnt(8)
	s_waitcnt lgkmcnt(0)
	s_barrier
	s_setprio 1
	s_waitcnt lgkmcnt(0)
	v_mfma_f32_16x16x32_bf16 v[60:63], v[148:151], v[188:191], 0
	v_mfma_f32_16x16x32_bf16 v[56:59], v[164:167], v[188:191], 0
	v_mfma_f32_16x16x32_bf16 v[44:47], v[148:151], v[196:199], 0
	v_mfma_f32_16x16x32_bf16 v[40:43], v[164:167], v[196:199], 0
	v_mfma_f32_16x16x32_bf16 v[28:31], v[148:151], v[204:207], 0
	v_mfma_f32_16x16x32_bf16 v[24:27], v[164:167], v[204:207], 0
	v_mfma_f32_16x16x32_bf16 v[12:15], v[148:151], v[212:215], 0
	v_mfma_f32_16x16x32_bf16 v[8:11], v[164:167], v[212:215], 0
	v_mfma_f32_16x16x32_bf16 v[60:63], v[152:155], v[192:195], v[60:63]
	v_mfma_f32_16x16x32_bf16 v[56:59], v[168:171], v[192:195], v[56:59]
	v_mfma_f32_16x16x32_bf16 v[44:47], v[152:155], v[200:203], v[44:47]
	v_mfma_f32_16x16x32_bf16 v[40:43], v[168:171], v[200:203], v[40:43]
	v_mfma_f32_16x16x32_bf16 v[28:31], v[152:155], v[208:211], v[28:31]
	v_mfma_f32_16x16x32_bf16 v[24:27], v[168:171], v[208:211], v[24:27]
	v_mfma_f32_16x16x32_bf16 v[12:15], v[152:155], v[216:219], v[12:15]
	v_mfma_f32_16x16x32_bf16 v[8:11], v[168:171], v[216:219], v[8:11]
	s_setprio 0
	s_setprio 1
	v_mfma_f32_16x16x32_bf16 v[52:55], v[172:175], v[188:191], 0
	v_mfma_f32_16x16x32_bf16 v[48:51], v[180:183], v[188:191], 0
	v_mfma_f32_16x16x32_bf16 v[36:39], v[172:175], v[196:199], 0
	v_mfma_f32_16x16x32_bf16 v[32:35], v[180:183], v[196:199], 0
	v_mfma_f32_16x16x32_bf16 v[20:23], v[172:175], v[204:207], 0
	v_mfma_f32_16x16x32_bf16 v[16:19], v[180:183], v[204:207], 0
	v_mfma_f32_16x16x32_bf16 v[4:7], v[172:175], v[212:215], 0
	v_mfma_f32_16x16x32_bf16 v[0:3], v[180:183], v[212:215], 0
	v_mfma_f32_16x16x32_bf16 v[52:55], v[176:179], v[192:195], v[52:55]
	v_mfma_f32_16x16x32_bf16 v[48:51], v[184:187], v[192:195], v[48:51]
	v_mfma_f32_16x16x32_bf16 v[36:39], v[176:179], v[200:203], v[36:39]
	v_mfma_f32_16x16x32_bf16 v[32:35], v[184:187], v[200:203], v[32:35]
	v_mfma_f32_16x16x32_bf16 v[20:23], v[176:179], v[208:211], v[20:23]
	v_mfma_f32_16x16x32_bf16 v[16:19], v[184:187], v[208:211], v[16:19]
	v_mfma_f32_16x16x32_bf16 v[4:7], v[176:179], v[216:219], v[4:7]
	v_mfma_f32_16x16x32_bf16 v[0:3], v[184:187], v[216:219], v[0:3]
	s_setprio 0
	s_barrier
	s_add_i32 s90, 0, 0x18000
	s_add_i32 s95, 0, 0x1c000
	v_add_u32_e32 v168, s90, v157
	v_add_u32_e32 v184, s95, v157
	ds_read_b128 v[148:151], v168
	ds_read_b128 v[152:155], v168 offset:1024
	ds_read_b128 v[164:167], v168 offset:2048
	ds_read_b128 v[168:171], v168 offset:3072
	ds_read_b128 v[172:175], v184
	ds_read_b128 v[176:179], v184 offset:1024
	ds_read_b128 v[180:183], v184 offset:2048
	ds_read_b128 v[184:187], v184 offset:3072
	s_add_u32 s34, s56, 0x40000
	s_addc_u32 s35, s57, 0
	s_mov_b32 m0, s67
	v_lshl_add_u64 v[228:229], s[34:35], 0, v[132:133]
	ds_read_b128 v[188:191], v162 offset:32768
	ds_read_b128 v[192:195], v162 offset:33792
	ds_read_b128 v[196:199], v162 offset:34816
	ds_read_b128 v[200:203], v162 offset:35840
	ds_read_b128 v[204:207], v162 offset:36864
	ds_read_b128 v[208:211], v162 offset:37888
	ds_read_b128 v[212:215], v162 offset:38912
	ds_read_b128 v[216:219], v162 offset:39936
	global_load_lds_dwordx4 v[228:229], off
	v_lshl_add_u64 v[228:229], s[34:35], 0, v[136:137]
	s_mov_b32 m0, s79
	s_nop 0
	global_load_lds_dwordx4 v[228:229], off
	s_waitcnt vmcnt(8)
	s_waitcnt lgkmcnt(0)
	s_barrier
	s_setprio 1
	s_waitcnt lgkmcnt(0)
	v_mfma_f32_16x16x32_bf16 v[124:127], v[148:151], v[188:191], v[124:127]
	v_mfma_f32_16x16x32_bf16 v[120:123], v[164:167], v[188:191], v[120:123]
	v_mfma_f32_16x16x32_bf16 v[108:111], v[148:151], v[196:199], v[108:111]
	v_mfma_f32_16x16x32_bf16 v[104:107], v[164:167], v[196:199], v[104:107]
	v_mfma_f32_16x16x32_bf16 v[92:95], v[148:151], v[204:207], v[92:95]
	v_mfma_f32_16x16x32_bf16 v[88:91], v[164:167], v[204:207], v[88:91]
	v_mfma_f32_16x16x32_bf16 v[76:79], v[148:151], v[212:215], v[76:79]
	v_mfma_f32_16x16x32_bf16 v[72:75], v[164:167], v[212:215], v[72:75]
	v_mfma_f32_16x16x32_bf16 v[124:127], v[152:155], v[192:195], v[124:127]
	v_mfma_f32_16x16x32_bf16 v[120:123], v[168:171], v[192:195], v[120:123]
	v_mfma_f32_16x16x32_bf16 v[108:111], v[152:155], v[200:203], v[108:111]
	v_mfma_f32_16x16x32_bf16 v[104:107], v[168:171], v[200:203], v[104:107]
	v_mfma_f32_16x16x32_bf16 v[92:95], v[152:155], v[208:211], v[92:95]
	v_mfma_f32_16x16x32_bf16 v[88:91], v[168:171], v[208:211], v[88:91]
	v_mfma_f32_16x16x32_bf16 v[76:79], v[152:155], v[216:219], v[76:79]
	v_mfma_f32_16x16x32_bf16 v[72:75], v[168:171], v[216:219], v[72:75]
	s_setprio 0
	s_setprio 1
	v_mfma_f32_16x16x32_bf16 v[116:119], v[172:175], v[188:191], v[116:119]
	v_mfma_f32_16x16x32_bf16 v[112:115], v[180:183], v[188:191], v[112:115]
	v_mfma_f32_16x16x32_bf16 v[100:103], v[172:175], v[196:199], v[100:103]
	v_mfma_f32_16x16x32_bf16 v[96:99], v[180:183], v[196:199], v[96:99]
	v_mfma_f32_16x16x32_bf16 v[84:87], v[172:175], v[204:207], v[84:87]
	v_mfma_f32_16x16x32_bf16 v[80:83], v[180:183], v[204:207], v[80:83]
	v_mfma_f32_16x16x32_bf16 v[68:71], v[172:175], v[212:215], v[68:71]
	v_mfma_f32_16x16x32_bf16 v[64:67], v[180:183], v[212:215], v[64:67]
	v_mfma_f32_16x16x32_bf16 v[116:119], v[176:179], v[192:195], v[116:119]
	v_mfma_f32_16x16x32_bf16 v[112:115], v[184:187], v[192:195], v[112:115]
	v_mfma_f32_16x16x32_bf16 v[100:103], v[176:179], v[200:203], v[100:103]
	v_mfma_f32_16x16x32_bf16 v[96:99], v[184:187], v[200:203], v[96:99]
	v_mfma_f32_16x16x32_bf16 v[84:87], v[176:179], v[208:211], v[84:87]
	v_mfma_f32_16x16x32_bf16 v[80:83], v[184:187], v[208:211], v[80:83]
	v_mfma_f32_16x16x32_bf16 v[68:71], v[176:179], v[216:219], v[68:71]
	v_mfma_f32_16x16x32_bf16 v[64:67], v[184:187], v[216:219], v[64:67]
	s_setprio 0
	s_barrier
	s_add_i32 s34, s90, s62
	v_lshl_add_u64 v[220:221], v[220:221], 0, s[26:27]
	s_mov_b32 m0, s34
	ds_read_b128 v[188:191], v162 offset:49152
	ds_read_b128 v[192:195], v162 offset:50176
	ds_read_b128 v[196:199], v162 offset:51200
	ds_read_b128 v[200:203], v162 offset:52224
	ds_read_b128 v[204:207], v162 offset:53248
	ds_read_b128 v[208:211], v162 offset:54272
	ds_read_b128 v[212:215], v162 offset:55296
	ds_read_b128 v[216:219], v162 offset:56320
	global_load_lds_dwordx4 v[220:221], off
	s_add_i32 m0, s34, 0x2000
	s_add_u32 s34, s54, 0x40080
	v_lshl_add_u64 v[220:221], v[222:223], 0, s[26:27]
	s_addc_u32 s35, s55, 0
	s_add_i32 s54, s95, s62
	global_load_lds_dwordx4 v[220:221], off
	v_lshl_add_u64 v[220:221], s[34:35], 0, v[134:135]
	s_mov_b32 m0, s54
	s_nop 0
	global_load_lds_dwordx4 v[220:221], off
	v_lshl_add_u64 v[220:221], s[34:35], 0, v[138:139]
	s_add_i32 m0, s54, 0x2000
	s_nop 0
	global_load_lds_dwordx4 v[220:221], off
	v_lshl_add_u64 v[220:221], v[224:225], 0, s[26:27]
	s_mov_b32 m0, s83
	s_nop 0
	global_load_lds_dwordx4 v[220:221], off
	v_lshl_add_u64 v[220:221], v[226:227], 0, s[26:27]
	s_mov_b32 m0, s84
	s_nop 0
	global_load_lds_dwordx4 v[220:221], off
	s_waitcnt vmcnt(8)
	s_waitcnt lgkmcnt(0)
	s_barrier
	s_add_u32 s52, s52, 0x100
	s_addc_u32 s53, s53, 0
	s_add_u32 s41, s41, 0x100
	s_addc_u32 s43, s43, 0
	s_setprio 1
	s_waitcnt lgkmcnt(0)
	v_mfma_f32_16x16x32_bf16 v[60:63], v[148:151], v[188:191], v[60:63]
	v_mfma_f32_16x16x32_bf16 v[56:59], v[164:167], v[188:191], v[56:59]
	v_mfma_f32_16x16x32_bf16 v[44:47], v[148:151], v[196:199], v[44:47]
	v_mfma_f32_16x16x32_bf16 v[40:43], v[164:167], v[196:199], v[40:43]
	v_mfma_f32_16x16x32_bf16 v[28:31], v[148:151], v[204:207], v[28:31]
	v_mfma_f32_16x16x32_bf16 v[24:27], v[164:167], v[204:207], v[24:27]
	v_mfma_f32_16x16x32_bf16 v[12:15], v[148:151], v[212:215], v[12:15]
	v_mfma_f32_16x16x32_bf16 v[8:11], v[164:167], v[212:215], v[8:11]
	v_mfma_f32_16x16x32_bf16 v[60:63], v[152:155], v[192:195], v[60:63]
	v_mfma_f32_16x16x32_bf16 v[56:59], v[168:171], v[192:195], v[56:59]
	v_mfma_f32_16x16x32_bf16 v[44:47], v[152:155], v[200:203], v[44:47]
	v_mfma_f32_16x16x32_bf16 v[40:43], v[168:171], v[200:203], v[40:43]
	v_mfma_f32_16x16x32_bf16 v[28:31], v[152:155], v[208:211], v[28:31]
	v_mfma_f32_16x16x32_bf16 v[24:27], v[168:171], v[208:211], v[24:27]
	v_mfma_f32_16x16x32_bf16 v[12:15], v[152:155], v[216:219], v[12:15]
	v_mfma_f32_16x16x32_bf16 v[8:11], v[168:171], v[216:219], v[8:11]
	s_setprio 0
	s_setprio 1
	v_mfma_f32_16x16x32_bf16 v[52:55], v[172:175], v[188:191], v[52:55]
	v_mfma_f32_16x16x32_bf16 v[48:51], v[180:183], v[188:191], v[48:51]
	v_mfma_f32_16x16x32_bf16 v[36:39], v[172:175], v[196:199], v[36:39]
	v_mfma_f32_16x16x32_bf16 v[32:35], v[180:183], v[196:199], v[32:35]
	v_mfma_f32_16x16x32_bf16 v[20:23], v[172:175], v[204:207], v[20:23]
	v_mfma_f32_16x16x32_bf16 v[16:19], v[180:183], v[204:207], v[16:19]
	v_mfma_f32_16x16x32_bf16 v[4:7], v[172:175], v[212:215], v[4:7]
	v_mfma_f32_16x16x32_bf16 v[0:3], v[180:183], v[212:215], v[0:3]
	v_mfma_f32_16x16x32_bf16 v[52:55], v[176:179], v[192:195], v[52:55]
	v_mfma_f32_16x16x32_bf16 v[48:51], v[184:187], v[192:195], v[48:51]
	v_mfma_f32_16x16x32_bf16 v[36:39], v[176:179], v[200:203], v[36:39]
	v_mfma_f32_16x16x32_bf16 v[32:35], v[184:187], v[200:203], v[32:35]
	v_mfma_f32_16x16x32_bf16 v[20:23], v[176:179], v[208:211], v[20:23]
	v_mfma_f32_16x16x32_bf16 v[16:19], v[184:187], v[208:211], v[16:19]
	v_mfma_f32_16x16x32_bf16 v[4:7], v[176:179], v[216:219], v[4:7]
	v_mfma_f32_16x16x32_bf16 v[0:3], v[184:187], v[216:219], v[0:3]
	s_setprio 0
	s_add_i32 s77, s77, 2
.LBB0_655:
	s_barrier
	ds_read_b128 v[148:151], v160
	ds_read_b128 v[152:155], v160 offset:1024
	ds_read_b128 v[164:167], v160 offset:2048
	ds_read_b128 v[168:171], v160 offset:3072
	ds_read_b128 v[172:175], v161
	ds_read_b128 v[176:179], v161 offset:1024
	ds_read_b128 v[180:183], v161 offset:2048
	ds_read_b128 v[184:187], v161 offset:3072
	s_add_u32 s34, s52, 0xfffc0080
	s_addc_u32 s35, s53, -1
	s_cmp_eq_u32 s77, 12
	s_cselect_b32 s57, s9, s35
	s_cselect_b32 s56, s10, s34
	s_cselect_b32 s55, s12, s43
	s_cselect_b32 s54, s13, s41
	v_lshl_add_u64 v[220:221], s[52:53], 0, v[140:141]
	s_add_i32 m0, s65, 0xc000
	ds_read_b128 v[188:191], v162
	ds_read_b128 v[192:195], v162 offset:1024
	ds_read_b128 v[196:199], v162 offset:2048
	ds_read_b128 v[200:203], v162 offset:3072
	ds_read_b128 v[204:207], v162 offset:4096
	ds_read_b128 v[208:211], v162 offset:5120
	ds_read_b128 v[212:215], v162 offset:6144
	ds_read_b128 v[216:219], v162 offset:7168
	global_load_lds_dwordx4 v[220:221], off
	v_lshl_add_u64 v[220:221], s[52:53], 0, v[142:143]
	s_add_i32 m0, s65, 0xe000
	s_nop 0
	global_load_lds_dwordx4 v[220:221], off
	s_waitcnt vmcnt(8)
	s_waitcnt lgkmcnt(0)
	s_barrier
	s_setprio 1
	s_waitcnt lgkmcnt(0)
	v_mfma_f32_16x16x32_bf16 v[124:127], v[148:151], v[188:191], v[124:127]
	v_mfma_f32_16x16x32_bf16 v[120:123], v[164:167], v[188:191], v[120:123]
	v_mfma_f32_16x16x32_bf16 v[108:111], v[148:151], v[196:199], v[108:111]
	v_mfma_f32_16x16x32_bf16 v[104:107], v[164:167], v[196:199], v[104:107]
	v_mfma_f32_16x16x32_bf16 v[92:95], v[148:151], v[204:207], v[92:95]
	v_mfma_f32_16x16x32_bf16 v[88:91], v[164:167], v[204:207], v[88:91]
	v_mfma_f32_16x16x32_bf16 v[76:79], v[148:151], v[212:215], v[76:79]
	v_mfma_f32_16x16x32_bf16 v[72:75], v[164:167], v[212:215], v[72:75]
	v_mfma_f32_16x16x32_bf16 v[124:127], v[152:155], v[192:195], v[124:127]
	v_mfma_f32_16x16x32_bf16 v[120:123], v[168:171], v[192:195], v[120:123]
	v_mfma_f32_16x16x32_bf16 v[108:111], v[152:155], v[200:203], v[108:111]
	v_mfma_f32_16x16x32_bf16 v[104:107], v[168:171], v[200:203], v[104:107]
	v_mfma_f32_16x16x32_bf16 v[92:95], v[152:155], v[208:211], v[92:95]
	v_mfma_f32_16x16x32_bf16 v[88:91], v[168:171], v[208:211], v[88:91]
	v_mfma_f32_16x16x32_bf16 v[76:79], v[152:155], v[216:219], v[76:79]
	v_mfma_f32_16x16x32_bf16 v[72:75], v[168:171], v[216:219], v[72:75]
	s_setprio 0
	s_setprio 1
	v_mfma_f32_16x16x32_bf16 v[116:119], v[172:175], v[188:191], v[116:119]
	v_mfma_f32_16x16x32_bf16 v[112:115], v[180:183], v[188:191], v[112:115]
	v_mfma_f32_16x16x32_bf16 v[100:103], v[172:175], v[196:199], v[100:103]
	v_mfma_f32_16x16x32_bf16 v[96:99], v[180:183], v[196:199], v[96:99]
	v_mfma_f32_16x16x32_bf16 v[84:87], v[172:175], v[204:207], v[84:87]
	v_mfma_f32_16x16x32_bf16 v[80:83], v[180:183], v[204:207], v[80:83]
	v_mfma_f32_16x16x32_bf16 v[68:71], v[172:175], v[212:215], v[68:71]
	v_mfma_f32_16x16x32_bf16 v[64:67], v[180:183], v[212:215], v[64:67]
	v_mfma_f32_16x16x32_bf16 v[116:119], v[176:179], v[192:195], v[116:119]
	v_mfma_f32_16x16x32_bf16 v[112:115], v[184:187], v[192:195], v[112:115]
	v_mfma_f32_16x16x32_bf16 v[100:103], v[176:179], v[200:203], v[100:103]
	v_mfma_f32_16x16x32_bf16 v[96:99], v[184:187], v[200:203], v[96:99]
	v_mfma_f32_16x16x32_bf16 v[84:87], v[176:179], v[208:211], v[84:87]
	v_mfma_f32_16x16x32_bf16 v[80:83], v[184:187], v[208:211], v[80:83]
	v_mfma_f32_16x16x32_bf16 v[68:71], v[176:179], v[216:219], v[68:71]
	v_mfma_f32_16x16x32_bf16 v[64:67], v[184:187], v[216:219], v[64:67]
	s_setprio 0
	s_barrier
	s_add_i32 s34, s88, s62
	v_lshl_add_u64 v[220:221], s[54:55], 0, v[134:135]
	s_mov_b32 m0, s34
	ds_read_b128 v[188:191], v162 offset:16384
	ds_read_b128 v[192:195], v162 offset:17408
	ds_read_b128 v[196:199], v162 offset:18432
	ds_read_b128 v[200:203], v162 offset:19456
	ds_read_b128 v[204:207], v162 offset:20480
	ds_read_b128 v[208:211], v162 offset:21504
	ds_read_b128 v[212:215], v162 offset:22528
	ds_read_b128 v[216:219], v162 offset:23552
	global_load_lds_dwordx4 v[220:221], off
	s_add_i32 m0, s34, 0x2000
	s_add_u32 s34, s54, 0x40000
	v_lshl_add_u64 v[222:223], s[54:55], 0, v[138:139]
	s_addc_u32 s35, s55, 0
	s_add_i32 s90, s89, s62
	global_load_lds_dwordx4 v[222:223], off
	v_lshl_add_u64 v[224:225], s[34:35], 0, v[134:135]
	s_mov_b32 m0, s90
	v_lshl_add_u64 v[226:227], s[56:57], 0, v[136:137]
	global_load_lds_dwordx4 v[224:225], off
	v_lshl_add_u64 v[224:225], s[34:35], 0, v[138:139]
	s_add_i32 m0, s90, 0x2000
	s_nop 0
	global_load_lds_dwordx4 v[224:225], off
	v_lshl_add_u64 v[224:225], s[56:57], 0, v[132:133]
	s_mov_b32 m0, s65
	s_nop 0
	global_load_lds_dwordx4 v[224:225], off
	s_mov_b32 m0, s66
	s_nop 0
	global_load_lds_dwordx4 v[226:227], off
	s_waitcnt vmcnt(8)
	s_waitcnt lgkmcnt(0)
	s_barrier
	s_setprio 1
	s_waitcnt lgkmcnt(0)
	v_mfma_f32_16x16x32_bf16 v[60:63], v[148:151], v[188:191], v[60:63]
	v_mfma_f32_16x16x32_bf16 v[56:59], v[164:167], v[188:191], v[56:59]
	v_mfma_f32_16x16x32_bf16 v[44:47], v[148:151], v[196:199], v[44:47]
	v_mfma_f32_16x16x32_bf16 v[40:43], v[164:167], v[196:199], v[40:43]
	v_mfma_f32_16x16x32_bf16 v[28:31], v[148:151], v[204:207], v[28:31]
	v_mfma_f32_16x16x32_bf16 v[24:27], v[164:167], v[204:207], v[24:27]
	v_mfma_f32_16x16x32_bf16 v[12:15], v[148:151], v[212:215], v[12:15]
	v_mfma_f32_16x16x32_bf16 v[8:11], v[164:167], v[212:215], v[8:11]
	v_mfma_f32_16x16x32_bf16 v[60:63], v[152:155], v[192:195], v[60:63]
	v_mfma_f32_16x16x32_bf16 v[56:59], v[168:171], v[192:195], v[56:59]
	v_mfma_f32_16x16x32_bf16 v[44:47], v[152:155], v[200:203], v[44:47]
	v_mfma_f32_16x16x32_bf16 v[40:43], v[168:171], v[200:203], v[40:43]
	v_mfma_f32_16x16x32_bf16 v[28:31], v[152:155], v[208:211], v[28:31]
	v_mfma_f32_16x16x32_bf16 v[24:27], v[168:171], v[208:211], v[24:27]
	v_mfma_f32_16x16x32_bf16 v[12:15], v[152:155], v[216:219], v[12:15]
	v_mfma_f32_16x16x32_bf16 v[8:11], v[168:171], v[216:219], v[8:11]
	s_setprio 0
	s_setprio 1
	v_mfma_f32_16x16x32_bf16 v[52:55], v[172:175], v[188:191], v[52:55]
	v_mfma_f32_16x16x32_bf16 v[48:51], v[180:183], v[188:191], v[48:51]
	v_mfma_f32_16x16x32_bf16 v[36:39], v[172:175], v[196:199], v[36:39]
	v_mfma_f32_16x16x32_bf16 v[32:35], v[180:183], v[196:199], v[32:35]
	v_mfma_f32_16x16x32_bf16 v[20:23], v[172:175], v[204:207], v[20:23]
	v_mfma_f32_16x16x32_bf16 v[16:19], v[180:183], v[204:207], v[16:19]
	v_mfma_f32_16x16x32_bf16 v[4:7], v[172:175], v[212:215], v[4:7]
	v_mfma_f32_16x16x32_bf16 v[0:3], v[180:183], v[212:215], v[0:3]
	v_mfma_f32_16x16x32_bf16 v[52:55], v[176:179], v[192:195], v[52:55]
	v_mfma_f32_16x16x32_bf16 v[48:51], v[184:187], v[192:195], v[48:51]
	v_mfma_f32_16x16x32_bf16 v[36:39], v[176:179], v[200:203], v[36:39]
	v_mfma_f32_16x16x32_bf16 v[32:35], v[184:187], v[200:203], v[32:35]
	v_mfma_f32_16x16x32_bf16 v[20:23], v[176:179], v[208:211], v[20:23]
	v_mfma_f32_16x16x32_bf16 v[16:19], v[184:187], v[208:211], v[16:19]
	v_mfma_f32_16x16x32_bf16 v[4:7], v[176:179], v[216:219], v[4:7]
	v_mfma_f32_16x16x32_bf16 v[0:3], v[184:187], v[216:219], v[0:3]
	s_setprio 0
	s_barrier
	s_add_i32 s90, 0, 0x18000
	s_add_i32 s95, 0, 0x1c000
	v_add_u32_e32 v168, s90, v157
	v_add_u32_e32 v184, s95, v157
	ds_read_b128 v[148:151], v168
	ds_read_b128 v[152:155], v168 offset:1024
	ds_read_b128 v[164:167], v168 offset:2048
	ds_read_b128 v[168:171], v168 offset:3072
	ds_read_b128 v[172:175], v184
	ds_read_b128 v[176:179], v184 offset:1024
	ds_read_b128 v[180:183], v184 offset:2048
	ds_read_b128 v[184:187], v184 offset:3072
	s_add_u32 s34, s56, 0x40000
	s_addc_u32 s35, s57, 0
	s_mov_b32 m0, s67
	v_lshl_add_u64 v[228:229], s[34:35], 0, v[132:133]
	ds_read_b128 v[188:191], v162 offset:32768
	ds_read_b128 v[192:195], v162 offset:33792
	ds_read_b128 v[196:199], v162 offset:34816
	ds_read_b128 v[200:203], v162 offset:35840
	ds_read_b128 v[204:207], v162 offset:36864
	ds_read_b128 v[208:211], v162 offset:37888
	ds_read_b128 v[212:215], v162 offset:38912
	ds_read_b128 v[216:219], v162 offset:39936
	global_load_lds_dwordx4 v[228:229], off
	v_lshl_add_u64 v[228:229], s[34:35], 0, v[136:137]
	s_mov_b32 m0, s79
	s_nop 0
	global_load_lds_dwordx4 v[228:229], off
	s_waitcnt vmcnt(8)
	s_waitcnt lgkmcnt(0)
	s_barrier
	s_setprio 1
	s_waitcnt lgkmcnt(0)
	v_mfma_f32_16x16x32_bf16 v[124:127], v[148:151], v[188:191], v[124:127]
	v_mfma_f32_16x16x32_bf16 v[120:123], v[164:167], v[188:191], v[120:123]
	v_mfma_f32_16x16x32_bf16 v[108:111], v[148:151], v[196:199], v[108:111]
	v_mfma_f32_16x16x32_bf16 v[104:107], v[164:167], v[196:199], v[104:107]
	v_mfma_f32_16x16x32_bf16 v[92:95], v[148:151], v[204:207], v[92:95]
	v_mfma_f32_16x16x32_bf16 v[88:91], v[164:167], v[204:207], v[88:91]
	v_mfma_f32_16x16x32_bf16 v[76:79], v[148:151], v[212:215], v[76:79]
	v_mfma_f32_16x16x32_bf16 v[72:75], v[164:167], v[212:215], v[72:75]
	v_mfma_f32_16x16x32_bf16 v[124:127], v[152:155], v[192:195], v[124:127]
	v_mfma_f32_16x16x32_bf16 v[120:123], v[168:171], v[192:195], v[120:123]
	v_mfma_f32_16x16x32_bf16 v[108:111], v[152:155], v[200:203], v[108:111]
	v_mfma_f32_16x16x32_bf16 v[104:107], v[168:171], v[200:203], v[104:107]
	v_mfma_f32_16x16x32_bf16 v[92:95], v[152:155], v[208:211], v[92:95]
	v_mfma_f32_16x16x32_bf16 v[88:91], v[168:171], v[208:211], v[88:91]
	v_mfma_f32_16x16x32_bf16 v[76:79], v[152:155], v[216:219], v[76:79]
	v_mfma_f32_16x16x32_bf16 v[72:75], v[168:171], v[216:219], v[72:75]
	s_setprio 0
	s_setprio 1
	v_mfma_f32_16x16x32_bf16 v[116:119], v[172:175], v[188:191], v[116:119]
	v_mfma_f32_16x16x32_bf16 v[112:115], v[180:183], v[188:191], v[112:115]
	v_mfma_f32_16x16x32_bf16 v[100:103], v[172:175], v[196:199], v[100:103]
	v_mfma_f32_16x16x32_bf16 v[96:99], v[180:183], v[196:199], v[96:99]
	v_mfma_f32_16x16x32_bf16 v[84:87], v[172:175], v[204:207], v[84:87]
	v_mfma_f32_16x16x32_bf16 v[80:83], v[180:183], v[204:207], v[80:83]
	v_mfma_f32_16x16x32_bf16 v[68:71], v[172:175], v[212:215], v[68:71]
	v_mfma_f32_16x16x32_bf16 v[64:67], v[180:183], v[212:215], v[64:67]
	v_mfma_f32_16x16x32_bf16 v[116:119], v[176:179], v[192:195], v[116:119]
	v_mfma_f32_16x16x32_bf16 v[112:115], v[184:187], v[192:195], v[112:115]
	v_mfma_f32_16x16x32_bf16 v[100:103], v[176:179], v[200:203], v[100:103]
	v_mfma_f32_16x16x32_bf16 v[96:99], v[184:187], v[200:203], v[96:99]
	v_mfma_f32_16x16x32_bf16 v[84:87], v[176:179], v[208:211], v[84:87]
	v_mfma_f32_16x16x32_bf16 v[80:83], v[184:187], v[208:211], v[80:83]
	v_mfma_f32_16x16x32_bf16 v[68:71], v[176:179], v[216:219], v[68:71]
	v_mfma_f32_16x16x32_bf16 v[64:67], v[184:187], v[216:219], v[64:67]
	s_setprio 0
	s_barrier
	s_add_i32 s34, s90, s62
	v_lshl_add_u64 v[220:221], v[220:221], 0, s[26:27]
	s_mov_b32 m0, s34
	ds_read_b128 v[188:191], v162 offset:49152
	ds_read_b128 v[192:195], v162 offset:50176
	ds_read_b128 v[196:199], v162 offset:51200
	ds_read_b128 v[200:203], v162 offset:52224
	ds_read_b128 v[204:207], v162 offset:53248
	ds_read_b128 v[208:211], v162 offset:54272
	ds_read_b128 v[212:215], v162 offset:55296
	ds_read_b128 v[216:219], v162 offset:56320
	global_load_lds_dwordx4 v[220:221], off
	s_add_i32 m0, s34, 0x2000
	s_add_u32 s34, s54, 0x40080
	v_lshl_add_u64 v[220:221], v[222:223], 0, s[26:27]
	s_addc_u32 s35, s55, 0
	s_add_i32 s54, s95, s62
	global_load_lds_dwordx4 v[220:221], off
	v_lshl_add_u64 v[220:221], s[34:35], 0, v[134:135]
	s_mov_b32 m0, s54
	s_nop 0
	global_load_lds_dwordx4 v[220:221], off
	v_lshl_add_u64 v[220:221], s[34:35], 0, v[138:139]
	s_add_i32 m0, s54, 0x2000
	s_nop 0
	global_load_lds_dwordx4 v[220:221], off
	v_lshl_add_u64 v[220:221], v[224:225], 0, s[26:27]
	s_mov_b32 m0, s83
	s_nop 0
	global_load_lds_dwordx4 v[220:221], off
	v_lshl_add_u64 v[220:221], v[226:227], 0, s[26:27]
	s_mov_b32 m0, s84
	s_nop 0
	global_load_lds_dwordx4 v[220:221], off
	s_waitcnt vmcnt(8)
	s_waitcnt lgkmcnt(0)
	s_barrier
	s_add_u32 s52, s52, 0x100
	s_addc_u32 s53, s53, 0
	s_add_u32 s41, s41, 0x100
	s_addc_u32 s43, s43, 0
	s_setprio 1
	s_waitcnt lgkmcnt(0)
	v_mfma_f32_16x16x32_bf16 v[60:63], v[148:151], v[188:191], v[60:63]
	v_mfma_f32_16x16x32_bf16 v[56:59], v[164:167], v[188:191], v[56:59]
	v_mfma_f32_16x16x32_bf16 v[44:47], v[148:151], v[196:199], v[44:47]
	v_mfma_f32_16x16x32_bf16 v[40:43], v[164:167], v[196:199], v[40:43]
	v_mfma_f32_16x16x32_bf16 v[28:31], v[148:151], v[204:207], v[28:31]
	v_mfma_f32_16x16x32_bf16 v[24:27], v[164:167], v[204:207], v[24:27]
	v_mfma_f32_16x16x32_bf16 v[12:15], v[148:151], v[212:215], v[12:15]
	v_mfma_f32_16x16x32_bf16 v[8:11], v[164:167], v[212:215], v[8:11]
	v_mfma_f32_16x16x32_bf16 v[60:63], v[152:155], v[192:195], v[60:63]
	v_mfma_f32_16x16x32_bf16 v[56:59], v[168:171], v[192:195], v[56:59]
	v_mfma_f32_16x16x32_bf16 v[44:47], v[152:155], v[200:203], v[44:47]
	v_mfma_f32_16x16x32_bf16 v[40:43], v[168:171], v[200:203], v[40:43]
	v_mfma_f32_16x16x32_bf16 v[28:31], v[152:155], v[208:211], v[28:31]
	v_mfma_f32_16x16x32_bf16 v[24:27], v[168:171], v[208:211], v[24:27]
	v_mfma_f32_16x16x32_bf16 v[12:15], v[152:155], v[216:219], v[12:15]
	v_mfma_f32_16x16x32_bf16 v[8:11], v[168:171], v[216:219], v[8:11]
	s_setprio 0
	s_setprio 1
	v_mfma_f32_16x16x32_bf16 v[52:55], v[172:175], v[188:191], v[52:55]
	v_mfma_f32_16x16x32_bf16 v[48:51], v[180:183], v[188:191], v[48:51]
	v_mfma_f32_16x16x32_bf16 v[36:39], v[172:175], v[196:199], v[36:39]
	v_mfma_f32_16x16x32_bf16 v[32:35], v[180:183], v[196:199], v[32:35]
	v_mfma_f32_16x16x32_bf16 v[20:23], v[172:175], v[204:207], v[20:23]
	v_mfma_f32_16x16x32_bf16 v[16:19], v[180:183], v[204:207], v[16:19]
	v_mfma_f32_16x16x32_bf16 v[4:7], v[172:175], v[212:215], v[4:7]
	v_mfma_f32_16x16x32_bf16 v[0:3], v[180:183], v[212:215], v[0:3]
	v_mfma_f32_16x16x32_bf16 v[52:55], v[176:179], v[192:195], v[52:55]
	v_mfma_f32_16x16x32_bf16 v[48:51], v[184:187], v[192:195], v[48:51]
	v_mfma_f32_16x16x32_bf16 v[36:39], v[176:179], v[200:203], v[36:39]
	v_mfma_f32_16x16x32_bf16 v[32:35], v[184:187], v[200:203], v[32:35]
	v_mfma_f32_16x16x32_bf16 v[20:23], v[176:179], v[208:211], v[20:23]
	v_mfma_f32_16x16x32_bf16 v[16:19], v[184:187], v[208:211], v[16:19]
	v_mfma_f32_16x16x32_bf16 v[4:7], v[176:179], v[216:219], v[4:7]
	v_mfma_f32_16x16x32_bf16 v[0:3], v[184:187], v[216:219], v[0:3]
	s_setprio 0
	s_add_i32 s77, s77, 2
	s_cmp_gt_u32 s77, 13
	s_cbranch_scc0 .LBB0_655
	s_sub_i32 s100, s77, 2
	s_cmp_eq_u32 s100, s98
	s_cbranch_scc1 .Lmy_nobar_7
	s_barrier
.Lmy_nobar_7:
	s_and_b64 vcc, exec, s[28:29]
	s_cbranch_vccz .LBB0_658
	s_nop 0

.Lmy_nobar2_9:
	ds_read_b128 v[148:151], v154
	ds_read_b128 v[160:163], v154 offset:1024
	ds_read_b128 v[164:167], v154 offset:2048
	ds_read_b128 v[168:171], v154 offset:3072
	ds_read_b128 v[172:175], v155
	ds_read_b128 v[176:179], v155 offset:1024
	ds_read_b128 v[180:183], v155 offset:2048
	ds_read_b128 v[184:187], v155 offset:3072
	s_add_u32 s34, s40, 0xfffc0080
	s_addc_u32 s35, s41, -1
	s_cmp_eq_u32 s77, 12
	s_cselect_b32 s49, s12, s35
	s_cselect_b32 s48, s13, s34
	s_cselect_b32 s43, s27, s67
	s_cselect_b32 s42, s29, s39
	v_lshl_add_u64 v[220:221], s[40:41], 0, v[140:141]
	s_add_i32 m0, s52, 0xc000
	ds_read_b128 v[188:191], v157
	ds_read_b128 v[192:195], v157 offset:1024
	ds_read_b128 v[196:199], v157 offset:2048
	ds_read_b128 v[200:203], v157 offset:3072
	ds_read_b128 v[204:207], v157 offset:4096
	ds_read_b128 v[208:211], v157 offset:5120
	ds_read_b128 v[212:215], v157 offset:6144
	ds_read_b128 v[216:219], v157 offset:7168
	global_load_lds_dwordx4 v[220:221], off
	v_lshl_add_u64 v[220:221], s[40:41], 0, v[142:143]
	s_add_i32 m0, s52, 0xe000
	s_nop 0
	global_load_lds_dwordx4 v[220:221], off
	s_waitcnt vmcnt(8)
	s_waitcnt lgkmcnt(0)
	s_barrier
	s_setprio 1
	s_waitcnt lgkmcnt(0)
	v_mfma_f32_16x16x32_bf16 v[124:127], v[148:151], v[188:191], 0
	v_mfma_f32_16x16x32_bf16 v[120:123], v[164:167], v[188:191], 0
	v_mfma_f32_16x16x32_bf16 v[108:111], v[148:151], v[196:199], 0
	v_mfma_f32_16x16x32_bf16 v[104:107], v[164:167], v[196:199], 0
	v_mfma_f32_16x16x32_bf16 v[92:95], v[148:151], v[204:207], 0
	v_mfma_f32_16x16x32_bf16 v[88:91], v[164:167], v[204:207], 0
	v_mfma_f32_16x16x32_bf16 v[76:79], v[148:151], v[212:215], 0
	v_mfma_f32_16x16x32_bf16 v[72:75], v[164:167], v[212:215], 0
	v_mfma_f32_16x16x32_bf16 v[124:127], v[160:163], v[192:195], v[124:127]
	v_mfma_f32_16x16x32_bf16 v[120:123], v[168:171], v[192:195], v[120:123]
	v_mfma_f32_16x16x32_bf16 v[108:111], v[160:163], v[200:203], v[108:111]
	v_mfma_f32_16x16x32_bf16 v[104:107], v[168:171], v[200:203], v[104:107]
	v_mfma_f32_16x16x32_bf16 v[92:95], v[160:163], v[208:211], v[92:95]
	v_mfma_f32_16x16x32_bf16 v[88:91], v[168:171], v[208:211], v[88:91]
	v_mfma_f32_16x16x32_bf16 v[76:79], v[160:163], v[216:219], v[76:79]
	v_mfma_f32_16x16x32_bf16 v[72:75], v[168:171], v[216:219], v[72:75]
	s_setprio 0
	s_setprio 1
	v_mfma_f32_16x16x32_bf16 v[116:119], v[172:175], v[188:191], 0
	v_mfma_f32_16x16x32_bf16 v[112:115], v[180:183], v[188:191], 0
	v_mfma_f32_16x16x32_bf16 v[100:103], v[172:175], v[196:199], 0
	v_mfma_f32_16x16x32_bf16 v[96:99], v[180:183], v[196:199], 0
	v_mfma_f32_16x16x32_bf16 v[84:87], v[172:175], v[204:207], 0
	v_mfma_f32_16x16x32_bf16 v[80:83], v[180:183], v[204:207], 0
	v_mfma_f32_16x16x32_bf16 v[68:71], v[172:175], v[212:215], 0
	v_mfma_f32_16x16x32_bf16 v[64:67], v[180:183], v[212:215], 0
	v_mfma_f32_16x16x32_bf16 v[116:119], v[176:179], v[192:195], v[116:119]
	v_mfma_f32_16x16x32_bf16 v[112:115], v[184:187], v[192:195], v[112:115]
	v_mfma_f32_16x16x32_bf16 v[100:103], v[176:179], v[200:203], v[100:103]
	v_mfma_f32_16x16x32_bf16 v[96:99], v[184:187], v[200:203], v[96:99]
	v_mfma_f32_16x16x32_bf16 v[84:87], v[176:179], v[208:211], v[84:87]
	v_mfma_f32_16x16x32_bf16 v[80:83], v[184:187], v[208:211], v[80:83]
	v_mfma_f32_16x16x32_bf16 v[68:71], v[176:179], v[216:219], v[68:71]
	v_mfma_f32_16x16x32_bf16 v[64:67], v[184:187], v[216:219], v[64:67]
	s_setprio 0
	s_barrier
	s_add_i32 s34, s64, s51
	v_lshl_add_u64 v[220:221], s[42:43], 0, v[134:135]
	s_mov_b32 m0, s34
	ds_read_b128 v[188:191], v157 offset:16384
	ds_read_b128 v[192:195], v157 offset:17408
	ds_read_b128 v[196:199], v157 offset:18432
	ds_read_b128 v[200:203], v157 offset:19456
	ds_read_b128 v[204:207], v157 offset:20480
	ds_read_b128 v[208:211], v157 offset:21504
	ds_read_b128 v[212:215], v157 offset:22528
	ds_read_b128 v[216:219], v157 offset:23552
	global_load_lds_dwordx4 v[220:221], off
	s_add_i32 m0, s34, 0x2000
	s_add_u32 s34, s42, 0x40000
	v_lshl_add_u64 v[222:223], s[42:43], 0, v[138:139]
	s_addc_u32 s35, s43, 0
	s_add_i32 s79, s65, s51
	global_load_lds_dwordx4 v[222:223], off
	v_lshl_add_u64 v[224:225], s[34:35], 0, v[134:135]
	s_mov_b32 m0, s79
	v_lshl_add_u64 v[226:227], s[48:49], 0, v[136:137]
	global_load_lds_dwordx4 v[224:225], off
	v_lshl_add_u64 v[224:225], s[34:35], 0, v[138:139]
	s_add_i32 m0, s79, 0x2000
	s_nop 0
	global_load_lds_dwordx4 v[224:225], off
	v_lshl_add_u64 v[224:225], s[48:49], 0, v[132:133]
	s_mov_b32 m0, s52
	s_nop 0
	global_load_lds_dwordx4 v[224:225], off
	s_mov_b32 m0, s53
	s_nop 0
	global_load_lds_dwordx4 v[226:227], off
	s_waitcnt vmcnt(8)
	s_waitcnt lgkmcnt(0)
	s_barrier
	s_setprio 1
	s_waitcnt lgkmcnt(0)
	v_mfma_f32_16x16x32_bf16 v[60:63], v[148:151], v[188:191], 0
	v_mfma_f32_16x16x32_bf16 v[56:59], v[164:167], v[188:191], 0
	v_mfma_f32_16x16x32_bf16 v[44:47], v[148:151], v[196:199], 0
	v_mfma_f32_16x16x32_bf16 v[40:43], v[164:167], v[196:199], 0
	v_mfma_f32_16x16x32_bf16 v[28:31], v[148:151], v[204:207], 0
	v_mfma_f32_16x16x32_bf16 v[24:27], v[164:167], v[204:207], 0
	v_mfma_f32_16x16x32_bf16 v[12:15], v[148:151], v[212:215], 0
	v_mfma_f32_16x16x32_bf16 v[8:11], v[164:167], v[212:215], 0
	v_mfma_f32_16x16x32_bf16 v[60:63], v[160:163], v[192:195], v[60:63]
	v_mfma_f32_16x16x32_bf16 v[56:59], v[168:171], v[192:195], v[56:59]
	v_mfma_f32_16x16x32_bf16 v[44:47], v[160:163], v[200:203], v[44:47]
	v_mfma_f32_16x16x32_bf16 v[40:43], v[168:171], v[200:203], v[40:43]
	v_mfma_f32_16x16x32_bf16 v[28:31], v[160:163], v[208:211], v[28:31]
	v_mfma_f32_16x16x32_bf16 v[24:27], v[168:171], v[208:211], v[24:27]
	v_mfma_f32_16x16x32_bf16 v[12:15], v[160:163], v[216:219], v[12:15]
	v_mfma_f32_16x16x32_bf16 v[8:11], v[168:171], v[216:219], v[8:11]
	s_setprio 0
	s_setprio 1
	v_mfma_f32_16x16x32_bf16 v[52:55], v[172:175], v[188:191], 0
	v_mfma_f32_16x16x32_bf16 v[48:51], v[180:183], v[188:191], 0
	v_mfma_f32_16x16x32_bf16 v[36:39], v[172:175], v[196:199], 0
	v_mfma_f32_16x16x32_bf16 v[32:35], v[180:183], v[196:199], 0
	v_mfma_f32_16x16x32_bf16 v[20:23], v[172:175], v[204:207], 0
	v_mfma_f32_16x16x32_bf16 v[16:19], v[180:183], v[204:207], 0
	v_mfma_f32_16x16x32_bf16 v[4:7], v[172:175], v[212:215], 0
	v_mfma_f32_16x16x32_bf16 v[0:3], v[180:183], v[212:215], 0
	v_mfma_f32_16x16x32_bf16 v[52:55], v[176:179], v[192:195], v[52:55]
	v_mfma_f32_16x16x32_bf16 v[48:51], v[184:187], v[192:195], v[48:51]
	v_mfma_f32_16x16x32_bf16 v[36:39], v[176:179], v[200:203], v[36:39]
	v_mfma_f32_16x16x32_bf16 v[32:35], v[184:187], v[200:203], v[32:35]
	v_mfma_f32_16x16x32_bf16 v[20:23], v[176:179], v[208:211], v[20:23]
	v_mfma_f32_16x16x32_bf16 v[16:19], v[184:187], v[208:211], v[16:19]
	v_mfma_f32_16x16x32_bf16 v[4:7], v[176:179], v[216:219], v[4:7]
	v_mfma_f32_16x16x32_bf16 v[0:3], v[184:187], v[216:219], v[0:3]
	s_setprio 0
	s_barrier
	s_add_i32 s79, 0, 0x18000
	v_add_u32_e32 v159, s79, v152
	s_add_i32 s81, 0, 0x1c000
	ds_read_b128 v[148:151], v159
	ds_read_b128 v[160:163], v159 offset:1024
	ds_read_b128 v[164:167], v159 offset:2048
	ds_read_b128 v[168:171], v159 offset:3072
	v_add_u32_e32 v159, s81, v152
	ds_read_b128 v[172:175], v159
	ds_read_b128 v[176:179], v159 offset:1024
	ds_read_b128 v[180:183], v159 offset:2048
	ds_read_b128 v[184:187], v159 offset:3072
	s_add_u32 s34, s48, 0x40000
	s_addc_u32 s35, s49, 0
	s_mov_b32 m0, s54
	v_lshl_add_u64 v[228:229], s[34:35], 0, v[132:133]
	ds_read_b128 v[188:191], v157 offset:32768
	ds_read_b128 v[192:195], v157 offset:33792
	ds_read_b128 v[196:199], v157 offset:34816
	ds_read_b128 v[200:203], v157 offset:35840
	ds_read_b128 v[204:207], v157 offset:36864
	ds_read_b128 v[208:211], v157 offset:37888
	ds_read_b128 v[212:215], v157 offset:38912
	ds_read_b128 v[216:219], v157 offset:39936
	global_load_lds_dwordx4 v[228:229], off
	v_lshl_add_u64 v[228:229], s[34:35], 0, v[136:137]
	s_mov_b32 m0, s55
	s_nop 0
	global_load_lds_dwordx4 v[228:229], off
	s_waitcnt vmcnt(8)
	s_waitcnt lgkmcnt(0)
	s_barrier
	s_setprio 1
	s_waitcnt lgkmcnt(0)
	v_mfma_f32_16x16x32_bf16 v[124:127], v[148:151], v[188:191], v[124:127]
	v_mfma_f32_16x16x32_bf16 v[120:123], v[164:167], v[188:191], v[120:123]
	v_mfma_f32_16x16x32_bf16 v[108:111], v[148:151], v[196:199], v[108:111]
	v_mfma_f32_16x16x32_bf16 v[104:107], v[164:167], v[196:199], v[104:107]
	v_mfma_f32_16x16x32_bf16 v[92:95], v[148:151], v[204:207], v[92:95]
	v_mfma_f32_16x16x32_bf16 v[88:91], v[164:167], v[204:207], v[88:91]
	v_mfma_f32_16x16x32_bf16 v[76:79], v[148:151], v[212:215], v[76:79]
	v_mfma_f32_16x16x32_bf16 v[72:75], v[164:167], v[212:215], v[72:75]
	v_mfma_f32_16x16x32_bf16 v[124:127], v[160:163], v[192:195], v[124:127]
	v_mfma_f32_16x16x32_bf16 v[120:123], v[168:171], v[192:195], v[120:123]
	v_mfma_f32_16x16x32_bf16 v[108:111], v[160:163], v[200:203], v[108:111]
	v_mfma_f32_16x16x32_bf16 v[104:107], v[168:171], v[200:203], v[104:107]
	v_mfma_f32_16x16x32_bf16 v[92:95], v[160:163], v[208:211], v[92:95]
	v_mfma_f32_16x16x32_bf16 v[88:91], v[168:171], v[208:211], v[88:91]
	v_mfma_f32_16x16x32_bf16 v[76:79], v[160:163], v[216:219], v[76:79]
	v_mfma_f32_16x16x32_bf16 v[72:75], v[168:171], v[216:219], v[72:75]
	s_setprio 0
	s_setprio 1
	v_mfma_f32_16x16x32_bf16 v[116:119], v[172:175], v[188:191], v[116:119]
	v_mfma_f32_16x16x32_bf16 v[112:115], v[180:183], v[188:191], v[112:115]
	v_mfma_f32_16x16x32_bf16 v[100:103], v[172:175], v[196:199], v[100:103]
	v_mfma_f32_16x16x32_bf16 v[96:99], v[180:183], v[196:199], v[96:99]
	v_mfma_f32_16x16x32_bf16 v[84:87], v[172:175], v[204:207], v[84:87]
	v_mfma_f32_16x16x32_bf16 v[80:83], v[180:183], v[204:207], v[80:83]
	v_mfma_f32_16x16x32_bf16 v[68:71], v[172:175], v[212:215], v[68:71]
	v_mfma_f32_16x16x32_bf16 v[64:67], v[180:183], v[212:215], v[64:67]
	v_mfma_f32_16x16x32_bf16 v[116:119], v[176:179], v[192:195], v[116:119]
	v_mfma_f32_16x16x32_bf16 v[112:115], v[184:187], v[192:195], v[112:115]
	v_mfma_f32_16x16x32_bf16 v[100:103], v[176:179], v[200:203], v[100:103]
	v_mfma_f32_16x16x32_bf16 v[96:99], v[184:187], v[200:203], v[96:99]
	v_mfma_f32_16x16x32_bf16 v[84:87], v[176:179], v[208:211], v[84:87]
	v_mfma_f32_16x16x32_bf16 v[80:83], v[184:187], v[208:211], v[80:83]
	v_mfma_f32_16x16x32_bf16 v[68:71], v[176:179], v[216:219], v[68:71]
	v_mfma_f32_16x16x32_bf16 v[64:67], v[184:187], v[216:219], v[64:67]
	s_setprio 0
	s_barrier
	s_add_i32 s34, s79, s51
	v_lshl_add_u64 v[220:221], v[220:221], 0, s[10:11]
	s_mov_b32 m0, s34
	ds_read_b128 v[188:191], v157 offset:49152
	ds_read_b128 v[192:195], v157 offset:50176
	ds_read_b128 v[196:199], v157 offset:51200
	ds_read_b128 v[200:203], v157 offset:52224
	ds_read_b128 v[204:207], v157 offset:53248
	ds_read_b128 v[208:211], v157 offset:54272
	ds_read_b128 v[212:215], v157 offset:55296
	ds_read_b128 v[216:219], v157 offset:56320
	global_load_lds_dwordx4 v[220:221], off
	s_add_i32 m0, s34, 0x2000
	s_add_u32 s34, s42, 0x40080
	v_lshl_add_u64 v[220:221], v[222:223], 0, s[10:11]
	s_addc_u32 s35, s43, 0
	s_add_i32 s42, s81, s51
	global_load_lds_dwordx4 v[220:221], off
	v_lshl_add_u64 v[220:221], s[34:35], 0, v[134:135]
	s_mov_b32 m0, s42
	s_nop 0
	global_load_lds_dwordx4 v[220:221], off
	v_lshl_add_u64 v[220:221], s[34:35], 0, v[138:139]
	s_add_i32 m0, s42, 0x2000
	s_nop 0
	global_load_lds_dwordx4 v[220:221], off
	v_lshl_add_u64 v[220:221], v[224:225], 0, s[10:11]
	s_mov_b32 m0, s57
	s_nop 0
	global_load_lds_dwordx4 v[220:221], off
	v_lshl_add_u64 v[220:221], v[226:227], 0, s[10:11]
	s_mov_b32 m0, s58
	s_nop 0
	global_load_lds_dwordx4 v[220:221], off
	s_waitcnt vmcnt(8)
	s_waitcnt lgkmcnt(0)
	s_barrier
	s_add_u32 s40, s40, 0x100
	s_addc_u32 s41, s41, 0
	s_add_u32 s39, s39, 0x100
	s_addc_u32 s67, s67, 0
	s_setprio 1
	s_waitcnt lgkmcnt(0)
	v_mfma_f32_16x16x32_bf16 v[60:63], v[148:151], v[188:191], v[60:63]
	v_mfma_f32_16x16x32_bf16 v[56:59], v[164:167], v[188:191], v[56:59]
	v_mfma_f32_16x16x32_bf16 v[44:47], v[148:151], v[196:199], v[44:47]
	v_mfma_f32_16x16x32_bf16 v[40:43], v[164:167], v[196:199], v[40:43]
	v_mfma_f32_16x16x32_bf16 v[28:31], v[148:151], v[204:207], v[28:31]
	v_mfma_f32_16x16x32_bf16 v[24:27], v[164:167], v[204:207], v[24:27]
	v_mfma_f32_16x16x32_bf16 v[12:15], v[148:151], v[212:215], v[12:15]
	v_mfma_f32_16x16x32_bf16 v[8:11], v[164:167], v[212:215], v[8:11]
	v_mfma_f32_16x16x32_bf16 v[60:63], v[160:163], v[192:195], v[60:63]
	v_mfma_f32_16x16x32_bf16 v[56:59], v[168:171], v[192:195], v[56:59]
	v_mfma_f32_16x16x32_bf16 v[44:47], v[160:163], v[200:203], v[44:47]
	v_mfma_f32_16x16x32_bf16 v[40:43], v[168:171], v[200:203], v[40:43]
	v_mfma_f32_16x16x32_bf16 v[28:31], v[160:163], v[208:211], v[28:31]
	v_mfma_f32_16x16x32_bf16 v[24:27], v[168:171], v[208:211], v[24:27]
	v_mfma_f32_16x16x32_bf16 v[12:15], v[160:163], v[216:219], v[12:15]
	v_mfma_f32_16x16x32_bf16 v[8:11], v[168:171], v[216:219], v[8:11]
	s_setprio 0
	s_setprio 1
	v_mfma_f32_16x16x32_bf16 v[52:55], v[172:175], v[188:191], v[52:55]
	v_mfma_f32_16x16x32_bf16 v[48:51], v[180:183], v[188:191], v[48:51]
	v_mfma_f32_16x16x32_bf16 v[36:39], v[172:175], v[196:199], v[36:39]
	v_mfma_f32_16x16x32_bf16 v[32:35], v[180:183], v[196:199], v[32:35]
	v_mfma_f32_16x16x32_bf16 v[20:23], v[172:175], v[204:207], v[20:23]
	v_mfma_f32_16x16x32_bf16 v[16:19], v[180:183], v[204:207], v[16:19]
	v_mfma_f32_16x16x32_bf16 v[4:7], v[172:175], v[212:215], v[4:7]
	v_mfma_f32_16x16x32_bf16 v[0:3], v[180:183], v[212:215], v[0:3]
	v_mfma_f32_16x16x32_bf16 v[52:55], v[176:179], v[192:195], v[52:55]
	v_mfma_f32_16x16x32_bf16 v[48:51], v[184:187], v[192:195], v[48:51]
	v_mfma_f32_16x16x32_bf16 v[36:39], v[176:179], v[200:203], v[36:39]
	v_mfma_f32_16x16x32_bf16 v[32:35], v[184:187], v[200:203], v[32:35]
	v_mfma_f32_16x16x32_bf16 v[20:23], v[176:179], v[208:211], v[20:23]
	v_mfma_f32_16x16x32_bf16 v[16:19], v[184:187], v[208:211], v[16:19]
	v_mfma_f32_16x16x32_bf16 v[4:7], v[176:179], v[216:219], v[4:7]
	v_mfma_f32_16x16x32_bf16 v[0:3], v[184:187], v[216:219], v[0:3]
	s_setprio 0
	s_add_i32 s77, s77, 2
.LBB0_969:
	s_barrier
	ds_read_b128 v[148:151], v154
	ds_read_b128 v[160:163], v154 offset:1024
	ds_read_b128 v[164:167], v154 offset:2048
	ds_read_b128 v[168:171], v154 offset:3072
	ds_read_b128 v[172:175], v155
	ds_read_b128 v[176:179], v155 offset:1024
	ds_read_b128 v[180:183], v155 offset:2048
	ds_read_b128 v[184:187], v155 offset:3072
	s_add_u32 s34, s40, 0xfffc0080
	s_addc_u32 s35, s41, -1
	s_cmp_eq_u32 s77, 12
	s_cselect_b32 s49, s12, s35
	s_cselect_b32 s48, s13, s34
	s_cselect_b32 s43, s27, s67
	s_cselect_b32 s42, s29, s39
	v_lshl_add_u64 v[220:221], s[40:41], 0, v[140:141]
	s_add_i32 m0, s52, 0xc000
	ds_read_b128 v[188:191], v157
	ds_read_b128 v[192:195], v157 offset:1024
	ds_read_b128 v[196:199], v157 offset:2048
	ds_read_b128 v[200:203], v157 offset:3072
	ds_read_b128 v[204:207], v157 offset:4096
	ds_read_b128 v[208:211], v157 offset:5120
	ds_read_b128 v[212:215], v157 offset:6144
	ds_read_b128 v[216:219], v157 offset:7168
	global_load_lds_dwordx4 v[220:221], off
	v_lshl_add_u64 v[220:221], s[40:41], 0, v[142:143]
	s_add_i32 m0, s52, 0xe000
	s_nop 0
	global_load_lds_dwordx4 v[220:221], off
	s_waitcnt vmcnt(8)
	s_waitcnt lgkmcnt(0)
	s_barrier
	s_setprio 1
	s_waitcnt lgkmcnt(0)
	v_mfma_f32_16x16x32_bf16 v[124:127], v[148:151], v[188:191], v[124:127]
	v_mfma_f32_16x16x32_bf16 v[120:123], v[164:167], v[188:191], v[120:123]
	v_mfma_f32_16x16x32_bf16 v[108:111], v[148:151], v[196:199], v[108:111]
	v_mfma_f32_16x16x32_bf16 v[104:107], v[164:167], v[196:199], v[104:107]
	v_mfma_f32_16x16x32_bf16 v[92:95], v[148:151], v[204:207], v[92:95]
	v_mfma_f32_16x16x32_bf16 v[88:91], v[164:167], v[204:207], v[88:91]
	v_mfma_f32_16x16x32_bf16 v[76:79], v[148:151], v[212:215], v[76:79]
	v_mfma_f32_16x16x32_bf16 v[72:75], v[164:167], v[212:215], v[72:75]
	v_mfma_f32_16x16x32_bf16 v[124:127], v[160:163], v[192:195], v[124:127]
	v_mfma_f32_16x16x32_bf16 v[120:123], v[168:171], v[192:195], v[120:123]
	v_mfma_f32_16x16x32_bf16 v[108:111], v[160:163], v[200:203], v[108:111]
	v_mfma_f32_16x16x32_bf16 v[104:107], v[168:171], v[200:203], v[104:107]
	v_mfma_f32_16x16x32_bf16 v[92:95], v[160:163], v[208:211], v[92:95]
	v_mfma_f32_16x16x32_bf16 v[88:91], v[168:171], v[208:211], v[88:91]
	v_mfma_f32_16x16x32_bf16 v[76:79], v[160:163], v[216:219], v[76:79]
	v_mfma_f32_16x16x32_bf16 v[72:75], v[168:171], v[216:219], v[72:75]
	s_setprio 0
	s_setprio 1
	v_mfma_f32_16x16x32_bf16 v[116:119], v[172:175], v[188:191], v[116:119]
	v_mfma_f32_16x16x32_bf16 v[112:115], v[180:183], v[188:191], v[112:115]
	v_mfma_f32_16x16x32_bf16 v[100:103], v[172:175], v[196:199], v[100:103]
	v_mfma_f32_16x16x32_bf16 v[96:99], v[180:183], v[196:199], v[96:99]
	v_mfma_f32_16x16x32_bf16 v[84:87], v[172:175], v[204:207], v[84:87]
	v_mfma_f32_16x16x32_bf16 v[80:83], v[180:183], v[204:207], v[80:83]
	v_mfma_f32_16x16x32_bf16 v[68:71], v[172:175], v[212:215], v[68:71]
	v_mfma_f32_16x16x32_bf16 v[64:67], v[180:183], v[212:215], v[64:67]
	v_mfma_f32_16x16x32_bf16 v[116:119], v[176:179], v[192:195], v[116:119]
	v_mfma_f32_16x16x32_bf16 v[112:115], v[184:187], v[192:195], v[112:115]
	v_mfma_f32_16x16x32_bf16 v[100:103], v[176:179], v[200:203], v[100:103]
	v_mfma_f32_16x16x32_bf16 v[96:99], v[184:187], v[200:203], v[96:99]
	v_mfma_f32_16x16x32_bf16 v[84:87], v[176:179], v[208:211], v[84:87]
	v_mfma_f32_16x16x32_bf16 v[80:83], v[184:187], v[208:211], v[80:83]
	v_mfma_f32_16x16x32_bf16 v[68:71], v[176:179], v[216:219], v[68:71]
	v_mfma_f32_16x16x32_bf16 v[64:67], v[184:187], v[216:219], v[64:67]
	s_setprio 0
	s_barrier
	s_add_i32 s34, s64, s51
	v_lshl_add_u64 v[220:221], s[42:43], 0, v[134:135]
	s_mov_b32 m0, s34
	ds_read_b128 v[188:191], v157 offset:16384
	ds_read_b128 v[192:195], v157 offset:17408
	ds_read_b128 v[196:199], v157 offset:18432
	ds_read_b128 v[200:203], v157 offset:19456
	ds_read_b128 v[204:207], v157 offset:20480
	ds_read_b128 v[208:211], v157 offset:21504
	ds_read_b128 v[212:215], v157 offset:22528
	ds_read_b128 v[216:219], v157 offset:23552
	global_load_lds_dwordx4 v[220:221], off
	s_add_i32 m0, s34, 0x2000
	s_add_u32 s34, s42, 0x40000
	v_lshl_add_u64 v[222:223], s[42:43], 0, v[138:139]
	s_addc_u32 s35, s43, 0
	s_add_i32 s79, s65, s51
	global_load_lds_dwordx4 v[222:223], off
	v_lshl_add_u64 v[224:225], s[34:35], 0, v[134:135]
	s_mov_b32 m0, s79
	v_lshl_add_u64 v[226:227], s[48:49], 0, v[136:137]
	global_load_lds_dwordx4 v[224:225], off
	v_lshl_add_u64 v[224:225], s[34:35], 0, v[138:139]
	s_add_i32 m0, s79, 0x2000
	s_nop 0
	global_load_lds_dwordx4 v[224:225], off
	v_lshl_add_u64 v[224:225], s[48:49], 0, v[132:133]
	s_mov_b32 m0, s52
	s_nop 0
	global_load_lds_dwordx4 v[224:225], off
	s_mov_b32 m0, s53
	s_nop 0
	global_load_lds_dwordx4 v[226:227], off
	s_waitcnt vmcnt(8)
	s_waitcnt lgkmcnt(0)
	s_barrier
	s_setprio 1
	s_waitcnt lgkmcnt(0)
	v_mfma_f32_16x16x32_bf16 v[60:63], v[148:151], v[188:191], v[60:63]
	v_mfma_f32_16x16x32_bf16 v[56:59], v[164:167], v[188:191], v[56:59]
	v_mfma_f32_16x16x32_bf16 v[44:47], v[148:151], v[196:199], v[44:47]
	v_mfma_f32_16x16x32_bf16 v[40:43], v[164:167], v[196:199], v[40:43]
	v_mfma_f32_16x16x32_bf16 v[28:31], v[148:151], v[204:207], v[28:31]
	v_mfma_f32_16x16x32_bf16 v[24:27], v[164:167], v[204:207], v[24:27]
	v_mfma_f32_16x16x32_bf16 v[12:15], v[148:151], v[212:215], v[12:15]
	v_mfma_f32_16x16x32_bf16 v[8:11], v[164:167], v[212:215], v[8:11]
	v_mfma_f32_16x16x32_bf16 v[60:63], v[160:163], v[192:195], v[60:63]
	v_mfma_f32_16x16x32_bf16 v[56:59], v[168:171], v[192:195], v[56:59]
	v_mfma_f32_16x16x32_bf16 v[44:47], v[160:163], v[200:203], v[44:47]
	v_mfma_f32_16x16x32_bf16 v[40:43], v[168:171], v[200:203], v[40:43]
	v_mfma_f32_16x16x32_bf16 v[28:31], v[160:163], v[208:211], v[28:31]
	v_mfma_f32_16x16x32_bf16 v[24:27], v[168:171], v[208:211], v[24:27]
	v_mfma_f32_16x16x32_bf16 v[12:15], v[160:163], v[216:219], v[12:15]
	v_mfma_f32_16x16x32_bf16 v[8:11], v[168:171], v[216:219], v[8:11]
	s_setprio 0
	s_setprio 1
	v_mfma_f32_16x16x32_bf16 v[52:55], v[172:175], v[188:191], v[52:55]
	v_mfma_f32_16x16x32_bf16 v[48:51], v[180:183], v[188:191], v[48:51]
	v_mfma_f32_16x16x32_bf16 v[36:39], v[172:175], v[196:199], v[36:39]
	v_mfma_f32_16x16x32_bf16 v[32:35], v[180:183], v[196:199], v[32:35]
	v_mfma_f32_16x16x32_bf16 v[20:23], v[172:175], v[204:207], v[20:23]
	v_mfma_f32_16x16x32_bf16 v[16:19], v[180:183], v[204:207], v[16:19]
	v_mfma_f32_16x16x32_bf16 v[4:7], v[172:175], v[212:215], v[4:7]
	v_mfma_f32_16x16x32_bf16 v[0:3], v[180:183], v[212:215], v[0:3]
	v_mfma_f32_16x16x32_bf16 v[52:55], v[176:179], v[192:195], v[52:55]
	v_mfma_f32_16x16x32_bf16 v[48:51], v[184:187], v[192:195], v[48:51]
	v_mfma_f32_16x16x32_bf16 v[36:39], v[176:179], v[200:203], v[36:39]
	v_mfma_f32_16x16x32_bf16 v[32:35], v[184:187], v[200:203], v[32:35]
	v_mfma_f32_16x16x32_bf16 v[20:23], v[176:179], v[208:211], v[20:23]
	v_mfma_f32_16x16x32_bf16 v[16:19], v[184:187], v[208:211], v[16:19]
	v_mfma_f32_16x16x32_bf16 v[4:7], v[176:179], v[216:219], v[4:7]
	v_mfma_f32_16x16x32_bf16 v[0:3], v[184:187], v[216:219], v[0:3]
	s_setprio 0
	s_barrier
	s_add_i32 s79, 0, 0x18000
	v_add_u32_e32 v159, s79, v152
	s_add_i32 s81, 0, 0x1c000
	ds_read_b128 v[148:151], v159
	ds_read_b128 v[160:163], v159 offset:1024
	ds_read_b128 v[164:167], v159 offset:2048
	ds_read_b128 v[168:171], v159 offset:3072
	v_add_u32_e32 v159, s81, v152
	ds_read_b128 v[172:175], v159
	ds_read_b128 v[176:179], v159 offset:1024
	ds_read_b128 v[180:183], v159 offset:2048
	ds_read_b128 v[184:187], v159 offset:3072
	s_add_u32 s34, s48, 0x40000
	s_addc_u32 s35, s49, 0
	s_mov_b32 m0, s54
	v_lshl_add_u64 v[228:229], s[34:35], 0, v[132:133]
	ds_read_b128 v[188:191], v157 offset:32768
	ds_read_b128 v[192:195], v157 offset:33792
	ds_read_b128 v[196:199], v157 offset:34816
	ds_read_b128 v[200:203], v157 offset:35840
	ds_read_b128 v[204:207], v157 offset:36864
	ds_read_b128 v[208:211], v157 offset:37888
	ds_read_b128 v[212:215], v157 offset:38912
	ds_read_b128 v[216:219], v157 offset:39936
	global_load_lds_dwordx4 v[228:229], off
	v_lshl_add_u64 v[228:229], s[34:35], 0, v[136:137]
	s_mov_b32 m0, s55
	s_nop 0
	global_load_lds_dwordx4 v[228:229], off
	s_waitcnt vmcnt(8)
	s_waitcnt lgkmcnt(0)
	s_barrier
	s_setprio 1
	s_waitcnt lgkmcnt(0)
	v_mfma_f32_16x16x32_bf16 v[124:127], v[148:151], v[188:191], v[124:127]
	v_mfma_f32_16x16x32_bf16 v[120:123], v[164:167], v[188:191], v[120:123]
	v_mfma_f32_16x16x32_bf16 v[108:111], v[148:151], v[196:199], v[108:111]
	v_mfma_f32_16x16x32_bf16 v[104:107], v[164:167], v[196:199], v[104:107]
	v_mfma_f32_16x16x32_bf16 v[92:95], v[148:151], v[204:207], v[92:95]
	v_mfma_f32_16x16x32_bf16 v[88:91], v[164:167], v[204:207], v[88:91]
	v_mfma_f32_16x16x32_bf16 v[76:79], v[148:151], v[212:215], v[76:79]
	v_mfma_f32_16x16x32_bf16 v[72:75], v[164:167], v[212:215], v[72:75]
	v_mfma_f32_16x16x32_bf16 v[124:127], v[160:163], v[192:195], v[124:127]
	v_mfma_f32_16x16x32_bf16 v[120:123], v[168:171], v[192:195], v[120:123]
	v_mfma_f32_16x16x32_bf16 v[108:111], v[160:163], v[200:203], v[108:111]
	v_mfma_f32_16x16x32_bf16 v[104:107], v[168:171], v[200:203], v[104:107]
	v_mfma_f32_16x16x32_bf16 v[92:95], v[160:163], v[208:211], v[92:95]
	v_mfma_f32_16x16x32_bf16 v[88:91], v[168:171], v[208:211], v[88:91]
	v_mfma_f32_16x16x32_bf16 v[76:79], v[160:163], v[216:219], v[76:79]
	v_mfma_f32_16x16x32_bf16 v[72:75], v[168:171], v[216:219], v[72:75]
	s_setprio 0
	s_setprio 1
	v_mfma_f32_16x16x32_bf16 v[116:119], v[172:175], v[188:191], v[116:119]
	v_mfma_f32_16x16x32_bf16 v[112:115], v[180:183], v[188:191], v[112:115]
	v_mfma_f32_16x16x32_bf16 v[100:103], v[172:175], v[196:199], v[100:103]
	v_mfma_f32_16x16x32_bf16 v[96:99], v[180:183], v[196:199], v[96:99]
	v_mfma_f32_16x16x32_bf16 v[84:87], v[172:175], v[204:207], v[84:87]
	v_mfma_f32_16x16x32_bf16 v[80:83], v[180:183], v[204:207], v[80:83]
	v_mfma_f32_16x16x32_bf16 v[68:71], v[172:175], v[212:215], v[68:71]
	v_mfma_f32_16x16x32_bf16 v[64:67], v[180:183], v[212:215], v[64:67]
	v_mfma_f32_16x16x32_bf16 v[116:119], v[176:179], v[192:195], v[116:119]
	v_mfma_f32_16x16x32_bf16 v[112:115], v[184:187], v[192:195], v[112:115]
	v_mfma_f32_16x16x32_bf16 v[100:103], v[176:179], v[200:203], v[100:103]
	v_mfma_f32_16x16x32_bf16 v[96:99], v[184:187], v[200:203], v[96:99]
	v_mfma_f32_16x16x32_bf16 v[84:87], v[176:179], v[208:211], v[84:87]
	v_mfma_f32_16x16x32_bf16 v[80:83], v[184:187], v[208:211], v[80:83]
	v_mfma_f32_16x16x32_bf16 v[68:71], v[176:179], v[216:219], v[68:71]
	v_mfma_f32_16x16x32_bf16 v[64:67], v[184:187], v[216:219], v[64:67]
	s_setprio 0
	s_barrier
	s_add_i32 s34, s79, s51
	v_lshl_add_u64 v[220:221], v[220:221], 0, s[10:11]
	s_mov_b32 m0, s34
	ds_read_b128 v[188:191], v157 offset:49152
	ds_read_b128 v[192:195], v157 offset:50176
	ds_read_b128 v[196:199], v157 offset:51200
	ds_read_b128 v[200:203], v157 offset:52224
	ds_read_b128 v[204:207], v157 offset:53248
	ds_read_b128 v[208:211], v157 offset:54272
	ds_read_b128 v[212:215], v157 offset:55296
	ds_read_b128 v[216:219], v157 offset:56320
	global_load_lds_dwordx4 v[220:221], off
	s_add_i32 m0, s34, 0x2000
	s_add_u32 s34, s42, 0x40080
	v_lshl_add_u64 v[220:221], v[222:223], 0, s[10:11]
	s_addc_u32 s35, s43, 0
	s_add_i32 s42, s81, s51
	global_load_lds_dwordx4 v[220:221], off
	v_lshl_add_u64 v[220:221], s[34:35], 0, v[134:135]
	s_mov_b32 m0, s42
	s_nop 0
	global_load_lds_dwordx4 v[220:221], off
	v_lshl_add_u64 v[220:221], s[34:35], 0, v[138:139]
	s_add_i32 m0, s42, 0x2000
	s_nop 0
	global_load_lds_dwordx4 v[220:221], off
	v_lshl_add_u64 v[220:221], v[224:225], 0, s[10:11]
	s_mov_b32 m0, s57
	s_nop 0
	global_load_lds_dwordx4 v[220:221], off
	v_lshl_add_u64 v[220:221], v[226:227], 0, s[10:11]
	s_mov_b32 m0, s58
	s_nop 0
	global_load_lds_dwordx4 v[220:221], off
	s_waitcnt vmcnt(8)
	s_waitcnt lgkmcnt(0)
	s_barrier
	s_add_u32 s40, s40, 0x100
	s_addc_u32 s41, s41, 0
	s_add_u32 s39, s39, 0x100
	s_addc_u32 s67, s67, 0
	s_setprio 1
	s_waitcnt lgkmcnt(0)
	v_mfma_f32_16x16x32_bf16 v[60:63], v[148:151], v[188:191], v[60:63]
	v_mfma_f32_16x16x32_bf16 v[56:59], v[164:167], v[188:191], v[56:59]
	v_mfma_f32_16x16x32_bf16 v[44:47], v[148:151], v[196:199], v[44:47]
	v_mfma_f32_16x16x32_bf16 v[40:43], v[164:167], v[196:199], v[40:43]
	v_mfma_f32_16x16x32_bf16 v[28:31], v[148:151], v[204:207], v[28:31]
	v_mfma_f32_16x16x32_bf16 v[24:27], v[164:167], v[204:207], v[24:27]
	v_mfma_f32_16x16x32_bf16 v[12:15], v[148:151], v[212:215], v[12:15]
	v_mfma_f32_16x16x32_bf16 v[8:11], v[164:167], v[212:215], v[8:11]
	v_mfma_f32_16x16x32_bf16 v[60:63], v[160:163], v[192:195], v[60:63]
	v_mfma_f32_16x16x32_bf16 v[56:59], v[168:171], v[192:195], v[56:59]
	v_mfma_f32_16x16x32_bf16 v[44:47], v[160:163], v[200:203], v[44:47]
	v_mfma_f32_16x16x32_bf16 v[40:43], v[168:171], v[200:203], v[40:43]
	v_mfma_f32_16x16x32_bf16 v[28:31], v[160:163], v[208:211], v[28:31]
	v_mfma_f32_16x16x32_bf16 v[24:27], v[168:171], v[208:211], v[24:27]
	v_mfma_f32_16x16x32_bf16 v[12:15], v[160:163], v[216:219], v[12:15]
	v_mfma_f32_16x16x32_bf16 v[8:11], v[168:171], v[216:219], v[8:11]
	s_setprio 0
	s_setprio 1
	v_mfma_f32_16x16x32_bf16 v[52:55], v[172:175], v[188:191], v[52:55]
	v_mfma_f32_16x16x32_bf16 v[48:51], v[180:183], v[188:191], v[48:51]
	v_mfma_f32_16x16x32_bf16 v[36:39], v[172:175], v[196:199], v[36:39]
	v_mfma_f32_16x16x32_bf16 v[32:35], v[180:183], v[196:199], v[32:35]
	v_mfma_f32_16x16x32_bf16 v[20:23], v[172:175], v[204:207], v[20:23]
	v_mfma_f32_16x16x32_bf16 v[16:19], v[180:183], v[204:207], v[16:19]
	v_mfma_f32_16x16x32_bf16 v[4:7], v[172:175], v[212:215], v[4:7]
	v_mfma_f32_16x16x32_bf16 v[0:3], v[180:183], v[212:215], v[0:3]
	v_mfma_f32_16x16x32_bf16 v[52:55], v[176:179], v[192:195], v[52:55]
	v_mfma_f32_16x16x32_bf16 v[48:51], v[184:187], v[192:195], v[48:51]
	v_mfma_f32_16x16x32_bf16 v[36:39], v[176:179], v[200:203], v[36:39]
	v_mfma_f32_16x16x32_bf16 v[32:35], v[184:187], v[200:203], v[32:35]
	v_mfma_f32_16x16x32_bf16 v[20:23], v[176:179], v[208:211], v[20:23]
	v_mfma_f32_16x16x32_bf16 v[16:19], v[184:187], v[208:211], v[16:19]
	v_mfma_f32_16x16x32_bf16 v[4:7], v[176:179], v[216:219], v[4:7]
	v_mfma_f32_16x16x32_bf16 v[0:3], v[184:187], v[216:219], v[0:3]
	s_setprio 0
	s_add_i32 s77, s77, 2
	s_cmp_gt_u32 s77, 13
	s_cbranch_scc0 .LBB0_969
	s_sub_i32 s100, s77, 2
	s_cmp_eq_u32 s100, s98
	s_cbranch_scc1 .Lmy_nobar_9
	s_barrier

.Lmy_nobar2_10:
	ds_read_b128 v[148:151], v155
	ds_read_b128 v[160:163], v155 offset:1024
	ds_read_b128 v[164:167], v155 offset:2048
	ds_read_b128 v[168:171], v155 offset:3072
	ds_read_b128 v[172:175], v157
	ds_read_b128 v[176:179], v157 offset:1024
	ds_read_b128 v[180:183], v157 offset:2048
	ds_read_b128 v[184:187], v157 offset:3072
	s_add_u32 s34, s36, 0xfffc0080
	s_addc_u32 s35, s37, -1
	s_cmp_eq_u32 s77, 12
	s_cselect_b32 s41, s23, s35
	s_cselect_b32 s40, s64, s34
	s_cselect_b32 s39, s11, s67
	s_cselect_b32 s38, s65, s66
	v_lshl_add_u64 v[220:221], s[36:37], 0, v[140:141]
	s_add_i32 m0, s31, 0xc000
	ds_read_b128 v[188:191], v158
	ds_read_b128 v[192:195], v158 offset:1024
	ds_read_b128 v[196:199], v158 offset:2048
	ds_read_b128 v[200:203], v158 offset:3072
	ds_read_b128 v[204:207], v158 offset:4096
	ds_read_b128 v[208:211], v158 offset:5120
	ds_read_b128 v[212:215], v158 offset:6144
	ds_read_b128 v[216:219], v158 offset:7168
	global_load_lds_dwordx4 v[220:221], off
	v_lshl_add_u64 v[220:221], s[36:37], 0, v[142:143]
	s_add_i32 m0, s31, 0xe000
	s_nop 0
	global_load_lds_dwordx4 v[220:221], off
	s_waitcnt vmcnt(8)
	s_waitcnt lgkmcnt(0)
	s_barrier
	s_setprio 1
	s_waitcnt lgkmcnt(0)
	v_mfma_f32_16x16x32_bf16 v[124:127], v[148:151], v[188:191], 0
	v_mfma_f32_16x16x32_bf16 v[120:123], v[164:167], v[188:191], 0
	v_mfma_f32_16x16x32_bf16 v[108:111], v[148:151], v[196:199], 0
	v_mfma_f32_16x16x32_bf16 v[104:107], v[164:167], v[196:199], 0
	v_mfma_f32_16x16x32_bf16 v[92:95], v[148:151], v[204:207], 0
	v_mfma_f32_16x16x32_bf16 v[88:91], v[164:167], v[204:207], 0
	v_mfma_f32_16x16x32_bf16 v[76:79], v[148:151], v[212:215], 0
	v_mfma_f32_16x16x32_bf16 v[72:75], v[164:167], v[212:215], 0
	v_mfma_f32_16x16x32_bf16 v[124:127], v[160:163], v[192:195], v[124:127]
	v_mfma_f32_16x16x32_bf16 v[120:123], v[168:171], v[192:195], v[120:123]
	v_mfma_f32_16x16x32_bf16 v[108:111], v[160:163], v[200:203], v[108:111]
	v_mfma_f32_16x16x32_bf16 v[104:107], v[168:171], v[200:203], v[104:107]
	v_mfma_f32_16x16x32_bf16 v[92:95], v[160:163], v[208:211], v[92:95]
	v_mfma_f32_16x16x32_bf16 v[88:91], v[168:171], v[208:211], v[88:91]
	v_mfma_f32_16x16x32_bf16 v[76:79], v[160:163], v[216:219], v[76:79]
	v_mfma_f32_16x16x32_bf16 v[72:75], v[168:171], v[216:219], v[72:75]
	s_setprio 0
	s_setprio 1
	v_mfma_f32_16x16x32_bf16 v[116:119], v[172:175], v[188:191], 0
	v_mfma_f32_16x16x32_bf16 v[112:115], v[180:183], v[188:191], 0
	v_mfma_f32_16x16x32_bf16 v[100:103], v[172:175], v[196:199], 0
	v_mfma_f32_16x16x32_bf16 v[96:99], v[180:183], v[196:199], 0
	v_mfma_f32_16x16x32_bf16 v[84:87], v[172:175], v[204:207], 0
	v_mfma_f32_16x16x32_bf16 v[80:83], v[180:183], v[204:207], 0
	v_mfma_f32_16x16x32_bf16 v[68:71], v[172:175], v[212:215], 0
	v_mfma_f32_16x16x32_bf16 v[64:67], v[180:183], v[212:215], 0
	v_mfma_f32_16x16x32_bf16 v[116:119], v[176:179], v[192:195], v[116:119]
	v_mfma_f32_16x16x32_bf16 v[112:115], v[184:187], v[192:195], v[112:115]
	v_mfma_f32_16x16x32_bf16 v[100:103], v[176:179], v[200:203], v[100:103]
	v_mfma_f32_16x16x32_bf16 v[96:99], v[184:187], v[200:203], v[96:99]
	v_mfma_f32_16x16x32_bf16 v[84:87], v[176:179], v[208:211], v[84:87]
	v_mfma_f32_16x16x32_bf16 v[80:83], v[184:187], v[208:211], v[80:83]
	v_mfma_f32_16x16x32_bf16 v[68:71], v[176:179], v[216:219], v[68:71]
	v_mfma_f32_16x16x32_bf16 v[64:67], v[184:187], v[216:219], v[64:67]
	s_setprio 0
	s_barrier
	s_add_i32 s34, s57, s48
	v_lshl_add_u64 v[220:221], s[38:39], 0, v[136:137]
	s_mov_b32 m0, s34
	ds_read_b128 v[188:191], v158 offset:16384
	ds_read_b128 v[192:195], v158 offset:17408
	ds_read_b128 v[196:199], v158 offset:18432
	ds_read_b128 v[200:203], v158 offset:19456
	ds_read_b128 v[204:207], v158 offset:20480
	ds_read_b128 v[208:211], v158 offset:21504
	ds_read_b128 v[212:215], v158 offset:22528
	ds_read_b128 v[216:219], v158 offset:23552
	global_load_lds_dwordx4 v[220:221], off
	s_add_i32 m0, s34, 0x2000
	s_add_u32 s34, s38, 0x40000
	v_lshl_add_u64 v[222:223], s[38:39], 0, v[132:133]
	s_addc_u32 s35, s39, 0
	s_add_i32 s79, s58, s48
	global_load_lds_dwordx4 v[222:223], off
	v_lshl_add_u64 v[224:225], s[34:35], 0, v[136:137]
	s_mov_b32 m0, s79
	v_lshl_add_u64 v[226:227], s[40:41], 0, v[134:135]
	global_load_lds_dwordx4 v[224:225], off
	v_lshl_add_u64 v[224:225], s[34:35], 0, v[132:133]
	s_add_i32 m0, s79, 0x2000
	s_nop 0
	global_load_lds_dwordx4 v[224:225], off
	v_lshl_add_u64 v[224:225], s[40:41], 0, v[138:139]
	s_mov_b32 m0, s31
	s_nop 0
	global_load_lds_dwordx4 v[224:225], off
	s_mov_b32 m0, s52
	s_nop 0
	global_load_lds_dwordx4 v[226:227], off
	s_waitcnt vmcnt(8)
	s_waitcnt lgkmcnt(0)
	s_barrier
	s_setprio 1
	s_waitcnt lgkmcnt(0)
	v_mfma_f32_16x16x32_bf16 v[60:63], v[148:151], v[188:191], 0
	v_mfma_f32_16x16x32_bf16 v[56:59], v[164:167], v[188:191], 0
	v_mfma_f32_16x16x32_bf16 v[44:47], v[148:151], v[196:199], 0
	v_mfma_f32_16x16x32_bf16 v[40:43], v[164:167], v[196:199], 0
	v_mfma_f32_16x16x32_bf16 v[28:31], v[148:151], v[204:207], 0
	v_mfma_f32_16x16x32_bf16 v[24:27], v[164:167], v[204:207], 0
	v_mfma_f32_16x16x32_bf16 v[12:15], v[148:151], v[212:215], 0
	v_mfma_f32_16x16x32_bf16 v[8:11], v[164:167], v[212:215], 0
	v_mfma_f32_16x16x32_bf16 v[60:63], v[160:163], v[192:195], v[60:63]
	v_mfma_f32_16x16x32_bf16 v[56:59], v[168:171], v[192:195], v[56:59]
	v_mfma_f32_16x16x32_bf16 v[44:47], v[160:163], v[200:203], v[44:47]
	v_mfma_f32_16x16x32_bf16 v[40:43], v[168:171], v[200:203], v[40:43]
	v_mfma_f32_16x16x32_bf16 v[28:31], v[160:163], v[208:211], v[28:31]
	v_mfma_f32_16x16x32_bf16 v[24:27], v[168:171], v[208:211], v[24:27]
	v_mfma_f32_16x16x32_bf16 v[12:15], v[160:163], v[216:219], v[12:15]
	v_mfma_f32_16x16x32_bf16 v[8:11], v[168:171], v[216:219], v[8:11]
	s_setprio 0
	s_setprio 1
	v_mfma_f32_16x16x32_bf16 v[52:55], v[172:175], v[188:191], 0
	v_mfma_f32_16x16x32_bf16 v[48:51], v[180:183], v[188:191], 0
	v_mfma_f32_16x16x32_bf16 v[36:39], v[172:175], v[196:199], 0
	v_mfma_f32_16x16x32_bf16 v[32:35], v[180:183], v[196:199], 0
	v_mfma_f32_16x16x32_bf16 v[20:23], v[172:175], v[204:207], 0
	v_mfma_f32_16x16x32_bf16 v[16:19], v[180:183], v[204:207], 0
	v_mfma_f32_16x16x32_bf16 v[4:7], v[172:175], v[212:215], 0
	v_mfma_f32_16x16x32_bf16 v[0:3], v[180:183], v[212:215], 0
	v_mfma_f32_16x16x32_bf16 v[52:55], v[176:179], v[192:195], v[52:55]
	v_mfma_f32_16x16x32_bf16 v[48:51], v[184:187], v[192:195], v[48:51]
	v_mfma_f32_16x16x32_bf16 v[36:39], v[176:179], v[200:203], v[36:39]
	v_mfma_f32_16x16x32_bf16 v[32:35], v[184:187], v[200:203], v[32:35]
	v_mfma_f32_16x16x32_bf16 v[20:23], v[176:179], v[208:211], v[20:23]
	v_mfma_f32_16x16x32_bf16 v[16:19], v[184:187], v[208:211], v[16:19]
	v_mfma_f32_16x16x32_bf16 v[4:7], v[176:179], v[216:219], v[4:7]
	v_mfma_f32_16x16x32_bf16 v[0:3], v[184:187], v[216:219], v[0:3]
	s_setprio 0
	s_barrier
	s_add_i32 s79, 0, 0x18000
	v_add_u32_e32 v159, s79, v152
	s_add_i32 s81, 0, 0x1c000
	ds_read_b128 v[148:151], v159
	ds_read_b128 v[160:163], v159 offset:1024
	ds_read_b128 v[164:167], v159 offset:2048
	ds_read_b128 v[168:171], v159 offset:3072
	v_add_u32_e32 v159, s81, v152
	ds_read_b128 v[172:175], v159
	ds_read_b128 v[176:179], v159 offset:1024
	ds_read_b128 v[180:183], v159 offset:2048
	ds_read_b128 v[184:187], v159 offset:3072
	s_add_u32 s34, s40, 0x40000
	s_addc_u32 s35, s41, 0
	s_mov_b32 m0, s53
	v_lshl_add_u64 v[228:229], s[34:35], 0, v[138:139]
	ds_read_b128 v[188:191], v158 offset:32768
	ds_read_b128 v[192:195], v158 offset:33792
	ds_read_b128 v[196:199], v158 offset:34816
	ds_read_b128 v[200:203], v158 offset:35840
	ds_read_b128 v[204:207], v158 offset:36864
	ds_read_b128 v[208:211], v158 offset:37888
	ds_read_b128 v[212:215], v158 offset:38912
	ds_read_b128 v[216:219], v158 offset:39936
	global_load_lds_dwordx4 v[228:229], off
	v_lshl_add_u64 v[228:229], s[34:35], 0, v[134:135]
	s_mov_b32 m0, s54
	s_nop 0
	global_load_lds_dwordx4 v[228:229], off
	s_waitcnt vmcnt(8)
	s_waitcnt lgkmcnt(0)
	s_barrier
	s_setprio 1
	s_waitcnt lgkmcnt(0)
	v_mfma_f32_16x16x32_bf16 v[124:127], v[148:151], v[188:191], v[124:127]
	v_mfma_f32_16x16x32_bf16 v[120:123], v[164:167], v[188:191], v[120:123]
	v_mfma_f32_16x16x32_bf16 v[108:111], v[148:151], v[196:199], v[108:111]
	v_mfma_f32_16x16x32_bf16 v[104:107], v[164:167], v[196:199], v[104:107]
	v_mfma_f32_16x16x32_bf16 v[92:95], v[148:151], v[204:207], v[92:95]
	v_mfma_f32_16x16x32_bf16 v[88:91], v[164:167], v[204:207], v[88:91]
	v_mfma_f32_16x16x32_bf16 v[76:79], v[148:151], v[212:215], v[76:79]
	v_mfma_f32_16x16x32_bf16 v[72:75], v[164:167], v[212:215], v[72:75]
	v_mfma_f32_16x16x32_bf16 v[124:127], v[160:163], v[192:195], v[124:127]
	v_mfma_f32_16x16x32_bf16 v[120:123], v[168:171], v[192:195], v[120:123]
	v_mfma_f32_16x16x32_bf16 v[108:111], v[160:163], v[200:203], v[108:111]
	v_mfma_f32_16x16x32_bf16 v[104:107], v[168:171], v[200:203], v[104:107]
	v_mfma_f32_16x16x32_bf16 v[92:95], v[160:163], v[208:211], v[92:95]
	v_mfma_f32_16x16x32_bf16 v[88:91], v[168:171], v[208:211], v[88:91]
	v_mfma_f32_16x16x32_bf16 v[76:79], v[160:163], v[216:219], v[76:79]
	v_mfma_f32_16x16x32_bf16 v[72:75], v[168:171], v[216:219], v[72:75]
	s_setprio 0
	s_setprio 1
	v_mfma_f32_16x16x32_bf16 v[116:119], v[172:175], v[188:191], v[116:119]
	v_mfma_f32_16x16x32_bf16 v[112:115], v[180:183], v[188:191], v[112:115]
	v_mfma_f32_16x16x32_bf16 v[100:103], v[172:175], v[196:199], v[100:103]
	v_mfma_f32_16x16x32_bf16 v[96:99], v[180:183], v[196:199], v[96:99]
	v_mfma_f32_16x16x32_bf16 v[84:87], v[172:175], v[204:207], v[84:87]
	v_mfma_f32_16x16x32_bf16 v[80:83], v[180:183], v[204:207], v[80:83]
	v_mfma_f32_16x16x32_bf16 v[68:71], v[172:175], v[212:215], v[68:71]
	v_mfma_f32_16x16x32_bf16 v[64:67], v[180:183], v[212:215], v[64:67]
	v_mfma_f32_16x16x32_bf16 v[116:119], v[176:179], v[192:195], v[116:119]
	v_mfma_f32_16x16x32_bf16 v[112:115], v[184:187], v[192:195], v[112:115]
	v_mfma_f32_16x16x32_bf16 v[100:103], v[176:179], v[200:203], v[100:103]
	v_mfma_f32_16x16x32_bf16 v[96:99], v[184:187], v[200:203], v[96:99]
	v_mfma_f32_16x16x32_bf16 v[84:87], v[176:179], v[208:211], v[84:87]
	v_mfma_f32_16x16x32_bf16 v[80:83], v[184:187], v[208:211], v[80:83]
	v_mfma_f32_16x16x32_bf16 v[68:71], v[176:179], v[216:219], v[68:71]
	v_mfma_f32_16x16x32_bf16 v[64:67], v[184:187], v[216:219], v[64:67]
	s_setprio 0
	s_barrier
	s_add_i32 s34, s79, s48
	v_lshl_add_u64 v[220:221], v[220:221], 0, s[6:7]
	s_mov_b32 m0, s34
	ds_read_b128 v[188:191], v158 offset:49152
	ds_read_b128 v[192:195], v158 offset:50176
	ds_read_b128 v[196:199], v158 offset:51200
	ds_read_b128 v[200:203], v158 offset:52224
	ds_read_b128 v[204:207], v158 offset:53248
	ds_read_b128 v[208:211], v158 offset:54272
	ds_read_b128 v[212:215], v158 offset:55296
	ds_read_b128 v[216:219], v158 offset:56320
	global_load_lds_dwordx4 v[220:221], off
	s_add_i32 m0, s34, 0x2000
	s_add_u32 s34, s38, 0x40080
	v_lshl_add_u64 v[220:221], v[222:223], 0, s[6:7]
	s_addc_u32 s35, s39, 0
	s_add_i32 s38, s81, s48
	global_load_lds_dwordx4 v[220:221], off
	v_lshl_add_u64 v[220:221], s[34:35], 0, v[136:137]
	s_mov_b32 m0, s38
	s_nop 0
	global_load_lds_dwordx4 v[220:221], off
	v_lshl_add_u64 v[220:221], s[34:35], 0, v[132:133]
	s_add_i32 m0, s38, 0x2000
	s_nop 0
	global_load_lds_dwordx4 v[220:221], off
	v_lshl_add_u64 v[220:221], v[224:225], 0, s[6:7]
	s_mov_b32 m0, s55
	s_nop 0
	global_load_lds_dwordx4 v[220:221], off
	v_lshl_add_u64 v[220:221], v[226:227], 0, s[6:7]
	s_mov_b32 m0, s56
	s_nop 0
	global_load_lds_dwordx4 v[220:221], off
	s_waitcnt vmcnt(8)
	s_waitcnt lgkmcnt(0)
	s_barrier
	s_add_u32 s36, s36, 0x100
	s_addc_u32 s37, s37, 0
	s_add_u32 s66, s66, 0x100
	s_addc_u32 s67, s67, 0
	s_setprio 1
	s_waitcnt lgkmcnt(0)
	v_mfma_f32_16x16x32_bf16 v[60:63], v[148:151], v[188:191], v[60:63]
	v_mfma_f32_16x16x32_bf16 v[56:59], v[164:167], v[188:191], v[56:59]
	v_mfma_f32_16x16x32_bf16 v[44:47], v[148:151], v[196:199], v[44:47]
	v_mfma_f32_16x16x32_bf16 v[40:43], v[164:167], v[196:199], v[40:43]
	v_mfma_f32_16x16x32_bf16 v[28:31], v[148:151], v[204:207], v[28:31]
	v_mfma_f32_16x16x32_bf16 v[24:27], v[164:167], v[204:207], v[24:27]
	v_mfma_f32_16x16x32_bf16 v[12:15], v[148:151], v[212:215], v[12:15]
	v_mfma_f32_16x16x32_bf16 v[8:11], v[164:167], v[212:215], v[8:11]
	v_mfma_f32_16x16x32_bf16 v[60:63], v[160:163], v[192:195], v[60:63]
	v_mfma_f32_16x16x32_bf16 v[56:59], v[168:171], v[192:195], v[56:59]
	v_mfma_f32_16x16x32_bf16 v[44:47], v[160:163], v[200:203], v[44:47]
	v_mfma_f32_16x16x32_bf16 v[40:43], v[168:171], v[200:203], v[40:43]
	v_mfma_f32_16x16x32_bf16 v[28:31], v[160:163], v[208:211], v[28:31]
	v_mfma_f32_16x16x32_bf16 v[24:27], v[168:171], v[208:211], v[24:27]
	v_mfma_f32_16x16x32_bf16 v[12:15], v[160:163], v[216:219], v[12:15]
	v_mfma_f32_16x16x32_bf16 v[8:11], v[168:171], v[216:219], v[8:11]
	s_setprio 0
	s_setprio 1
	v_mfma_f32_16x16x32_bf16 v[52:55], v[172:175], v[188:191], v[52:55]
	v_mfma_f32_16x16x32_bf16 v[48:51], v[180:183], v[188:191], v[48:51]
	v_mfma_f32_16x16x32_bf16 v[36:39], v[172:175], v[196:199], v[36:39]
	v_mfma_f32_16x16x32_bf16 v[32:35], v[180:183], v[196:199], v[32:35]
	v_mfma_f32_16x16x32_bf16 v[20:23], v[172:175], v[204:207], v[20:23]
	v_mfma_f32_16x16x32_bf16 v[16:19], v[180:183], v[204:207], v[16:19]
	v_mfma_f32_16x16x32_bf16 v[4:7], v[172:175], v[212:215], v[4:7]
	v_mfma_f32_16x16x32_bf16 v[0:3], v[180:183], v[212:215], v[0:3]
	v_mfma_f32_16x16x32_bf16 v[52:55], v[176:179], v[192:195], v[52:55]
	v_mfma_f32_16x16x32_bf16 v[48:51], v[184:187], v[192:195], v[48:51]
	v_mfma_f32_16x16x32_bf16 v[36:39], v[176:179], v[200:203], v[36:39]
	v_mfma_f32_16x16x32_bf16 v[32:35], v[184:187], v[200:203], v[32:35]
	v_mfma_f32_16x16x32_bf16 v[20:23], v[176:179], v[208:211], v[20:23]
	v_mfma_f32_16x16x32_bf16 v[16:19], v[184:187], v[208:211], v[16:19]
	v_mfma_f32_16x16x32_bf16 v[4:7], v[176:179], v[216:219], v[4:7]
	v_mfma_f32_16x16x32_bf16 v[0:3], v[184:187], v[216:219], v[0:3]
	s_setprio 0
	s_add_i32 s77, s77, 2
.LBB0_1059:
	s_barrier
	ds_read_b128 v[148:151], v155
	ds_read_b128 v[160:163], v155 offset:1024
	ds_read_b128 v[164:167], v155 offset:2048
	ds_read_b128 v[168:171], v155 offset:3072
	ds_read_b128 v[172:175], v157
	ds_read_b128 v[176:179], v157 offset:1024
	ds_read_b128 v[180:183], v157 offset:2048
	ds_read_b128 v[184:187], v157 offset:3072
	s_add_u32 s34, s36, 0xfffc0080
	s_addc_u32 s35, s37, -1
	s_cmp_eq_u32 s77, 12
	s_cselect_b32 s41, s23, s35
	s_cselect_b32 s40, s64, s34
	s_cselect_b32 s39, s11, s67
	s_cselect_b32 s38, s65, s66
	v_lshl_add_u64 v[220:221], s[36:37], 0, v[140:141]
	s_add_i32 m0, s31, 0xc000
	ds_read_b128 v[188:191], v158
	ds_read_b128 v[192:195], v158 offset:1024
	ds_read_b128 v[196:199], v158 offset:2048
	ds_read_b128 v[200:203], v158 offset:3072
	ds_read_b128 v[204:207], v158 offset:4096
	ds_read_b128 v[208:211], v158 offset:5120
	ds_read_b128 v[212:215], v158 offset:6144
	ds_read_b128 v[216:219], v158 offset:7168
	global_load_lds_dwordx4 v[220:221], off
	v_lshl_add_u64 v[220:221], s[36:37], 0, v[142:143]
	s_add_i32 m0, s31, 0xe000
	s_nop 0
	global_load_lds_dwordx4 v[220:221], off
	s_waitcnt vmcnt(8)
	s_waitcnt lgkmcnt(0)
	s_barrier
	s_setprio 1
	s_waitcnt lgkmcnt(0)
	v_mfma_f32_16x16x32_bf16 v[124:127], v[148:151], v[188:191], v[124:127]
	v_mfma_f32_16x16x32_bf16 v[120:123], v[164:167], v[188:191], v[120:123]
	v_mfma_f32_16x16x32_bf16 v[108:111], v[148:151], v[196:199], v[108:111]
	v_mfma_f32_16x16x32_bf16 v[104:107], v[164:167], v[196:199], v[104:107]
	v_mfma_f32_16x16x32_bf16 v[92:95], v[148:151], v[204:207], v[92:95]
	v_mfma_f32_16x16x32_bf16 v[88:91], v[164:167], v[204:207], v[88:91]
	v_mfma_f32_16x16x32_bf16 v[76:79], v[148:151], v[212:215], v[76:79]
	v_mfma_f32_16x16x32_bf16 v[72:75], v[164:167], v[212:215], v[72:75]
	v_mfma_f32_16x16x32_bf16 v[124:127], v[160:163], v[192:195], v[124:127]
	v_mfma_f32_16x16x32_bf16 v[120:123], v[168:171], v[192:195], v[120:123]
	v_mfma_f32_16x16x32_bf16 v[108:111], v[160:163], v[200:203], v[108:111]
	v_mfma_f32_16x16x32_bf16 v[104:107], v[168:171], v[200:203], v[104:107]
	v_mfma_f32_16x16x32_bf16 v[92:95], v[160:163], v[208:211], v[92:95]
	v_mfma_f32_16x16x32_bf16 v[88:91], v[168:171], v[208:211], v[88:91]
	v_mfma_f32_16x16x32_bf16 v[76:79], v[160:163], v[216:219], v[76:79]
	v_mfma_f32_16x16x32_bf16 v[72:75], v[168:171], v[216:219], v[72:75]
	s_setprio 0
	s_setprio 1
	v_mfma_f32_16x16x32_bf16 v[116:119], v[172:175], v[188:191], v[116:119]
	v_mfma_f32_16x16x32_bf16 v[112:115], v[180:183], v[188:191], v[112:115]
	v_mfma_f32_16x16x32_bf16 v[100:103], v[172:175], v[196:199], v[100:103]
	v_mfma_f32_16x16x32_bf16 v[96:99], v[180:183], v[196:199], v[96:99]
	v_mfma_f32_16x16x32_bf16 v[84:87], v[172:175], v[204:207], v[84:87]
	v_mfma_f32_16x16x32_bf16 v[80:83], v[180:183], v[204:207], v[80:83]
	v_mfma_f32_16x16x32_bf16 v[68:71], v[172:175], v[212:215], v[68:71]
	v_mfma_f32_16x16x32_bf16 v[64:67], v[180:183], v[212:215], v[64:67]
	v_mfma_f32_16x16x32_bf16 v[116:119], v[176:179], v[192:195], v[116:119]
	v_mfma_f32_16x16x32_bf16 v[112:115], v[184:187], v[192:195], v[112:115]
	v_mfma_f32_16x16x32_bf16 v[100:103], v[176:179], v[200:203], v[100:103]
	v_mfma_f32_16x16x32_bf16 v[96:99], v[184:187], v[200:203], v[96:99]
	v_mfma_f32_16x16x32_bf16 v[84:87], v[176:179], v[208:211], v[84:87]
	v_mfma_f32_16x16x32_bf16 v[80:83], v[184:187], v[208:211], v[80:83]
	v_mfma_f32_16x16x32_bf16 v[68:71], v[176:179], v[216:219], v[68:71]
	v_mfma_f32_16x16x32_bf16 v[64:67], v[184:187], v[216:219], v[64:67]
	s_setprio 0
	s_barrier
	s_add_i32 s34, s57, s48
	v_lshl_add_u64 v[220:221], s[38:39], 0, v[136:137]
	s_mov_b32 m0, s34
	ds_read_b128 v[188:191], v158 offset:16384
	ds_read_b128 v[192:195], v158 offset:17408
	ds_read_b128 v[196:199], v158 offset:18432
	ds_read_b128 v[200:203], v158 offset:19456
	ds_read_b128 v[204:207], v158 offset:20480
	ds_read_b128 v[208:211], v158 offset:21504
	ds_read_b128 v[212:215], v158 offset:22528
	ds_read_b128 v[216:219], v158 offset:23552
	global_load_lds_dwordx4 v[220:221], off
	s_add_i32 m0, s34, 0x2000
	s_add_u32 s34, s38, 0x40000
	v_lshl_add_u64 v[222:223], s[38:39], 0, v[132:133]
	s_addc_u32 s35, s39, 0
	s_add_i32 s79, s58, s48
	global_load_lds_dwordx4 v[222:223], off
	v_lshl_add_u64 v[224:225], s[34:35], 0, v[136:137]
	s_mov_b32 m0, s79
	v_lshl_add_u64 v[226:227], s[40:41], 0, v[134:135]
	global_load_lds_dwordx4 v[224:225], off
	v_lshl_add_u64 v[224:225], s[34:35], 0, v[132:133]
	s_add_i32 m0, s79, 0x2000
	s_nop 0
	global_load_lds_dwordx4 v[224:225], off
	v_lshl_add_u64 v[224:225], s[40:41], 0, v[138:139]
	s_mov_b32 m0, s31
	s_nop 0
	global_load_lds_dwordx4 v[224:225], off
	s_mov_b32 m0, s52
	s_nop 0
	global_load_lds_dwordx4 v[226:227], off
	s_waitcnt vmcnt(8)
	s_waitcnt lgkmcnt(0)
	s_barrier
	s_setprio 1
	s_waitcnt lgkmcnt(0)
	v_mfma_f32_16x16x32_bf16 v[60:63], v[148:151], v[188:191], v[60:63]
	v_mfma_f32_16x16x32_bf16 v[56:59], v[164:167], v[188:191], v[56:59]
	v_mfma_f32_16x16x32_bf16 v[44:47], v[148:151], v[196:199], v[44:47]
	v_mfma_f32_16x16x32_bf16 v[40:43], v[164:167], v[196:199], v[40:43]
	v_mfma_f32_16x16x32_bf16 v[28:31], v[148:151], v[204:207], v[28:31]
	v_mfma_f32_16x16x32_bf16 v[24:27], v[164:167], v[204:207], v[24:27]
	v_mfma_f32_16x16x32_bf16 v[12:15], v[148:151], v[212:215], v[12:15]
	v_mfma_f32_16x16x32_bf16 v[8:11], v[164:167], v[212:215], v[8:11]
	v_mfma_f32_16x16x32_bf16 v[60:63], v[160:163], v[192:195], v[60:63]
	v_mfma_f32_16x16x32_bf16 v[56:59], v[168:171], v[192:195], v[56:59]
	v_mfma_f32_16x16x32_bf16 v[44:47], v[160:163], v[200:203], v[44:47]
	v_mfma_f32_16x16x32_bf16 v[40:43], v[168:171], v[200:203], v[40:43]
	v_mfma_f32_16x16x32_bf16 v[28:31], v[160:163], v[208:211], v[28:31]
	v_mfma_f32_16x16x32_bf16 v[24:27], v[168:171], v[208:211], v[24:27]
	v_mfma_f32_16x16x32_bf16 v[12:15], v[160:163], v[216:219], v[12:15]
	v_mfma_f32_16x16x32_bf16 v[8:11], v[168:171], v[216:219], v[8:11]
	s_setprio 0
	s_setprio 1
	v_mfma_f32_16x16x32_bf16 v[52:55], v[172:175], v[188:191], v[52:55]
	v_mfma_f32_16x16x32_bf16 v[48:51], v[180:183], v[188:191], v[48:51]
	v_mfma_f32_16x16x32_bf16 v[36:39], v[172:175], v[196:199], v[36:39]
	v_mfma_f32_16x16x32_bf16 v[32:35], v[180:183], v[196:199], v[32:35]
	v_mfma_f32_16x16x32_bf16 v[20:23], v[172:175], v[204:207], v[20:23]
	v_mfma_f32_16x16x32_bf16 v[16:19], v[180:183], v[204:207], v[16:19]
	v_mfma_f32_16x16x32_bf16 v[4:7], v[172:175], v[212:215], v[4:7]
	v_mfma_f32_16x16x32_bf16 v[0:3], v[180:183], v[212:215], v[0:3]
	v_mfma_f32_16x16x32_bf16 v[52:55], v[176:179], v[192:195], v[52:55]
	v_mfma_f32_16x16x32_bf16 v[48:51], v[184:187], v[192:195], v[48:51]
	v_mfma_f32_16x16x32_bf16 v[36:39], v[176:179], v[200:203], v[36:39]
	v_mfma_f32_16x16x32_bf16 v[32:35], v[184:187], v[200:203], v[32:35]
	v_mfma_f32_16x16x32_bf16 v[20:23], v[176:179], v[208:211], v[20:23]
	v_mfma_f32_16x16x32_bf16 v[16:19], v[184:187], v[208:211], v[16:19]
	v_mfma_f32_16x16x32_bf16 v[4:7], v[176:179], v[216:219], v[4:7]
	v_mfma_f32_16x16x32_bf16 v[0:3], v[184:187], v[216:219], v[0:3]
	s_setprio 0
	s_barrier
	s_add_i32 s79, 0, 0x18000
	v_add_u32_e32 v159, s79, v152
	s_add_i32 s81, 0, 0x1c000
	ds_read_b128 v[148:151], v159
	ds_read_b128 v[160:163], v159 offset:1024
	ds_read_b128 v[164:167], v159 offset:2048
	ds_read_b128 v[168:171], v159 offset:3072
	v_add_u32_e32 v159, s81, v152
	ds_read_b128 v[172:175], v159
	ds_read_b128 v[176:179], v159 offset:1024
	ds_read_b128 v[180:183], v159 offset:2048
	ds_read_b128 v[184:187], v159 offset:3072
	s_add_u32 s34, s40, 0x40000
	s_addc_u32 s35, s41, 0
	s_mov_b32 m0, s53
	v_lshl_add_u64 v[228:229], s[34:35], 0, v[138:139]
	ds_read_b128 v[188:191], v158 offset:32768
	ds_read_b128 v[192:195], v158 offset:33792
	ds_read_b128 v[196:199], v158 offset:34816
	ds_read_b128 v[200:203], v158 offset:35840
	ds_read_b128 v[204:207], v158 offset:36864
	ds_read_b128 v[208:211], v158 offset:37888
	ds_read_b128 v[212:215], v158 offset:38912
	ds_read_b128 v[216:219], v158 offset:39936
	global_load_lds_dwordx4 v[228:229], off
	v_lshl_add_u64 v[228:229], s[34:35], 0, v[134:135]
	s_mov_b32 m0, s54
	s_nop 0
	global_load_lds_dwordx4 v[228:229], off
	s_waitcnt vmcnt(8)
	s_waitcnt lgkmcnt(0)
	s_barrier
	s_setprio 1
	s_waitcnt lgkmcnt(0)
	v_mfma_f32_16x16x32_bf16 v[124:127], v[148:151], v[188:191], v[124:127]
	v_mfma_f32_16x16x32_bf16 v[120:123], v[164:167], v[188:191], v[120:123]
	v_mfma_f32_16x16x32_bf16 v[108:111], v[148:151], v[196:199], v[108:111]
	v_mfma_f32_16x16x32_bf16 v[104:107], v[164:167], v[196:199], v[104:107]
	v_mfma_f32_16x16x32_bf16 v[92:95], v[148:151], v[204:207], v[92:95]
	v_mfma_f32_16x16x32_bf16 v[88:91], v[164:167], v[204:207], v[88:91]
	v_mfma_f32_16x16x32_bf16 v[76:79], v[148:151], v[212:215], v[76:79]
	v_mfma_f32_16x16x32_bf16 v[72:75], v[164:167], v[212:215], v[72:75]
	v_mfma_f32_16x16x32_bf16 v[124:127], v[160:163], v[192:195], v[124:127]
	v_mfma_f32_16x16x32_bf16 v[120:123], v[168:171], v[192:195], v[120:123]
	v_mfma_f32_16x16x32_bf16 v[108:111], v[160:163], v[200:203], v[108:111]
	v_mfma_f32_16x16x32_bf16 v[104:107], v[168:171], v[200:203], v[104:107]
	v_mfma_f32_16x16x32_bf16 v[92:95], v[160:163], v[208:211], v[92:95]
	v_mfma_f32_16x16x32_bf16 v[88:91], v[168:171], v[208:211], v[88:91]
	v_mfma_f32_16x16x32_bf16 v[76:79], v[160:163], v[216:219], v[76:79]
	v_mfma_f32_16x16x32_bf16 v[72:75], v[168:171], v[216:219], v[72:75]
	s_setprio 0
	s_setprio 1
	v_mfma_f32_16x16x32_bf16 v[116:119], v[172:175], v[188:191], v[116:119]
	v_mfma_f32_16x16x32_bf16 v[112:115], v[180:183], v[188:191], v[112:115]
	v_mfma_f32_16x16x32_bf16 v[100:103], v[172:175], v[196:199], v[100:103]
	v_mfma_f32_16x16x32_bf16 v[96:99], v[180:183], v[196:199], v[96:99]
	v_mfma_f32_16x16x32_bf16 v[84:87], v[172:175], v[204:207], v[84:87]
	v_mfma_f32_16x16x32_bf16 v[80:83], v[180:183], v[204:207], v[80:83]
	v_mfma_f32_16x16x32_bf16 v[68:71], v[172:175], v[212:215], v[68:71]
	v_mfma_f32_16x16x32_bf16 v[64:67], v[180:183], v[212:215], v[64:67]
	v_mfma_f32_16x16x32_bf16 v[116:119], v[176:179], v[192:195], v[116:119]
	v_mfma_f32_16x16x32_bf16 v[112:115], v[184:187], v[192:195], v[112:115]
	v_mfma_f32_16x16x32_bf16 v[100:103], v[176:179], v[200:203], v[100:103]
	v_mfma_f32_16x16x32_bf16 v[96:99], v[184:187], v[200:203], v[96:99]
	v_mfma_f32_16x16x32_bf16 v[84:87], v[176:179], v[208:211], v[84:87]
	v_mfma_f32_16x16x32_bf16 v[80:83], v[184:187], v[208:211], v[80:83]
	v_mfma_f32_16x16x32_bf16 v[68:71], v[176:179], v[216:219], v[68:71]
	v_mfma_f32_16x16x32_bf16 v[64:67], v[184:187], v[216:219], v[64:67]
	s_setprio 0
	s_barrier
	s_add_i32 s34, s79, s48
	v_lshl_add_u64 v[220:221], v[220:221], 0, s[6:7]
	s_mov_b32 m0, s34
	ds_read_b128 v[188:191], v158 offset:49152
	ds_read_b128 v[192:195], v158 offset:50176
	ds_read_b128 v[196:199], v158 offset:51200
	ds_read_b128 v[200:203], v158 offset:52224
	ds_read_b128 v[204:207], v158 offset:53248
	ds_read_b128 v[208:211], v158 offset:54272
	ds_read_b128 v[212:215], v158 offset:55296
	ds_read_b128 v[216:219], v158 offset:56320
	global_load_lds_dwordx4 v[220:221], off
	s_add_i32 m0, s34, 0x2000
	s_add_u32 s34, s38, 0x40080
	v_lshl_add_u64 v[220:221], v[222:223], 0, s[6:7]
	s_addc_u32 s35, s39, 0
	s_add_i32 s38, s81, s48
	global_load_lds_dwordx4 v[220:221], off
	v_lshl_add_u64 v[220:221], s[34:35], 0, v[136:137]
	s_mov_b32 m0, s38
	s_nop 0
	global_load_lds_dwordx4 v[220:221], off
	v_lshl_add_u64 v[220:221], s[34:35], 0, v[132:133]
	s_add_i32 m0, s38, 0x2000
	s_nop 0
	global_load_lds_dwordx4 v[220:221], off
	v_lshl_add_u64 v[220:221], v[224:225], 0, s[6:7]
	s_mov_b32 m0, s55
	s_nop 0
	global_load_lds_dwordx4 v[220:221], off
	v_lshl_add_u64 v[220:221], v[226:227], 0, s[6:7]
	s_mov_b32 m0, s56
	s_nop 0
	global_load_lds_dwordx4 v[220:221], off
	s_waitcnt vmcnt(8)
	s_waitcnt lgkmcnt(0)
	s_barrier
	s_add_u32 s36, s36, 0x100
	s_addc_u32 s37, s37, 0
	s_add_u32 s66, s66, 0x100
	s_addc_u32 s67, s67, 0
	s_setprio 1
	s_waitcnt lgkmcnt(0)
	v_mfma_f32_16x16x32_bf16 v[60:63], v[148:151], v[188:191], v[60:63]
	v_mfma_f32_16x16x32_bf16 v[56:59], v[164:167], v[188:191], v[56:59]
	v_mfma_f32_16x16x32_bf16 v[44:47], v[148:151], v[196:199], v[44:47]
	v_mfma_f32_16x16x32_bf16 v[40:43], v[164:167], v[196:199], v[40:43]
	v_mfma_f32_16x16x32_bf16 v[28:31], v[148:151], v[204:207], v[28:31]
	v_mfma_f32_16x16x32_bf16 v[24:27], v[164:167], v[204:207], v[24:27]
	v_mfma_f32_16x16x32_bf16 v[12:15], v[148:151], v[212:215], v[12:15]
	v_mfma_f32_16x16x32_bf16 v[8:11], v[164:167], v[212:215], v[8:11]
	v_mfma_f32_16x16x32_bf16 v[60:63], v[160:163], v[192:195], v[60:63]
	v_mfma_f32_16x16x32_bf16 v[56:59], v[168:171], v[192:195], v[56:59]
	v_mfma_f32_16x16x32_bf16 v[44:47], v[160:163], v[200:203], v[44:47]
	v_mfma_f32_16x16x32_bf16 v[40:43], v[168:171], v[200:203], v[40:43]
	v_mfma_f32_16x16x32_bf16 v[28:31], v[160:163], v[208:211], v[28:31]
	v_mfma_f32_16x16x32_bf16 v[24:27], v[168:171], v[208:211], v[24:27]
	v_mfma_f32_16x16x32_bf16 v[12:15], v[160:163], v[216:219], v[12:15]
	v_mfma_f32_16x16x32_bf16 v[8:11], v[168:171], v[216:219], v[8:11]
	s_setprio 0
	s_setprio 1
	v_mfma_f32_16x16x32_bf16 v[52:55], v[172:175], v[188:191], v[52:55]
	v_mfma_f32_16x16x32_bf16 v[48:51], v[180:183], v[188:191], v[48:51]
	v_mfma_f32_16x16x32_bf16 v[36:39], v[172:175], v[196:199], v[36:39]
	v_mfma_f32_16x16x32_bf16 v[32:35], v[180:183], v[196:199], v[32:35]
	v_mfma_f32_16x16x32_bf16 v[20:23], v[172:175], v[204:207], v[20:23]
	v_mfma_f32_16x16x32_bf16 v[16:19], v[180:183], v[204:207], v[16:19]
	v_mfma_f32_16x16x32_bf16 v[4:7], v[172:175], v[212:215], v[4:7]
	v_mfma_f32_16x16x32_bf16 v[0:3], v[180:183], v[212:215], v[0:3]
	v_mfma_f32_16x16x32_bf16 v[52:55], v[176:179], v[192:195], v[52:55]
	v_mfma_f32_16x16x32_bf16 v[48:51], v[184:187], v[192:195], v[48:51]
	v_mfma_f32_16x16x32_bf16 v[36:39], v[176:179], v[200:203], v[36:39]
	v_mfma_f32_16x16x32_bf16 v[32:35], v[184:187], v[200:203], v[32:35]
	v_mfma_f32_16x16x32_bf16 v[20:23], v[176:179], v[208:211], v[20:23]
	v_mfma_f32_16x16x32_bf16 v[16:19], v[184:187], v[208:211], v[16:19]
	v_mfma_f32_16x16x32_bf16 v[4:7], v[176:179], v[216:219], v[4:7]
	v_mfma_f32_16x16x32_bf16 v[0:3], v[184:187], v[216:219], v[0:3]
	s_setprio 0
	s_add_i32 s77, s77, 2
	s_cmp_gt_u32 s77, 13
	s_cbranch_scc0 .LBB0_1059
	s_sub_i32 s100, s77, 2
	s_cmp_eq_u32 s100, s98
	s_cbranch_scc1 .Lmy_nobar_10
	s_barrier

.Lmy_nobar2_11:
	ds_read_b128 v[148:151], v154
	ds_read_b128 v[160:163], v154 offset:1024
	ds_read_b128 v[164:167], v154 offset:2048
	ds_read_b128 v[168:171], v154 offset:3072
	ds_read_b128 v[172:175], v155
	ds_read_b128 v[176:179], v155 offset:1024
	ds_read_b128 v[180:183], v155 offset:2048
	ds_read_b128 v[184:187], v155 offset:3072
	s_add_u32 s34, s30, 0xfff50080
	s_addc_u32 s35, s31, -1
	s_cmp_eq_u32 s64, 40
	s_cselect_b32 s39, s1, s35
	s_cselect_b32 s38, s0, s34
	s_cselect_b32 s37, s29, s63
	s_cselect_b32 s36, s28, s13
	v_lshl_add_u64 v[220:221], s[30:31], 0, v[140:141]
	s_add_i32 m0, s42, 0xc000
	ds_read_b128 v[188:191], v157
	ds_read_b128 v[192:195], v157 offset:1024
	ds_read_b128 v[196:199], v157 offset:2048
	ds_read_b128 v[200:203], v157 offset:3072
	ds_read_b128 v[204:207], v157 offset:4096
	ds_read_b128 v[208:211], v157 offset:5120
	ds_read_b128 v[212:215], v157 offset:6144
	ds_read_b128 v[216:219], v157 offset:7168
	global_load_lds_dwordx4 v[220:221], off
	v_lshl_add_u64 v[220:221], s[30:31], 0, v[142:143]
	s_add_i32 m0, s42, 0xe000
	s_nop 0
	global_load_lds_dwordx4 v[220:221], off
	s_waitcnt vmcnt(8)
	s_waitcnt lgkmcnt(0)
	s_barrier
	s_setprio 1
	s_waitcnt lgkmcnt(0)
	v_mfma_f32_16x16x32_bf16 v[124:127], v[148:151], v[188:191], 0
	v_mfma_f32_16x16x32_bf16 v[120:123], v[164:167], v[188:191], 0
	v_mfma_f32_16x16x32_bf16 v[108:111], v[148:151], v[196:199], 0
	v_mfma_f32_16x16x32_bf16 v[104:107], v[164:167], v[196:199], 0
	v_mfma_f32_16x16x32_bf16 v[92:95], v[148:151], v[204:207], 0
	v_mfma_f32_16x16x32_bf16 v[88:91], v[164:167], v[204:207], 0
	v_mfma_f32_16x16x32_bf16 v[76:79], v[148:151], v[212:215], 0
	v_mfma_f32_16x16x32_bf16 v[72:75], v[164:167], v[212:215], 0
	v_mfma_f32_16x16x32_bf16 v[124:127], v[160:163], v[192:195], v[124:127]
	v_mfma_f32_16x16x32_bf16 v[120:123], v[168:171], v[192:195], v[120:123]
	v_mfma_f32_16x16x32_bf16 v[108:111], v[160:163], v[200:203], v[108:111]
	v_mfma_f32_16x16x32_bf16 v[104:107], v[168:171], v[200:203], v[104:107]
	v_mfma_f32_16x16x32_bf16 v[92:95], v[160:163], v[208:211], v[92:95]
	v_mfma_f32_16x16x32_bf16 v[88:91], v[168:171], v[208:211], v[88:91]
	v_mfma_f32_16x16x32_bf16 v[76:79], v[160:163], v[216:219], v[76:79]
	v_mfma_f32_16x16x32_bf16 v[72:75], v[168:171], v[216:219], v[72:75]
	s_setprio 0
	s_setprio 1
	v_mfma_f32_16x16x32_bf16 v[116:119], v[172:175], v[188:191], 0
	v_mfma_f32_16x16x32_bf16 v[112:115], v[180:183], v[188:191], 0
	v_mfma_f32_16x16x32_bf16 v[100:103], v[172:175], v[196:199], 0
	v_mfma_f32_16x16x32_bf16 v[96:99], v[180:183], v[196:199], 0
	v_mfma_f32_16x16x32_bf16 v[84:87], v[172:175], v[204:207], 0
	v_mfma_f32_16x16x32_bf16 v[80:83], v[180:183], v[204:207], 0
	v_mfma_f32_16x16x32_bf16 v[68:71], v[172:175], v[212:215], 0
	v_mfma_f32_16x16x32_bf16 v[64:67], v[180:183], v[212:215], 0
	v_mfma_f32_16x16x32_bf16 v[116:119], v[176:179], v[192:195], v[116:119]
	v_mfma_f32_16x16x32_bf16 v[112:115], v[184:187], v[192:195], v[112:115]
	v_mfma_f32_16x16x32_bf16 v[100:103], v[176:179], v[200:203], v[100:103]
	v_mfma_f32_16x16x32_bf16 v[96:99], v[184:187], v[200:203], v[96:99]
	v_mfma_f32_16x16x32_bf16 v[84:87], v[176:179], v[208:211], v[84:87]
	v_mfma_f32_16x16x32_bf16 v[80:83], v[184:187], v[208:211], v[80:83]
	v_mfma_f32_16x16x32_bf16 v[68:71], v[176:179], v[216:219], v[68:71]
	v_mfma_f32_16x16x32_bf16 v[64:67], v[184:187], v[216:219], v[64:67]
	s_setprio 0
	s_barrier
	s_add_i32 s34, s56, s41
	v_lshl_add_u64 v[220:221], s[36:37], 0, v[134:135]
	s_mov_b32 m0, s34
	ds_read_b128 v[188:191], v157 offset:16384
	ds_read_b128 v[192:195], v157 offset:17408
	ds_read_b128 v[196:199], v157 offset:18432
	ds_read_b128 v[200:203], v157 offset:19456
	ds_read_b128 v[204:207], v157 offset:20480
	ds_read_b128 v[208:211], v157 offset:21504
	ds_read_b128 v[212:215], v157 offset:22528
	ds_read_b128 v[216:219], v157 offset:23552
	global_load_lds_dwordx4 v[220:221], off
	s_add_i32 m0, s34, 0x2000
	s_add_u32 s34, s36, 0xb0000
	v_lshl_add_u64 v[222:223], s[36:37], 0, v[138:139]
	s_addc_u32 s35, s37, 0
	s_add_i32 s65, s57, s41
	global_load_lds_dwordx4 v[222:223], off
	v_lshl_add_u64 v[224:225], s[34:35], 0, v[134:135]
	s_mov_b32 m0, s65
	v_lshl_add_u64 v[226:227], s[38:39], 0, v[136:137]
	global_load_lds_dwordx4 v[224:225], off
	v_lshl_add_u64 v[224:225], s[34:35], 0, v[138:139]
	s_add_i32 m0, s65, 0x2000
	s_nop 0
	global_load_lds_dwordx4 v[224:225], off
	v_lshl_add_u64 v[224:225], s[38:39], 0, v[132:133]
	s_mov_b32 m0, s42
	s_nop 0
	global_load_lds_dwordx4 v[224:225], off
	s_mov_b32 m0, s43
	s_nop 0
	global_load_lds_dwordx4 v[226:227], off
	s_waitcnt vmcnt(8)
	s_waitcnt lgkmcnt(0)
	s_barrier
	s_setprio 1
	s_waitcnt lgkmcnt(0)
	v_mfma_f32_16x16x32_bf16 v[60:63], v[148:151], v[188:191], 0
	v_mfma_f32_16x16x32_bf16 v[56:59], v[164:167], v[188:191], 0
	v_mfma_f32_16x16x32_bf16 v[44:47], v[148:151], v[196:199], 0
	v_mfma_f32_16x16x32_bf16 v[40:43], v[164:167], v[196:199], 0
	v_mfma_f32_16x16x32_bf16 v[28:31], v[148:151], v[204:207], 0
	v_mfma_f32_16x16x32_bf16 v[24:27], v[164:167], v[204:207], 0
	v_mfma_f32_16x16x32_bf16 v[12:15], v[148:151], v[212:215], 0
	v_mfma_f32_16x16x32_bf16 v[8:11], v[164:167], v[212:215], 0
	v_mfma_f32_16x16x32_bf16 v[60:63], v[160:163], v[192:195], v[60:63]
	v_mfma_f32_16x16x32_bf16 v[56:59], v[168:171], v[192:195], v[56:59]
	v_mfma_f32_16x16x32_bf16 v[44:47], v[160:163], v[200:203], v[44:47]
	v_mfma_f32_16x16x32_bf16 v[40:43], v[168:171], v[200:203], v[40:43]
	v_mfma_f32_16x16x32_bf16 v[28:31], v[160:163], v[208:211], v[28:31]
	v_mfma_f32_16x16x32_bf16 v[24:27], v[168:171], v[208:211], v[24:27]
	v_mfma_f32_16x16x32_bf16 v[12:15], v[160:163], v[216:219], v[12:15]
	v_mfma_f32_16x16x32_bf16 v[8:11], v[168:171], v[216:219], v[8:11]
	s_setprio 0
	s_setprio 1
	v_mfma_f32_16x16x32_bf16 v[52:55], v[172:175], v[188:191], 0
	v_mfma_f32_16x16x32_bf16 v[48:51], v[180:183], v[188:191], 0
	v_mfma_f32_16x16x32_bf16 v[36:39], v[172:175], v[196:199], 0
	v_mfma_f32_16x16x32_bf16 v[32:35], v[180:183], v[196:199], 0
	v_mfma_f32_16x16x32_bf16 v[20:23], v[172:175], v[204:207], 0
	v_mfma_f32_16x16x32_bf16 v[16:19], v[180:183], v[204:207], 0
	v_mfma_f32_16x16x32_bf16 v[4:7], v[172:175], v[212:215], 0
	v_mfma_f32_16x16x32_bf16 v[0:3], v[180:183], v[212:215], 0
	v_mfma_f32_16x16x32_bf16 v[52:55], v[176:179], v[192:195], v[52:55]
	v_mfma_f32_16x16x32_bf16 v[48:51], v[184:187], v[192:195], v[48:51]
	v_mfma_f32_16x16x32_bf16 v[36:39], v[176:179], v[200:203], v[36:39]
	v_mfma_f32_16x16x32_bf16 v[32:35], v[184:187], v[200:203], v[32:35]
	v_mfma_f32_16x16x32_bf16 v[20:23], v[176:179], v[208:211], v[20:23]
	v_mfma_f32_16x16x32_bf16 v[16:19], v[184:187], v[208:211], v[16:19]
	v_mfma_f32_16x16x32_bf16 v[4:7], v[176:179], v[216:219], v[4:7]
	v_mfma_f32_16x16x32_bf16 v[0:3], v[184:187], v[216:219], v[0:3]
	s_setprio 0
	s_barrier
	s_add_i32 s65, 0, 0x18000
	v_add_u32_e32 v159, s65, v152
	s_add_i32 s66, 0, 0x1c000
	ds_read_b128 v[148:151], v159
	ds_read_b128 v[160:163], v159 offset:1024
	ds_read_b128 v[164:167], v159 offset:2048
	ds_read_b128 v[168:171], v159 offset:3072
	v_add_u32_e32 v159, s66, v152
	ds_read_b128 v[172:175], v159
	ds_read_b128 v[176:179], v159 offset:1024
	ds_read_b128 v[180:183], v159 offset:2048
	ds_read_b128 v[184:187], v159 offset:3072
	s_add_u32 s34, s38, 0xb0000
	s_addc_u32 s35, s39, 0
	s_mov_b32 m0, s48
	v_lshl_add_u64 v[228:229], s[34:35], 0, v[132:133]
	ds_read_b128 v[188:191], v157 offset:32768
	ds_read_b128 v[192:195], v157 offset:33792
	ds_read_b128 v[196:199], v157 offset:34816
	ds_read_b128 v[200:203], v157 offset:35840
	ds_read_b128 v[204:207], v157 offset:36864
	ds_read_b128 v[208:211], v157 offset:37888
	ds_read_b128 v[212:215], v157 offset:38912
	ds_read_b128 v[216:219], v157 offset:39936
	global_load_lds_dwordx4 v[228:229], off
	v_lshl_add_u64 v[228:229], s[34:35], 0, v[136:137]
	s_mov_b32 m0, s49
	s_nop 0
	global_load_lds_dwordx4 v[228:229], off
	s_waitcnt vmcnt(8)
	s_waitcnt lgkmcnt(0)
	s_barrier
	s_setprio 1
	s_waitcnt lgkmcnt(0)
	v_mfma_f32_16x16x32_bf16 v[124:127], v[148:151], v[188:191], v[124:127]
	v_mfma_f32_16x16x32_bf16 v[120:123], v[164:167], v[188:191], v[120:123]
	v_mfma_f32_16x16x32_bf16 v[108:111], v[148:151], v[196:199], v[108:111]
	v_mfma_f32_16x16x32_bf16 v[104:107], v[164:167], v[196:199], v[104:107]
	v_mfma_f32_16x16x32_bf16 v[92:95], v[148:151], v[204:207], v[92:95]
	v_mfma_f32_16x16x32_bf16 v[88:91], v[164:167], v[204:207], v[88:91]
	v_mfma_f32_16x16x32_bf16 v[76:79], v[148:151], v[212:215], v[76:79]
	v_mfma_f32_16x16x32_bf16 v[72:75], v[164:167], v[212:215], v[72:75]
	v_mfma_f32_16x16x32_bf16 v[124:127], v[160:163], v[192:195], v[124:127]
	v_mfma_f32_16x16x32_bf16 v[120:123], v[168:171], v[192:195], v[120:123]
	v_mfma_f32_16x16x32_bf16 v[108:111], v[160:163], v[200:203], v[108:111]
	v_mfma_f32_16x16x32_bf16 v[104:107], v[168:171], v[200:203], v[104:107]
	v_mfma_f32_16x16x32_bf16 v[92:95], v[160:163], v[208:211], v[92:95]
	v_mfma_f32_16x16x32_bf16 v[88:91], v[168:171], v[208:211], v[88:91]
	v_mfma_f32_16x16x32_bf16 v[76:79], v[160:163], v[216:219], v[76:79]
	v_mfma_f32_16x16x32_bf16 v[72:75], v[168:171], v[216:219], v[72:75]
	s_setprio 0
	s_setprio 1
	v_mfma_f32_16x16x32_bf16 v[116:119], v[172:175], v[188:191], v[116:119]
	v_mfma_f32_16x16x32_bf16 v[112:115], v[180:183], v[188:191], v[112:115]
	v_mfma_f32_16x16x32_bf16 v[100:103], v[172:175], v[196:199], v[100:103]
	v_mfma_f32_16x16x32_bf16 v[96:99], v[180:183], v[196:199], v[96:99]
	v_mfma_f32_16x16x32_bf16 v[84:87], v[172:175], v[204:207], v[84:87]
	v_mfma_f32_16x16x32_bf16 v[80:83], v[180:183], v[204:207], v[80:83]
	v_mfma_f32_16x16x32_bf16 v[68:71], v[172:175], v[212:215], v[68:71]
	v_mfma_f32_16x16x32_bf16 v[64:67], v[180:183], v[212:215], v[64:67]
	v_mfma_f32_16x16x32_bf16 v[116:119], v[176:179], v[192:195], v[116:119]
	v_mfma_f32_16x16x32_bf16 v[112:115], v[184:187], v[192:195], v[112:115]
	v_mfma_f32_16x16x32_bf16 v[100:103], v[176:179], v[200:203], v[100:103]
	v_mfma_f32_16x16x32_bf16 v[96:99], v[184:187], v[200:203], v[96:99]
	v_mfma_f32_16x16x32_bf16 v[84:87], v[176:179], v[208:211], v[84:87]
	v_mfma_f32_16x16x32_bf16 v[80:83], v[184:187], v[208:211], v[80:83]
	v_mfma_f32_16x16x32_bf16 v[68:71], v[176:179], v[216:219], v[68:71]
	v_mfma_f32_16x16x32_bf16 v[64:67], v[184:187], v[216:219], v[64:67]
	s_setprio 0
	s_barrier
	s_add_i32 s34, s65, s41
	v_lshl_add_u64 v[220:221], v[220:221], 0, s[22:23]
	s_mov_b32 m0, s34
	ds_read_b128 v[188:191], v157 offset:49152
	ds_read_b128 v[192:195], v157 offset:50176
	ds_read_b128 v[196:199], v157 offset:51200
	ds_read_b128 v[200:203], v157 offset:52224
	ds_read_b128 v[204:207], v157 offset:53248
	ds_read_b128 v[208:211], v157 offset:54272
	ds_read_b128 v[212:215], v157 offset:55296
	ds_read_b128 v[216:219], v157 offset:56320
	global_load_lds_dwordx4 v[220:221], off
	s_add_i32 m0, s34, 0x2000
	s_add_u32 s34, s36, 0xb0080
	v_lshl_add_u64 v[220:221], v[222:223], 0, s[22:23]
	s_addc_u32 s35, s37, 0
	s_add_i32 s36, s66, s41
	global_load_lds_dwordx4 v[220:221], off
	v_lshl_add_u64 v[220:221], s[34:35], 0, v[134:135]
	s_mov_b32 m0, s36
	s_nop 0
	global_load_lds_dwordx4 v[220:221], off
	v_lshl_add_u64 v[220:221], s[34:35], 0, v[138:139]
	s_add_i32 m0, s36, 0x2000
	s_nop 0
	global_load_lds_dwordx4 v[220:221], off
	v_lshl_add_u64 v[220:221], v[224:225], 0, s[22:23]
	s_mov_b32 m0, s51
	s_nop 0
	global_load_lds_dwordx4 v[220:221], off
	v_lshl_add_u64 v[220:221], v[226:227], 0, s[22:23]
	s_mov_b32 m0, s52
	s_nop 0
	global_load_lds_dwordx4 v[220:221], off
	s_waitcnt vmcnt(8)
	s_waitcnt lgkmcnt(0)
	s_barrier
	s_add_u32 s30, s30, 0x100
	s_addc_u32 s31, s31, 0
	s_add_u32 s13, s13, 0x100
	s_addc_u32 s63, s63, 0
	s_setprio 1
	s_waitcnt lgkmcnt(0)
	v_mfma_f32_16x16x32_bf16 v[60:63], v[148:151], v[188:191], v[60:63]
	v_mfma_f32_16x16x32_bf16 v[56:59], v[164:167], v[188:191], v[56:59]
	v_mfma_f32_16x16x32_bf16 v[44:47], v[148:151], v[196:199], v[44:47]
	v_mfma_f32_16x16x32_bf16 v[40:43], v[164:167], v[196:199], v[40:43]
	v_mfma_f32_16x16x32_bf16 v[28:31], v[148:151], v[204:207], v[28:31]
	v_mfma_f32_16x16x32_bf16 v[24:27], v[164:167], v[204:207], v[24:27]
	v_mfma_f32_16x16x32_bf16 v[12:15], v[148:151], v[212:215], v[12:15]
	v_mfma_f32_16x16x32_bf16 v[8:11], v[164:167], v[212:215], v[8:11]
	v_mfma_f32_16x16x32_bf16 v[60:63], v[160:163], v[192:195], v[60:63]
	v_mfma_f32_16x16x32_bf16 v[56:59], v[168:171], v[192:195], v[56:59]
	v_mfma_f32_16x16x32_bf16 v[44:47], v[160:163], v[200:203], v[44:47]
	v_mfma_f32_16x16x32_bf16 v[40:43], v[168:171], v[200:203], v[40:43]
	v_mfma_f32_16x16x32_bf16 v[28:31], v[160:163], v[208:211], v[28:31]
	v_mfma_f32_16x16x32_bf16 v[24:27], v[168:171], v[208:211], v[24:27]
	v_mfma_f32_16x16x32_bf16 v[12:15], v[160:163], v[216:219], v[12:15]
	v_mfma_f32_16x16x32_bf16 v[8:11], v[168:171], v[216:219], v[8:11]
	s_setprio 0
	s_setprio 1
	v_mfma_f32_16x16x32_bf16 v[52:55], v[172:175], v[188:191], v[52:55]
	v_mfma_f32_16x16x32_bf16 v[48:51], v[180:183], v[188:191], v[48:51]
	v_mfma_f32_16x16x32_bf16 v[36:39], v[172:175], v[196:199], v[36:39]
	v_mfma_f32_16x16x32_bf16 v[32:35], v[180:183], v[196:199], v[32:35]
	v_mfma_f32_16x16x32_bf16 v[20:23], v[172:175], v[204:207], v[20:23]
	v_mfma_f32_16x16x32_bf16 v[16:19], v[180:183], v[204:207], v[16:19]
	v_mfma_f32_16x16x32_bf16 v[4:7], v[172:175], v[212:215], v[4:7]
	v_mfma_f32_16x16x32_bf16 v[0:3], v[180:183], v[212:215], v[0:3]
	v_mfma_f32_16x16x32_bf16 v[52:55], v[176:179], v[192:195], v[52:55]
	v_mfma_f32_16x16x32_bf16 v[48:51], v[184:187], v[192:195], v[48:51]
	v_mfma_f32_16x16x32_bf16 v[36:39], v[176:179], v[200:203], v[36:39]
	v_mfma_f32_16x16x32_bf16 v[32:35], v[184:187], v[200:203], v[32:35]
	v_mfma_f32_16x16x32_bf16 v[20:23], v[176:179], v[208:211], v[20:23]
	v_mfma_f32_16x16x32_bf16 v[16:19], v[184:187], v[208:211], v[16:19]
	v_mfma_f32_16x16x32_bf16 v[4:7], v[176:179], v[216:219], v[4:7]
	v_mfma_f32_16x16x32_bf16 v[0:3], v[184:187], v[216:219], v[0:3]
	s_setprio 0
	s_add_i32 s64, s64, 2
.LBB0_1145:
	s_barrier
	ds_read_b128 v[148:151], v154
	ds_read_b128 v[160:163], v154 offset:1024
	ds_read_b128 v[164:167], v154 offset:2048
	ds_read_b128 v[168:171], v154 offset:3072
	ds_read_b128 v[172:175], v155
	ds_read_b128 v[176:179], v155 offset:1024
	ds_read_b128 v[180:183], v155 offset:2048
	ds_read_b128 v[184:187], v155 offset:3072
	s_add_u32 s34, s30, 0xfff50080
	s_addc_u32 s35, s31, -1
	s_cmp_eq_u32 s64, 40
	s_cselect_b32 s39, s1, s35
	s_cselect_b32 s38, s0, s34
	s_cselect_b32 s37, s29, s63
	s_cselect_b32 s36, s28, s13
	v_lshl_add_u64 v[220:221], s[30:31], 0, v[140:141]
	s_add_i32 m0, s42, 0xc000
	ds_read_b128 v[188:191], v157
	ds_read_b128 v[192:195], v157 offset:1024
	ds_read_b128 v[196:199], v157 offset:2048
	ds_read_b128 v[200:203], v157 offset:3072
	ds_read_b128 v[204:207], v157 offset:4096
	ds_read_b128 v[208:211], v157 offset:5120
	ds_read_b128 v[212:215], v157 offset:6144
	ds_read_b128 v[216:219], v157 offset:7168
	global_load_lds_dwordx4 v[220:221], off
	v_lshl_add_u64 v[220:221], s[30:31], 0, v[142:143]
	s_add_i32 m0, s42, 0xe000
	s_nop 0
	global_load_lds_dwordx4 v[220:221], off
	s_waitcnt vmcnt(8)
	s_waitcnt lgkmcnt(0)
	s_barrier
	s_setprio 1
	s_waitcnt lgkmcnt(0)
	v_mfma_f32_16x16x32_bf16 v[124:127], v[148:151], v[188:191], v[124:127]
	v_mfma_f32_16x16x32_bf16 v[120:123], v[164:167], v[188:191], v[120:123]
	v_mfma_f32_16x16x32_bf16 v[108:111], v[148:151], v[196:199], v[108:111]
	v_mfma_f32_16x16x32_bf16 v[104:107], v[164:167], v[196:199], v[104:107]
	v_mfma_f32_16x16x32_bf16 v[92:95], v[148:151], v[204:207], v[92:95]
	v_mfma_f32_16x16x32_bf16 v[88:91], v[164:167], v[204:207], v[88:91]
	v_mfma_f32_16x16x32_bf16 v[76:79], v[148:151], v[212:215], v[76:79]
	v_mfma_f32_16x16x32_bf16 v[72:75], v[164:167], v[212:215], v[72:75]
	v_mfma_f32_16x16x32_bf16 v[124:127], v[160:163], v[192:195], v[124:127]
	v_mfma_f32_16x16x32_bf16 v[120:123], v[168:171], v[192:195], v[120:123]
	v_mfma_f32_16x16x32_bf16 v[108:111], v[160:163], v[200:203], v[108:111]
	v_mfma_f32_16x16x32_bf16 v[104:107], v[168:171], v[200:203], v[104:107]
	v_mfma_f32_16x16x32_bf16 v[92:95], v[160:163], v[208:211], v[92:95]
	v_mfma_f32_16x16x32_bf16 v[88:91], v[168:171], v[208:211], v[88:91]
	v_mfma_f32_16x16x32_bf16 v[76:79], v[160:163], v[216:219], v[76:79]
	v_mfma_f32_16x16x32_bf16 v[72:75], v[168:171], v[216:219], v[72:75]
	s_setprio 0
	s_setprio 1
	v_mfma_f32_16x16x32_bf16 v[116:119], v[172:175], v[188:191], v[116:119]
	v_mfma_f32_16x16x32_bf16 v[112:115], v[180:183], v[188:191], v[112:115]
	v_mfma_f32_16x16x32_bf16 v[100:103], v[172:175], v[196:199], v[100:103]
	v_mfma_f32_16x16x32_bf16 v[96:99], v[180:183], v[196:199], v[96:99]
	v_mfma_f32_16x16x32_bf16 v[84:87], v[172:175], v[204:207], v[84:87]
	v_mfma_f32_16x16x32_bf16 v[80:83], v[180:183], v[204:207], v[80:83]
	v_mfma_f32_16x16x32_bf16 v[68:71], v[172:175], v[212:215], v[68:71]
	v_mfma_f32_16x16x32_bf16 v[64:67], v[180:183], v[212:215], v[64:67]
	v_mfma_f32_16x16x32_bf16 v[116:119], v[176:179], v[192:195], v[116:119]
	v_mfma_f32_16x16x32_bf16 v[112:115], v[184:187], v[192:195], v[112:115]
	v_mfma_f32_16x16x32_bf16 v[100:103], v[176:179], v[200:203], v[100:103]
	v_mfma_f32_16x16x32_bf16 v[96:99], v[184:187], v[200:203], v[96:99]
	v_mfma_f32_16x16x32_bf16 v[84:87], v[176:179], v[208:211], v[84:87]
	v_mfma_f32_16x16x32_bf16 v[80:83], v[184:187], v[208:211], v[80:83]
	v_mfma_f32_16x16x32_bf16 v[68:71], v[176:179], v[216:219], v[68:71]
	v_mfma_f32_16x16x32_bf16 v[64:67], v[184:187], v[216:219], v[64:67]
	s_setprio 0
	s_barrier
	s_add_i32 s34, s56, s41
	v_lshl_add_u64 v[220:221], s[36:37], 0, v[134:135]
	s_mov_b32 m0, s34
	ds_read_b128 v[188:191], v157 offset:16384
	ds_read_b128 v[192:195], v157 offset:17408
	ds_read_b128 v[196:199], v157 offset:18432
	ds_read_b128 v[200:203], v157 offset:19456
	ds_read_b128 v[204:207], v157 offset:20480
	ds_read_b128 v[208:211], v157 offset:21504
	ds_read_b128 v[212:215], v157 offset:22528
	ds_read_b128 v[216:219], v157 offset:23552
	global_load_lds_dwordx4 v[220:221], off
	s_add_i32 m0, s34, 0x2000
	s_add_u32 s34, s36, 0xb0000
	v_lshl_add_u64 v[222:223], s[36:37], 0, v[138:139]
	s_addc_u32 s35, s37, 0
	s_add_i32 s65, s57, s41
	global_load_lds_dwordx4 v[222:223], off
	v_lshl_add_u64 v[224:225], s[34:35], 0, v[134:135]
	s_mov_b32 m0, s65
	v_lshl_add_u64 v[226:227], s[38:39], 0, v[136:137]
	global_load_lds_dwordx4 v[224:225], off
	v_lshl_add_u64 v[224:225], s[34:35], 0, v[138:139]
	s_add_i32 m0, s65, 0x2000
	s_nop 0
	global_load_lds_dwordx4 v[224:225], off
	v_lshl_add_u64 v[224:225], s[38:39], 0, v[132:133]
	s_mov_b32 m0, s42
	s_nop 0
	global_load_lds_dwordx4 v[224:225], off
	s_mov_b32 m0, s43
	s_nop 0
	global_load_lds_dwordx4 v[226:227], off
	s_waitcnt vmcnt(8)
	s_waitcnt lgkmcnt(0)
	s_barrier
	s_setprio 1
	s_waitcnt lgkmcnt(0)
	v_mfma_f32_16x16x32_bf16 v[60:63], v[148:151], v[188:191], v[60:63]
	v_mfma_f32_16x16x32_bf16 v[56:59], v[164:167], v[188:191], v[56:59]
	v_mfma_f32_16x16x32_bf16 v[44:47], v[148:151], v[196:199], v[44:47]
	v_mfma_f32_16x16x32_bf16 v[40:43], v[164:167], v[196:199], v[40:43]
	v_mfma_f32_16x16x32_bf16 v[28:31], v[148:151], v[204:207], v[28:31]
	v_mfma_f32_16x16x32_bf16 v[24:27], v[164:167], v[204:207], v[24:27]
	v_mfma_f32_16x16x32_bf16 v[12:15], v[148:151], v[212:215], v[12:15]
	v_mfma_f32_16x16x32_bf16 v[8:11], v[164:167], v[212:215], v[8:11]
	v_mfma_f32_16x16x32_bf16 v[60:63], v[160:163], v[192:195], v[60:63]
	v_mfma_f32_16x16x32_bf16 v[56:59], v[168:171], v[192:195], v[56:59]
	v_mfma_f32_16x16x32_bf16 v[44:47], v[160:163], v[200:203], v[44:47]
	v_mfma_f32_16x16x32_bf16 v[40:43], v[168:171], v[200:203], v[40:43]
	v_mfma_f32_16x16x32_bf16 v[28:31], v[160:163], v[208:211], v[28:31]
	v_mfma_f32_16x16x32_bf16 v[24:27], v[168:171], v[208:211], v[24:27]
	v_mfma_f32_16x16x32_bf16 v[12:15], v[160:163], v[216:219], v[12:15]
	v_mfma_f32_16x16x32_bf16 v[8:11], v[168:171], v[216:219], v[8:11]
	s_setprio 0
	s_setprio 1
	v_mfma_f32_16x16x32_bf16 v[52:55], v[172:175], v[188:191], v[52:55]
	v_mfma_f32_16x16x32_bf16 v[48:51], v[180:183], v[188:191], v[48:51]
	v_mfma_f32_16x16x32_bf16 v[36:39], v[172:175], v[196:199], v[36:39]
	v_mfma_f32_16x16x32_bf16 v[32:35], v[180:183], v[196:199], v[32:35]
	v_mfma_f32_16x16x32_bf16 v[20:23], v[172:175], v[204:207], v[20:23]
	v_mfma_f32_16x16x32_bf16 v[16:19], v[180:183], v[204:207], v[16:19]
	v_mfma_f32_16x16x32_bf16 v[4:7], v[172:175], v[212:215], v[4:7]
	v_mfma_f32_16x16x32_bf16 v[0:3], v[180:183], v[212:215], v[0:3]
	v_mfma_f32_16x16x32_bf16 v[52:55], v[176:179], v[192:195], v[52:55]
	v_mfma_f32_16x16x32_bf16 v[48:51], v[184:187], v[192:195], v[48:51]
	v_mfma_f32_16x16x32_bf16 v[36:39], v[176:179], v[200:203], v[36:39]
	v_mfma_f32_16x16x32_bf16 v[32:35], v[184:187], v[200:203], v[32:35]
	v_mfma_f32_16x16x32_bf16 v[20:23], v[176:179], v[208:211], v[20:23]
	v_mfma_f32_16x16x32_bf16 v[16:19], v[184:187], v[208:211], v[16:19]
	v_mfma_f32_16x16x32_bf16 v[4:7], v[176:179], v[216:219], v[4:7]
	v_mfma_f32_16x16x32_bf16 v[0:3], v[184:187], v[216:219], v[0:3]
	s_setprio 0
	s_barrier
	s_add_i32 s65, 0, 0x18000
	v_add_u32_e32 v159, s65, v152
	s_add_i32 s66, 0, 0x1c000
	ds_read_b128 v[148:151], v159
	ds_read_b128 v[160:163], v159 offset:1024
	ds_read_b128 v[164:167], v159 offset:2048
	ds_read_b128 v[168:171], v159 offset:3072
	v_add_u32_e32 v159, s66, v152
	ds_read_b128 v[172:175], v159
	ds_read_b128 v[176:179], v159 offset:1024
	ds_read_b128 v[180:183], v159 offset:2048
	ds_read_b128 v[184:187], v159 offset:3072
	s_add_u32 s34, s38, 0xb0000
	s_addc_u32 s35, s39, 0
	s_mov_b32 m0, s48
	v_lshl_add_u64 v[228:229], s[34:35], 0, v[132:133]
	ds_read_b128 v[188:191], v157 offset:32768
	ds_read_b128 v[192:195], v157 offset:33792
	ds_read_b128 v[196:199], v157 offset:34816
	ds_read_b128 v[200:203], v157 offset:35840
	ds_read_b128 v[204:207], v157 offset:36864
	ds_read_b128 v[208:211], v157 offset:37888
	ds_read_b128 v[212:215], v157 offset:38912
	ds_read_b128 v[216:219], v157 offset:39936
	global_load_lds_dwordx4 v[228:229], off
	v_lshl_add_u64 v[228:229], s[34:35], 0, v[136:137]
	s_mov_b32 m0, s49
	s_nop 0
	global_load_lds_dwordx4 v[228:229], off
	s_waitcnt vmcnt(8)
	s_waitcnt lgkmcnt(0)
	s_barrier
	s_setprio 1
	s_waitcnt lgkmcnt(0)
	v_mfma_f32_16x16x32_bf16 v[124:127], v[148:151], v[188:191], v[124:127]
	v_mfma_f32_16x16x32_bf16 v[120:123], v[164:167], v[188:191], v[120:123]
	v_mfma_f32_16x16x32_bf16 v[108:111], v[148:151], v[196:199], v[108:111]
	v_mfma_f32_16x16x32_bf16 v[104:107], v[164:167], v[196:199], v[104:107]
	v_mfma_f32_16x16x32_bf16 v[92:95], v[148:151], v[204:207], v[92:95]
	v_mfma_f32_16x16x32_bf16 v[88:91], v[164:167], v[204:207], v[88:91]
	v_mfma_f32_16x16x32_bf16 v[76:79], v[148:151], v[212:215], v[76:79]
	v_mfma_f32_16x16x32_bf16 v[72:75], v[164:167], v[212:215], v[72:75]
	v_mfma_f32_16x16x32_bf16 v[124:127], v[160:163], v[192:195], v[124:127]
	v_mfma_f32_16x16x32_bf16 v[120:123], v[168:171], v[192:195], v[120:123]
	v_mfma_f32_16x16x32_bf16 v[108:111], v[160:163], v[200:203], v[108:111]
	v_mfma_f32_16x16x32_bf16 v[104:107], v[168:171], v[200:203], v[104:107]
	v_mfma_f32_16x16x32_bf16 v[92:95], v[160:163], v[208:211], v[92:95]
	v_mfma_f32_16x16x32_bf16 v[88:91], v[168:171], v[208:211], v[88:91]
	v_mfma_f32_16x16x32_bf16 v[76:79], v[160:163], v[216:219], v[76:79]
	v_mfma_f32_16x16x32_bf16 v[72:75], v[168:171], v[216:219], v[72:75]
	s_setprio 0
	s_setprio 1
	v_mfma_f32_16x16x32_bf16 v[116:119], v[172:175], v[188:191], v[116:119]
	v_mfma_f32_16x16x32_bf16 v[112:115], v[180:183], v[188:191], v[112:115]
	v_mfma_f32_16x16x32_bf16 v[100:103], v[172:175], v[196:199], v[100:103]
	v_mfma_f32_16x16x32_bf16 v[96:99], v[180:183], v[196:199], v[96:99]
	v_mfma_f32_16x16x32_bf16 v[84:87], v[172:175], v[204:207], v[84:87]
	v_mfma_f32_16x16x32_bf16 v[80:83], v[180:183], v[204:207], v[80:83]
	v_mfma_f32_16x16x32_bf16 v[68:71], v[172:175], v[212:215], v[68:71]
	v_mfma_f32_16x16x32_bf16 v[64:67], v[180:183], v[212:215], v[64:67]
	v_mfma_f32_16x16x32_bf16 v[116:119], v[176:179], v[192:195], v[116:119]
	v_mfma_f32_16x16x32_bf16 v[112:115], v[184:187], v[192:195], v[112:115]
	v_mfma_f32_16x16x32_bf16 v[100:103], v[176:179], v[200:203], v[100:103]
	v_mfma_f32_16x16x32_bf16 v[96:99], v[184:187], v[200:203], v[96:99]
	v_mfma_f32_16x16x32_bf16 v[84:87], v[176:179], v[208:211], v[84:87]
	v_mfma_f32_16x16x32_bf16 v[80:83], v[184:187], v[208:211], v[80:83]
	v_mfma_f32_16x16x32_bf16 v[68:71], v[176:179], v[216:219], v[68:71]
	v_mfma_f32_16x16x32_bf16 v[64:67], v[184:187], v[216:219], v[64:67]
	s_setprio 0
	s_barrier
	s_add_i32 s34, s65, s41
	v_lshl_add_u64 v[220:221], v[220:221], 0, s[22:23]
	s_mov_b32 m0, s34
	ds_read_b128 v[188:191], v157 offset:49152
	ds_read_b128 v[192:195], v157 offset:50176
	ds_read_b128 v[196:199], v157 offset:51200
	ds_read_b128 v[200:203], v157 offset:52224
	ds_read_b128 v[204:207], v157 offset:53248
	ds_read_b128 v[208:211], v157 offset:54272
	ds_read_b128 v[212:215], v157 offset:55296
	ds_read_b128 v[216:219], v157 offset:56320
	global_load_lds_dwordx4 v[220:221], off
	s_add_i32 m0, s34, 0x2000
	s_add_u32 s34, s36, 0xb0080
	v_lshl_add_u64 v[220:221], v[222:223], 0, s[22:23]
	s_addc_u32 s35, s37, 0
	s_add_i32 s36, s66, s41
	global_load_lds_dwordx4 v[220:221], off
	v_lshl_add_u64 v[220:221], s[34:35], 0, v[134:135]
	s_mov_b32 m0, s36
	s_nop 0
	global_load_lds_dwordx4 v[220:221], off
	v_lshl_add_u64 v[220:221], s[34:35], 0, v[138:139]
	s_add_i32 m0, s36, 0x2000
	s_nop 0
	global_load_lds_dwordx4 v[220:221], off
	v_lshl_add_u64 v[220:221], v[224:225], 0, s[22:23]
	s_mov_b32 m0, s51
	s_nop 0
	global_load_lds_dwordx4 v[220:221], off
	v_lshl_add_u64 v[220:221], v[226:227], 0, s[22:23]
	s_mov_b32 m0, s52
	s_nop 0
	global_load_lds_dwordx4 v[220:221], off
	s_waitcnt vmcnt(8)
	s_waitcnt lgkmcnt(0)
	s_barrier
	s_add_u32 s30, s30, 0x100
	s_addc_u32 s31, s31, 0
	s_add_u32 s13, s13, 0x100
	s_addc_u32 s63, s63, 0
	s_setprio 1
	s_waitcnt lgkmcnt(0)
	v_mfma_f32_16x16x32_bf16 v[60:63], v[148:151], v[188:191], v[60:63]
	v_mfma_f32_16x16x32_bf16 v[56:59], v[164:167], v[188:191], v[56:59]
	v_mfma_f32_16x16x32_bf16 v[44:47], v[148:151], v[196:199], v[44:47]
	v_mfma_f32_16x16x32_bf16 v[40:43], v[164:167], v[196:199], v[40:43]
	v_mfma_f32_16x16x32_bf16 v[28:31], v[148:151], v[204:207], v[28:31]
	v_mfma_f32_16x16x32_bf16 v[24:27], v[164:167], v[204:207], v[24:27]
	v_mfma_f32_16x16x32_bf16 v[12:15], v[148:151], v[212:215], v[12:15]
	v_mfma_f32_16x16x32_bf16 v[8:11], v[164:167], v[212:215], v[8:11]
	v_mfma_f32_16x16x32_bf16 v[60:63], v[160:163], v[192:195], v[60:63]
	v_mfma_f32_16x16x32_bf16 v[56:59], v[168:171], v[192:195], v[56:59]
	v_mfma_f32_16x16x32_bf16 v[44:47], v[160:163], v[200:203], v[44:47]
	v_mfma_f32_16x16x32_bf16 v[40:43], v[168:171], v[200:203], v[40:43]
	v_mfma_f32_16x16x32_bf16 v[28:31], v[160:163], v[208:211], v[28:31]
	v_mfma_f32_16x16x32_bf16 v[24:27], v[168:171], v[208:211], v[24:27]
	v_mfma_f32_16x16x32_bf16 v[12:15], v[160:163], v[216:219], v[12:15]
	v_mfma_f32_16x16x32_bf16 v[8:11], v[168:171], v[216:219], v[8:11]
	s_setprio 0
	s_setprio 1
	v_mfma_f32_16x16x32_bf16 v[52:55], v[172:175], v[188:191], v[52:55]
	v_mfma_f32_16x16x32_bf16 v[48:51], v[180:183], v[188:191], v[48:51]
	v_mfma_f32_16x16x32_bf16 v[36:39], v[172:175], v[196:199], v[36:39]
	v_mfma_f32_16x16x32_bf16 v[32:35], v[180:183], v[196:199], v[32:35]
	v_mfma_f32_16x16x32_bf16 v[20:23], v[172:175], v[204:207], v[20:23]
	v_mfma_f32_16x16x32_bf16 v[16:19], v[180:183], v[204:207], v[16:19]
	v_mfma_f32_16x16x32_bf16 v[4:7], v[172:175], v[212:215], v[4:7]
	v_mfma_f32_16x16x32_bf16 v[0:3], v[180:183], v[212:215], v[0:3]
	v_mfma_f32_16x16x32_bf16 v[52:55], v[176:179], v[192:195], v[52:55]
	v_mfma_f32_16x16x32_bf16 v[48:51], v[184:187], v[192:195], v[48:51]
	v_mfma_f32_16x16x32_bf16 v[36:39], v[176:179], v[200:203], v[36:39]
	v_mfma_f32_16x16x32_bf16 v[32:35], v[184:187], v[200:203], v[32:35]
	v_mfma_f32_16x16x32_bf16 v[20:23], v[176:179], v[208:211], v[20:23]
	v_mfma_f32_16x16x32_bf16 v[16:19], v[184:187], v[208:211], v[16:19]
	v_mfma_f32_16x16x32_bf16 v[4:7], v[176:179], v[216:219], v[4:7]
	v_mfma_f32_16x16x32_bf16 v[0:3], v[184:187], v[216:219], v[0:3]
	s_setprio 0
	s_add_i32 s64, s64, 2
	s_cmp_gt_u32 s64, 41
	s_cbranch_scc0 .LBB0_1145
	s_sub_i32 s100, s64, 2
	s_cmp_eq_u32 s100, s98
	s_cbranch_scc1 .Lmy_nobar_11
	s_barrier

.Lmy_nobar2_12:
	ds_read_b128 v[148:151], v155
	ds_read_b128 v[160:163], v155 offset:1024
	ds_read_b128 v[164:167], v155 offset:2048
	ds_read_b128 v[168:171], v155 offset:3072
	ds_read_b128 v[172:175], v157
	ds_read_b128 v[176:179], v157 offset:1024
	ds_read_b128 v[180:183], v157 offset:2048
	ds_read_b128 v[184:187], v157 offset:3072
	s_add_u32 s34, s36, 0xfffc0080
	s_addc_u32 s35, s37, -1
	s_cmp_eq_u32 s77, 12
	s_cselect_b32 s41, s23, s35
	s_cselect_b32 s40, s64, s34
	s_cselect_b32 s39, s11, s67
	s_cselect_b32 s38, s65, s66
	v_lshl_add_u64 v[220:221], s[36:37], 0, v[140:141]
	s_add_i32 m0, s31, 0xc000
	ds_read_b128 v[188:191], v158
	ds_read_b128 v[192:195], v158 offset:1024
	ds_read_b128 v[196:199], v158 offset:2048
	ds_read_b128 v[200:203], v158 offset:3072
	ds_read_b128 v[204:207], v158 offset:4096
	ds_read_b128 v[208:211], v158 offset:5120
	ds_read_b128 v[212:215], v158 offset:6144
	ds_read_b128 v[216:219], v158 offset:7168
	global_load_lds_dwordx4 v[220:221], off
	v_lshl_add_u64 v[220:221], s[36:37], 0, v[142:143]
	s_add_i32 m0, s31, 0xe000
	s_nop 0
	global_load_lds_dwordx4 v[220:221], off
	s_waitcnt vmcnt(8)
	s_waitcnt lgkmcnt(0)
	s_barrier
	s_setprio 1
	s_waitcnt lgkmcnt(0)
	v_mfma_f32_16x16x32_bf16 v[124:127], v[148:151], v[188:191], 0
	v_mfma_f32_16x16x32_bf16 v[120:123], v[164:167], v[188:191], 0
	v_mfma_f32_16x16x32_bf16 v[108:111], v[148:151], v[196:199], 0
	v_mfma_f32_16x16x32_bf16 v[104:107], v[164:167], v[196:199], 0
	v_mfma_f32_16x16x32_bf16 v[92:95], v[148:151], v[204:207], 0
	v_mfma_f32_16x16x32_bf16 v[88:91], v[164:167], v[204:207], 0
	v_mfma_f32_16x16x32_bf16 v[76:79], v[148:151], v[212:215], 0
	v_mfma_f32_16x16x32_bf16 v[72:75], v[164:167], v[212:215], 0
	v_mfma_f32_16x16x32_bf16 v[124:127], v[160:163], v[192:195], v[124:127]
	v_mfma_f32_16x16x32_bf16 v[120:123], v[168:171], v[192:195], v[120:123]
	v_mfma_f32_16x16x32_bf16 v[108:111], v[160:163], v[200:203], v[108:111]
	v_mfma_f32_16x16x32_bf16 v[104:107], v[168:171], v[200:203], v[104:107]
	v_mfma_f32_16x16x32_bf16 v[92:95], v[160:163], v[208:211], v[92:95]
	v_mfma_f32_16x16x32_bf16 v[88:91], v[168:171], v[208:211], v[88:91]
	v_mfma_f32_16x16x32_bf16 v[76:79], v[160:163], v[216:219], v[76:79]
	v_mfma_f32_16x16x32_bf16 v[72:75], v[168:171], v[216:219], v[72:75]
	s_setprio 0
	s_setprio 1
	v_mfma_f32_16x16x32_bf16 v[116:119], v[172:175], v[188:191], 0
	v_mfma_f32_16x16x32_bf16 v[112:115], v[180:183], v[188:191], 0
	v_mfma_f32_16x16x32_bf16 v[100:103], v[172:175], v[196:199], 0
	v_mfma_f32_16x16x32_bf16 v[96:99], v[180:183], v[196:199], 0
	v_mfma_f32_16x16x32_bf16 v[84:87], v[172:175], v[204:207], 0
	v_mfma_f32_16x16x32_bf16 v[80:83], v[180:183], v[204:207], 0
	v_mfma_f32_16x16x32_bf16 v[68:71], v[172:175], v[212:215], 0
	v_mfma_f32_16x16x32_bf16 v[64:67], v[180:183], v[212:215], 0
	v_mfma_f32_16x16x32_bf16 v[116:119], v[176:179], v[192:195], v[116:119]
	v_mfma_f32_16x16x32_bf16 v[112:115], v[184:187], v[192:195], v[112:115]
	v_mfma_f32_16x16x32_bf16 v[100:103], v[176:179], v[200:203], v[100:103]
	v_mfma_f32_16x16x32_bf16 v[96:99], v[184:187], v[200:203], v[96:99]
	v_mfma_f32_16x16x32_bf16 v[84:87], v[176:179], v[208:211], v[84:87]
	v_mfma_f32_16x16x32_bf16 v[80:83], v[184:187], v[208:211], v[80:83]
	v_mfma_f32_16x16x32_bf16 v[68:71], v[176:179], v[216:219], v[68:71]
	v_mfma_f32_16x16x32_bf16 v[64:67], v[184:187], v[216:219], v[64:67]
	s_setprio 0
	s_barrier
	s_add_i32 s34, s55, s48
	v_lshl_add_u64 v[220:221], s[38:39], 0, v[136:137]
	s_mov_b32 m0, s34
	ds_read_b128 v[188:191], v158 offset:16384
	ds_read_b128 v[192:195], v158 offset:17408
	ds_read_b128 v[196:199], v158 offset:18432
	ds_read_b128 v[200:203], v158 offset:19456
	ds_read_b128 v[204:207], v158 offset:20480
	ds_read_b128 v[208:211], v158 offset:21504
	ds_read_b128 v[212:215], v158 offset:22528
	ds_read_b128 v[216:219], v158 offset:23552
	global_load_lds_dwordx4 v[220:221], off
	s_add_i32 m0, s34, 0x2000
	s_add_u32 s34, s38, 0x40000
	v_lshl_add_u64 v[222:223], s[38:39], 0, v[132:133]
	s_addc_u32 s35, s39, 0
	s_add_i32 s79, s56, s48
	global_load_lds_dwordx4 v[222:223], off
	v_lshl_add_u64 v[224:225], s[34:35], 0, v[136:137]
	s_mov_b32 m0, s79
	v_lshl_add_u64 v[226:227], s[40:41], 0, v[134:135]
	global_load_lds_dwordx4 v[224:225], off
	v_lshl_add_u64 v[224:225], s[34:35], 0, v[132:133]
	s_add_i32 m0, s79, 0x2000
	s_nop 0
	global_load_lds_dwordx4 v[224:225], off
	v_lshl_add_u64 v[224:225], s[40:41], 0, v[138:139]
	s_mov_b32 m0, s31
	s_nop 0
	global_load_lds_dwordx4 v[224:225], off
	s_mov_b32 m0, s52
	s_nop 0
	global_load_lds_dwordx4 v[226:227], off
	s_waitcnt vmcnt(8)
	s_waitcnt lgkmcnt(0)
	s_barrier
	s_setprio 1
	s_waitcnt lgkmcnt(0)
	v_mfma_f32_16x16x32_bf16 v[60:63], v[148:151], v[188:191], 0
	v_mfma_f32_16x16x32_bf16 v[56:59], v[164:167], v[188:191], 0
	v_mfma_f32_16x16x32_bf16 v[44:47], v[148:151], v[196:199], 0
	v_mfma_f32_16x16x32_bf16 v[40:43], v[164:167], v[196:199], 0
	v_mfma_f32_16x16x32_bf16 v[28:31], v[148:151], v[204:207], 0
	v_mfma_f32_16x16x32_bf16 v[24:27], v[164:167], v[204:207], 0
	v_mfma_f32_16x16x32_bf16 v[12:15], v[148:151], v[212:215], 0
	v_mfma_f32_16x16x32_bf16 v[8:11], v[164:167], v[212:215], 0
	v_mfma_f32_16x16x32_bf16 v[60:63], v[160:163], v[192:195], v[60:63]
	v_mfma_f32_16x16x32_bf16 v[56:59], v[168:171], v[192:195], v[56:59]
	v_mfma_f32_16x16x32_bf16 v[44:47], v[160:163], v[200:203], v[44:47]
	v_mfma_f32_16x16x32_bf16 v[40:43], v[168:171], v[200:203], v[40:43]
	v_mfma_f32_16x16x32_bf16 v[28:31], v[160:163], v[208:211], v[28:31]
	v_mfma_f32_16x16x32_bf16 v[24:27], v[168:171], v[208:211], v[24:27]
	v_mfma_f32_16x16x32_bf16 v[12:15], v[160:163], v[216:219], v[12:15]
	v_mfma_f32_16x16x32_bf16 v[8:11], v[168:171], v[216:219], v[8:11]
	s_setprio 0
	s_setprio 1
	v_mfma_f32_16x16x32_bf16 v[52:55], v[172:175], v[188:191], 0
	v_mfma_f32_16x16x32_bf16 v[48:51], v[180:183], v[188:191], 0
	v_mfma_f32_16x16x32_bf16 v[36:39], v[172:175], v[196:199], 0
	v_mfma_f32_16x16x32_bf16 v[32:35], v[180:183], v[196:199], 0
	v_mfma_f32_16x16x32_bf16 v[20:23], v[172:175], v[204:207], 0
	v_mfma_f32_16x16x32_bf16 v[16:19], v[180:183], v[204:207], 0
	v_mfma_f32_16x16x32_bf16 v[4:7], v[172:175], v[212:215], 0
	v_mfma_f32_16x16x32_bf16 v[0:3], v[180:183], v[212:215], 0
	v_mfma_f32_16x16x32_bf16 v[52:55], v[176:179], v[192:195], v[52:55]
	v_mfma_f32_16x16x32_bf16 v[48:51], v[184:187], v[192:195], v[48:51]
	v_mfma_f32_16x16x32_bf16 v[36:39], v[176:179], v[200:203], v[36:39]
	v_mfma_f32_16x16x32_bf16 v[32:35], v[184:187], v[200:203], v[32:35]
	v_mfma_f32_16x16x32_bf16 v[20:23], v[176:179], v[208:211], v[20:23]
	v_mfma_f32_16x16x32_bf16 v[16:19], v[184:187], v[208:211], v[16:19]
	v_mfma_f32_16x16x32_bf16 v[4:7], v[176:179], v[216:219], v[4:7]
	v_mfma_f32_16x16x32_bf16 v[0:3], v[184:187], v[216:219], v[0:3]
	s_setprio 0
	s_barrier
	s_add_i32 s79, 0, 0x18000
	v_add_u32_e32 v159, s79, v152
	s_add_i32 s81, 0, 0x1c000
	ds_read_b128 v[148:151], v159
	ds_read_b128 v[160:163], v159 offset:1024
	ds_read_b128 v[164:167], v159 offset:2048
	ds_read_b128 v[168:171], v159 offset:3072
	v_add_u32_e32 v159, s81, v152
	ds_read_b128 v[172:175], v159
	ds_read_b128 v[176:179], v159 offset:1024
	ds_read_b128 v[180:183], v159 offset:2048
	ds_read_b128 v[184:187], v159 offset:3072
	s_add_u32 s34, s40, 0x40000
	s_addc_u32 s35, s41, 0
	s_mov_b32 m0, s53
	v_lshl_add_u64 v[228:229], s[34:35], 0, v[138:139]
	ds_read_b128 v[188:191], v158 offset:32768
	ds_read_b128 v[192:195], v158 offset:33792
	ds_read_b128 v[196:199], v158 offset:34816
	ds_read_b128 v[200:203], v158 offset:35840
	ds_read_b128 v[204:207], v158 offset:36864
	ds_read_b128 v[208:211], v158 offset:37888
	ds_read_b128 v[212:215], v158 offset:38912
	ds_read_b128 v[216:219], v158 offset:39936
	global_load_lds_dwordx4 v[228:229], off
	v_lshl_add_u64 v[228:229], s[34:35], 0, v[134:135]
	s_mov_b32 m0, s54
	s_nop 0
	global_load_lds_dwordx4 v[228:229], off
	s_waitcnt vmcnt(8)
	s_waitcnt lgkmcnt(0)
	s_barrier
	s_setprio 1
	s_waitcnt lgkmcnt(0)
	v_mfma_f32_16x16x32_bf16 v[124:127], v[148:151], v[188:191], v[124:127]
	v_mfma_f32_16x16x32_bf16 v[120:123], v[164:167], v[188:191], v[120:123]
	v_mfma_f32_16x16x32_bf16 v[108:111], v[148:151], v[196:199], v[108:111]
	v_mfma_f32_16x16x32_bf16 v[104:107], v[164:167], v[196:199], v[104:107]
	v_mfma_f32_16x16x32_bf16 v[92:95], v[148:151], v[204:207], v[92:95]
	v_mfma_f32_16x16x32_bf16 v[88:91], v[164:167], v[204:207], v[88:91]
	v_mfma_f32_16x16x32_bf16 v[76:79], v[148:151], v[212:215], v[76:79]
	v_mfma_f32_16x16x32_bf16 v[72:75], v[164:167], v[212:215], v[72:75]
	v_mfma_f32_16x16x32_bf16 v[124:127], v[160:163], v[192:195], v[124:127]
	v_mfma_f32_16x16x32_bf16 v[120:123], v[168:171], v[192:195], v[120:123]
	v_mfma_f32_16x16x32_bf16 v[108:111], v[160:163], v[200:203], v[108:111]
	v_mfma_f32_16x16x32_bf16 v[104:107], v[168:171], v[200:203], v[104:107]
	v_mfma_f32_16x16x32_bf16 v[92:95], v[160:163], v[208:211], v[92:95]
	v_mfma_f32_16x16x32_bf16 v[88:91], v[168:171], v[208:211], v[88:91]
	v_mfma_f32_16x16x32_bf16 v[76:79], v[160:163], v[216:219], v[76:79]
	v_mfma_f32_16x16x32_bf16 v[72:75], v[168:171], v[216:219], v[72:75]
	s_setprio 0
	s_setprio 1
	v_mfma_f32_16x16x32_bf16 v[116:119], v[172:175], v[188:191], v[116:119]
	v_mfma_f32_16x16x32_bf16 v[112:115], v[180:183], v[188:191], v[112:115]
	v_mfma_f32_16x16x32_bf16 v[100:103], v[172:175], v[196:199], v[100:103]
	v_mfma_f32_16x16x32_bf16 v[96:99], v[180:183], v[196:199], v[96:99]
	v_mfma_f32_16x16x32_bf16 v[84:87], v[172:175], v[204:207], v[84:87]
	v_mfma_f32_16x16x32_bf16 v[80:83], v[180:183], v[204:207], v[80:83]
	v_mfma_f32_16x16x32_bf16 v[68:71], v[172:175], v[212:215], v[68:71]
	v_mfma_f32_16x16x32_bf16 v[64:67], v[180:183], v[212:215], v[64:67]
	v_mfma_f32_16x16x32_bf16 v[116:119], v[176:179], v[192:195], v[116:119]
	v_mfma_f32_16x16x32_bf16 v[112:115], v[184:187], v[192:195], v[112:115]
	v_mfma_f32_16x16x32_bf16 v[100:103], v[176:179], v[200:203], v[100:103]
	v_mfma_f32_16x16x32_bf16 v[96:99], v[184:187], v[200:203], v[96:99]
	v_mfma_f32_16x16x32_bf16 v[84:87], v[176:179], v[208:211], v[84:87]
	v_mfma_f32_16x16x32_bf16 v[80:83], v[184:187], v[208:211], v[80:83]
	v_mfma_f32_16x16x32_bf16 v[68:71], v[176:179], v[216:219], v[68:71]
	v_mfma_f32_16x16x32_bf16 v[64:67], v[184:187], v[216:219], v[64:67]
	s_setprio 0
	s_barrier
	s_add_i32 s34, s79, s48
	v_lshl_add_u64 v[220:221], v[220:221], 0, s[6:7]
	s_mov_b32 m0, s34
	ds_read_b128 v[188:191], v158 offset:49152
	ds_read_b128 v[192:195], v158 offset:50176
	ds_read_b128 v[196:199], v158 offset:51200
	ds_read_b128 v[200:203], v158 offset:52224
	ds_read_b128 v[204:207], v158 offset:53248
	ds_read_b128 v[208:211], v158 offset:54272
	ds_read_b128 v[212:215], v158 offset:55296
	ds_read_b128 v[216:219], v158 offset:56320
	global_load_lds_dwordx4 v[220:221], off
	s_add_i32 m0, s34, 0x2000
	s_add_u32 s34, s38, 0x40080
	v_lshl_add_u64 v[220:221], v[222:223], 0, s[6:7]
	s_addc_u32 s35, s39, 0
	s_add_i32 s38, s81, s48
	global_load_lds_dwordx4 v[220:221], off
	v_lshl_add_u64 v[220:221], s[34:35], 0, v[136:137]
	s_mov_b32 m0, s38
	s_nop 0
	global_load_lds_dwordx4 v[220:221], off
	v_lshl_add_u64 v[220:221], s[34:35], 0, v[132:133]
	s_add_i32 m0, s38, 0x2000
	s_nop 0
	global_load_lds_dwordx4 v[220:221], off
	v_lshl_add_u64 v[220:221], v[224:225], 0, s[6:7]
	s_mov_b32 m0, s12
	s_nop 0
	global_load_lds_dwordx4 v[220:221], off
	v_lshl_add_u64 v[220:221], v[226:227], 0, s[6:7]
	s_mov_b32 m0, s13
	s_nop 0
	global_load_lds_dwordx4 v[220:221], off
	s_waitcnt vmcnt(8)
	s_waitcnt lgkmcnt(0)
	s_barrier
	s_add_u32 s36, s36, 0x100
	s_addc_u32 s37, s37, 0
	s_add_u32 s66, s66, 0x100
	s_addc_u32 s67, s67, 0
	s_setprio 1
	s_waitcnt lgkmcnt(0)
	v_mfma_f32_16x16x32_bf16 v[60:63], v[148:151], v[188:191], v[60:63]
	v_mfma_f32_16x16x32_bf16 v[56:59], v[164:167], v[188:191], v[56:59]
	v_mfma_f32_16x16x32_bf16 v[44:47], v[148:151], v[196:199], v[44:47]
	v_mfma_f32_16x16x32_bf16 v[40:43], v[164:167], v[196:199], v[40:43]
	v_mfma_f32_16x16x32_bf16 v[28:31], v[148:151], v[204:207], v[28:31]
	v_mfma_f32_16x16x32_bf16 v[24:27], v[164:167], v[204:207], v[24:27]
	v_mfma_f32_16x16x32_bf16 v[12:15], v[148:151], v[212:215], v[12:15]
	v_mfma_f32_16x16x32_bf16 v[8:11], v[164:167], v[212:215], v[8:11]
	v_mfma_f32_16x16x32_bf16 v[60:63], v[160:163], v[192:195], v[60:63]
	v_mfma_f32_16x16x32_bf16 v[56:59], v[168:171], v[192:195], v[56:59]
	v_mfma_f32_16x16x32_bf16 v[44:47], v[160:163], v[200:203], v[44:47]
	v_mfma_f32_16x16x32_bf16 v[40:43], v[168:171], v[200:203], v[40:43]
	v_mfma_f32_16x16x32_bf16 v[28:31], v[160:163], v[208:211], v[28:31]
	v_mfma_f32_16x16x32_bf16 v[24:27], v[168:171], v[208:211], v[24:27]
	v_mfma_f32_16x16x32_bf16 v[12:15], v[160:163], v[216:219], v[12:15]
	v_mfma_f32_16x16x32_bf16 v[8:11], v[168:171], v[216:219], v[8:11]
	s_setprio 0
	s_setprio 1
	v_mfma_f32_16x16x32_bf16 v[52:55], v[172:175], v[188:191], v[52:55]
	v_mfma_f32_16x16x32_bf16 v[48:51], v[180:183], v[188:191], v[48:51]
	v_mfma_f32_16x16x32_bf16 v[36:39], v[172:175], v[196:199], v[36:39]
	v_mfma_f32_16x16x32_bf16 v[32:35], v[180:183], v[196:199], v[32:35]
	v_mfma_f32_16x16x32_bf16 v[20:23], v[172:175], v[204:207], v[20:23]
	v_mfma_f32_16x16x32_bf16 v[16:19], v[180:183], v[204:207], v[16:19]
	v_mfma_f32_16x16x32_bf16 v[4:7], v[172:175], v[212:215], v[4:7]
	v_mfma_f32_16x16x32_bf16 v[0:3], v[180:183], v[212:215], v[0:3]
	v_mfma_f32_16x16x32_bf16 v[52:55], v[176:179], v[192:195], v[52:55]
	v_mfma_f32_16x16x32_bf16 v[48:51], v[184:187], v[192:195], v[48:51]
	v_mfma_f32_16x16x32_bf16 v[36:39], v[176:179], v[200:203], v[36:39]
	v_mfma_f32_16x16x32_bf16 v[32:35], v[184:187], v[200:203], v[32:35]
	v_mfma_f32_16x16x32_bf16 v[20:23], v[176:179], v[208:211], v[20:23]
	v_mfma_f32_16x16x32_bf16 v[16:19], v[184:187], v[208:211], v[16:19]
	v_mfma_f32_16x16x32_bf16 v[4:7], v[176:179], v[216:219], v[4:7]
	v_mfma_f32_16x16x32_bf16 v[0:3], v[184:187], v[216:219], v[0:3]
	s_setprio 0
	s_add_i32 s77, s77, 2
.LBB0_1235:
	s_barrier
	ds_read_b128 v[148:151], v155
	ds_read_b128 v[160:163], v155 offset:1024
	ds_read_b128 v[164:167], v155 offset:2048
	ds_read_b128 v[168:171], v155 offset:3072
	ds_read_b128 v[172:175], v157
	ds_read_b128 v[176:179], v157 offset:1024
	ds_read_b128 v[180:183], v157 offset:2048
	ds_read_b128 v[184:187], v157 offset:3072
	s_add_u32 s34, s36, 0xfffc0080
	s_addc_u32 s35, s37, -1
	s_cmp_eq_u32 s77, 12
	s_cselect_b32 s41, s23, s35
	s_cselect_b32 s40, s64, s34
	s_cselect_b32 s39, s11, s67
	s_cselect_b32 s38, s65, s66
	v_lshl_add_u64 v[220:221], s[36:37], 0, v[140:141]
	s_add_i32 m0, s31, 0xc000
	ds_read_b128 v[188:191], v158
	ds_read_b128 v[192:195], v158 offset:1024
	ds_read_b128 v[196:199], v158 offset:2048
	ds_read_b128 v[200:203], v158 offset:3072
	ds_read_b128 v[204:207], v158 offset:4096
	ds_read_b128 v[208:211], v158 offset:5120
	ds_read_b128 v[212:215], v158 offset:6144
	ds_read_b128 v[216:219], v158 offset:7168
	global_load_lds_dwordx4 v[220:221], off
	v_lshl_add_u64 v[220:221], s[36:37], 0, v[142:143]
	s_add_i32 m0, s31, 0xe000
	s_nop 0
	global_load_lds_dwordx4 v[220:221], off
	s_waitcnt vmcnt(8)
	s_waitcnt lgkmcnt(0)
	s_barrier
	s_setprio 1
	s_waitcnt lgkmcnt(0)
	v_mfma_f32_16x16x32_bf16 v[124:127], v[148:151], v[188:191], v[124:127]
	v_mfma_f32_16x16x32_bf16 v[120:123], v[164:167], v[188:191], v[120:123]
	v_mfma_f32_16x16x32_bf16 v[108:111], v[148:151], v[196:199], v[108:111]
	v_mfma_f32_16x16x32_bf16 v[104:107], v[164:167], v[196:199], v[104:107]
	v_mfma_f32_16x16x32_bf16 v[92:95], v[148:151], v[204:207], v[92:95]
	v_mfma_f32_16x16x32_bf16 v[88:91], v[164:167], v[204:207], v[88:91]
	v_mfma_f32_16x16x32_bf16 v[76:79], v[148:151], v[212:215], v[76:79]
	v_mfma_f32_16x16x32_bf16 v[72:75], v[164:167], v[212:215], v[72:75]
	v_mfma_f32_16x16x32_bf16 v[124:127], v[160:163], v[192:195], v[124:127]
	v_mfma_f32_16x16x32_bf16 v[120:123], v[168:171], v[192:195], v[120:123]
	v_mfma_f32_16x16x32_bf16 v[108:111], v[160:163], v[200:203], v[108:111]
	v_mfma_f32_16x16x32_bf16 v[104:107], v[168:171], v[200:203], v[104:107]
	v_mfma_f32_16x16x32_bf16 v[92:95], v[160:163], v[208:211], v[92:95]
	v_mfma_f32_16x16x32_bf16 v[88:91], v[168:171], v[208:211], v[88:91]
	v_mfma_f32_16x16x32_bf16 v[76:79], v[160:163], v[216:219], v[76:79]
	v_mfma_f32_16x16x32_bf16 v[72:75], v[168:171], v[216:219], v[72:75]
	s_setprio 0
	s_setprio 1
	v_mfma_f32_16x16x32_bf16 v[116:119], v[172:175], v[188:191], v[116:119]
	v_mfma_f32_16x16x32_bf16 v[112:115], v[180:183], v[188:191], v[112:115]
	v_mfma_f32_16x16x32_bf16 v[100:103], v[172:175], v[196:199], v[100:103]
	v_mfma_f32_16x16x32_bf16 v[96:99], v[180:183], v[196:199], v[96:99]
	v_mfma_f32_16x16x32_bf16 v[84:87], v[172:175], v[204:207], v[84:87]
	v_mfma_f32_16x16x32_bf16 v[80:83], v[180:183], v[204:207], v[80:83]
	v_mfma_f32_16x16x32_bf16 v[68:71], v[172:175], v[212:215], v[68:71]
	v_mfma_f32_16x16x32_bf16 v[64:67], v[180:183], v[212:215], v[64:67]
	v_mfma_f32_16x16x32_bf16 v[116:119], v[176:179], v[192:195], v[116:119]
	v_mfma_f32_16x16x32_bf16 v[112:115], v[184:187], v[192:195], v[112:115]
	v_mfma_f32_16x16x32_bf16 v[100:103], v[176:179], v[200:203], v[100:103]
	v_mfma_f32_16x16x32_bf16 v[96:99], v[184:187], v[200:203], v[96:99]
	v_mfma_f32_16x16x32_bf16 v[84:87], v[176:179], v[208:211], v[84:87]
	v_mfma_f32_16x16x32_bf16 v[80:83], v[184:187], v[208:211], v[80:83]
	v_mfma_f32_16x16x32_bf16 v[68:71], v[176:179], v[216:219], v[68:71]
	v_mfma_f32_16x16x32_bf16 v[64:67], v[184:187], v[216:219], v[64:67]
	s_setprio 0
	s_barrier
	s_add_i32 s34, s55, s48
	v_lshl_add_u64 v[220:221], s[38:39], 0, v[136:137]
	s_mov_b32 m0, s34
	ds_read_b128 v[188:191], v158 offset:16384
	ds_read_b128 v[192:195], v158 offset:17408
	ds_read_b128 v[196:199], v158 offset:18432
	ds_read_b128 v[200:203], v158 offset:19456
	ds_read_b128 v[204:207], v158 offset:20480
	ds_read_b128 v[208:211], v158 offset:21504
	ds_read_b128 v[212:215], v158 offset:22528
	ds_read_b128 v[216:219], v158 offset:23552
	global_load_lds_dwordx4 v[220:221], off
	s_add_i32 m0, s34, 0x2000
	s_add_u32 s34, s38, 0x40000
	v_lshl_add_u64 v[222:223], s[38:39], 0, v[132:133]
	s_addc_u32 s35, s39, 0
	s_add_i32 s79, s56, s48
	global_load_lds_dwordx4 v[222:223], off
	v_lshl_add_u64 v[224:225], s[34:35], 0, v[136:137]
	s_mov_b32 m0, s79
	v_lshl_add_u64 v[226:227], s[40:41], 0, v[134:135]
	global_load_lds_dwordx4 v[224:225], off
	v_lshl_add_u64 v[224:225], s[34:35], 0, v[132:133]
	s_add_i32 m0, s79, 0x2000
	s_nop 0
	global_load_lds_dwordx4 v[224:225], off
	v_lshl_add_u64 v[224:225], s[40:41], 0, v[138:139]
	s_mov_b32 m0, s31
	s_nop 0
	global_load_lds_dwordx4 v[224:225], off
	s_mov_b32 m0, s52
	s_nop 0
	global_load_lds_dwordx4 v[226:227], off
	s_waitcnt vmcnt(8)
	s_waitcnt lgkmcnt(0)
	s_barrier
	s_setprio 1
	s_waitcnt lgkmcnt(0)
	v_mfma_f32_16x16x32_bf16 v[60:63], v[148:151], v[188:191], v[60:63]
	v_mfma_f32_16x16x32_bf16 v[56:59], v[164:167], v[188:191], v[56:59]
	v_mfma_f32_16x16x32_bf16 v[44:47], v[148:151], v[196:199], v[44:47]
	v_mfma_f32_16x16x32_bf16 v[40:43], v[164:167], v[196:199], v[40:43]
	v_mfma_f32_16x16x32_bf16 v[28:31], v[148:151], v[204:207], v[28:31]
	v_mfma_f32_16x16x32_bf16 v[24:27], v[164:167], v[204:207], v[24:27]
	v_mfma_f32_16x16x32_bf16 v[12:15], v[148:151], v[212:215], v[12:15]
	v_mfma_f32_16x16x32_bf16 v[8:11], v[164:167], v[212:215], v[8:11]
	v_mfma_f32_16x16x32_bf16 v[60:63], v[160:163], v[192:195], v[60:63]
	v_mfma_f32_16x16x32_bf16 v[56:59], v[168:171], v[192:195], v[56:59]
	v_mfma_f32_16x16x32_bf16 v[44:47], v[160:163], v[200:203], v[44:47]
	v_mfma_f32_16x16x32_bf16 v[40:43], v[168:171], v[200:203], v[40:43]
	v_mfma_f32_16x16x32_bf16 v[28:31], v[160:163], v[208:211], v[28:31]
	v_mfma_f32_16x16x32_bf16 v[24:27], v[168:171], v[208:211], v[24:27]
	v_mfma_f32_16x16x32_bf16 v[12:15], v[160:163], v[216:219], v[12:15]
	v_mfma_f32_16x16x32_bf16 v[8:11], v[168:171], v[216:219], v[8:11]
	s_setprio 0
	s_setprio 1
	v_mfma_f32_16x16x32_bf16 v[52:55], v[172:175], v[188:191], v[52:55]
	v_mfma_f32_16x16x32_bf16 v[48:51], v[180:183], v[188:191], v[48:51]
	v_mfma_f32_16x16x32_bf16 v[36:39], v[172:175], v[196:199], v[36:39]
	v_mfma_f32_16x16x32_bf16 v[32:35], v[180:183], v[196:199], v[32:35]
	v_mfma_f32_16x16x32_bf16 v[20:23], v[172:175], v[204:207], v[20:23]
	v_mfma_f32_16x16x32_bf16 v[16:19], v[180:183], v[204:207], v[16:19]
	v_mfma_f32_16x16x32_bf16 v[4:7], v[172:175], v[212:215], v[4:7]
	v_mfma_f32_16x16x32_bf16 v[0:3], v[180:183], v[212:215], v[0:3]
	v_mfma_f32_16x16x32_bf16 v[52:55], v[176:179], v[192:195], v[52:55]
	v_mfma_f32_16x16x32_bf16 v[48:51], v[184:187], v[192:195], v[48:51]
	v_mfma_f32_16x16x32_bf16 v[36:39], v[176:179], v[200:203], v[36:39]
	v_mfma_f32_16x16x32_bf16 v[32:35], v[184:187], v[200:203], v[32:35]
	v_mfma_f32_16x16x32_bf16 v[20:23], v[176:179], v[208:211], v[20:23]
	v_mfma_f32_16x16x32_bf16 v[16:19], v[184:187], v[208:211], v[16:19]
	v_mfma_f32_16x16x32_bf16 v[4:7], v[176:179], v[216:219], v[4:7]
	v_mfma_f32_16x16x32_bf16 v[0:3], v[184:187], v[216:219], v[0:3]
	s_setprio 0
	s_barrier
	s_add_i32 s79, 0, 0x18000
	v_add_u32_e32 v159, s79, v152
	s_add_i32 s81, 0, 0x1c000
	ds_read_b128 v[148:151], v159
	ds_read_b128 v[160:163], v159 offset:1024
	ds_read_b128 v[164:167], v159 offset:2048
	ds_read_b128 v[168:171], v159 offset:3072
	v_add_u32_e32 v159, s81, v152
	ds_read_b128 v[172:175], v159
	ds_read_b128 v[176:179], v159 offset:1024
	ds_read_b128 v[180:183], v159 offset:2048
	ds_read_b128 v[184:187], v159 offset:3072
	s_add_u32 s34, s40, 0x40000
	s_addc_u32 s35, s41, 0
	s_mov_b32 m0, s53
	v_lshl_add_u64 v[228:229], s[34:35], 0, v[138:139]
	ds_read_b128 v[188:191], v158 offset:32768
	ds_read_b128 v[192:195], v158 offset:33792
	ds_read_b128 v[196:199], v158 offset:34816
	ds_read_b128 v[200:203], v158 offset:35840
	ds_read_b128 v[204:207], v158 offset:36864
	ds_read_b128 v[208:211], v158 offset:37888
	ds_read_b128 v[212:215], v158 offset:38912
	ds_read_b128 v[216:219], v158 offset:39936
	global_load_lds_dwordx4 v[228:229], off
	v_lshl_add_u64 v[228:229], s[34:35], 0, v[134:135]
	s_mov_b32 m0, s54
	s_nop 0
	global_load_lds_dwordx4 v[228:229], off
	s_waitcnt vmcnt(8)
	s_waitcnt lgkmcnt(0)
	s_barrier
	s_setprio 1
	s_waitcnt lgkmcnt(0)
	v_mfma_f32_16x16x32_bf16 v[124:127], v[148:151], v[188:191], v[124:127]
	v_mfma_f32_16x16x32_bf16 v[120:123], v[164:167], v[188:191], v[120:123]
	v_mfma_f32_16x16x32_bf16 v[108:111], v[148:151], v[196:199], v[108:111]
	v_mfma_f32_16x16x32_bf16 v[104:107], v[164:167], v[196:199], v[104:107]
	v_mfma_f32_16x16x32_bf16 v[92:95], v[148:151], v[204:207], v[92:95]
	v_mfma_f32_16x16x32_bf16 v[88:91], v[164:167], v[204:207], v[88:91]
	v_mfma_f32_16x16x32_bf16 v[76:79], v[148:151], v[212:215], v[76:79]
	v_mfma_f32_16x16x32_bf16 v[72:75], v[164:167], v[212:215], v[72:75]
	v_mfma_f32_16x16x32_bf16 v[124:127], v[160:163], v[192:195], v[124:127]
	v_mfma_f32_16x16x32_bf16 v[120:123], v[168:171], v[192:195], v[120:123]
	v_mfma_f32_16x16x32_bf16 v[108:111], v[160:163], v[200:203], v[108:111]
	v_mfma_f32_16x16x32_bf16 v[104:107], v[168:171], v[200:203], v[104:107]
	v_mfma_f32_16x16x32_bf16 v[92:95], v[160:163], v[208:211], v[92:95]
	v_mfma_f32_16x16x32_bf16 v[88:91], v[168:171], v[208:211], v[88:91]
	v_mfma_f32_16x16x32_bf16 v[76:79], v[160:163], v[216:219], v[76:79]
	v_mfma_f32_16x16x32_bf16 v[72:75], v[168:171], v[216:219], v[72:75]
	s_setprio 0
	s_setprio 1
	v_mfma_f32_16x16x32_bf16 v[116:119], v[172:175], v[188:191], v[116:119]
	v_mfma_f32_16x16x32_bf16 v[112:115], v[180:183], v[188:191], v[112:115]
	v_mfma_f32_16x16x32_bf16 v[100:103], v[172:175], v[196:199], v[100:103]
	v_mfma_f32_16x16x32_bf16 v[96:99], v[180:183], v[196:199], v[96:99]
	v_mfma_f32_16x16x32_bf16 v[84:87], v[172:175], v[204:207], v[84:87]
	v_mfma_f32_16x16x32_bf16 v[80:83], v[180:183], v[204:207], v[80:83]
	v_mfma_f32_16x16x32_bf16 v[68:71], v[172:175], v[212:215], v[68:71]
	v_mfma_f32_16x16x32_bf16 v[64:67], v[180:183], v[212:215], v[64:67]
	v_mfma_f32_16x16x32_bf16 v[116:119], v[176:179], v[192:195], v[116:119]
	v_mfma_f32_16x16x32_bf16 v[112:115], v[184:187], v[192:195], v[112:115]
	v_mfma_f32_16x16x32_bf16 v[100:103], v[176:179], v[200:203], v[100:103]
	v_mfma_f32_16x16x32_bf16 v[96:99], v[184:187], v[200:203], v[96:99]
	v_mfma_f32_16x16x32_bf16 v[84:87], v[176:179], v[208:211], v[84:87]
	v_mfma_f32_16x16x32_bf16 v[80:83], v[184:187], v[208:211], v[80:83]
	v_mfma_f32_16x16x32_bf16 v[68:71], v[176:179], v[216:219], v[68:71]
	v_mfma_f32_16x16x32_bf16 v[64:67], v[184:187], v[216:219], v[64:67]
	s_setprio 0
	s_barrier
	s_add_i32 s34, s79, s48
	v_lshl_add_u64 v[220:221], v[220:221], 0, s[6:7]
	s_mov_b32 m0, s34
	ds_read_b128 v[188:191], v158 offset:49152
	ds_read_b128 v[192:195], v158 offset:50176
	ds_read_b128 v[196:199], v158 offset:51200
	ds_read_b128 v[200:203], v158 offset:52224
	ds_read_b128 v[204:207], v158 offset:53248
	ds_read_b128 v[208:211], v158 offset:54272
	ds_read_b128 v[212:215], v158 offset:55296
	ds_read_b128 v[216:219], v158 offset:56320
	global_load_lds_dwordx4 v[220:221], off
	s_add_i32 m0, s34, 0x2000
	s_add_u32 s34, s38, 0x40080
	v_lshl_add_u64 v[220:221], v[222:223], 0, s[6:7]
	s_addc_u32 s35, s39, 0
	s_add_i32 s38, s81, s48
	global_load_lds_dwordx4 v[220:221], off
	v_lshl_add_u64 v[220:221], s[34:35], 0, v[136:137]
	s_mov_b32 m0, s38
	s_nop 0
	global_load_lds_dwordx4 v[220:221], off
	v_lshl_add_u64 v[220:221], s[34:35], 0, v[132:133]
	s_add_i32 m0, s38, 0x2000
	s_nop 0
	global_load_lds_dwordx4 v[220:221], off
	v_lshl_add_u64 v[220:221], v[224:225], 0, s[6:7]
	s_mov_b32 m0, s12
	s_nop 0
	global_load_lds_dwordx4 v[220:221], off
	v_lshl_add_u64 v[220:221], v[226:227], 0, s[6:7]
	s_mov_b32 m0, s13
	s_nop 0
	global_load_lds_dwordx4 v[220:221], off
	s_waitcnt vmcnt(8)
	s_waitcnt lgkmcnt(0)
	s_barrier
	s_add_u32 s36, s36, 0x100
	s_addc_u32 s37, s37, 0
	s_add_u32 s66, s66, 0x100
	s_addc_u32 s67, s67, 0
	s_setprio 1
	s_waitcnt lgkmcnt(0)
	v_mfma_f32_16x16x32_bf16 v[60:63], v[148:151], v[188:191], v[60:63]
	v_mfma_f32_16x16x32_bf16 v[56:59], v[164:167], v[188:191], v[56:59]
	v_mfma_f32_16x16x32_bf16 v[44:47], v[148:151], v[196:199], v[44:47]
	v_mfma_f32_16x16x32_bf16 v[40:43], v[164:167], v[196:199], v[40:43]
	v_mfma_f32_16x16x32_bf16 v[28:31], v[148:151], v[204:207], v[28:31]
	v_mfma_f32_16x16x32_bf16 v[24:27], v[164:167], v[204:207], v[24:27]
	v_mfma_f32_16x16x32_bf16 v[12:15], v[148:151], v[212:215], v[12:15]
	v_mfma_f32_16x16x32_bf16 v[8:11], v[164:167], v[212:215], v[8:11]
	v_mfma_f32_16x16x32_bf16 v[60:63], v[160:163], v[192:195], v[60:63]
	v_mfma_f32_16x16x32_bf16 v[56:59], v[168:171], v[192:195], v[56:59]
	v_mfma_f32_16x16x32_bf16 v[44:47], v[160:163], v[200:203], v[44:47]
	v_mfma_f32_16x16x32_bf16 v[40:43], v[168:171], v[200:203], v[40:43]
	v_mfma_f32_16x16x32_bf16 v[28:31], v[160:163], v[208:211], v[28:31]
	v_mfma_f32_16x16x32_bf16 v[24:27], v[168:171], v[208:211], v[24:27]
	v_mfma_f32_16x16x32_bf16 v[12:15], v[160:163], v[216:219], v[12:15]
	v_mfma_f32_16x16x32_bf16 v[8:11], v[168:171], v[216:219], v[8:11]
	s_setprio 0
	s_setprio 1
	v_mfma_f32_16x16x32_bf16 v[52:55], v[172:175], v[188:191], v[52:55]
	v_mfma_f32_16x16x32_bf16 v[48:51], v[180:183], v[188:191], v[48:51]
	v_mfma_f32_16x16x32_bf16 v[36:39], v[172:175], v[196:199], v[36:39]
	v_mfma_f32_16x16x32_bf16 v[32:35], v[180:183], v[196:199], v[32:35]
	v_mfma_f32_16x16x32_bf16 v[20:23], v[172:175], v[204:207], v[20:23]
	v_mfma_f32_16x16x32_bf16 v[16:19], v[180:183], v[204:207], v[16:19]
	v_mfma_f32_16x16x32_bf16 v[4:7], v[172:175], v[212:215], v[4:7]
	v_mfma_f32_16x16x32_bf16 v[0:3], v[180:183], v[212:215], v[0:3]
	v_mfma_f32_16x16x32_bf16 v[52:55], v[176:179], v[192:195], v[52:55]
	v_mfma_f32_16x16x32_bf16 v[48:51], v[184:187], v[192:195], v[48:51]
	v_mfma_f32_16x16x32_bf16 v[36:39], v[176:179], v[200:203], v[36:39]
	v_mfma_f32_16x16x32_bf16 v[32:35], v[184:187], v[200:203], v[32:35]
	v_mfma_f32_16x16x32_bf16 v[20:23], v[176:179], v[208:211], v[20:23]
	v_mfma_f32_16x16x32_bf16 v[16:19], v[184:187], v[208:211], v[16:19]
	v_mfma_f32_16x16x32_bf16 v[4:7], v[176:179], v[216:219], v[4:7]
	v_mfma_f32_16x16x32_bf16 v[0:3], v[184:187], v[216:219], v[0:3]
	s_setprio 0
	s_add_i32 s77, s77, 2
	s_cmp_gt_u32 s77, 13
	s_cbranch_scc0 .LBB0_1235
	s_sub_i32 s100, s77, 2
	s_cmp_eq_u32 s100, s98
	s_cbranch_scc1 .Lmy_nobar_12
	s_barrier

.Lmy_nobar2_16:
	ds_read_b128 v[146:149], v153
	ds_read_b128 v[158:161], v153 offset:1024
	ds_read_b128 v[162:165], v153 offset:2048
	ds_read_b128 v[166:169], v153 offset:3072
	ds_read_b128 v[170:173], v154
	ds_read_b128 v[174:177], v154 offset:1024
	ds_read_b128 v[178:181], v154 offset:2048
	ds_read_b128 v[182:185], v154 offset:3072
	s_add_u32 s34, s40, 0xfffc0080
	s_addc_u32 s35, s41, -1
	s_cmp_eq_u32 s62, 12
	s_cselect_b32 s45, s12, s35
	s_cselect_b32 s44, s13, s34
	s_cselect_b32 s43, s27, s61
	s_cselect_b32 s42, s29, s39
	v_lshl_add_u64 v[218:219], s[40:41], 0, v[138:139]
	s_add_i32 m0, s48, 0xc000
	ds_read_b128 v[186:189], v155
	ds_read_b128 v[190:193], v155 offset:1024
	ds_read_b128 v[194:197], v155 offset:2048
	ds_read_b128 v[198:201], v155 offset:3072
	ds_read_b128 v[202:205], v155 offset:4096
	ds_read_b128 v[206:209], v155 offset:5120
	ds_read_b128 v[210:213], v155 offset:6144
	ds_read_b128 v[214:217], v155 offset:7168
	global_load_lds_dwordx4 v[218:219], off
	v_lshl_add_u64 v[218:219], s[40:41], 0, v[140:141]
	s_add_i32 m0, s48, 0xe000
	s_nop 0
	global_load_lds_dwordx4 v[218:219], off
	s_waitcnt vmcnt(8)
	s_waitcnt lgkmcnt(0)
	s_barrier
	s_setprio 1
	s_waitcnt lgkmcnt(0)
	v_mfma_f32_16x16x32_bf16 v[124:127], v[146:149], v[186:189], 0
	v_mfma_f32_16x16x32_bf16 v[120:123], v[162:165], v[186:189], 0
	v_mfma_f32_16x16x32_bf16 v[108:111], v[146:149], v[194:197], 0
	v_mfma_f32_16x16x32_bf16 v[104:107], v[162:165], v[194:197], 0
	v_mfma_f32_16x16x32_bf16 v[92:95], v[146:149], v[202:205], 0
	v_mfma_f32_16x16x32_bf16 v[88:91], v[162:165], v[202:205], 0
	v_mfma_f32_16x16x32_bf16 v[76:79], v[146:149], v[210:213], 0
	v_mfma_f32_16x16x32_bf16 v[72:75], v[162:165], v[210:213], 0
	v_mfma_f32_16x16x32_bf16 v[124:127], v[158:161], v[190:193], v[124:127]
	v_mfma_f32_16x16x32_bf16 v[120:123], v[166:169], v[190:193], v[120:123]
	v_mfma_f32_16x16x32_bf16 v[108:111], v[158:161], v[198:201], v[108:111]
	v_mfma_f32_16x16x32_bf16 v[104:107], v[166:169], v[198:201], v[104:107]
	v_mfma_f32_16x16x32_bf16 v[92:95], v[158:161], v[206:209], v[92:95]
	v_mfma_f32_16x16x32_bf16 v[88:91], v[166:169], v[206:209], v[88:91]
	v_mfma_f32_16x16x32_bf16 v[76:79], v[158:161], v[214:217], v[76:79]
	v_mfma_f32_16x16x32_bf16 v[72:75], v[166:169], v[214:217], v[72:75]
	s_setprio 0
	s_setprio 1
	v_mfma_f32_16x16x32_bf16 v[116:119], v[170:173], v[186:189], 0
	v_mfma_f32_16x16x32_bf16 v[112:115], v[178:181], v[186:189], 0
	v_mfma_f32_16x16x32_bf16 v[100:103], v[170:173], v[194:197], 0
	v_mfma_f32_16x16x32_bf16 v[96:99], v[178:181], v[194:197], 0
	v_mfma_f32_16x16x32_bf16 v[84:87], v[170:173], v[202:205], 0
	v_mfma_f32_16x16x32_bf16 v[80:83], v[178:181], v[202:205], 0
	v_mfma_f32_16x16x32_bf16 v[68:71], v[170:173], v[210:213], 0
	v_mfma_f32_16x16x32_bf16 v[64:67], v[178:181], v[210:213], 0
	v_mfma_f32_16x16x32_bf16 v[116:119], v[174:177], v[190:193], v[116:119]
	v_mfma_f32_16x16x32_bf16 v[112:115], v[182:185], v[190:193], v[112:115]
	v_mfma_f32_16x16x32_bf16 v[100:103], v[174:177], v[198:201], v[100:103]
	v_mfma_f32_16x16x32_bf16 v[96:99], v[182:185], v[198:201], v[96:99]
	v_mfma_f32_16x16x32_bf16 v[84:87], v[174:177], v[206:209], v[84:87]
	v_mfma_f32_16x16x32_bf16 v[80:83], v[182:185], v[206:209], v[80:83]
	v_mfma_f32_16x16x32_bf16 v[68:71], v[174:177], v[214:217], v[68:71]
	v_mfma_f32_16x16x32_bf16 v[64:67], v[182:185], v[214:217], v[64:67]
	s_setprio 0
	s_barrier
	s_add_i32 s34, s58, s47
	v_lshl_add_u64 v[218:219], s[42:43], 0, v[132:133]
	s_mov_b32 m0, s34
	ds_read_b128 v[186:189], v155 offset:16384
	ds_read_b128 v[190:193], v155 offset:17408
	ds_read_b128 v[194:197], v155 offset:18432
	ds_read_b128 v[198:201], v155 offset:19456
	ds_read_b128 v[202:205], v155 offset:20480
	ds_read_b128 v[206:209], v155 offset:21504
	ds_read_b128 v[210:213], v155 offset:22528
	ds_read_b128 v[214:217], v155 offset:23552
	global_load_lds_dwordx4 v[218:219], off
	s_add_i32 m0, s34, 0x2000
	s_add_u32 s34, s42, 0x40000
	v_lshl_add_u64 v[220:221], s[42:43], 0, v[136:137]
	s_addc_u32 s35, s43, 0
	s_add_i32 s63, s59, s47
	global_load_lds_dwordx4 v[220:221], off
	v_lshl_add_u64 v[222:223], s[34:35], 0, v[132:133]
	s_mov_b32 m0, s63
	v_lshl_add_u64 v[224:225], s[44:45], 0, v[134:135]
	global_load_lds_dwordx4 v[222:223], off
	v_lshl_add_u64 v[222:223], s[34:35], 0, v[136:137]
	s_add_i32 m0, s63, 0x2000
	s_nop 0
	global_load_lds_dwordx4 v[222:223], off
	v_lshl_add_u64 v[222:223], s[44:45], 0, v[130:131]
	s_mov_b32 m0, s48
	s_nop 0
	global_load_lds_dwordx4 v[222:223], off
	s_mov_b32 m0, s49
	s_nop 0
	global_load_lds_dwordx4 v[224:225], off
	s_waitcnt vmcnt(8)
	s_waitcnt lgkmcnt(0)
	s_barrier
	s_setprio 1
	s_waitcnt lgkmcnt(0)
	v_mfma_f32_16x16x32_bf16 v[60:63], v[146:149], v[186:189], 0
	v_mfma_f32_16x16x32_bf16 v[56:59], v[162:165], v[186:189], 0
	v_mfma_f32_16x16x32_bf16 v[44:47], v[146:149], v[194:197], 0
	v_mfma_f32_16x16x32_bf16 v[40:43], v[162:165], v[194:197], 0
	v_mfma_f32_16x16x32_bf16 v[28:31], v[146:149], v[202:205], 0
	v_mfma_f32_16x16x32_bf16 v[24:27], v[162:165], v[202:205], 0
	v_mfma_f32_16x16x32_bf16 v[12:15], v[146:149], v[210:213], 0
	v_mfma_f32_16x16x32_bf16 v[8:11], v[162:165], v[210:213], 0
	v_mfma_f32_16x16x32_bf16 v[60:63], v[158:161], v[190:193], v[60:63]
	v_mfma_f32_16x16x32_bf16 v[56:59], v[166:169], v[190:193], v[56:59]
	v_mfma_f32_16x16x32_bf16 v[44:47], v[158:161], v[198:201], v[44:47]
	v_mfma_f32_16x16x32_bf16 v[40:43], v[166:169], v[198:201], v[40:43]
	v_mfma_f32_16x16x32_bf16 v[28:31], v[158:161], v[206:209], v[28:31]
	v_mfma_f32_16x16x32_bf16 v[24:27], v[166:169], v[206:209], v[24:27]
	v_mfma_f32_16x16x32_bf16 v[12:15], v[158:161], v[214:217], v[12:15]
	v_mfma_f32_16x16x32_bf16 v[8:11], v[166:169], v[214:217], v[8:11]
	s_setprio 0
	s_setprio 1
	v_mfma_f32_16x16x32_bf16 v[52:55], v[170:173], v[186:189], 0
	v_mfma_f32_16x16x32_bf16 v[48:51], v[178:181], v[186:189], 0
	v_mfma_f32_16x16x32_bf16 v[36:39], v[170:173], v[194:197], 0
	v_mfma_f32_16x16x32_bf16 v[32:35], v[178:181], v[194:197], 0
	v_mfma_f32_16x16x32_bf16 v[20:23], v[170:173], v[202:205], 0
	v_mfma_f32_16x16x32_bf16 v[16:19], v[178:181], v[202:205], 0
	v_mfma_f32_16x16x32_bf16 v[4:7], v[170:173], v[210:213], 0
	v_mfma_f32_16x16x32_bf16 v[0:3], v[178:181], v[210:213], 0
	v_mfma_f32_16x16x32_bf16 v[52:55], v[174:177], v[190:193], v[52:55]
	v_mfma_f32_16x16x32_bf16 v[48:51], v[182:185], v[190:193], v[48:51]
	v_mfma_f32_16x16x32_bf16 v[36:39], v[174:177], v[198:201], v[36:39]
	v_mfma_f32_16x16x32_bf16 v[32:35], v[182:185], v[198:201], v[32:35]
	v_mfma_f32_16x16x32_bf16 v[20:23], v[174:177], v[206:209], v[20:23]
	v_mfma_f32_16x16x32_bf16 v[16:19], v[182:185], v[206:209], v[16:19]
	v_mfma_f32_16x16x32_bf16 v[4:7], v[174:177], v[214:217], v[4:7]
	v_mfma_f32_16x16x32_bf16 v[0:3], v[182:185], v[214:217], v[0:3]
	s_setprio 0
	s_barrier
	s_add_i32 s63, 0, 0x18000
	s_add_i32 s64, 0, 0x1c000
	v_add_u32_e32 v166, s63, v151
	v_add_u32_e32 v182, s64, v151
	ds_read_b128 v[146:149], v166
	ds_read_b128 v[158:161], v166 offset:1024
	ds_read_b128 v[162:165], v166 offset:2048
	ds_read_b128 v[166:169], v166 offset:3072
	ds_read_b128 v[170:173], v182
	ds_read_b128 v[174:177], v182 offset:1024
	ds_read_b128 v[178:181], v182 offset:2048
	ds_read_b128 v[182:185], v182 offset:3072
	s_add_u32 s34, s44, 0x40000
	s_addc_u32 s35, s45, 0
	s_mov_b32 m0, s50
	v_lshl_add_u64 v[226:227], s[34:35], 0, v[130:131]
	ds_read_b128 v[186:189], v155 offset:32768
	ds_read_b128 v[190:193], v155 offset:33792
	ds_read_b128 v[194:197], v155 offset:34816
	ds_read_b128 v[198:201], v155 offset:35840
	ds_read_b128 v[202:205], v155 offset:36864
	ds_read_b128 v[206:209], v155 offset:37888
	ds_read_b128 v[210:213], v155 offset:38912
	ds_read_b128 v[214:217], v155 offset:39936
	global_load_lds_dwordx4 v[226:227], off
	v_lshl_add_u64 v[226:227], s[34:35], 0, v[134:135]
	s_mov_b32 m0, s51
	s_nop 0
	global_load_lds_dwordx4 v[226:227], off
	s_waitcnt vmcnt(8)
	s_waitcnt lgkmcnt(0)
	s_barrier
	s_setprio 1
	s_waitcnt lgkmcnt(0)
	v_mfma_f32_16x16x32_bf16 v[124:127], v[146:149], v[186:189], v[124:127]
	v_mfma_f32_16x16x32_bf16 v[120:123], v[162:165], v[186:189], v[120:123]
	v_mfma_f32_16x16x32_bf16 v[108:111], v[146:149], v[194:197], v[108:111]
	v_mfma_f32_16x16x32_bf16 v[104:107], v[162:165], v[194:197], v[104:107]
	v_mfma_f32_16x16x32_bf16 v[92:95], v[146:149], v[202:205], v[92:95]
	v_mfma_f32_16x16x32_bf16 v[88:91], v[162:165], v[202:205], v[88:91]
	v_mfma_f32_16x16x32_bf16 v[76:79], v[146:149], v[210:213], v[76:79]
	v_mfma_f32_16x16x32_bf16 v[72:75], v[162:165], v[210:213], v[72:75]
	v_mfma_f32_16x16x32_bf16 v[124:127], v[158:161], v[190:193], v[124:127]
	v_mfma_f32_16x16x32_bf16 v[120:123], v[166:169], v[190:193], v[120:123]
	v_mfma_f32_16x16x32_bf16 v[108:111], v[158:161], v[198:201], v[108:111]
	v_mfma_f32_16x16x32_bf16 v[104:107], v[166:169], v[198:201], v[104:107]
	v_mfma_f32_16x16x32_bf16 v[92:95], v[158:161], v[206:209], v[92:95]
	v_mfma_f32_16x16x32_bf16 v[88:91], v[166:169], v[206:209], v[88:91]
	v_mfma_f32_16x16x32_bf16 v[76:79], v[158:161], v[214:217], v[76:79]
	v_mfma_f32_16x16x32_bf16 v[72:75], v[166:169], v[214:217], v[72:75]
	s_setprio 0
	s_setprio 1
	v_mfma_f32_16x16x32_bf16 v[116:119], v[170:173], v[186:189], v[116:119]
	v_mfma_f32_16x16x32_bf16 v[112:115], v[178:181], v[186:189], v[112:115]
	v_mfma_f32_16x16x32_bf16 v[100:103], v[170:173], v[194:197], v[100:103]
	v_mfma_f32_16x16x32_bf16 v[96:99], v[178:181], v[194:197], v[96:99]
	v_mfma_f32_16x16x32_bf16 v[84:87], v[170:173], v[202:205], v[84:87]
	v_mfma_f32_16x16x32_bf16 v[80:83], v[178:181], v[202:205], v[80:83]
	v_mfma_f32_16x16x32_bf16 v[68:71], v[170:173], v[210:213], v[68:71]
	v_mfma_f32_16x16x32_bf16 v[64:67], v[178:181], v[210:213], v[64:67]
	v_mfma_f32_16x16x32_bf16 v[116:119], v[174:177], v[190:193], v[116:119]
	v_mfma_f32_16x16x32_bf16 v[112:115], v[182:185], v[190:193], v[112:115]
	v_mfma_f32_16x16x32_bf16 v[100:103], v[174:177], v[198:201], v[100:103]
	v_mfma_f32_16x16x32_bf16 v[96:99], v[182:185], v[198:201], v[96:99]
	v_mfma_f32_16x16x32_bf16 v[84:87], v[174:177], v[206:209], v[84:87]
	v_mfma_f32_16x16x32_bf16 v[80:83], v[182:185], v[206:209], v[80:83]
	v_mfma_f32_16x16x32_bf16 v[68:71], v[174:177], v[214:217], v[68:71]
	v_mfma_f32_16x16x32_bf16 v[64:67], v[182:185], v[214:217], v[64:67]
	s_setprio 0
	s_barrier
	s_add_i32 s34, s63, s47
	v_lshl_add_u64 v[218:219], v[218:219], 0, s[10:11]
	s_mov_b32 m0, s34
	ds_read_b128 v[186:189], v155 offset:49152
	ds_read_b128 v[190:193], v155 offset:50176
	ds_read_b128 v[194:197], v155 offset:51200
	ds_read_b128 v[198:201], v155 offset:52224
	ds_read_b128 v[202:205], v155 offset:53248
	ds_read_b128 v[206:209], v155 offset:54272
	ds_read_b128 v[210:213], v155 offset:55296
	ds_read_b128 v[214:217], v155 offset:56320
	global_load_lds_dwordx4 v[218:219], off
	s_add_i32 m0, s34, 0x2000
	s_add_u32 s34, s42, 0x40080
	v_lshl_add_u64 v[218:219], v[220:221], 0, s[10:11]
	s_addc_u32 s35, s43, 0
	s_add_i32 s42, s64, s47
	global_load_lds_dwordx4 v[218:219], off
	v_lshl_add_u64 v[218:219], s[34:35], 0, v[132:133]
	s_mov_b32 m0, s42
	s_nop 0
	global_load_lds_dwordx4 v[218:219], off
	v_lshl_add_u64 v[218:219], s[34:35], 0, v[136:137]
	s_add_i32 m0, s42, 0x2000
	s_nop 0
	global_load_lds_dwordx4 v[218:219], off
	v_lshl_add_u64 v[218:219], v[222:223], 0, s[10:11]
	s_mov_b32 m0, s53
	s_nop 0
	global_load_lds_dwordx4 v[218:219], off
	v_lshl_add_u64 v[218:219], v[224:225], 0, s[10:11]
	s_mov_b32 m0, s54
	s_nop 0
	global_load_lds_dwordx4 v[218:219], off
	s_waitcnt vmcnt(8)
	s_waitcnt lgkmcnt(0)
	s_barrier
	s_add_u32 s40, s40, 0x100
	s_addc_u32 s41, s41, 0
	s_add_u32 s39, s39, 0x100
	s_addc_u32 s61, s61, 0
	s_setprio 1
	s_waitcnt lgkmcnt(0)
	v_mfma_f32_16x16x32_bf16 v[60:63], v[146:149], v[186:189], v[60:63]
	v_mfma_f32_16x16x32_bf16 v[56:59], v[162:165], v[186:189], v[56:59]
	v_mfma_f32_16x16x32_bf16 v[44:47], v[146:149], v[194:197], v[44:47]
	v_mfma_f32_16x16x32_bf16 v[40:43], v[162:165], v[194:197], v[40:43]
	v_mfma_f32_16x16x32_bf16 v[28:31], v[146:149], v[202:205], v[28:31]
	v_mfma_f32_16x16x32_bf16 v[24:27], v[162:165], v[202:205], v[24:27]
	v_mfma_f32_16x16x32_bf16 v[12:15], v[146:149], v[210:213], v[12:15]
	v_mfma_f32_16x16x32_bf16 v[8:11], v[162:165], v[210:213], v[8:11]
	v_mfma_f32_16x16x32_bf16 v[60:63], v[158:161], v[190:193], v[60:63]
	v_mfma_f32_16x16x32_bf16 v[56:59], v[166:169], v[190:193], v[56:59]
	v_mfma_f32_16x16x32_bf16 v[44:47], v[158:161], v[198:201], v[44:47]
	v_mfma_f32_16x16x32_bf16 v[40:43], v[166:169], v[198:201], v[40:43]
	v_mfma_f32_16x16x32_bf16 v[28:31], v[158:161], v[206:209], v[28:31]
	v_mfma_f32_16x16x32_bf16 v[24:27], v[166:169], v[206:209], v[24:27]
	v_mfma_f32_16x16x32_bf16 v[12:15], v[158:161], v[214:217], v[12:15]
	v_mfma_f32_16x16x32_bf16 v[8:11], v[166:169], v[214:217], v[8:11]
	s_setprio 0
	s_setprio 1
	v_mfma_f32_16x16x32_bf16 v[52:55], v[170:173], v[186:189], v[52:55]
	v_mfma_f32_16x16x32_bf16 v[48:51], v[178:181], v[186:189], v[48:51]
	v_mfma_f32_16x16x32_bf16 v[36:39], v[170:173], v[194:197], v[36:39]
	v_mfma_f32_16x16x32_bf16 v[32:35], v[178:181], v[194:197], v[32:35]
	v_mfma_f32_16x16x32_bf16 v[20:23], v[170:173], v[202:205], v[20:23]
	v_mfma_f32_16x16x32_bf16 v[16:19], v[178:181], v[202:205], v[16:19]
	v_mfma_f32_16x16x32_bf16 v[4:7], v[170:173], v[210:213], v[4:7]
	v_mfma_f32_16x16x32_bf16 v[0:3], v[178:181], v[210:213], v[0:3]
	v_mfma_f32_16x16x32_bf16 v[52:55], v[174:177], v[190:193], v[52:55]
	v_mfma_f32_16x16x32_bf16 v[48:51], v[182:185], v[190:193], v[48:51]
	v_mfma_f32_16x16x32_bf16 v[36:39], v[174:177], v[198:201], v[36:39]
	v_mfma_f32_16x16x32_bf16 v[32:35], v[182:185], v[198:201], v[32:35]
	v_mfma_f32_16x16x32_bf16 v[20:23], v[174:177], v[206:209], v[20:23]
	v_mfma_f32_16x16x32_bf16 v[16:19], v[182:185], v[206:209], v[16:19]
	v_mfma_f32_16x16x32_bf16 v[4:7], v[174:177], v[214:217], v[4:7]
	v_mfma_f32_16x16x32_bf16 v[0:3], v[182:185], v[214:217], v[0:3]
	s_setprio 0
	s_add_i32 s62, s62, 2
.LBB0_1557:
	s_barrier
	ds_read_b128 v[146:149], v153
	ds_read_b128 v[158:161], v153 offset:1024
	ds_read_b128 v[162:165], v153 offset:2048
	ds_read_b128 v[166:169], v153 offset:3072
	ds_read_b128 v[170:173], v154
	ds_read_b128 v[174:177], v154 offset:1024
	ds_read_b128 v[178:181], v154 offset:2048
	ds_read_b128 v[182:185], v154 offset:3072
	s_add_u32 s34, s40, 0xfffc0080
	s_addc_u32 s35, s41, -1
	s_cmp_eq_u32 s62, 12
	s_cselect_b32 s45, s12, s35
	s_cselect_b32 s44, s13, s34
	s_cselect_b32 s43, s27, s61
	s_cselect_b32 s42, s29, s39
	v_lshl_add_u64 v[218:219], s[40:41], 0, v[138:139]
	s_add_i32 m0, s48, 0xc000
	ds_read_b128 v[186:189], v155
	ds_read_b128 v[190:193], v155 offset:1024
	ds_read_b128 v[194:197], v155 offset:2048
	ds_read_b128 v[198:201], v155 offset:3072
	ds_read_b128 v[202:205], v155 offset:4096
	ds_read_b128 v[206:209], v155 offset:5120
	ds_read_b128 v[210:213], v155 offset:6144
	ds_read_b128 v[214:217], v155 offset:7168
	global_load_lds_dwordx4 v[218:219], off
	v_lshl_add_u64 v[218:219], s[40:41], 0, v[140:141]
	s_add_i32 m0, s48, 0xe000
	s_nop 0
	global_load_lds_dwordx4 v[218:219], off
	s_waitcnt vmcnt(8)
	s_waitcnt lgkmcnt(0)
	s_barrier
	s_setprio 1
	s_waitcnt lgkmcnt(0)
	v_mfma_f32_16x16x32_bf16 v[124:127], v[146:149], v[186:189], v[124:127]
	v_mfma_f32_16x16x32_bf16 v[120:123], v[162:165], v[186:189], v[120:123]
	v_mfma_f32_16x16x32_bf16 v[108:111], v[146:149], v[194:197], v[108:111]
	v_mfma_f32_16x16x32_bf16 v[104:107], v[162:165], v[194:197], v[104:107]
	v_mfma_f32_16x16x32_bf16 v[92:95], v[146:149], v[202:205], v[92:95]
	v_mfma_f32_16x16x32_bf16 v[88:91], v[162:165], v[202:205], v[88:91]
	v_mfma_f32_16x16x32_bf16 v[76:79], v[146:149], v[210:213], v[76:79]
	v_mfma_f32_16x16x32_bf16 v[72:75], v[162:165], v[210:213], v[72:75]
	v_mfma_f32_16x16x32_bf16 v[124:127], v[158:161], v[190:193], v[124:127]
	v_mfma_f32_16x16x32_bf16 v[120:123], v[166:169], v[190:193], v[120:123]
	v_mfma_f32_16x16x32_bf16 v[108:111], v[158:161], v[198:201], v[108:111]
	v_mfma_f32_16x16x32_bf16 v[104:107], v[166:169], v[198:201], v[104:107]
	v_mfma_f32_16x16x32_bf16 v[92:95], v[158:161], v[206:209], v[92:95]
	v_mfma_f32_16x16x32_bf16 v[88:91], v[166:169], v[206:209], v[88:91]
	v_mfma_f32_16x16x32_bf16 v[76:79], v[158:161], v[214:217], v[76:79]
	v_mfma_f32_16x16x32_bf16 v[72:75], v[166:169], v[214:217], v[72:75]
	s_setprio 0
	s_setprio 1
	v_mfma_f32_16x16x32_bf16 v[116:119], v[170:173], v[186:189], v[116:119]
	v_mfma_f32_16x16x32_bf16 v[112:115], v[178:181], v[186:189], v[112:115]
	v_mfma_f32_16x16x32_bf16 v[100:103], v[170:173], v[194:197], v[100:103]
	v_mfma_f32_16x16x32_bf16 v[96:99], v[178:181], v[194:197], v[96:99]
	v_mfma_f32_16x16x32_bf16 v[84:87], v[170:173], v[202:205], v[84:87]
	v_mfma_f32_16x16x32_bf16 v[80:83], v[178:181], v[202:205], v[80:83]
	v_mfma_f32_16x16x32_bf16 v[68:71], v[170:173], v[210:213], v[68:71]
	v_mfma_f32_16x16x32_bf16 v[64:67], v[178:181], v[210:213], v[64:67]
	v_mfma_f32_16x16x32_bf16 v[116:119], v[174:177], v[190:193], v[116:119]
	v_mfma_f32_16x16x32_bf16 v[112:115], v[182:185], v[190:193], v[112:115]
	v_mfma_f32_16x16x32_bf16 v[100:103], v[174:177], v[198:201], v[100:103]
	v_mfma_f32_16x16x32_bf16 v[96:99], v[182:185], v[198:201], v[96:99]
	v_mfma_f32_16x16x32_bf16 v[84:87], v[174:177], v[206:209], v[84:87]
	v_mfma_f32_16x16x32_bf16 v[80:83], v[182:185], v[206:209], v[80:83]
	v_mfma_f32_16x16x32_bf16 v[68:71], v[174:177], v[214:217], v[68:71]
	v_mfma_f32_16x16x32_bf16 v[64:67], v[182:185], v[214:217], v[64:67]
	s_setprio 0
	s_barrier
	s_add_i32 s34, s58, s47
	v_lshl_add_u64 v[218:219], s[42:43], 0, v[132:133]
	s_mov_b32 m0, s34
	ds_read_b128 v[186:189], v155 offset:16384
	ds_read_b128 v[190:193], v155 offset:17408
	ds_read_b128 v[194:197], v155 offset:18432
	ds_read_b128 v[198:201], v155 offset:19456
	ds_read_b128 v[202:205], v155 offset:20480
	ds_read_b128 v[206:209], v155 offset:21504
	ds_read_b128 v[210:213], v155 offset:22528
	ds_read_b128 v[214:217], v155 offset:23552
	global_load_lds_dwordx4 v[218:219], off
	s_add_i32 m0, s34, 0x2000
	s_add_u32 s34, s42, 0x40000
	v_lshl_add_u64 v[220:221], s[42:43], 0, v[136:137]
	s_addc_u32 s35, s43, 0
	s_add_i32 s63, s59, s47
	global_load_lds_dwordx4 v[220:221], off
	v_lshl_add_u64 v[222:223], s[34:35], 0, v[132:133]
	s_mov_b32 m0, s63
	v_lshl_add_u64 v[224:225], s[44:45], 0, v[134:135]
	global_load_lds_dwordx4 v[222:223], off
	v_lshl_add_u64 v[222:223], s[34:35], 0, v[136:137]
	s_add_i32 m0, s63, 0x2000
	s_nop 0
	global_load_lds_dwordx4 v[222:223], off
	v_lshl_add_u64 v[222:223], s[44:45], 0, v[130:131]
	s_mov_b32 m0, s48
	s_nop 0
	global_load_lds_dwordx4 v[222:223], off
	s_mov_b32 m0, s49
	s_nop 0
	global_load_lds_dwordx4 v[224:225], off
	s_waitcnt vmcnt(8)
	s_waitcnt lgkmcnt(0)
	s_barrier
	s_setprio 1
	s_waitcnt lgkmcnt(0)
	v_mfma_f32_16x16x32_bf16 v[60:63], v[146:149], v[186:189], v[60:63]
	v_mfma_f32_16x16x32_bf16 v[56:59], v[162:165], v[186:189], v[56:59]
	v_mfma_f32_16x16x32_bf16 v[44:47], v[146:149], v[194:197], v[44:47]
	v_mfma_f32_16x16x32_bf16 v[40:43], v[162:165], v[194:197], v[40:43]
	v_mfma_f32_16x16x32_bf16 v[28:31], v[146:149], v[202:205], v[28:31]
	v_mfma_f32_16x16x32_bf16 v[24:27], v[162:165], v[202:205], v[24:27]
	v_mfma_f32_16x16x32_bf16 v[12:15], v[146:149], v[210:213], v[12:15]
	v_mfma_f32_16x16x32_bf16 v[8:11], v[162:165], v[210:213], v[8:11]
	v_mfma_f32_16x16x32_bf16 v[60:63], v[158:161], v[190:193], v[60:63]
	v_mfma_f32_16x16x32_bf16 v[56:59], v[166:169], v[190:193], v[56:59]
	v_mfma_f32_16x16x32_bf16 v[44:47], v[158:161], v[198:201], v[44:47]
	v_mfma_f32_16x16x32_bf16 v[40:43], v[166:169], v[198:201], v[40:43]
	v_mfma_f32_16x16x32_bf16 v[28:31], v[158:161], v[206:209], v[28:31]
	v_mfma_f32_16x16x32_bf16 v[24:27], v[166:169], v[206:209], v[24:27]
	v_mfma_f32_16x16x32_bf16 v[12:15], v[158:161], v[214:217], v[12:15]
	v_mfma_f32_16x16x32_bf16 v[8:11], v[166:169], v[214:217], v[8:11]
	s_setprio 0
	s_setprio 1
	v_mfma_f32_16x16x32_bf16 v[52:55], v[170:173], v[186:189], v[52:55]
	v_mfma_f32_16x16x32_bf16 v[48:51], v[178:181], v[186:189], v[48:51]
	v_mfma_f32_16x16x32_bf16 v[36:39], v[170:173], v[194:197], v[36:39]
	v_mfma_f32_16x16x32_bf16 v[32:35], v[178:181], v[194:197], v[32:35]
	v_mfma_f32_16x16x32_bf16 v[20:23], v[170:173], v[202:205], v[20:23]
	v_mfma_f32_16x16x32_bf16 v[16:19], v[178:181], v[202:205], v[16:19]
	v_mfma_f32_16x16x32_bf16 v[4:7], v[170:173], v[210:213], v[4:7]
	v_mfma_f32_16x16x32_bf16 v[0:3], v[178:181], v[210:213], v[0:3]
	v_mfma_f32_16x16x32_bf16 v[52:55], v[174:177], v[190:193], v[52:55]
	v_mfma_f32_16x16x32_bf16 v[48:51], v[182:185], v[190:193], v[48:51]
	v_mfma_f32_16x16x32_bf16 v[36:39], v[174:177], v[198:201], v[36:39]
	v_mfma_f32_16x16x32_bf16 v[32:35], v[182:185], v[198:201], v[32:35]
	v_mfma_f32_16x16x32_bf16 v[20:23], v[174:177], v[206:209], v[20:23]
	v_mfma_f32_16x16x32_bf16 v[16:19], v[182:185], v[206:209], v[16:19]
	v_mfma_f32_16x16x32_bf16 v[4:7], v[174:177], v[214:217], v[4:7]
	v_mfma_f32_16x16x32_bf16 v[0:3], v[182:185], v[214:217], v[0:3]
	s_setprio 0
	s_barrier
	s_add_i32 s63, 0, 0x18000
	s_add_i32 s64, 0, 0x1c000
	v_add_u32_e32 v166, s63, v151
	v_add_u32_e32 v182, s64, v151
	ds_read_b128 v[146:149], v166
	ds_read_b128 v[158:161], v166 offset:1024
	ds_read_b128 v[162:165], v166 offset:2048
	ds_read_b128 v[166:169], v166 offset:3072
	ds_read_b128 v[170:173], v182
	ds_read_b128 v[174:177], v182 offset:1024
	ds_read_b128 v[178:181], v182 offset:2048
	ds_read_b128 v[182:185], v182 offset:3072
	s_add_u32 s34, s44, 0x40000
	s_addc_u32 s35, s45, 0
	s_mov_b32 m0, s50
	v_lshl_add_u64 v[226:227], s[34:35], 0, v[130:131]
	ds_read_b128 v[186:189], v155 offset:32768
	ds_read_b128 v[190:193], v155 offset:33792
	ds_read_b128 v[194:197], v155 offset:34816
	ds_read_b128 v[198:201], v155 offset:35840
	ds_read_b128 v[202:205], v155 offset:36864
	ds_read_b128 v[206:209], v155 offset:37888
	ds_read_b128 v[210:213], v155 offset:38912
	ds_read_b128 v[214:217], v155 offset:39936
	global_load_lds_dwordx4 v[226:227], off
	v_lshl_add_u64 v[226:227], s[34:35], 0, v[134:135]
	s_mov_b32 m0, s51
	s_nop 0
	global_load_lds_dwordx4 v[226:227], off
	s_waitcnt vmcnt(8)
	s_waitcnt lgkmcnt(0)
	s_barrier
	s_setprio 1
	s_waitcnt lgkmcnt(0)
	v_mfma_f32_16x16x32_bf16 v[124:127], v[146:149], v[186:189], v[124:127]
	v_mfma_f32_16x16x32_bf16 v[120:123], v[162:165], v[186:189], v[120:123]
	v_mfma_f32_16x16x32_bf16 v[108:111], v[146:149], v[194:197], v[108:111]
	v_mfma_f32_16x16x32_bf16 v[104:107], v[162:165], v[194:197], v[104:107]
	v_mfma_f32_16x16x32_bf16 v[92:95], v[146:149], v[202:205], v[92:95]
	v_mfma_f32_16x16x32_bf16 v[88:91], v[162:165], v[202:205], v[88:91]
	v_mfma_f32_16x16x32_bf16 v[76:79], v[146:149], v[210:213], v[76:79]
	v_mfma_f32_16x16x32_bf16 v[72:75], v[162:165], v[210:213], v[72:75]
	v_mfma_f32_16x16x32_bf16 v[124:127], v[158:161], v[190:193], v[124:127]
	v_mfma_f32_16x16x32_bf16 v[120:123], v[166:169], v[190:193], v[120:123]
	v_mfma_f32_16x16x32_bf16 v[108:111], v[158:161], v[198:201], v[108:111]
	v_mfma_f32_16x16x32_bf16 v[104:107], v[166:169], v[198:201], v[104:107]
	v_mfma_f32_16x16x32_bf16 v[92:95], v[158:161], v[206:209], v[92:95]
	v_mfma_f32_16x16x32_bf16 v[88:91], v[166:169], v[206:209], v[88:91]
	v_mfma_f32_16x16x32_bf16 v[76:79], v[158:161], v[214:217], v[76:79]
	v_mfma_f32_16x16x32_bf16 v[72:75], v[166:169], v[214:217], v[72:75]
	s_setprio 0
	s_setprio 1
	v_mfma_f32_16x16x32_bf16 v[116:119], v[170:173], v[186:189], v[116:119]
	v_mfma_f32_16x16x32_bf16 v[112:115], v[178:181], v[186:189], v[112:115]
	v_mfma_f32_16x16x32_bf16 v[100:103], v[170:173], v[194:197], v[100:103]
	v_mfma_f32_16x16x32_bf16 v[96:99], v[178:181], v[194:197], v[96:99]
	v_mfma_f32_16x16x32_bf16 v[84:87], v[170:173], v[202:205], v[84:87]
	v_mfma_f32_16x16x32_bf16 v[80:83], v[178:181], v[202:205], v[80:83]
	v_mfma_f32_16x16x32_bf16 v[68:71], v[170:173], v[210:213], v[68:71]
	v_mfma_f32_16x16x32_bf16 v[64:67], v[178:181], v[210:213], v[64:67]
	v_mfma_f32_16x16x32_bf16 v[116:119], v[174:177], v[190:193], v[116:119]
	v_mfma_f32_16x16x32_bf16 v[112:115], v[182:185], v[190:193], v[112:115]
	v_mfma_f32_16x16x32_bf16 v[100:103], v[174:177], v[198:201], v[100:103]
	v_mfma_f32_16x16x32_bf16 v[96:99], v[182:185], v[198:201], v[96:99]
	v_mfma_f32_16x16x32_bf16 v[84:87], v[174:177], v[206:209], v[84:87]
	v_mfma_f32_16x16x32_bf16 v[80:83], v[182:185], v[206:209], v[80:83]
	v_mfma_f32_16x16x32_bf16 v[68:71], v[174:177], v[214:217], v[68:71]
	v_mfma_f32_16x16x32_bf16 v[64:67], v[182:185], v[214:217], v[64:67]
	s_setprio 0
	s_barrier
	s_add_i32 s34, s63, s47
	v_lshl_add_u64 v[218:219], v[218:219], 0, s[10:11]
	s_mov_b32 m0, s34
	ds_read_b128 v[186:189], v155 offset:49152
	ds_read_b128 v[190:193], v155 offset:50176
	ds_read_b128 v[194:197], v155 offset:51200
	ds_read_b128 v[198:201], v155 offset:52224
	ds_read_b128 v[202:205], v155 offset:53248
	ds_read_b128 v[206:209], v155 offset:54272
	ds_read_b128 v[210:213], v155 offset:55296
	ds_read_b128 v[214:217], v155 offset:56320
	global_load_lds_dwordx4 v[218:219], off
	s_add_i32 m0, s34, 0x2000
	s_add_u32 s34, s42, 0x40080
	v_lshl_add_u64 v[218:219], v[220:221], 0, s[10:11]
	s_addc_u32 s35, s43, 0
	s_add_i32 s42, s64, s47
	global_load_lds_dwordx4 v[218:219], off
	v_lshl_add_u64 v[218:219], s[34:35], 0, v[132:133]
	s_mov_b32 m0, s42
	s_nop 0
	global_load_lds_dwordx4 v[218:219], off
	v_lshl_add_u64 v[218:219], s[34:35], 0, v[136:137]
	s_add_i32 m0, s42, 0x2000
	s_nop 0
	global_load_lds_dwordx4 v[218:219], off
	v_lshl_add_u64 v[218:219], v[222:223], 0, s[10:11]
	s_mov_b32 m0, s53
	s_nop 0
	global_load_lds_dwordx4 v[218:219], off
	v_lshl_add_u64 v[218:219], v[224:225], 0, s[10:11]
	s_mov_b32 m0, s54
	s_nop 0
	global_load_lds_dwordx4 v[218:219], off
	s_waitcnt vmcnt(8)
	s_waitcnt lgkmcnt(0)
	s_barrier
	s_add_u32 s40, s40, 0x100
	s_addc_u32 s41, s41, 0
	s_add_u32 s39, s39, 0x100
	s_addc_u32 s61, s61, 0
	s_setprio 1
	s_waitcnt lgkmcnt(0)
	v_mfma_f32_16x16x32_bf16 v[60:63], v[146:149], v[186:189], v[60:63]
	v_mfma_f32_16x16x32_bf16 v[56:59], v[162:165], v[186:189], v[56:59]
	v_mfma_f32_16x16x32_bf16 v[44:47], v[146:149], v[194:197], v[44:47]
	v_mfma_f32_16x16x32_bf16 v[40:43], v[162:165], v[194:197], v[40:43]
	v_mfma_f32_16x16x32_bf16 v[28:31], v[146:149], v[202:205], v[28:31]
	v_mfma_f32_16x16x32_bf16 v[24:27], v[162:165], v[202:205], v[24:27]
	v_mfma_f32_16x16x32_bf16 v[12:15], v[146:149], v[210:213], v[12:15]
	v_mfma_f32_16x16x32_bf16 v[8:11], v[162:165], v[210:213], v[8:11]
	v_mfma_f32_16x16x32_bf16 v[60:63], v[158:161], v[190:193], v[60:63]
	v_mfma_f32_16x16x32_bf16 v[56:59], v[166:169], v[190:193], v[56:59]
	v_mfma_f32_16x16x32_bf16 v[44:47], v[158:161], v[198:201], v[44:47]
	v_mfma_f32_16x16x32_bf16 v[40:43], v[166:169], v[198:201], v[40:43]
	v_mfma_f32_16x16x32_bf16 v[28:31], v[158:161], v[206:209], v[28:31]
	v_mfma_f32_16x16x32_bf16 v[24:27], v[166:169], v[206:209], v[24:27]
	v_mfma_f32_16x16x32_bf16 v[12:15], v[158:161], v[214:217], v[12:15]
	v_mfma_f32_16x16x32_bf16 v[8:11], v[166:169], v[214:217], v[8:11]
	s_setprio 0
	s_setprio 1
	v_mfma_f32_16x16x32_bf16 v[52:55], v[170:173], v[186:189], v[52:55]
	v_mfma_f32_16x16x32_bf16 v[48:51], v[178:181], v[186:189], v[48:51]
	v_mfma_f32_16x16x32_bf16 v[36:39], v[170:173], v[194:197], v[36:39]
	v_mfma_f32_16x16x32_bf16 v[32:35], v[178:181], v[194:197], v[32:35]
	v_mfma_f32_16x16x32_bf16 v[20:23], v[170:173], v[202:205], v[20:23]
	v_mfma_f32_16x16x32_bf16 v[16:19], v[178:181], v[202:205], v[16:19]
	v_mfma_f32_16x16x32_bf16 v[4:7], v[170:173], v[210:213], v[4:7]
	v_mfma_f32_16x16x32_bf16 v[0:3], v[178:181], v[210:213], v[0:3]
	v_mfma_f32_16x16x32_bf16 v[52:55], v[174:177], v[190:193], v[52:55]
	v_mfma_f32_16x16x32_bf16 v[48:51], v[182:185], v[190:193], v[48:51]
	v_mfma_f32_16x16x32_bf16 v[36:39], v[174:177], v[198:201], v[36:39]
	v_mfma_f32_16x16x32_bf16 v[32:35], v[182:185], v[198:201], v[32:35]
	v_mfma_f32_16x16x32_bf16 v[20:23], v[174:177], v[206:209], v[20:23]
	v_mfma_f32_16x16x32_bf16 v[16:19], v[182:185], v[206:209], v[16:19]
	v_mfma_f32_16x16x32_bf16 v[4:7], v[174:177], v[214:217], v[4:7]
	v_mfma_f32_16x16x32_bf16 v[0:3], v[182:185], v[214:217], v[0:3]
	s_setprio 0
	s_add_i32 s62, s62, 2
	s_cmp_gt_u32 s62, 13
	s_cbranch_scc0 .LBB0_1557
	s_sub_i32 s100, s62, 2
	s_cmp_eq_u32 s100, s98
	s_cbranch_scc1 .Lmy_nobar_16
	s_barrier

.Lmy_nobar2_17:
	ds_read_b128 v[146:149], v154
	ds_read_b128 v[158:161], v154 offset:1024
	ds_read_b128 v[162:165], v154 offset:2048
	ds_read_b128 v[166:169], v154 offset:3072
	ds_read_b128 v[170:173], v155
	ds_read_b128 v[174:177], v155 offset:1024
	ds_read_b128 v[178:181], v155 offset:2048
	ds_read_b128 v[182:185], v155 offset:3072
	s_add_u32 s34, s36, 0xfffc0080
	s_addc_u32 s35, s37, -1
	s_cmp_eq_u32 s62, 12
	s_cselect_b32 s41, s23, s35
	s_cselect_b32 s40, s58, s34
	s_cselect_b32 s39, s11, s61
	s_cselect_b32 s38, s59, s60
	v_lshl_add_u64 v[218:219], s[36:37], 0, v[138:139]
	s_add_i32 m0, s31, 0xc000
	ds_read_b128 v[186:189], v157
	ds_read_b128 v[190:193], v157 offset:1024
	ds_read_b128 v[194:197], v157 offset:2048
	ds_read_b128 v[198:201], v157 offset:3072
	ds_read_b128 v[202:205], v157 offset:4096
	ds_read_b128 v[206:209], v157 offset:5120
	ds_read_b128 v[210:213], v157 offset:6144
	ds_read_b128 v[214:217], v157 offset:7168
	global_load_lds_dwordx4 v[218:219], off
	v_lshl_add_u64 v[218:219], s[36:37], 0, v[140:141]
	s_add_i32 m0, s31, 0xe000
	s_nop 0
	global_load_lds_dwordx4 v[218:219], off
	s_waitcnt vmcnt(8)
	s_waitcnt lgkmcnt(0)
	s_barrier
	s_setprio 1
	s_waitcnt lgkmcnt(0)
	v_mfma_f32_16x16x32_bf16 v[124:127], v[146:149], v[186:189], 0
	v_mfma_f32_16x16x32_bf16 v[120:123], v[162:165], v[186:189], 0
	v_mfma_f32_16x16x32_bf16 v[108:111], v[146:149], v[194:197], 0
	v_mfma_f32_16x16x32_bf16 v[104:107], v[162:165], v[194:197], 0
	v_mfma_f32_16x16x32_bf16 v[92:95], v[146:149], v[202:205], 0
	v_mfma_f32_16x16x32_bf16 v[88:91], v[162:165], v[202:205], 0
	v_mfma_f32_16x16x32_bf16 v[76:79], v[146:149], v[210:213], 0
	v_mfma_f32_16x16x32_bf16 v[72:75], v[162:165], v[210:213], 0
	v_mfma_f32_16x16x32_bf16 v[124:127], v[158:161], v[190:193], v[124:127]
	v_mfma_f32_16x16x32_bf16 v[120:123], v[166:169], v[190:193], v[120:123]
	v_mfma_f32_16x16x32_bf16 v[108:111], v[158:161], v[198:201], v[108:111]
	v_mfma_f32_16x16x32_bf16 v[104:107], v[166:169], v[198:201], v[104:107]
	v_mfma_f32_16x16x32_bf16 v[92:95], v[158:161], v[206:209], v[92:95]
	v_mfma_f32_16x16x32_bf16 v[88:91], v[166:169], v[206:209], v[88:91]
	v_mfma_f32_16x16x32_bf16 v[76:79], v[158:161], v[214:217], v[76:79]
	v_mfma_f32_16x16x32_bf16 v[72:75], v[166:169], v[214:217], v[72:75]
	s_setprio 0
	s_setprio 1
	v_mfma_f32_16x16x32_bf16 v[116:119], v[170:173], v[186:189], 0
	v_mfma_f32_16x16x32_bf16 v[112:115], v[178:181], v[186:189], 0
	v_mfma_f32_16x16x32_bf16 v[100:103], v[170:173], v[194:197], 0
	v_mfma_f32_16x16x32_bf16 v[96:99], v[178:181], v[194:197], 0
	v_mfma_f32_16x16x32_bf16 v[84:87], v[170:173], v[202:205], 0
	v_mfma_f32_16x16x32_bf16 v[80:83], v[178:181], v[202:205], 0
	v_mfma_f32_16x16x32_bf16 v[68:71], v[170:173], v[210:213], 0
	v_mfma_f32_16x16x32_bf16 v[64:67], v[178:181], v[210:213], 0
	v_mfma_f32_16x16x32_bf16 v[116:119], v[174:177], v[190:193], v[116:119]
	v_mfma_f32_16x16x32_bf16 v[112:115], v[182:185], v[190:193], v[112:115]
	v_mfma_f32_16x16x32_bf16 v[100:103], v[174:177], v[198:201], v[100:103]
	v_mfma_f32_16x16x32_bf16 v[96:99], v[182:185], v[198:201], v[96:99]
	v_mfma_f32_16x16x32_bf16 v[84:87], v[174:177], v[206:209], v[84:87]
	v_mfma_f32_16x16x32_bf16 v[80:83], v[182:185], v[206:209], v[80:83]
	v_mfma_f32_16x16x32_bf16 v[68:71], v[174:177], v[214:217], v[68:71]
	v_mfma_f32_16x16x32_bf16 v[64:67], v[182:185], v[214:217], v[64:67]
	s_setprio 0
	s_barrier
	s_add_i32 s34, s53, s44
	v_lshl_add_u64 v[218:219], s[38:39], 0, v[134:135]
	s_mov_b32 m0, s34
	ds_read_b128 v[186:189], v157 offset:16384
	ds_read_b128 v[190:193], v157 offset:17408
	ds_read_b128 v[194:197], v157 offset:18432
	ds_read_b128 v[198:201], v157 offset:19456
	ds_read_b128 v[202:205], v157 offset:20480
	ds_read_b128 v[206:209], v157 offset:21504
	ds_read_b128 v[210:213], v157 offset:22528
	ds_read_b128 v[214:217], v157 offset:23552
	global_load_lds_dwordx4 v[218:219], off
	s_add_i32 m0, s34, 0x2000
	s_add_u32 s34, s38, 0x40000
	v_lshl_add_u64 v[220:221], s[38:39], 0, v[130:131]
	s_addc_u32 s35, s39, 0
	s_add_i32 s63, s54, s44
	global_load_lds_dwordx4 v[220:221], off
	v_lshl_add_u64 v[222:223], s[34:35], 0, v[134:135]
	s_mov_b32 m0, s63
	v_lshl_add_u64 v[224:225], s[40:41], 0, v[132:133]
	global_load_lds_dwordx4 v[222:223], off
	v_lshl_add_u64 v[222:223], s[34:35], 0, v[130:131]
	s_add_i32 m0, s63, 0x2000
	s_nop 0
	global_load_lds_dwordx4 v[222:223], off
	v_lshl_add_u64 v[222:223], s[40:41], 0, v[136:137]
	s_mov_b32 m0, s31
	s_nop 0
	global_load_lds_dwordx4 v[222:223], off
	s_mov_b32 m0, s48
	s_nop 0
	global_load_lds_dwordx4 v[224:225], off
	s_waitcnt vmcnt(8)
	s_waitcnt lgkmcnt(0)
	s_barrier
	s_setprio 1
	s_waitcnt lgkmcnt(0)
	v_mfma_f32_16x16x32_bf16 v[60:63], v[146:149], v[186:189], 0
	v_mfma_f32_16x16x32_bf16 v[56:59], v[162:165], v[186:189], 0
	v_mfma_f32_16x16x32_bf16 v[44:47], v[146:149], v[194:197], 0
	v_mfma_f32_16x16x32_bf16 v[40:43], v[162:165], v[194:197], 0
	v_mfma_f32_16x16x32_bf16 v[28:31], v[146:149], v[202:205], 0
	v_mfma_f32_16x16x32_bf16 v[24:27], v[162:165], v[202:205], 0
	v_mfma_f32_16x16x32_bf16 v[12:15], v[146:149], v[210:213], 0
	v_mfma_f32_16x16x32_bf16 v[8:11], v[162:165], v[210:213], 0
	v_mfma_f32_16x16x32_bf16 v[60:63], v[158:161], v[190:193], v[60:63]
	v_mfma_f32_16x16x32_bf16 v[56:59], v[166:169], v[190:193], v[56:59]
	v_mfma_f32_16x16x32_bf16 v[44:47], v[158:161], v[198:201], v[44:47]
	v_mfma_f32_16x16x32_bf16 v[40:43], v[166:169], v[198:201], v[40:43]
	v_mfma_f32_16x16x32_bf16 v[28:31], v[158:161], v[206:209], v[28:31]
	v_mfma_f32_16x16x32_bf16 v[24:27], v[166:169], v[206:209], v[24:27]
	v_mfma_f32_16x16x32_bf16 v[12:15], v[158:161], v[214:217], v[12:15]
	v_mfma_f32_16x16x32_bf16 v[8:11], v[166:169], v[214:217], v[8:11]
	s_setprio 0
	s_setprio 1
	v_mfma_f32_16x16x32_bf16 v[52:55], v[170:173], v[186:189], 0
	v_mfma_f32_16x16x32_bf16 v[48:51], v[178:181], v[186:189], 0
	v_mfma_f32_16x16x32_bf16 v[36:39], v[170:173], v[194:197], 0
	v_mfma_f32_16x16x32_bf16 v[32:35], v[178:181], v[194:197], 0
	v_mfma_f32_16x16x32_bf16 v[20:23], v[170:173], v[202:205], 0
	v_mfma_f32_16x16x32_bf16 v[16:19], v[178:181], v[202:205], 0
	v_mfma_f32_16x16x32_bf16 v[4:7], v[170:173], v[210:213], 0
	v_mfma_f32_16x16x32_bf16 v[0:3], v[178:181], v[210:213], 0
	v_mfma_f32_16x16x32_bf16 v[52:55], v[174:177], v[190:193], v[52:55]
	v_mfma_f32_16x16x32_bf16 v[48:51], v[182:185], v[190:193], v[48:51]
	v_mfma_f32_16x16x32_bf16 v[36:39], v[174:177], v[198:201], v[36:39]
	v_mfma_f32_16x16x32_bf16 v[32:35], v[182:185], v[198:201], v[32:35]
	v_mfma_f32_16x16x32_bf16 v[20:23], v[174:177], v[206:209], v[20:23]
	v_mfma_f32_16x16x32_bf16 v[16:19], v[182:185], v[206:209], v[16:19]
	v_mfma_f32_16x16x32_bf16 v[4:7], v[174:177], v[214:217], v[4:7]
	v_mfma_f32_16x16x32_bf16 v[0:3], v[182:185], v[214:217], v[0:3]
	s_setprio 0
	s_barrier
	s_add_i32 s63, 0, 0x18000
	s_add_i32 s64, 0, 0x1c000
	v_add_u32_e32 v166, s63, v151
	v_add_u32_e32 v182, s64, v151
	ds_read_b128 v[146:149], v166
	ds_read_b128 v[158:161], v166 offset:1024
	ds_read_b128 v[162:165], v166 offset:2048
	ds_read_b128 v[166:169], v166 offset:3072
	ds_read_b128 v[170:173], v182
	ds_read_b128 v[174:177], v182 offset:1024
	ds_read_b128 v[178:181], v182 offset:2048
	ds_read_b128 v[182:185], v182 offset:3072
	s_add_u32 s34, s40, 0x40000
	s_addc_u32 s35, s41, 0
	s_mov_b32 m0, s49
	v_lshl_add_u64 v[226:227], s[34:35], 0, v[136:137]
	ds_read_b128 v[186:189], v157 offset:32768
	ds_read_b128 v[190:193], v157 offset:33792
	ds_read_b128 v[194:197], v157 offset:34816
	ds_read_b128 v[198:201], v157 offset:35840
	ds_read_b128 v[202:205], v157 offset:36864
	ds_read_b128 v[206:209], v157 offset:37888
	ds_read_b128 v[210:213], v157 offset:38912
	ds_read_b128 v[214:217], v157 offset:39936
	global_load_lds_dwordx4 v[226:227], off
	v_lshl_add_u64 v[226:227], s[34:35], 0, v[132:133]
	s_mov_b32 m0, s50
	s_nop 0
	global_load_lds_dwordx4 v[226:227], off
	s_waitcnt vmcnt(8)
	s_waitcnt lgkmcnt(0)
	s_barrier
	s_setprio 1
	s_waitcnt lgkmcnt(0)
	v_mfma_f32_16x16x32_bf16 v[124:127], v[146:149], v[186:189], v[124:127]
	v_mfma_f32_16x16x32_bf16 v[120:123], v[162:165], v[186:189], v[120:123]
	v_mfma_f32_16x16x32_bf16 v[108:111], v[146:149], v[194:197], v[108:111]
	v_mfma_f32_16x16x32_bf16 v[104:107], v[162:165], v[194:197], v[104:107]
	v_mfma_f32_16x16x32_bf16 v[92:95], v[146:149], v[202:205], v[92:95]
	v_mfma_f32_16x16x32_bf16 v[88:91], v[162:165], v[202:205], v[88:91]
	v_mfma_f32_16x16x32_bf16 v[76:79], v[146:149], v[210:213], v[76:79]
	v_mfma_f32_16x16x32_bf16 v[72:75], v[162:165], v[210:213], v[72:75]
	v_mfma_f32_16x16x32_bf16 v[124:127], v[158:161], v[190:193], v[124:127]
	v_mfma_f32_16x16x32_bf16 v[120:123], v[166:169], v[190:193], v[120:123]
	v_mfma_f32_16x16x32_bf16 v[108:111], v[158:161], v[198:201], v[108:111]
	v_mfma_f32_16x16x32_bf16 v[104:107], v[166:169], v[198:201], v[104:107]
	v_mfma_f32_16x16x32_bf16 v[92:95], v[158:161], v[206:209], v[92:95]
	v_mfma_f32_16x16x32_bf16 v[88:91], v[166:169], v[206:209], v[88:91]
	v_mfma_f32_16x16x32_bf16 v[76:79], v[158:161], v[214:217], v[76:79]
	v_mfma_f32_16x16x32_bf16 v[72:75], v[166:169], v[214:217], v[72:75]
	s_setprio 0
	s_setprio 1
	v_mfma_f32_16x16x32_bf16 v[116:119], v[170:173], v[186:189], v[116:119]
	v_mfma_f32_16x16x32_bf16 v[112:115], v[178:181], v[186:189], v[112:115]
	v_mfma_f32_16x16x32_bf16 v[100:103], v[170:173], v[194:197], v[100:103]
	v_mfma_f32_16x16x32_bf16 v[96:99], v[178:181], v[194:197], v[96:99]
	v_mfma_f32_16x16x32_bf16 v[84:87], v[170:173], v[202:205], v[84:87]
	v_mfma_f32_16x16x32_bf16 v[80:83], v[178:181], v[202:205], v[80:83]
	v_mfma_f32_16x16x32_bf16 v[68:71], v[170:173], v[210:213], v[68:71]
	v_mfma_f32_16x16x32_bf16 v[64:67], v[178:181], v[210:213], v[64:67]
	v_mfma_f32_16x16x32_bf16 v[116:119], v[174:177], v[190:193], v[116:119]
	v_mfma_f32_16x16x32_bf16 v[112:115], v[182:185], v[190:193], v[112:115]
	v_mfma_f32_16x16x32_bf16 v[100:103], v[174:177], v[198:201], v[100:103]
	v_mfma_f32_16x16x32_bf16 v[96:99], v[182:185], v[198:201], v[96:99]
	v_mfma_f32_16x16x32_bf16 v[84:87], v[174:177], v[206:209], v[84:87]
	v_mfma_f32_16x16x32_bf16 v[80:83], v[182:185], v[206:209], v[80:83]
	v_mfma_f32_16x16x32_bf16 v[68:71], v[174:177], v[214:217], v[68:71]
	v_mfma_f32_16x16x32_bf16 v[64:67], v[182:185], v[214:217], v[64:67]
	s_setprio 0
	s_barrier
	s_add_i32 s34, s63, s44
	v_lshl_add_u64 v[218:219], v[218:219], 0, s[6:7]
	s_mov_b32 m0, s34
	ds_read_b128 v[186:189], v157 offset:49152
	ds_read_b128 v[190:193], v157 offset:50176
	ds_read_b128 v[194:197], v157 offset:51200
	ds_read_b128 v[198:201], v157 offset:52224
	ds_read_b128 v[202:205], v157 offset:53248
	ds_read_b128 v[206:209], v157 offset:54272
	ds_read_b128 v[210:213], v157 offset:55296
	ds_read_b128 v[214:217], v157 offset:56320
	global_load_lds_dwordx4 v[218:219], off
	s_add_i32 m0, s34, 0x2000
	s_add_u32 s34, s38, 0x40080
	v_lshl_add_u64 v[218:219], v[220:221], 0, s[6:7]
	s_addc_u32 s35, s39, 0
	s_add_i32 s38, s64, s44
	global_load_lds_dwordx4 v[218:219], off
	v_lshl_add_u64 v[218:219], s[34:35], 0, v[134:135]
	s_mov_b32 m0, s38
	s_nop 0
	global_load_lds_dwordx4 v[218:219], off
	v_lshl_add_u64 v[218:219], s[34:35], 0, v[130:131]
	s_add_i32 m0, s38, 0x2000
	s_nop 0
	global_load_lds_dwordx4 v[218:219], off
	v_lshl_add_u64 v[218:219], v[222:223], 0, s[6:7]
	s_mov_b32 m0, s51
	s_nop 0
	global_load_lds_dwordx4 v[218:219], off
	v_lshl_add_u64 v[218:219], v[224:225], 0, s[6:7]
	s_mov_b32 m0, s52
	s_nop 0
	global_load_lds_dwordx4 v[218:219], off
	s_waitcnt vmcnt(8)
	s_waitcnt lgkmcnt(0)
	s_barrier
	s_add_u32 s36, s36, 0x100
	s_addc_u32 s37, s37, 0
	s_add_u32 s60, s60, 0x100
	s_addc_u32 s61, s61, 0
	s_setprio 1
	s_waitcnt lgkmcnt(0)
	v_mfma_f32_16x16x32_bf16 v[60:63], v[146:149], v[186:189], v[60:63]
	v_mfma_f32_16x16x32_bf16 v[56:59], v[162:165], v[186:189], v[56:59]
	v_mfma_f32_16x16x32_bf16 v[44:47], v[146:149], v[194:197], v[44:47]
	v_mfma_f32_16x16x32_bf16 v[40:43], v[162:165], v[194:197], v[40:43]
	v_mfma_f32_16x16x32_bf16 v[28:31], v[146:149], v[202:205], v[28:31]
	v_mfma_f32_16x16x32_bf16 v[24:27], v[162:165], v[202:205], v[24:27]
	v_mfma_f32_16x16x32_bf16 v[12:15], v[146:149], v[210:213], v[12:15]
	v_mfma_f32_16x16x32_bf16 v[8:11], v[162:165], v[210:213], v[8:11]
	v_mfma_f32_16x16x32_bf16 v[60:63], v[158:161], v[190:193], v[60:63]
	v_mfma_f32_16x16x32_bf16 v[56:59], v[166:169], v[190:193], v[56:59]
	v_mfma_f32_16x16x32_bf16 v[44:47], v[158:161], v[198:201], v[44:47]
	v_mfma_f32_16x16x32_bf16 v[40:43], v[166:169], v[198:201], v[40:43]
	v_mfma_f32_16x16x32_bf16 v[28:31], v[158:161], v[206:209], v[28:31]
	v_mfma_f32_16x16x32_bf16 v[24:27], v[166:169], v[206:209], v[24:27]
	v_mfma_f32_16x16x32_bf16 v[12:15], v[158:161], v[214:217], v[12:15]
	v_mfma_f32_16x16x32_bf16 v[8:11], v[166:169], v[214:217], v[8:11]
	s_setprio 0
	s_setprio 1
	v_mfma_f32_16x16x32_bf16 v[52:55], v[170:173], v[186:189], v[52:55]
	v_mfma_f32_16x16x32_bf16 v[48:51], v[178:181], v[186:189], v[48:51]
	v_mfma_f32_16x16x32_bf16 v[36:39], v[170:173], v[194:197], v[36:39]
	v_mfma_f32_16x16x32_bf16 v[32:35], v[178:181], v[194:197], v[32:35]
	v_mfma_f32_16x16x32_bf16 v[20:23], v[170:173], v[202:205], v[20:23]
	v_mfma_f32_16x16x32_bf16 v[16:19], v[178:181], v[202:205], v[16:19]
	v_mfma_f32_16x16x32_bf16 v[4:7], v[170:173], v[210:213], v[4:7]
	v_mfma_f32_16x16x32_bf16 v[0:3], v[178:181], v[210:213], v[0:3]
	v_mfma_f32_16x16x32_bf16 v[52:55], v[174:177], v[190:193], v[52:55]
	v_mfma_f32_16x16x32_bf16 v[48:51], v[182:185], v[190:193], v[48:51]
	v_mfma_f32_16x16x32_bf16 v[36:39], v[174:177], v[198:201], v[36:39]
	v_mfma_f32_16x16x32_bf16 v[32:35], v[182:185], v[198:201], v[32:35]
	v_mfma_f32_16x16x32_bf16 v[20:23], v[174:177], v[206:209], v[20:23]
	v_mfma_f32_16x16x32_bf16 v[16:19], v[182:185], v[206:209], v[16:19]
	v_mfma_f32_16x16x32_bf16 v[4:7], v[174:177], v[214:217], v[4:7]
	v_mfma_f32_16x16x32_bf16 v[0:3], v[182:185], v[214:217], v[0:3]
	s_setprio 0
	s_add_i32 s62, s62, 2
.LBB0_1647:
	s_barrier
	ds_read_b128 v[146:149], v154
	ds_read_b128 v[158:161], v154 offset:1024
	ds_read_b128 v[162:165], v154 offset:2048
	ds_read_b128 v[166:169], v154 offset:3072
	ds_read_b128 v[170:173], v155
	ds_read_b128 v[174:177], v155 offset:1024
	ds_read_b128 v[178:181], v155 offset:2048
	ds_read_b128 v[182:185], v155 offset:3072
	s_add_u32 s34, s36, 0xfffc0080
	s_addc_u32 s35, s37, -1
	s_cmp_eq_u32 s62, 12
	s_cselect_b32 s41, s23, s35
	s_cselect_b32 s40, s58, s34
	s_cselect_b32 s39, s11, s61
	s_cselect_b32 s38, s59, s60
	v_lshl_add_u64 v[218:219], s[36:37], 0, v[138:139]
	s_add_i32 m0, s31, 0xc000
	ds_read_b128 v[186:189], v157
	ds_read_b128 v[190:193], v157 offset:1024
	ds_read_b128 v[194:197], v157 offset:2048
	ds_read_b128 v[198:201], v157 offset:3072
	ds_read_b128 v[202:205], v157 offset:4096
	ds_read_b128 v[206:209], v157 offset:5120
	ds_read_b128 v[210:213], v157 offset:6144
	ds_read_b128 v[214:217], v157 offset:7168
	global_load_lds_dwordx4 v[218:219], off
	v_lshl_add_u64 v[218:219], s[36:37], 0, v[140:141]
	s_add_i32 m0, s31, 0xe000
	s_nop 0
	global_load_lds_dwordx4 v[218:219], off
	s_waitcnt vmcnt(8)
	s_waitcnt lgkmcnt(0)
	s_barrier
	s_setprio 1
	s_waitcnt lgkmcnt(0)
	v_mfma_f32_16x16x32_bf16 v[124:127], v[146:149], v[186:189], v[124:127]
	v_mfma_f32_16x16x32_bf16 v[120:123], v[162:165], v[186:189], v[120:123]
	v_mfma_f32_16x16x32_bf16 v[108:111], v[146:149], v[194:197], v[108:111]
	v_mfma_f32_16x16x32_bf16 v[104:107], v[162:165], v[194:197], v[104:107]
	v_mfma_f32_16x16x32_bf16 v[92:95], v[146:149], v[202:205], v[92:95]
	v_mfma_f32_16x16x32_bf16 v[88:91], v[162:165], v[202:205], v[88:91]
	v_mfma_f32_16x16x32_bf16 v[76:79], v[146:149], v[210:213], v[76:79]
	v_mfma_f32_16x16x32_bf16 v[72:75], v[162:165], v[210:213], v[72:75]
	v_mfma_f32_16x16x32_bf16 v[124:127], v[158:161], v[190:193], v[124:127]
	v_mfma_f32_16x16x32_bf16 v[120:123], v[166:169], v[190:193], v[120:123]
	v_mfma_f32_16x16x32_bf16 v[108:111], v[158:161], v[198:201], v[108:111]
	v_mfma_f32_16x16x32_bf16 v[104:107], v[166:169], v[198:201], v[104:107]
	v_mfma_f32_16x16x32_bf16 v[92:95], v[158:161], v[206:209], v[92:95]
	v_mfma_f32_16x16x32_bf16 v[88:91], v[166:169], v[206:209], v[88:91]
	v_mfma_f32_16x16x32_bf16 v[76:79], v[158:161], v[214:217], v[76:79]
	v_mfma_f32_16x16x32_bf16 v[72:75], v[166:169], v[214:217], v[72:75]
	s_setprio 0
	s_setprio 1
	v_mfma_f32_16x16x32_bf16 v[116:119], v[170:173], v[186:189], v[116:119]
	v_mfma_f32_16x16x32_bf16 v[112:115], v[178:181], v[186:189], v[112:115]
	v_mfma_f32_16x16x32_bf16 v[100:103], v[170:173], v[194:197], v[100:103]
	v_mfma_f32_16x16x32_bf16 v[96:99], v[178:181], v[194:197], v[96:99]
	v_mfma_f32_16x16x32_bf16 v[84:87], v[170:173], v[202:205], v[84:87]
	v_mfma_f32_16x16x32_bf16 v[80:83], v[178:181], v[202:205], v[80:83]
	v_mfma_f32_16x16x32_bf16 v[68:71], v[170:173], v[210:213], v[68:71]
	v_mfma_f32_16x16x32_bf16 v[64:67], v[178:181], v[210:213], v[64:67]
	v_mfma_f32_16x16x32_bf16 v[116:119], v[174:177], v[190:193], v[116:119]
	v_mfma_f32_16x16x32_bf16 v[112:115], v[182:185], v[190:193], v[112:115]
	v_mfma_f32_16x16x32_bf16 v[100:103], v[174:177], v[198:201], v[100:103]
	v_mfma_f32_16x16x32_bf16 v[96:99], v[182:185], v[198:201], v[96:99]
	v_mfma_f32_16x16x32_bf16 v[84:87], v[174:177], v[206:209], v[84:87]
	v_mfma_f32_16x16x32_bf16 v[80:83], v[182:185], v[206:209], v[80:83]
	v_mfma_f32_16x16x32_bf16 v[68:71], v[174:177], v[214:217], v[68:71]
	v_mfma_f32_16x16x32_bf16 v[64:67], v[182:185], v[214:217], v[64:67]
	s_setprio 0
	s_barrier
	s_add_i32 s34, s53, s44
	v_lshl_add_u64 v[218:219], s[38:39], 0, v[134:135]
	s_mov_b32 m0, s34
	ds_read_b128 v[186:189], v157 offset:16384
	ds_read_b128 v[190:193], v157 offset:17408
	ds_read_b128 v[194:197], v157 offset:18432
	ds_read_b128 v[198:201], v157 offset:19456
	ds_read_b128 v[202:205], v157 offset:20480
	ds_read_b128 v[206:209], v157 offset:21504
	ds_read_b128 v[210:213], v157 offset:22528
	ds_read_b128 v[214:217], v157 offset:23552
	global_load_lds_dwordx4 v[218:219], off
	s_add_i32 m0, s34, 0x2000
	s_add_u32 s34, s38, 0x40000
	v_lshl_add_u64 v[220:221], s[38:39], 0, v[130:131]
	s_addc_u32 s35, s39, 0
	s_add_i32 s63, s54, s44
	global_load_lds_dwordx4 v[220:221], off
	v_lshl_add_u64 v[222:223], s[34:35], 0, v[134:135]
	s_mov_b32 m0, s63
	v_lshl_add_u64 v[224:225], s[40:41], 0, v[132:133]
	global_load_lds_dwordx4 v[222:223], off
	v_lshl_add_u64 v[222:223], s[34:35], 0, v[130:131]
	s_add_i32 m0, s63, 0x2000
	s_nop 0
	global_load_lds_dwordx4 v[222:223], off
	v_lshl_add_u64 v[222:223], s[40:41], 0, v[136:137]
	s_mov_b32 m0, s31
	s_nop 0
	global_load_lds_dwordx4 v[222:223], off
	s_mov_b32 m0, s48
	s_nop 0
	global_load_lds_dwordx4 v[224:225], off
	s_waitcnt vmcnt(8)
	s_waitcnt lgkmcnt(0)
	s_barrier
	s_setprio 1
	s_waitcnt lgkmcnt(0)
	v_mfma_f32_16x16x32_bf16 v[60:63], v[146:149], v[186:189], v[60:63]
	v_mfma_f32_16x16x32_bf16 v[56:59], v[162:165], v[186:189], v[56:59]
	v_mfma_f32_16x16x32_bf16 v[44:47], v[146:149], v[194:197], v[44:47]
	v_mfma_f32_16x16x32_bf16 v[40:43], v[162:165], v[194:197], v[40:43]
	v_mfma_f32_16x16x32_bf16 v[28:31], v[146:149], v[202:205], v[28:31]
	v_mfma_f32_16x16x32_bf16 v[24:27], v[162:165], v[202:205], v[24:27]
	v_mfma_f32_16x16x32_bf16 v[12:15], v[146:149], v[210:213], v[12:15]
	v_mfma_f32_16x16x32_bf16 v[8:11], v[162:165], v[210:213], v[8:11]
	v_mfma_f32_16x16x32_bf16 v[60:63], v[158:161], v[190:193], v[60:63]
	v_mfma_f32_16x16x32_bf16 v[56:59], v[166:169], v[190:193], v[56:59]
	v_mfma_f32_16x16x32_bf16 v[44:47], v[158:161], v[198:201], v[44:47]
	v_mfma_f32_16x16x32_bf16 v[40:43], v[166:169], v[198:201], v[40:43]
	v_mfma_f32_16x16x32_bf16 v[28:31], v[158:161], v[206:209], v[28:31]
	v_mfma_f32_16x16x32_bf16 v[24:27], v[166:169], v[206:209], v[24:27]
	v_mfma_f32_16x16x32_bf16 v[12:15], v[158:161], v[214:217], v[12:15]
	v_mfma_f32_16x16x32_bf16 v[8:11], v[166:169], v[214:217], v[8:11]
	s_setprio 0
	s_setprio 1
	v_mfma_f32_16x16x32_bf16 v[52:55], v[170:173], v[186:189], v[52:55]
	v_mfma_f32_16x16x32_bf16 v[48:51], v[178:181], v[186:189], v[48:51]
	v_mfma_f32_16x16x32_bf16 v[36:39], v[170:173], v[194:197], v[36:39]
	v_mfma_f32_16x16x32_bf16 v[32:35], v[178:181], v[194:197], v[32:35]
	v_mfma_f32_16x16x32_bf16 v[20:23], v[170:173], v[202:205], v[20:23]
	v_mfma_f32_16x16x32_bf16 v[16:19], v[178:181], v[202:205], v[16:19]
	v_mfma_f32_16x16x32_bf16 v[4:7], v[170:173], v[210:213], v[4:7]
	v_mfma_f32_16x16x32_bf16 v[0:3], v[178:181], v[210:213], v[0:3]
	v_mfma_f32_16x16x32_bf16 v[52:55], v[174:177], v[190:193], v[52:55]
	v_mfma_f32_16x16x32_bf16 v[48:51], v[182:185], v[190:193], v[48:51]
	v_mfma_f32_16x16x32_bf16 v[36:39], v[174:177], v[198:201], v[36:39]
	v_mfma_f32_16x16x32_bf16 v[32:35], v[182:185], v[198:201], v[32:35]
	v_mfma_f32_16x16x32_bf16 v[20:23], v[174:177], v[206:209], v[20:23]
	v_mfma_f32_16x16x32_bf16 v[16:19], v[182:185], v[206:209], v[16:19]
	v_mfma_f32_16x16x32_bf16 v[4:7], v[174:177], v[214:217], v[4:7]
	v_mfma_f32_16x16x32_bf16 v[0:3], v[182:185], v[214:217], v[0:3]
	s_setprio 0
	s_barrier
	s_add_i32 s63, 0, 0x18000
	s_add_i32 s64, 0, 0x1c000
	v_add_u32_e32 v166, s63, v151
	v_add_u32_e32 v182, s64, v151
	ds_read_b128 v[146:149], v166
	ds_read_b128 v[158:161], v166 offset:1024
	ds_read_b128 v[162:165], v166 offset:2048
	ds_read_b128 v[166:169], v166 offset:3072
	ds_read_b128 v[170:173], v182
	ds_read_b128 v[174:177], v182 offset:1024
	ds_read_b128 v[178:181], v182 offset:2048
	ds_read_b128 v[182:185], v182 offset:3072
	s_add_u32 s34, s40, 0x40000
	s_addc_u32 s35, s41, 0
	s_mov_b32 m0, s49
	v_lshl_add_u64 v[226:227], s[34:35], 0, v[136:137]
	ds_read_b128 v[186:189], v157 offset:32768
	ds_read_b128 v[190:193], v157 offset:33792
	ds_read_b128 v[194:197], v157 offset:34816
	ds_read_b128 v[198:201], v157 offset:35840
	ds_read_b128 v[202:205], v157 offset:36864
	ds_read_b128 v[206:209], v157 offset:37888
	ds_read_b128 v[210:213], v157 offset:38912
	ds_read_b128 v[214:217], v157 offset:39936
	global_load_lds_dwordx4 v[226:227], off
	v_lshl_add_u64 v[226:227], s[34:35], 0, v[132:133]
	s_mov_b32 m0, s50
	s_nop 0
	global_load_lds_dwordx4 v[226:227], off
	s_waitcnt vmcnt(8)
	s_waitcnt lgkmcnt(0)
	s_barrier
	s_setprio 1
	s_waitcnt lgkmcnt(0)
	v_mfma_f32_16x16x32_bf16 v[124:127], v[146:149], v[186:189], v[124:127]
	v_mfma_f32_16x16x32_bf16 v[120:123], v[162:165], v[186:189], v[120:123]
	v_mfma_f32_16x16x32_bf16 v[108:111], v[146:149], v[194:197], v[108:111]
	v_mfma_f32_16x16x32_bf16 v[104:107], v[162:165], v[194:197], v[104:107]
	v_mfma_f32_16x16x32_bf16 v[92:95], v[146:149], v[202:205], v[92:95]
	v_mfma_f32_16x16x32_bf16 v[88:91], v[162:165], v[202:205], v[88:91]
	v_mfma_f32_16x16x32_bf16 v[76:79], v[146:149], v[210:213], v[76:79]
	v_mfma_f32_16x16x32_bf16 v[72:75], v[162:165], v[210:213], v[72:75]
	v_mfma_f32_16x16x32_bf16 v[124:127], v[158:161], v[190:193], v[124:127]
	v_mfma_f32_16x16x32_bf16 v[120:123], v[166:169], v[190:193], v[120:123]
	v_mfma_f32_16x16x32_bf16 v[108:111], v[158:161], v[198:201], v[108:111]
	v_mfma_f32_16x16x32_bf16 v[104:107], v[166:169], v[198:201], v[104:107]
	v_mfma_f32_16x16x32_bf16 v[92:95], v[158:161], v[206:209], v[92:95]
	v_mfma_f32_16x16x32_bf16 v[88:91], v[166:169], v[206:209], v[88:91]
	v_mfma_f32_16x16x32_bf16 v[76:79], v[158:161], v[214:217], v[76:79]
	v_mfma_f32_16x16x32_bf16 v[72:75], v[166:169], v[214:217], v[72:75]
	s_setprio 0
	s_setprio 1
	v_mfma_f32_16x16x32_bf16 v[116:119], v[170:173], v[186:189], v[116:119]
	v_mfma_f32_16x16x32_bf16 v[112:115], v[178:181], v[186:189], v[112:115]
	v_mfma_f32_16x16x32_bf16 v[100:103], v[170:173], v[194:197], v[100:103]
	v_mfma_f32_16x16x32_bf16 v[96:99], v[178:181], v[194:197], v[96:99]
	v_mfma_f32_16x16x32_bf16 v[84:87], v[170:173], v[202:205], v[84:87]
	v_mfma_f32_16x16x32_bf16 v[80:83], v[178:181], v[202:205], v[80:83]
	v_mfma_f32_16x16x32_bf16 v[68:71], v[170:173], v[210:213], v[68:71]
	v_mfma_f32_16x16x32_bf16 v[64:67], v[178:181], v[210:213], v[64:67]
	v_mfma_f32_16x16x32_bf16 v[116:119], v[174:177], v[190:193], v[116:119]
	v_mfma_f32_16x16x32_bf16 v[112:115], v[182:185], v[190:193], v[112:115]
	v_mfma_f32_16x16x32_bf16 v[100:103], v[174:177], v[198:201], v[100:103]
	v_mfma_f32_16x16x32_bf16 v[96:99], v[182:185], v[198:201], v[96:99]
	v_mfma_f32_16x16x32_bf16 v[84:87], v[174:177], v[206:209], v[84:87]
	v_mfma_f32_16x16x32_bf16 v[80:83], v[182:185], v[206:209], v[80:83]
	v_mfma_f32_16x16x32_bf16 v[68:71], v[174:177], v[214:217], v[68:71]
	v_mfma_f32_16x16x32_bf16 v[64:67], v[182:185], v[214:217], v[64:67]
	s_setprio 0
	s_barrier
	s_add_i32 s34, s63, s44
	v_lshl_add_u64 v[218:219], v[218:219], 0, s[6:7]
	s_mov_b32 m0, s34
	ds_read_b128 v[186:189], v157 offset:49152
	ds_read_b128 v[190:193], v157 offset:50176
	ds_read_b128 v[194:197], v157 offset:51200
	ds_read_b128 v[198:201], v157 offset:52224
	ds_read_b128 v[202:205], v157 offset:53248
	ds_read_b128 v[206:209], v157 offset:54272
	ds_read_b128 v[210:213], v157 offset:55296
	ds_read_b128 v[214:217], v157 offset:56320
	global_load_lds_dwordx4 v[218:219], off
	s_add_i32 m0, s34, 0x2000
	s_add_u32 s34, s38, 0x40080
	v_lshl_add_u64 v[218:219], v[220:221], 0, s[6:7]
	s_addc_u32 s35, s39, 0
	s_add_i32 s38, s64, s44
	global_load_lds_dwordx4 v[218:219], off
	v_lshl_add_u64 v[218:219], s[34:35], 0, v[134:135]
	s_mov_b32 m0, s38
	s_nop 0
	global_load_lds_dwordx4 v[218:219], off
	v_lshl_add_u64 v[218:219], s[34:35], 0, v[130:131]
	s_add_i32 m0, s38, 0x2000
	s_nop 0
	global_load_lds_dwordx4 v[218:219], off
	v_lshl_add_u64 v[218:219], v[222:223], 0, s[6:7]
	s_mov_b32 m0, s51
	s_nop 0
	global_load_lds_dwordx4 v[218:219], off
	v_lshl_add_u64 v[218:219], v[224:225], 0, s[6:7]
	s_mov_b32 m0, s52
	s_nop 0
	global_load_lds_dwordx4 v[218:219], off
	s_waitcnt vmcnt(8)
	s_waitcnt lgkmcnt(0)
	s_barrier
	s_add_u32 s36, s36, 0x100
	s_addc_u32 s37, s37, 0
	s_add_u32 s60, s60, 0x100
	s_addc_u32 s61, s61, 0
	s_setprio 1
	s_waitcnt lgkmcnt(0)
	v_mfma_f32_16x16x32_bf16 v[60:63], v[146:149], v[186:189], v[60:63]
	v_mfma_f32_16x16x32_bf16 v[56:59], v[162:165], v[186:189], v[56:59]
	v_mfma_f32_16x16x32_bf16 v[44:47], v[146:149], v[194:197], v[44:47]
	v_mfma_f32_16x16x32_bf16 v[40:43], v[162:165], v[194:197], v[40:43]
	v_mfma_f32_16x16x32_bf16 v[28:31], v[146:149], v[202:205], v[28:31]
	v_mfma_f32_16x16x32_bf16 v[24:27], v[162:165], v[202:205], v[24:27]
	v_mfma_f32_16x16x32_bf16 v[12:15], v[146:149], v[210:213], v[12:15]
	v_mfma_f32_16x16x32_bf16 v[8:11], v[162:165], v[210:213], v[8:11]
	v_mfma_f32_16x16x32_bf16 v[60:63], v[158:161], v[190:193], v[60:63]
	v_mfma_f32_16x16x32_bf16 v[56:59], v[166:169], v[190:193], v[56:59]
	v_mfma_f32_16x16x32_bf16 v[44:47], v[158:161], v[198:201], v[44:47]
	v_mfma_f32_16x16x32_bf16 v[40:43], v[166:169], v[198:201], v[40:43]
	v_mfma_f32_16x16x32_bf16 v[28:31], v[158:161], v[206:209], v[28:31]
	v_mfma_f32_16x16x32_bf16 v[24:27], v[166:169], v[206:209], v[24:27]
	v_mfma_f32_16x16x32_bf16 v[12:15], v[158:161], v[214:217], v[12:15]
	v_mfma_f32_16x16x32_bf16 v[8:11], v[166:169], v[214:217], v[8:11]
	s_setprio 0
	s_setprio 1
	v_mfma_f32_16x16x32_bf16 v[52:55], v[170:173], v[186:189], v[52:55]
	v_mfma_f32_16x16x32_bf16 v[48:51], v[178:181], v[186:189], v[48:51]
	v_mfma_f32_16x16x32_bf16 v[36:39], v[170:173], v[194:197], v[36:39]
	v_mfma_f32_16x16x32_bf16 v[32:35], v[178:181], v[194:197], v[32:35]
	v_mfma_f32_16x16x32_bf16 v[20:23], v[170:173], v[202:205], v[20:23]
	v_mfma_f32_16x16x32_bf16 v[16:19], v[178:181], v[202:205], v[16:19]
	v_mfma_f32_16x16x32_bf16 v[4:7], v[170:173], v[210:213], v[4:7]
	v_mfma_f32_16x16x32_bf16 v[0:3], v[178:181], v[210:213], v[0:3]
	v_mfma_f32_16x16x32_bf16 v[52:55], v[174:177], v[190:193], v[52:55]
	v_mfma_f32_16x16x32_bf16 v[48:51], v[182:185], v[190:193], v[48:51]
	v_mfma_f32_16x16x32_bf16 v[36:39], v[174:177], v[198:201], v[36:39]
	v_mfma_f32_16x16x32_bf16 v[32:35], v[182:185], v[198:201], v[32:35]
	v_mfma_f32_16x16x32_bf16 v[20:23], v[174:177], v[206:209], v[20:23]
	v_mfma_f32_16x16x32_bf16 v[16:19], v[182:185], v[206:209], v[16:19]
	v_mfma_f32_16x16x32_bf16 v[4:7], v[174:177], v[214:217], v[4:7]
	v_mfma_f32_16x16x32_bf16 v[0:3], v[182:185], v[214:217], v[0:3]
	s_setprio 0
	s_add_i32 s62, s62, 2
	s_cmp_gt_u32 s62, 13
	s_cbranch_scc0 .LBB0_1647
	s_sub_i32 s100, s62, 2
	s_cmp_eq_u32 s100, s98
	s_cbranch_scc1 .Lmy_nobar_17
	s_barrier

.Lmy_nobar2_18:
	ds_read_b128 v[146:149], v153
	ds_read_b128 v[158:161], v153 offset:1024
	ds_read_b128 v[162:165], v153 offset:2048
	ds_read_b128 v[166:169], v153 offset:3072
	ds_read_b128 v[170:173], v154
	ds_read_b128 v[174:177], v154 offset:1024
	ds_read_b128 v[178:181], v154 offset:2048
	ds_read_b128 v[182:185], v154 offset:3072
	s_add_u32 s34, s30, 0xfff50080
	s_addc_u32 s35, s31, -1
	s_cmp_eq_u32 s58, 40
	s_cselect_b32 s39, s1, s35
	s_cselect_b32 s38, s0, s34
	s_cselect_b32 s37, s29, s57
	s_cselect_b32 s36, s28, s13
	v_lshl_add_u64 v[218:219], s[30:31], 0, v[138:139]
	s_add_i32 m0, s42, 0xc000
	ds_read_b128 v[186:189], v155
	ds_read_b128 v[190:193], v155 offset:1024
	ds_read_b128 v[194:197], v155 offset:2048
	ds_read_b128 v[198:201], v155 offset:3072
	ds_read_b128 v[202:205], v155 offset:4096
	ds_read_b128 v[206:209], v155 offset:5120
	ds_read_b128 v[210:213], v155 offset:6144
	ds_read_b128 v[214:217], v155 offset:7168
	global_load_lds_dwordx4 v[218:219], off
	v_lshl_add_u64 v[218:219], s[30:31], 0, v[140:141]
	s_add_i32 m0, s42, 0xe000
	s_nop 0
	global_load_lds_dwordx4 v[218:219], off
	s_waitcnt vmcnt(8)
	s_waitcnt lgkmcnt(0)
	s_barrier
	s_setprio 1
	s_waitcnt lgkmcnt(0)
	v_mfma_f32_16x16x32_bf16 v[124:127], v[146:149], v[186:189], 0
	v_mfma_f32_16x16x32_bf16 v[120:123], v[162:165], v[186:189], 0
	v_mfma_f32_16x16x32_bf16 v[108:111], v[146:149], v[194:197], 0
	v_mfma_f32_16x16x32_bf16 v[104:107], v[162:165], v[194:197], 0
	v_mfma_f32_16x16x32_bf16 v[92:95], v[146:149], v[202:205], 0
	v_mfma_f32_16x16x32_bf16 v[88:91], v[162:165], v[202:205], 0
	v_mfma_f32_16x16x32_bf16 v[76:79], v[146:149], v[210:213], 0
	v_mfma_f32_16x16x32_bf16 v[72:75], v[162:165], v[210:213], 0
	v_mfma_f32_16x16x32_bf16 v[124:127], v[158:161], v[190:193], v[124:127]
	v_mfma_f32_16x16x32_bf16 v[120:123], v[166:169], v[190:193], v[120:123]
	v_mfma_f32_16x16x32_bf16 v[108:111], v[158:161], v[198:201], v[108:111]
	v_mfma_f32_16x16x32_bf16 v[104:107], v[166:169], v[198:201], v[104:107]
	v_mfma_f32_16x16x32_bf16 v[92:95], v[158:161], v[206:209], v[92:95]
	v_mfma_f32_16x16x32_bf16 v[88:91], v[166:169], v[206:209], v[88:91]
	v_mfma_f32_16x16x32_bf16 v[76:79], v[158:161], v[214:217], v[76:79]
	v_mfma_f32_16x16x32_bf16 v[72:75], v[166:169], v[214:217], v[72:75]
	s_setprio 0
	s_setprio 1
	v_mfma_f32_16x16x32_bf16 v[116:119], v[170:173], v[186:189], 0
	v_mfma_f32_16x16x32_bf16 v[112:115], v[178:181], v[186:189], 0
	v_mfma_f32_16x16x32_bf16 v[100:103], v[170:173], v[194:197], 0
	v_mfma_f32_16x16x32_bf16 v[96:99], v[178:181], v[194:197], 0
	v_mfma_f32_16x16x32_bf16 v[84:87], v[170:173], v[202:205], 0
	v_mfma_f32_16x16x32_bf16 v[80:83], v[178:181], v[202:205], 0
	v_mfma_f32_16x16x32_bf16 v[68:71], v[170:173], v[210:213], 0
	v_mfma_f32_16x16x32_bf16 v[64:67], v[178:181], v[210:213], 0
	v_mfma_f32_16x16x32_bf16 v[116:119], v[174:177], v[190:193], v[116:119]
	v_mfma_f32_16x16x32_bf16 v[112:115], v[182:185], v[190:193], v[112:115]
	v_mfma_f32_16x16x32_bf16 v[100:103], v[174:177], v[198:201], v[100:103]
	v_mfma_f32_16x16x32_bf16 v[96:99], v[182:185], v[198:201], v[96:99]
	v_mfma_f32_16x16x32_bf16 v[84:87], v[174:177], v[206:209], v[84:87]
	v_mfma_f32_16x16x32_bf16 v[80:83], v[182:185], v[206:209], v[80:83]
	v_mfma_f32_16x16x32_bf16 v[68:71], v[174:177], v[214:217], v[68:71]
	v_mfma_f32_16x16x32_bf16 v[64:67], v[182:185], v[214:217], v[64:67]
	s_setprio 0
	s_barrier
	s_add_i32 s34, s52, s41
	v_lshl_add_u64 v[218:219], s[36:37], 0, v[132:133]
	s_mov_b32 m0, s34
	ds_read_b128 v[186:189], v155 offset:16384
	ds_read_b128 v[190:193], v155 offset:17408
	ds_read_b128 v[194:197], v155 offset:18432
	ds_read_b128 v[198:201], v155 offset:19456
	ds_read_b128 v[202:205], v155 offset:20480
	ds_read_b128 v[206:209], v155 offset:21504
	ds_read_b128 v[210:213], v155 offset:22528
	ds_read_b128 v[214:217], v155 offset:23552
	global_load_lds_dwordx4 v[218:219], off
	s_add_i32 m0, s34, 0x2000
	s_add_u32 s34, s36, 0xb0000
	v_lshl_add_u64 v[220:221], s[36:37], 0, v[136:137]
	s_addc_u32 s35, s37, 0
	s_add_i32 s59, s53, s41
	global_load_lds_dwordx4 v[220:221], off
	v_lshl_add_u64 v[222:223], s[34:35], 0, v[132:133]
	s_mov_b32 m0, s59
	v_lshl_add_u64 v[224:225], s[38:39], 0, v[134:135]
	global_load_lds_dwordx4 v[222:223], off
	v_lshl_add_u64 v[222:223], s[34:35], 0, v[136:137]
	s_add_i32 m0, s59, 0x2000
	s_nop 0
	global_load_lds_dwordx4 v[222:223], off
	v_lshl_add_u64 v[222:223], s[38:39], 0, v[130:131]
	s_mov_b32 m0, s42
	s_nop 0
	global_load_lds_dwordx4 v[222:223], off
	s_mov_b32 m0, s43
	s_nop 0
	global_load_lds_dwordx4 v[224:225], off
	s_waitcnt vmcnt(8)
	s_waitcnt lgkmcnt(0)
	s_barrier
	s_setprio 1
	s_waitcnt lgkmcnt(0)
	v_mfma_f32_16x16x32_bf16 v[60:63], v[146:149], v[186:189], 0
	v_mfma_f32_16x16x32_bf16 v[56:59], v[162:165], v[186:189], 0
	v_mfma_f32_16x16x32_bf16 v[44:47], v[146:149], v[194:197], 0
	v_mfma_f32_16x16x32_bf16 v[40:43], v[162:165], v[194:197], 0
	v_mfma_f32_16x16x32_bf16 v[28:31], v[146:149], v[202:205], 0
	v_mfma_f32_16x16x32_bf16 v[24:27], v[162:165], v[202:205], 0
	v_mfma_f32_16x16x32_bf16 v[12:15], v[146:149], v[210:213], 0
	v_mfma_f32_16x16x32_bf16 v[8:11], v[162:165], v[210:213], 0
	v_mfma_f32_16x16x32_bf16 v[60:63], v[158:161], v[190:193], v[60:63]
	v_mfma_f32_16x16x32_bf16 v[56:59], v[166:169], v[190:193], v[56:59]
	v_mfma_f32_16x16x32_bf16 v[44:47], v[158:161], v[198:201], v[44:47]
	v_mfma_f32_16x16x32_bf16 v[40:43], v[166:169], v[198:201], v[40:43]
	v_mfma_f32_16x16x32_bf16 v[28:31], v[158:161], v[206:209], v[28:31]
	v_mfma_f32_16x16x32_bf16 v[24:27], v[166:169], v[206:209], v[24:27]
	v_mfma_f32_16x16x32_bf16 v[12:15], v[158:161], v[214:217], v[12:15]
	v_mfma_f32_16x16x32_bf16 v[8:11], v[166:169], v[214:217], v[8:11]
	s_setprio 0
	s_setprio 1
	v_mfma_f32_16x16x32_bf16 v[52:55], v[170:173], v[186:189], 0
	v_mfma_f32_16x16x32_bf16 v[48:51], v[178:181], v[186:189], 0
	v_mfma_f32_16x16x32_bf16 v[36:39], v[170:173], v[194:197], 0
	v_mfma_f32_16x16x32_bf16 v[32:35], v[178:181], v[194:197], 0
	v_mfma_f32_16x16x32_bf16 v[20:23], v[170:173], v[202:205], 0
	v_mfma_f32_16x16x32_bf16 v[16:19], v[178:181], v[202:205], 0
	v_mfma_f32_16x16x32_bf16 v[4:7], v[170:173], v[210:213], 0
	v_mfma_f32_16x16x32_bf16 v[0:3], v[178:181], v[210:213], 0
	v_mfma_f32_16x16x32_bf16 v[52:55], v[174:177], v[190:193], v[52:55]
	v_mfma_f32_16x16x32_bf16 v[48:51], v[182:185], v[190:193], v[48:51]
	v_mfma_f32_16x16x32_bf16 v[36:39], v[174:177], v[198:201], v[36:39]
	v_mfma_f32_16x16x32_bf16 v[32:35], v[182:185], v[198:201], v[32:35]
	v_mfma_f32_16x16x32_bf16 v[20:23], v[174:177], v[206:209], v[20:23]
	v_mfma_f32_16x16x32_bf16 v[16:19], v[182:185], v[206:209], v[16:19]
	v_mfma_f32_16x16x32_bf16 v[4:7], v[174:177], v[214:217], v[4:7]
	v_mfma_f32_16x16x32_bf16 v[0:3], v[182:185], v[214:217], v[0:3]
	s_setprio 0
	s_barrier
	s_add_i32 s59, 0, 0x18000
	s_add_i32 s60, 0, 0x1c000
	v_add_u32_e32 v166, s59, v151
	v_add_u32_e32 v182, s60, v151
	ds_read_b128 v[146:149], v166
	ds_read_b128 v[158:161], v166 offset:1024
	ds_read_b128 v[162:165], v166 offset:2048
	ds_read_b128 v[166:169], v166 offset:3072
	ds_read_b128 v[170:173], v182
	ds_read_b128 v[174:177], v182 offset:1024
	ds_read_b128 v[178:181], v182 offset:2048
	ds_read_b128 v[182:185], v182 offset:3072
	s_add_u32 s34, s38, 0xb0000
	s_addc_u32 s35, s39, 0
	s_mov_b32 m0, s44
	v_lshl_add_u64 v[226:227], s[34:35], 0, v[130:131]
	ds_read_b128 v[186:189], v155 offset:32768
	ds_read_b128 v[190:193], v155 offset:33792
	ds_read_b128 v[194:197], v155 offset:34816
	ds_read_b128 v[198:201], v155 offset:35840
	ds_read_b128 v[202:205], v155 offset:36864
	ds_read_b128 v[206:209], v155 offset:37888
	ds_read_b128 v[210:213], v155 offset:38912
	ds_read_b128 v[214:217], v155 offset:39936
	global_load_lds_dwordx4 v[226:227], off
	v_lshl_add_u64 v[226:227], s[34:35], 0, v[134:135]
	s_mov_b32 m0, s45
	s_nop 0
	global_load_lds_dwordx4 v[226:227], off
	s_waitcnt vmcnt(8)
	s_waitcnt lgkmcnt(0)
	s_barrier
	s_setprio 1
	s_waitcnt lgkmcnt(0)
	v_mfma_f32_16x16x32_bf16 v[124:127], v[146:149], v[186:189], v[124:127]
	v_mfma_f32_16x16x32_bf16 v[120:123], v[162:165], v[186:189], v[120:123]
	v_mfma_f32_16x16x32_bf16 v[108:111], v[146:149], v[194:197], v[108:111]
	v_mfma_f32_16x16x32_bf16 v[104:107], v[162:165], v[194:197], v[104:107]
	v_mfma_f32_16x16x32_bf16 v[92:95], v[146:149], v[202:205], v[92:95]
	v_mfma_f32_16x16x32_bf16 v[88:91], v[162:165], v[202:205], v[88:91]
	v_mfma_f32_16x16x32_bf16 v[76:79], v[146:149], v[210:213], v[76:79]
	v_mfma_f32_16x16x32_bf16 v[72:75], v[162:165], v[210:213], v[72:75]
	v_mfma_f32_16x16x32_bf16 v[124:127], v[158:161], v[190:193], v[124:127]
	v_mfma_f32_16x16x32_bf16 v[120:123], v[166:169], v[190:193], v[120:123]
	v_mfma_f32_16x16x32_bf16 v[108:111], v[158:161], v[198:201], v[108:111]
	v_mfma_f32_16x16x32_bf16 v[104:107], v[166:169], v[198:201], v[104:107]
	v_mfma_f32_16x16x32_bf16 v[92:95], v[158:161], v[206:209], v[92:95]
	v_mfma_f32_16x16x32_bf16 v[88:91], v[166:169], v[206:209], v[88:91]
	v_mfma_f32_16x16x32_bf16 v[76:79], v[158:161], v[214:217], v[76:79]
	v_mfma_f32_16x16x32_bf16 v[72:75], v[166:169], v[214:217], v[72:75]
	s_setprio 0
	s_setprio 1
	v_mfma_f32_16x16x32_bf16 v[116:119], v[170:173], v[186:189], v[116:119]
	v_mfma_f32_16x16x32_bf16 v[112:115], v[178:181], v[186:189], v[112:115]
	v_mfma_f32_16x16x32_bf16 v[100:103], v[170:173], v[194:197], v[100:103]
	v_mfma_f32_16x16x32_bf16 v[96:99], v[178:181], v[194:197], v[96:99]
	v_mfma_f32_16x16x32_bf16 v[84:87], v[170:173], v[202:205], v[84:87]
	v_mfma_f32_16x16x32_bf16 v[80:83], v[178:181], v[202:205], v[80:83]
	v_mfma_f32_16x16x32_bf16 v[68:71], v[170:173], v[210:213], v[68:71]
	v_mfma_f32_16x16x32_bf16 v[64:67], v[178:181], v[210:213], v[64:67]
	v_mfma_f32_16x16x32_bf16 v[116:119], v[174:177], v[190:193], v[116:119]
	v_mfma_f32_16x16x32_bf16 v[112:115], v[182:185], v[190:193], v[112:115]
	v_mfma_f32_16x16x32_bf16 v[100:103], v[174:177], v[198:201], v[100:103]
	v_mfma_f32_16x16x32_bf16 v[96:99], v[182:185], v[198:201], v[96:99]
	v_mfma_f32_16x16x32_bf16 v[84:87], v[174:177], v[206:209], v[84:87]
	v_mfma_f32_16x16x32_bf16 v[80:83], v[182:185], v[206:209], v[80:83]
	v_mfma_f32_16x16x32_bf16 v[68:71], v[174:177], v[214:217], v[68:71]
	v_mfma_f32_16x16x32_bf16 v[64:67], v[182:185], v[214:217], v[64:67]
	s_setprio 0
	s_barrier
	s_add_i32 s34, s59, s41
	v_lshl_add_u64 v[218:219], v[218:219], 0, s[22:23]
	s_mov_b32 m0, s34
	ds_read_b128 v[186:189], v155 offset:49152
	ds_read_b128 v[190:193], v155 offset:50176
	ds_read_b128 v[194:197], v155 offset:51200
	ds_read_b128 v[198:201], v155 offset:52224
	ds_read_b128 v[202:205], v155 offset:53248
	ds_read_b128 v[206:209], v155 offset:54272
	ds_read_b128 v[210:213], v155 offset:55296
	ds_read_b128 v[214:217], v155 offset:56320
	global_load_lds_dwordx4 v[218:219], off
	s_add_i32 m0, s34, 0x2000
	s_add_u32 s34, s36, 0xb0080
	v_lshl_add_u64 v[218:219], v[220:221], 0, s[22:23]
	s_addc_u32 s35, s37, 0
	s_add_i32 s36, s60, s41
	global_load_lds_dwordx4 v[218:219], off
	v_lshl_add_u64 v[218:219], s[34:35], 0, v[132:133]
	s_mov_b32 m0, s36
	s_nop 0
	global_load_lds_dwordx4 v[218:219], off
	v_lshl_add_u64 v[218:219], s[34:35], 0, v[136:137]
	s_add_i32 m0, s36, 0x2000
	s_nop 0
	global_load_lds_dwordx4 v[218:219], off
	v_lshl_add_u64 v[218:219], v[222:223], 0, s[22:23]
	s_mov_b32 m0, s47
	s_nop 0
	global_load_lds_dwordx4 v[218:219], off
	v_lshl_add_u64 v[218:219], v[224:225], 0, s[22:23]
	s_mov_b32 m0, s48
	s_nop 0
	global_load_lds_dwordx4 v[218:219], off
	s_waitcnt vmcnt(8)
	s_waitcnt lgkmcnt(0)
	s_barrier
	s_add_u32 s30, s30, 0x100
	s_addc_u32 s31, s31, 0
	s_add_u32 s13, s13, 0x100
	s_addc_u32 s57, s57, 0
	s_setprio 1
	s_waitcnt lgkmcnt(0)
	v_mfma_f32_16x16x32_bf16 v[60:63], v[146:149], v[186:189], v[60:63]
	v_mfma_f32_16x16x32_bf16 v[56:59], v[162:165], v[186:189], v[56:59]
	v_mfma_f32_16x16x32_bf16 v[44:47], v[146:149], v[194:197], v[44:47]
	v_mfma_f32_16x16x32_bf16 v[40:43], v[162:165], v[194:197], v[40:43]
	v_mfma_f32_16x16x32_bf16 v[28:31], v[146:149], v[202:205], v[28:31]
	v_mfma_f32_16x16x32_bf16 v[24:27], v[162:165], v[202:205], v[24:27]
	v_mfma_f32_16x16x32_bf16 v[12:15], v[146:149], v[210:213], v[12:15]
	v_mfma_f32_16x16x32_bf16 v[8:11], v[162:165], v[210:213], v[8:11]
	v_mfma_f32_16x16x32_bf16 v[60:63], v[158:161], v[190:193], v[60:63]
	v_mfma_f32_16x16x32_bf16 v[56:59], v[166:169], v[190:193], v[56:59]
	v_mfma_f32_16x16x32_bf16 v[44:47], v[158:161], v[198:201], v[44:47]
	v_mfma_f32_16x16x32_bf16 v[40:43], v[166:169], v[198:201], v[40:43]
	v_mfma_f32_16x16x32_bf16 v[28:31], v[158:161], v[206:209], v[28:31]
	v_mfma_f32_16x16x32_bf16 v[24:27], v[166:169], v[206:209], v[24:27]
	v_mfma_f32_16x16x32_bf16 v[12:15], v[158:161], v[214:217], v[12:15]
	v_mfma_f32_16x16x32_bf16 v[8:11], v[166:169], v[214:217], v[8:11]
	s_setprio 0
	s_setprio 1
	v_mfma_f32_16x16x32_bf16 v[52:55], v[170:173], v[186:189], v[52:55]
	v_mfma_f32_16x16x32_bf16 v[48:51], v[178:181], v[186:189], v[48:51]
	v_mfma_f32_16x16x32_bf16 v[36:39], v[170:173], v[194:197], v[36:39]
	v_mfma_f32_16x16x32_bf16 v[32:35], v[178:181], v[194:197], v[32:35]
	v_mfma_f32_16x16x32_bf16 v[20:23], v[170:173], v[202:205], v[20:23]
	v_mfma_f32_16x16x32_bf16 v[16:19], v[178:181], v[202:205], v[16:19]
	v_mfma_f32_16x16x32_bf16 v[4:7], v[170:173], v[210:213], v[4:7]
	v_mfma_f32_16x16x32_bf16 v[0:3], v[178:181], v[210:213], v[0:3]
	v_mfma_f32_16x16x32_bf16 v[52:55], v[174:177], v[190:193], v[52:55]
	v_mfma_f32_16x16x32_bf16 v[48:51], v[182:185], v[190:193], v[48:51]
	v_mfma_f32_16x16x32_bf16 v[36:39], v[174:177], v[198:201], v[36:39]
	v_mfma_f32_16x16x32_bf16 v[32:35], v[182:185], v[198:201], v[32:35]
	v_mfma_f32_16x16x32_bf16 v[20:23], v[174:177], v[206:209], v[20:23]
	v_mfma_f32_16x16x32_bf16 v[16:19], v[182:185], v[206:209], v[16:19]
	v_mfma_f32_16x16x32_bf16 v[4:7], v[174:177], v[214:217], v[4:7]
	v_mfma_f32_16x16x32_bf16 v[0:3], v[182:185], v[214:217], v[0:3]
	s_setprio 0
	s_add_i32 s58, s58, 2
.LBB0_1733:
	s_barrier
	ds_read_b128 v[146:149], v153
	ds_read_b128 v[158:161], v153 offset:1024
	ds_read_b128 v[162:165], v153 offset:2048
	ds_read_b128 v[166:169], v153 offset:3072
	ds_read_b128 v[170:173], v154
	ds_read_b128 v[174:177], v154 offset:1024
	ds_read_b128 v[178:181], v154 offset:2048
	ds_read_b128 v[182:185], v154 offset:3072
	s_add_u32 s34, s30, 0xfff50080
	s_addc_u32 s35, s31, -1
	s_cmp_eq_u32 s58, 40
	s_cselect_b32 s39, s1, s35
	s_cselect_b32 s38, s0, s34
	s_cselect_b32 s37, s29, s57
	s_cselect_b32 s36, s28, s13
	v_lshl_add_u64 v[218:219], s[30:31], 0, v[138:139]
	s_add_i32 m0, s42, 0xc000
	ds_read_b128 v[186:189], v155
	ds_read_b128 v[190:193], v155 offset:1024
	ds_read_b128 v[194:197], v155 offset:2048
	ds_read_b128 v[198:201], v155 offset:3072
	ds_read_b128 v[202:205], v155 offset:4096
	ds_read_b128 v[206:209], v155 offset:5120
	ds_read_b128 v[210:213], v155 offset:6144
	ds_read_b128 v[214:217], v155 offset:7168
	global_load_lds_dwordx4 v[218:219], off
	v_lshl_add_u64 v[218:219], s[30:31], 0, v[140:141]
	s_add_i32 m0, s42, 0xe000
	s_nop 0
	global_load_lds_dwordx4 v[218:219], off
	s_waitcnt vmcnt(8)
	s_waitcnt lgkmcnt(0)
	s_barrier
	s_setprio 1
	s_waitcnt lgkmcnt(0)
	v_mfma_f32_16x16x32_bf16 v[124:127], v[146:149], v[186:189], v[124:127]
	v_mfma_f32_16x16x32_bf16 v[120:123], v[162:165], v[186:189], v[120:123]
	v_mfma_f32_16x16x32_bf16 v[108:111], v[146:149], v[194:197], v[108:111]
	v_mfma_f32_16x16x32_bf16 v[104:107], v[162:165], v[194:197], v[104:107]
	v_mfma_f32_16x16x32_bf16 v[92:95], v[146:149], v[202:205], v[92:95]
	v_mfma_f32_16x16x32_bf16 v[88:91], v[162:165], v[202:205], v[88:91]
	v_mfma_f32_16x16x32_bf16 v[76:79], v[146:149], v[210:213], v[76:79]
	v_mfma_f32_16x16x32_bf16 v[72:75], v[162:165], v[210:213], v[72:75]
	v_mfma_f32_16x16x32_bf16 v[124:127], v[158:161], v[190:193], v[124:127]
	v_mfma_f32_16x16x32_bf16 v[120:123], v[166:169], v[190:193], v[120:123]
	v_mfma_f32_16x16x32_bf16 v[108:111], v[158:161], v[198:201], v[108:111]
	v_mfma_f32_16x16x32_bf16 v[104:107], v[166:169], v[198:201], v[104:107]
	v_mfma_f32_16x16x32_bf16 v[92:95], v[158:161], v[206:209], v[92:95]
	v_mfma_f32_16x16x32_bf16 v[88:91], v[166:169], v[206:209], v[88:91]
	v_mfma_f32_16x16x32_bf16 v[76:79], v[158:161], v[214:217], v[76:79]
	v_mfma_f32_16x16x32_bf16 v[72:75], v[166:169], v[214:217], v[72:75]
	s_setprio 0
	s_setprio 1
	v_mfma_f32_16x16x32_bf16 v[116:119], v[170:173], v[186:189], v[116:119]
	v_mfma_f32_16x16x32_bf16 v[112:115], v[178:181], v[186:189], v[112:115]
	v_mfma_f32_16x16x32_bf16 v[100:103], v[170:173], v[194:197], v[100:103]
	v_mfma_f32_16x16x32_bf16 v[96:99], v[178:181], v[194:197], v[96:99]
	v_mfma_f32_16x16x32_bf16 v[84:87], v[170:173], v[202:205], v[84:87]
	v_mfma_f32_16x16x32_bf16 v[80:83], v[178:181], v[202:205], v[80:83]
	v_mfma_f32_16x16x32_bf16 v[68:71], v[170:173], v[210:213], v[68:71]
	v_mfma_f32_16x16x32_bf16 v[64:67], v[178:181], v[210:213], v[64:67]
	v_mfma_f32_16x16x32_bf16 v[116:119], v[174:177], v[190:193], v[116:119]
	v_mfma_f32_16x16x32_bf16 v[112:115], v[182:185], v[190:193], v[112:115]
	v_mfma_f32_16x16x32_bf16 v[100:103], v[174:177], v[198:201], v[100:103]
	v_mfma_f32_16x16x32_bf16 v[96:99], v[182:185], v[198:201], v[96:99]
	v_mfma_f32_16x16x32_bf16 v[84:87], v[174:177], v[206:209], v[84:87]
	v_mfma_f32_16x16x32_bf16 v[80:83], v[182:185], v[206:209], v[80:83]
	v_mfma_f32_16x16x32_bf16 v[68:71], v[174:177], v[214:217], v[68:71]
	v_mfma_f32_16x16x32_bf16 v[64:67], v[182:185], v[214:217], v[64:67]
	s_setprio 0
	s_barrier
	s_add_i32 s34, s52, s41
	v_lshl_add_u64 v[218:219], s[36:37], 0, v[132:133]
	s_mov_b32 m0, s34
	ds_read_b128 v[186:189], v155 offset:16384
	ds_read_b128 v[190:193], v155 offset:17408
	ds_read_b128 v[194:197], v155 offset:18432
	ds_read_b128 v[198:201], v155 offset:19456
	ds_read_b128 v[202:205], v155 offset:20480
	ds_read_b128 v[206:209], v155 offset:21504
	ds_read_b128 v[210:213], v155 offset:22528
	ds_read_b128 v[214:217], v155 offset:23552
	global_load_lds_dwordx4 v[218:219], off
	s_add_i32 m0, s34, 0x2000
	s_add_u32 s34, s36, 0xb0000
	v_lshl_add_u64 v[220:221], s[36:37], 0, v[136:137]
	s_addc_u32 s35, s37, 0
	s_add_i32 s59, s53, s41
	global_load_lds_dwordx4 v[220:221], off
	v_lshl_add_u64 v[222:223], s[34:35], 0, v[132:133]
	s_mov_b32 m0, s59
	v_lshl_add_u64 v[224:225], s[38:39], 0, v[134:135]
	global_load_lds_dwordx4 v[222:223], off
	v_lshl_add_u64 v[222:223], s[34:35], 0, v[136:137]
	s_add_i32 m0, s59, 0x2000
	s_nop 0
	global_load_lds_dwordx4 v[222:223], off
	v_lshl_add_u64 v[222:223], s[38:39], 0, v[130:131]
	s_mov_b32 m0, s42
	s_nop 0
	global_load_lds_dwordx4 v[222:223], off
	s_mov_b32 m0, s43
	s_nop 0
	global_load_lds_dwordx4 v[224:225], off
	s_waitcnt vmcnt(8)
	s_waitcnt lgkmcnt(0)
	s_barrier
	s_setprio 1
	s_waitcnt lgkmcnt(0)
	v_mfma_f32_16x16x32_bf16 v[60:63], v[146:149], v[186:189], v[60:63]
	v_mfma_f32_16x16x32_bf16 v[56:59], v[162:165], v[186:189], v[56:59]
	v_mfma_f32_16x16x32_bf16 v[44:47], v[146:149], v[194:197], v[44:47]
	v_mfma_f32_16x16x32_bf16 v[40:43], v[162:165], v[194:197], v[40:43]
	v_mfma_f32_16x16x32_bf16 v[28:31], v[146:149], v[202:205], v[28:31]
	v_mfma_f32_16x16x32_bf16 v[24:27], v[162:165], v[202:205], v[24:27]
	v_mfma_f32_16x16x32_bf16 v[12:15], v[146:149], v[210:213], v[12:15]
	v_mfma_f32_16x16x32_bf16 v[8:11], v[162:165], v[210:213], v[8:11]
	v_mfma_f32_16x16x32_bf16 v[60:63], v[158:161], v[190:193], v[60:63]
	v_mfma_f32_16x16x32_bf16 v[56:59], v[166:169], v[190:193], v[56:59]
	v_mfma_f32_16x16x32_bf16 v[44:47], v[158:161], v[198:201], v[44:47]
	v_mfma_f32_16x16x32_bf16 v[40:43], v[166:169], v[198:201], v[40:43]
	v_mfma_f32_16x16x32_bf16 v[28:31], v[158:161], v[206:209], v[28:31]
	v_mfma_f32_16x16x32_bf16 v[24:27], v[166:169], v[206:209], v[24:27]
	v_mfma_f32_16x16x32_bf16 v[12:15], v[158:161], v[214:217], v[12:15]
	v_mfma_f32_16x16x32_bf16 v[8:11], v[166:169], v[214:217], v[8:11]
	s_setprio 0
	s_setprio 1
	v_mfma_f32_16x16x32_bf16 v[52:55], v[170:173], v[186:189], v[52:55]
	v_mfma_f32_16x16x32_bf16 v[48:51], v[178:181], v[186:189], v[48:51]
	v_mfma_f32_16x16x32_bf16 v[36:39], v[170:173], v[194:197], v[36:39]
	v_mfma_f32_16x16x32_bf16 v[32:35], v[178:181], v[194:197], v[32:35]
	v_mfma_f32_16x16x32_bf16 v[20:23], v[170:173], v[202:205], v[20:23]
	v_mfma_f32_16x16x32_bf16 v[16:19], v[178:181], v[202:205], v[16:19]
	v_mfma_f32_16x16x32_bf16 v[4:7], v[170:173], v[210:213], v[4:7]
	v_mfma_f32_16x16x32_bf16 v[0:3], v[178:181], v[210:213], v[0:3]
	v_mfma_f32_16x16x32_bf16 v[52:55], v[174:177], v[190:193], v[52:55]
	v_mfma_f32_16x16x32_bf16 v[48:51], v[182:185], v[190:193], v[48:51]
	v_mfma_f32_16x16x32_bf16 v[36:39], v[174:177], v[198:201], v[36:39]
	v_mfma_f32_16x16x32_bf16 v[32:35], v[182:185], v[198:201], v[32:35]
	v_mfma_f32_16x16x32_bf16 v[20:23], v[174:177], v[206:209], v[20:23]
	v_mfma_f32_16x16x32_bf16 v[16:19], v[182:185], v[206:209], v[16:19]
	v_mfma_f32_16x16x32_bf16 v[4:7], v[174:177], v[214:217], v[4:7]
	v_mfma_f32_16x16x32_bf16 v[0:3], v[182:185], v[214:217], v[0:3]
	s_setprio 0
	s_barrier
	s_add_i32 s59, 0, 0x18000
	s_add_i32 s60, 0, 0x1c000
	v_add_u32_e32 v166, s59, v151
	v_add_u32_e32 v182, s60, v151
	ds_read_b128 v[146:149], v166
	ds_read_b128 v[158:161], v166 offset:1024
	ds_read_b128 v[162:165], v166 offset:2048
	ds_read_b128 v[166:169], v166 offset:3072
	ds_read_b128 v[170:173], v182
	ds_read_b128 v[174:177], v182 offset:1024
	ds_read_b128 v[178:181], v182 offset:2048
	ds_read_b128 v[182:185], v182 offset:3072
	s_add_u32 s34, s38, 0xb0000
	s_addc_u32 s35, s39, 0
	s_mov_b32 m0, s44
	v_lshl_add_u64 v[226:227], s[34:35], 0, v[130:131]
	ds_read_b128 v[186:189], v155 offset:32768
	ds_read_b128 v[190:193], v155 offset:33792
	ds_read_b128 v[194:197], v155 offset:34816
	ds_read_b128 v[198:201], v155 offset:35840
	ds_read_b128 v[202:205], v155 offset:36864
	ds_read_b128 v[206:209], v155 offset:37888
	ds_read_b128 v[210:213], v155 offset:38912
	ds_read_b128 v[214:217], v155 offset:39936
	global_load_lds_dwordx4 v[226:227], off
	v_lshl_add_u64 v[226:227], s[34:35], 0, v[134:135]
	s_mov_b32 m0, s45
	s_nop 0
	global_load_lds_dwordx4 v[226:227], off
	s_waitcnt vmcnt(8)
	s_waitcnt lgkmcnt(0)
	s_barrier
	s_setprio 1
	s_waitcnt lgkmcnt(0)
	v_mfma_f32_16x16x32_bf16 v[124:127], v[146:149], v[186:189], v[124:127]
	v_mfma_f32_16x16x32_bf16 v[120:123], v[162:165], v[186:189], v[120:123]
	v_mfma_f32_16x16x32_bf16 v[108:111], v[146:149], v[194:197], v[108:111]
	v_mfma_f32_16x16x32_bf16 v[104:107], v[162:165], v[194:197], v[104:107]
	v_mfma_f32_16x16x32_bf16 v[92:95], v[146:149], v[202:205], v[92:95]
	v_mfma_f32_16x16x32_bf16 v[88:91], v[162:165], v[202:205], v[88:91]
	v_mfma_f32_16x16x32_bf16 v[76:79], v[146:149], v[210:213], v[76:79]
	v_mfma_f32_16x16x32_bf16 v[72:75], v[162:165], v[210:213], v[72:75]
	v_mfma_f32_16x16x32_bf16 v[124:127], v[158:161], v[190:193], v[124:127]
	v_mfma_f32_16x16x32_bf16 v[120:123], v[166:169], v[190:193], v[120:123]
	v_mfma_f32_16x16x32_bf16 v[108:111], v[158:161], v[198:201], v[108:111]
	v_mfma_f32_16x16x32_bf16 v[104:107], v[166:169], v[198:201], v[104:107]
	v_mfma_f32_16x16x32_bf16 v[92:95], v[158:161], v[206:209], v[92:95]
	v_mfma_f32_16x16x32_bf16 v[88:91], v[166:169], v[206:209], v[88:91]
	v_mfma_f32_16x16x32_bf16 v[76:79], v[158:161], v[214:217], v[76:79]
	v_mfma_f32_16x16x32_bf16 v[72:75], v[166:169], v[214:217], v[72:75]
	s_setprio 0
	s_setprio 1
	v_mfma_f32_16x16x32_bf16 v[116:119], v[170:173], v[186:189], v[116:119]
	v_mfma_f32_16x16x32_bf16 v[112:115], v[178:181], v[186:189], v[112:115]
	v_mfma_f32_16x16x32_bf16 v[100:103], v[170:173], v[194:197], v[100:103]
	v_mfma_f32_16x16x32_bf16 v[96:99], v[178:181], v[194:197], v[96:99]
	v_mfma_f32_16x16x32_bf16 v[84:87], v[170:173], v[202:205], v[84:87]
	v_mfma_f32_16x16x32_bf16 v[80:83], v[178:181], v[202:205], v[80:83]
	v_mfma_f32_16x16x32_bf16 v[68:71], v[170:173], v[210:213], v[68:71]
	v_mfma_f32_16x16x32_bf16 v[64:67], v[178:181], v[210:213], v[64:67]
	v_mfma_f32_16x16x32_bf16 v[116:119], v[174:177], v[190:193], v[116:119]
	v_mfma_f32_16x16x32_bf16 v[112:115], v[182:185], v[190:193], v[112:115]
	v_mfma_f32_16x16x32_bf16 v[100:103], v[174:177], v[198:201], v[100:103]
	v_mfma_f32_16x16x32_bf16 v[96:99], v[182:185], v[198:201], v[96:99]
	v_mfma_f32_16x16x32_bf16 v[84:87], v[174:177], v[206:209], v[84:87]
	v_mfma_f32_16x16x32_bf16 v[80:83], v[182:185], v[206:209], v[80:83]
	v_mfma_f32_16x16x32_bf16 v[68:71], v[174:177], v[214:217], v[68:71]
	v_mfma_f32_16x16x32_bf16 v[64:67], v[182:185], v[214:217], v[64:67]
	s_setprio 0
	s_barrier
	s_add_i32 s34, s59, s41
	v_lshl_add_u64 v[218:219], v[218:219], 0, s[22:23]
	s_mov_b32 m0, s34
	ds_read_b128 v[186:189], v155 offset:49152
	ds_read_b128 v[190:193], v155 offset:50176
	ds_read_b128 v[194:197], v155 offset:51200
	ds_read_b128 v[198:201], v155 offset:52224
	ds_read_b128 v[202:205], v155 offset:53248
	ds_read_b128 v[206:209], v155 offset:54272
	ds_read_b128 v[210:213], v155 offset:55296
	ds_read_b128 v[214:217], v155 offset:56320
	global_load_lds_dwordx4 v[218:219], off
	s_add_i32 m0, s34, 0x2000
	s_add_u32 s34, s36, 0xb0080
	v_lshl_add_u64 v[218:219], v[220:221], 0, s[22:23]
	s_addc_u32 s35, s37, 0
	s_add_i32 s36, s60, s41
	global_load_lds_dwordx4 v[218:219], off
	v_lshl_add_u64 v[218:219], s[34:35], 0, v[132:133]
	s_mov_b32 m0, s36
	s_nop 0
	global_load_lds_dwordx4 v[218:219], off
	v_lshl_add_u64 v[218:219], s[34:35], 0, v[136:137]
	s_add_i32 m0, s36, 0x2000
	s_nop 0
	global_load_lds_dwordx4 v[218:219], off
	v_lshl_add_u64 v[218:219], v[222:223], 0, s[22:23]
	s_mov_b32 m0, s47
	s_nop 0
	global_load_lds_dwordx4 v[218:219], off
	v_lshl_add_u64 v[218:219], v[224:225], 0, s[22:23]
	s_mov_b32 m0, s48
	s_nop 0
	global_load_lds_dwordx4 v[218:219], off
	s_waitcnt vmcnt(8)
	s_waitcnt lgkmcnt(0)
	s_barrier
	s_add_u32 s30, s30, 0x100
	s_addc_u32 s31, s31, 0
	s_add_u32 s13, s13, 0x100
	s_addc_u32 s57, s57, 0
	s_setprio 1
	s_waitcnt lgkmcnt(0)
	v_mfma_f32_16x16x32_bf16 v[60:63], v[146:149], v[186:189], v[60:63]
	v_mfma_f32_16x16x32_bf16 v[56:59], v[162:165], v[186:189], v[56:59]
	v_mfma_f32_16x16x32_bf16 v[44:47], v[146:149], v[194:197], v[44:47]
	v_mfma_f32_16x16x32_bf16 v[40:43], v[162:165], v[194:197], v[40:43]
	v_mfma_f32_16x16x32_bf16 v[28:31], v[146:149], v[202:205], v[28:31]
	v_mfma_f32_16x16x32_bf16 v[24:27], v[162:165], v[202:205], v[24:27]
	v_mfma_f32_16x16x32_bf16 v[12:15], v[146:149], v[210:213], v[12:15]
	v_mfma_f32_16x16x32_bf16 v[8:11], v[162:165], v[210:213], v[8:11]
	v_mfma_f32_16x16x32_bf16 v[60:63], v[158:161], v[190:193], v[60:63]
	v_mfma_f32_16x16x32_bf16 v[56:59], v[166:169], v[190:193], v[56:59]
	v_mfma_f32_16x16x32_bf16 v[44:47], v[158:161], v[198:201], v[44:47]
	v_mfma_f32_16x16x32_bf16 v[40:43], v[166:169], v[198:201], v[40:43]
	v_mfma_f32_16x16x32_bf16 v[28:31], v[158:161], v[206:209], v[28:31]
	v_mfma_f32_16x16x32_bf16 v[24:27], v[166:169], v[206:209], v[24:27]
	v_mfma_f32_16x16x32_bf16 v[12:15], v[158:161], v[214:217], v[12:15]
	v_mfma_f32_16x16x32_bf16 v[8:11], v[166:169], v[214:217], v[8:11]
	s_setprio 0
	s_setprio 1
	v_mfma_f32_16x16x32_bf16 v[52:55], v[170:173], v[186:189], v[52:55]
	v_mfma_f32_16x16x32_bf16 v[48:51], v[178:181], v[186:189], v[48:51]
	v_mfma_f32_16x16x32_bf16 v[36:39], v[170:173], v[194:197], v[36:39]
	v_mfma_f32_16x16x32_bf16 v[32:35], v[178:181], v[194:197], v[32:35]
	v_mfma_f32_16x16x32_bf16 v[20:23], v[170:173], v[202:205], v[20:23]
	v_mfma_f32_16x16x32_bf16 v[16:19], v[178:181], v[202:205], v[16:19]
	v_mfma_f32_16x16x32_bf16 v[4:7], v[170:173], v[210:213], v[4:7]
	v_mfma_f32_16x16x32_bf16 v[0:3], v[178:181], v[210:213], v[0:3]
	v_mfma_f32_16x16x32_bf16 v[52:55], v[174:177], v[190:193], v[52:55]
	v_mfma_f32_16x16x32_bf16 v[48:51], v[182:185], v[190:193], v[48:51]
	v_mfma_f32_16x16x32_bf16 v[36:39], v[174:177], v[198:201], v[36:39]
	v_mfma_f32_16x16x32_bf16 v[32:35], v[182:185], v[198:201], v[32:35]
	v_mfma_f32_16x16x32_bf16 v[20:23], v[174:177], v[206:209], v[20:23]
	v_mfma_f32_16x16x32_bf16 v[16:19], v[182:185], v[206:209], v[16:19]
	v_mfma_f32_16x16x32_bf16 v[4:7], v[174:177], v[214:217], v[4:7]
	v_mfma_f32_16x16x32_bf16 v[0:3], v[182:185], v[214:217], v[0:3]
	s_setprio 0
	s_add_i32 s58, s58, 2
	s_cmp_gt_u32 s58, 41
	s_cbranch_scc0 .LBB0_1733
	s_sub_i32 s100, s58, 2
	s_cmp_eq_u32 s100, s98
	s_cbranch_scc1 .Lmy_nobar_18
	s_barrier

.Lmy_nobar2_19:
	ds_read_b128 v[150:153], v157
	ds_read_b128 v[160:163], v157 offset:1024
	ds_read_b128 v[164:167], v157 offset:2048
	ds_read_b128 v[168:171], v157 offset:3072
	ds_read_b128 v[172:175], v158
	ds_read_b128 v[176:179], v158 offset:1024
	ds_read_b128 v[180:183], v158 offset:2048
	ds_read_b128 v[184:187], v158 offset:3072
	s_add_u32 s34, s42, 0xfffc0080
	s_addc_u32 s35, s43, -1
	s_cmp_eq_u32 s65, 12
	s_cselect_b32 s47, s7, s35
	s_cselect_b32 s46, s8, s34
	s_cselect_b32 s45, s12, s37
	s_cselect_b32 s44, s13, s31
	v_lshl_add_u64 v[220:221], s[42:43], 0, v[142:143]
	s_add_i32 m0, s53, 0xc000
	ds_read_b128 v[188:191], v159
	ds_read_b128 v[192:195], v159 offset:1024
	ds_read_b128 v[196:199], v159 offset:2048
	ds_read_b128 v[200:203], v159 offset:3072
	ds_read_b128 v[204:207], v159 offset:4096
	ds_read_b128 v[208:211], v159 offset:5120
	ds_read_b128 v[212:215], v159 offset:6144
	ds_read_b128 v[216:219], v159 offset:7168
	global_load_lds_dwordx4 v[220:221], off
	v_lshl_add_u64 v[220:221], s[42:43], 0, v[144:145]
	s_add_i32 m0, s53, 0xe000
	s_nop 0
	global_load_lds_dwordx4 v[220:221], off
	s_waitcnt vmcnt(8)
	s_waitcnt lgkmcnt(0)
	s_barrier
	s_setprio 1
	s_waitcnt lgkmcnt(0)
	v_mfma_f32_16x16x32_bf16 v[124:127], v[150:153], v[188:191], 0
	v_mfma_f32_16x16x32_bf16 v[120:123], v[164:167], v[188:191], 0
	v_mfma_f32_16x16x32_bf16 v[108:111], v[150:153], v[196:199], 0
	v_mfma_f32_16x16x32_bf16 v[104:107], v[164:167], v[196:199], 0
	v_mfma_f32_16x16x32_bf16 v[92:95], v[150:153], v[204:207], 0
	v_mfma_f32_16x16x32_bf16 v[88:91], v[164:167], v[204:207], 0
	v_mfma_f32_16x16x32_bf16 v[76:79], v[150:153], v[212:215], 0
	v_mfma_f32_16x16x32_bf16 v[72:75], v[164:167], v[212:215], 0
	v_mfma_f32_16x16x32_bf16 v[124:127], v[160:163], v[192:195], v[124:127]
	v_mfma_f32_16x16x32_bf16 v[120:123], v[168:171], v[192:195], v[120:123]
	v_mfma_f32_16x16x32_bf16 v[108:111], v[160:163], v[200:203], v[108:111]
	v_mfma_f32_16x16x32_bf16 v[104:107], v[168:171], v[200:203], v[104:107]
	v_mfma_f32_16x16x32_bf16 v[92:95], v[160:163], v[208:211], v[92:95]
	v_mfma_f32_16x16x32_bf16 v[88:91], v[168:171], v[208:211], v[88:91]
	v_mfma_f32_16x16x32_bf16 v[76:79], v[160:163], v[216:219], v[76:79]
	v_mfma_f32_16x16x32_bf16 v[72:75], v[168:171], v[216:219], v[72:75]
	s_setprio 0
	s_setprio 1
	v_mfma_f32_16x16x32_bf16 v[116:119], v[172:175], v[188:191], 0
	v_mfma_f32_16x16x32_bf16 v[112:115], v[180:183], v[188:191], 0
	v_mfma_f32_16x16x32_bf16 v[100:103], v[172:175], v[196:199], 0
	v_mfma_f32_16x16x32_bf16 v[96:99], v[180:183], v[196:199], 0
	v_mfma_f32_16x16x32_bf16 v[84:87], v[172:175], v[204:207], 0
	v_mfma_f32_16x16x32_bf16 v[80:83], v[180:183], v[204:207], 0
	v_mfma_f32_16x16x32_bf16 v[68:71], v[172:175], v[212:215], 0
	v_mfma_f32_16x16x32_bf16 v[64:67], v[180:183], v[212:215], 0
	v_mfma_f32_16x16x32_bf16 v[116:119], v[176:179], v[192:195], v[116:119]
	v_mfma_f32_16x16x32_bf16 v[112:115], v[184:187], v[192:195], v[112:115]
	v_mfma_f32_16x16x32_bf16 v[100:103], v[176:179], v[200:203], v[100:103]
	v_mfma_f32_16x16x32_bf16 v[96:99], v[184:187], v[200:203], v[96:99]
	v_mfma_f32_16x16x32_bf16 v[84:87], v[176:179], v[208:211], v[84:87]
	v_mfma_f32_16x16x32_bf16 v[80:83], v[184:187], v[208:211], v[80:83]
	v_mfma_f32_16x16x32_bf16 v[68:71], v[176:179], v[216:219], v[68:71]
	v_mfma_f32_16x16x32_bf16 v[64:67], v[184:187], v[216:219], v[64:67]
	s_setprio 0
	s_barrier
	s_add_i32 s34, s61, s50
	v_lshl_add_u64 v[220:221], s[44:45], 0, v[134:135]
	s_mov_b32 m0, s34
	ds_read_b128 v[188:191], v159 offset:16384
	ds_read_b128 v[192:195], v159 offset:17408
	ds_read_b128 v[196:199], v159 offset:18432
	ds_read_b128 v[200:203], v159 offset:19456
	ds_read_b128 v[204:207], v159 offset:20480
	ds_read_b128 v[208:211], v159 offset:21504
	ds_read_b128 v[212:215], v159 offset:22528
	ds_read_b128 v[216:219], v159 offset:23552
	global_load_lds_dwordx4 v[220:221], off
	s_add_i32 m0, s34, 0x2000
	s_add_u32 s34, s44, 0x40000
	v_lshl_add_u64 v[222:223], s[44:45], 0, v[138:139]
	s_addc_u32 s35, s45, 0
	s_add_i32 s66, s62, s50
	global_load_lds_dwordx4 v[222:223], off
	v_lshl_add_u64 v[224:225], s[34:35], 0, v[134:135]
	s_mov_b32 m0, s66
	v_lshl_add_u64 v[226:227], s[46:47], 0, v[136:137]
	global_load_lds_dwordx4 v[224:225], off
	v_lshl_add_u64 v[224:225], s[34:35], 0, v[138:139]
	s_add_i32 m0, s66, 0x2000
	s_nop 0
	global_load_lds_dwordx4 v[224:225], off
	v_lshl_add_u64 v[224:225], s[46:47], 0, v[132:133]
	s_mov_b32 m0, s53
	s_nop 0
	global_load_lds_dwordx4 v[224:225], off
	s_mov_b32 m0, s54
	s_nop 0
	global_load_lds_dwordx4 v[226:227], off
	s_waitcnt vmcnt(8)
	s_waitcnt lgkmcnt(0)
	s_barrier
	s_setprio 1
	s_waitcnt lgkmcnt(0)
	v_mfma_f32_16x16x32_bf16 v[60:63], v[150:153], v[188:191], 0
	v_mfma_f32_16x16x32_bf16 v[56:59], v[164:167], v[188:191], 0
	v_mfma_f32_16x16x32_bf16 v[44:47], v[150:153], v[196:199], 0
	v_mfma_f32_16x16x32_bf16 v[40:43], v[164:167], v[196:199], 0
	v_mfma_f32_16x16x32_bf16 v[28:31], v[150:153], v[204:207], 0
	v_mfma_f32_16x16x32_bf16 v[24:27], v[164:167], v[204:207], 0
	v_mfma_f32_16x16x32_bf16 v[12:15], v[150:153], v[212:215], 0
	v_mfma_f32_16x16x32_bf16 v[8:11], v[164:167], v[212:215], 0
	v_mfma_f32_16x16x32_bf16 v[60:63], v[160:163], v[192:195], v[60:63]
	v_mfma_f32_16x16x32_bf16 v[56:59], v[168:171], v[192:195], v[56:59]
	v_mfma_f32_16x16x32_bf16 v[44:47], v[160:163], v[200:203], v[44:47]
	v_mfma_f32_16x16x32_bf16 v[40:43], v[168:171], v[200:203], v[40:43]
	v_mfma_f32_16x16x32_bf16 v[28:31], v[160:163], v[208:211], v[28:31]
	v_mfma_f32_16x16x32_bf16 v[24:27], v[168:171], v[208:211], v[24:27]
	v_mfma_f32_16x16x32_bf16 v[12:15], v[160:163], v[216:219], v[12:15]
	v_mfma_f32_16x16x32_bf16 v[8:11], v[168:171], v[216:219], v[8:11]
	s_setprio 0
	s_setprio 1
	v_mfma_f32_16x16x32_bf16 v[52:55], v[172:175], v[188:191], 0
	v_mfma_f32_16x16x32_bf16 v[48:51], v[180:183], v[188:191], 0
	v_mfma_f32_16x16x32_bf16 v[36:39], v[172:175], v[196:199], 0
	v_mfma_f32_16x16x32_bf16 v[32:35], v[180:183], v[196:199], 0
	v_mfma_f32_16x16x32_bf16 v[20:23], v[172:175], v[204:207], 0
	v_mfma_f32_16x16x32_bf16 v[16:19], v[180:183], v[204:207], 0
	v_mfma_f32_16x16x32_bf16 v[4:7], v[172:175], v[212:215], 0
	v_mfma_f32_16x16x32_bf16 v[0:3], v[180:183], v[212:215], 0
	v_mfma_f32_16x16x32_bf16 v[52:55], v[176:179], v[192:195], v[52:55]
	v_mfma_f32_16x16x32_bf16 v[48:51], v[184:187], v[192:195], v[48:51]
	v_mfma_f32_16x16x32_bf16 v[36:39], v[176:179], v[200:203], v[36:39]
	v_mfma_f32_16x16x32_bf16 v[32:35], v[184:187], v[200:203], v[32:35]
	v_mfma_f32_16x16x32_bf16 v[20:23], v[176:179], v[208:211], v[20:23]
	v_mfma_f32_16x16x32_bf16 v[16:19], v[184:187], v[208:211], v[16:19]
	v_mfma_f32_16x16x32_bf16 v[4:7], v[176:179], v[216:219], v[4:7]
	v_mfma_f32_16x16x32_bf16 v[0:3], v[184:187], v[216:219], v[0:3]
	s_setprio 0
	s_barrier
	s_add_i32 s66, 0, 0x18000
	v_add_u32_e32 v140, s66, v154
	s_add_i32 s67, 0, 0x1c000
	ds_read_b128 v[150:153], v140
	ds_read_b128 v[160:163], v140 offset:1024
	ds_read_b128 v[164:167], v140 offset:2048
	ds_read_b128 v[168:171], v140 offset:3072
	v_add_u32_e32 v140, s67, v154
	ds_read_b128 v[172:175], v140
	ds_read_b128 v[176:179], v140 offset:1024
	ds_read_b128 v[180:183], v140 offset:2048
	ds_read_b128 v[184:187], v140 offset:3072
	s_add_u32 s34, s46, 0x40000
	s_addc_u32 s35, s47, 0
	s_mov_b32 m0, s55
	v_lshl_add_u64 v[228:229], s[34:35], 0, v[132:133]
	ds_read_b128 v[188:191], v159 offset:32768
	ds_read_b128 v[192:195], v159 offset:33792
	ds_read_b128 v[196:199], v159 offset:34816
	ds_read_b128 v[200:203], v159 offset:35840
	ds_read_b128 v[204:207], v159 offset:36864
	ds_read_b128 v[208:211], v159 offset:37888
	ds_read_b128 v[212:215], v159 offset:38912
	ds_read_b128 v[216:219], v159 offset:39936
	global_load_lds_dwordx4 v[228:229], off
	v_lshl_add_u64 v[228:229], s[34:35], 0, v[136:137]
	s_mov_b32 m0, s56
	s_nop 0
	global_load_lds_dwordx4 v[228:229], off
	s_waitcnt vmcnt(8)
	s_waitcnt lgkmcnt(0)
	s_barrier
	s_setprio 1
	s_waitcnt lgkmcnt(0)
	v_mfma_f32_16x16x32_bf16 v[124:127], v[150:153], v[188:191], v[124:127]
	v_mfma_f32_16x16x32_bf16 v[120:123], v[164:167], v[188:191], v[120:123]
	v_mfma_f32_16x16x32_bf16 v[108:111], v[150:153], v[196:199], v[108:111]
	v_mfma_f32_16x16x32_bf16 v[104:107], v[164:167], v[196:199], v[104:107]
	v_mfma_f32_16x16x32_bf16 v[92:95], v[150:153], v[204:207], v[92:95]
	v_mfma_f32_16x16x32_bf16 v[88:91], v[164:167], v[204:207], v[88:91]
	v_mfma_f32_16x16x32_bf16 v[76:79], v[150:153], v[212:215], v[76:79]
	v_mfma_f32_16x16x32_bf16 v[72:75], v[164:167], v[212:215], v[72:75]
	v_mfma_f32_16x16x32_bf16 v[124:127], v[160:163], v[192:195], v[124:127]
	v_mfma_f32_16x16x32_bf16 v[120:123], v[168:171], v[192:195], v[120:123]
	v_mfma_f32_16x16x32_bf16 v[108:111], v[160:163], v[200:203], v[108:111]
	v_mfma_f32_16x16x32_bf16 v[104:107], v[168:171], v[200:203], v[104:107]
	v_mfma_f32_16x16x32_bf16 v[92:95], v[160:163], v[208:211], v[92:95]
	v_mfma_f32_16x16x32_bf16 v[88:91], v[168:171], v[208:211], v[88:91]
	v_mfma_f32_16x16x32_bf16 v[76:79], v[160:163], v[216:219], v[76:79]
	v_mfma_f32_16x16x32_bf16 v[72:75], v[168:171], v[216:219], v[72:75]
	s_setprio 0
	s_setprio 1
	v_mfma_f32_16x16x32_bf16 v[116:119], v[172:175], v[188:191], v[116:119]
	v_mfma_f32_16x16x32_bf16 v[112:115], v[180:183], v[188:191], v[112:115]
	v_mfma_f32_16x16x32_bf16 v[100:103], v[172:175], v[196:199], v[100:103]
	v_mfma_f32_16x16x32_bf16 v[96:99], v[180:183], v[196:199], v[96:99]
	v_mfma_f32_16x16x32_bf16 v[84:87], v[172:175], v[204:207], v[84:87]
	v_mfma_f32_16x16x32_bf16 v[80:83], v[180:183], v[204:207], v[80:83]
	v_mfma_f32_16x16x32_bf16 v[68:71], v[172:175], v[212:215], v[68:71]
	v_mfma_f32_16x16x32_bf16 v[64:67], v[180:183], v[212:215], v[64:67]
	v_mfma_f32_16x16x32_bf16 v[116:119], v[176:179], v[192:195], v[116:119]
	v_mfma_f32_16x16x32_bf16 v[112:115], v[184:187], v[192:195], v[112:115]
	v_mfma_f32_16x16x32_bf16 v[100:103], v[176:179], v[200:203], v[100:103]
	v_mfma_f32_16x16x32_bf16 v[96:99], v[184:187], v[200:203], v[96:99]
	v_mfma_f32_16x16x32_bf16 v[84:87], v[176:179], v[208:211], v[84:87]
	v_mfma_f32_16x16x32_bf16 v[80:83], v[184:187], v[208:211], v[80:83]
	v_mfma_f32_16x16x32_bf16 v[68:71], v[176:179], v[216:219], v[68:71]
	v_mfma_f32_16x16x32_bf16 v[64:67], v[184:187], v[216:219], v[64:67]
	s_setprio 0
	s_barrier
	s_add_i32 s34, s66, s50
	v_lshl_add_u64 v[220:221], v[220:221], 0, s[26:27]
	s_mov_b32 m0, s34
	ds_read_b128 v[188:191], v159 offset:49152
	ds_read_b128 v[192:195], v159 offset:50176
	ds_read_b128 v[196:199], v159 offset:51200
	ds_read_b128 v[200:203], v159 offset:52224
	ds_read_b128 v[204:207], v159 offset:53248
	ds_read_b128 v[208:211], v159 offset:54272
	ds_read_b128 v[212:215], v159 offset:55296
	ds_read_b128 v[216:219], v159 offset:56320
	global_load_lds_dwordx4 v[220:221], off
	s_add_i32 m0, s34, 0x2000
	s_add_u32 s34, s44, 0x40080
	v_lshl_add_u64 v[220:221], v[222:223], 0, s[26:27]
	s_addc_u32 s35, s45, 0
	s_add_i32 s44, s67, s50
	global_load_lds_dwordx4 v[220:221], off
	v_lshl_add_u64 v[220:221], s[34:35], 0, v[134:135]
	s_mov_b32 m0, s44
	s_nop 0
	global_load_lds_dwordx4 v[220:221], off
	v_lshl_add_u64 v[220:221], s[34:35], 0, v[138:139]
	s_add_i32 m0, s44, 0x2000
	s_nop 0
	global_load_lds_dwordx4 v[220:221], off
	v_lshl_add_u64 v[220:221], v[224:225], 0, s[26:27]
	s_mov_b32 m0, s58
	s_nop 0
	global_load_lds_dwordx4 v[220:221], off
	v_lshl_add_u64 v[220:221], v[226:227], 0, s[26:27]
	s_mov_b32 m0, s59
	s_nop 0
	global_load_lds_dwordx4 v[220:221], off
	s_waitcnt vmcnt(8)
	s_waitcnt lgkmcnt(0)
	s_barrier
	s_add_u32 s42, s42, 0x100
	s_addc_u32 s43, s43, 0
	s_add_u32 s31, s31, 0x100
	s_addc_u32 s37, s37, 0
	s_setprio 1
	s_waitcnt lgkmcnt(0)
	v_mfma_f32_16x16x32_bf16 v[60:63], v[150:153], v[188:191], v[60:63]
	v_mfma_f32_16x16x32_bf16 v[56:59], v[164:167], v[188:191], v[56:59]
	v_mfma_f32_16x16x32_bf16 v[44:47], v[150:153], v[196:199], v[44:47]
	v_mfma_f32_16x16x32_bf16 v[40:43], v[164:167], v[196:199], v[40:43]
	v_mfma_f32_16x16x32_bf16 v[28:31], v[150:153], v[204:207], v[28:31]
	v_mfma_f32_16x16x32_bf16 v[24:27], v[164:167], v[204:207], v[24:27]
	v_mfma_f32_16x16x32_bf16 v[12:15], v[150:153], v[212:215], v[12:15]
	v_mfma_f32_16x16x32_bf16 v[8:11], v[164:167], v[212:215], v[8:11]
	v_mfma_f32_16x16x32_bf16 v[60:63], v[160:163], v[192:195], v[60:63]
	v_mfma_f32_16x16x32_bf16 v[56:59], v[168:171], v[192:195], v[56:59]
	v_mfma_f32_16x16x32_bf16 v[44:47], v[160:163], v[200:203], v[44:47]
	v_mfma_f32_16x16x32_bf16 v[40:43], v[168:171], v[200:203], v[40:43]
	v_mfma_f32_16x16x32_bf16 v[28:31], v[160:163], v[208:211], v[28:31]
	v_mfma_f32_16x16x32_bf16 v[24:27], v[168:171], v[208:211], v[24:27]
	v_mfma_f32_16x16x32_bf16 v[12:15], v[160:163], v[216:219], v[12:15]
	v_mfma_f32_16x16x32_bf16 v[8:11], v[168:171], v[216:219], v[8:11]
	s_setprio 0
	s_setprio 1
	v_mfma_f32_16x16x32_bf16 v[52:55], v[172:175], v[188:191], v[52:55]
	v_mfma_f32_16x16x32_bf16 v[48:51], v[180:183], v[188:191], v[48:51]
	v_mfma_f32_16x16x32_bf16 v[36:39], v[172:175], v[196:199], v[36:39]
	v_mfma_f32_16x16x32_bf16 v[32:35], v[180:183], v[196:199], v[32:35]
	v_mfma_f32_16x16x32_bf16 v[20:23], v[172:175], v[204:207], v[20:23]
	v_mfma_f32_16x16x32_bf16 v[16:19], v[180:183], v[204:207], v[16:19]
	v_mfma_f32_16x16x32_bf16 v[4:7], v[172:175], v[212:215], v[4:7]
	v_mfma_f32_16x16x32_bf16 v[0:3], v[180:183], v[212:215], v[0:3]
	v_mfma_f32_16x16x32_bf16 v[52:55], v[176:179], v[192:195], v[52:55]
	v_mfma_f32_16x16x32_bf16 v[48:51], v[184:187], v[192:195], v[48:51]
	v_mfma_f32_16x16x32_bf16 v[36:39], v[176:179], v[200:203], v[36:39]
	v_mfma_f32_16x16x32_bf16 v[32:35], v[184:187], v[200:203], v[32:35]
	v_mfma_f32_16x16x32_bf16 v[20:23], v[176:179], v[208:211], v[20:23]
	v_mfma_f32_16x16x32_bf16 v[16:19], v[184:187], v[208:211], v[16:19]
	v_mfma_f32_16x16x32_bf16 v[4:7], v[176:179], v[216:219], v[4:7]
	v_mfma_f32_16x16x32_bf16 v[0:3], v[184:187], v[216:219], v[0:3]
	s_setprio 0
	s_add_i32 s65, s65, 2
.LBB0_1826:
	s_barrier
	ds_read_b128 v[150:153], v157
	ds_read_b128 v[160:163], v157 offset:1024
	ds_read_b128 v[164:167], v157 offset:2048
	ds_read_b128 v[168:171], v157 offset:3072
	ds_read_b128 v[172:175], v158
	ds_read_b128 v[176:179], v158 offset:1024
	ds_read_b128 v[180:183], v158 offset:2048
	ds_read_b128 v[184:187], v158 offset:3072
	s_add_u32 s34, s42, 0xfffc0080
	s_addc_u32 s35, s43, -1
	s_cmp_eq_u32 s65, 12
	s_cselect_b32 s47, s7, s35
	s_cselect_b32 s46, s8, s34
	s_cselect_b32 s45, s12, s37
	s_cselect_b32 s44, s13, s31
	v_lshl_add_u64 v[220:221], s[42:43], 0, v[142:143]
	s_add_i32 m0, s53, 0xc000
	ds_read_b128 v[188:191], v159
	ds_read_b128 v[192:195], v159 offset:1024
	ds_read_b128 v[196:199], v159 offset:2048
	ds_read_b128 v[200:203], v159 offset:3072
	ds_read_b128 v[204:207], v159 offset:4096
	ds_read_b128 v[208:211], v159 offset:5120
	ds_read_b128 v[212:215], v159 offset:6144
	ds_read_b128 v[216:219], v159 offset:7168
	global_load_lds_dwordx4 v[220:221], off
	v_lshl_add_u64 v[220:221], s[42:43], 0, v[144:145]
	s_add_i32 m0, s53, 0xe000
	s_nop 0
	global_load_lds_dwordx4 v[220:221], off
	s_waitcnt vmcnt(8)
	s_waitcnt lgkmcnt(0)
	s_barrier
	s_setprio 1
	s_waitcnt lgkmcnt(0)
	v_mfma_f32_16x16x32_bf16 v[124:127], v[150:153], v[188:191], v[124:127]
	v_mfma_f32_16x16x32_bf16 v[120:123], v[164:167], v[188:191], v[120:123]
	v_mfma_f32_16x16x32_bf16 v[108:111], v[150:153], v[196:199], v[108:111]
	v_mfma_f32_16x16x32_bf16 v[104:107], v[164:167], v[196:199], v[104:107]
	v_mfma_f32_16x16x32_bf16 v[92:95], v[150:153], v[204:207], v[92:95]
	v_mfma_f32_16x16x32_bf16 v[88:91], v[164:167], v[204:207], v[88:91]
	v_mfma_f32_16x16x32_bf16 v[76:79], v[150:153], v[212:215], v[76:79]
	v_mfma_f32_16x16x32_bf16 v[72:75], v[164:167], v[212:215], v[72:75]
	v_mfma_f32_16x16x32_bf16 v[124:127], v[160:163], v[192:195], v[124:127]
	v_mfma_f32_16x16x32_bf16 v[120:123], v[168:171], v[192:195], v[120:123]
	v_mfma_f32_16x16x32_bf16 v[108:111], v[160:163], v[200:203], v[108:111]
	v_mfma_f32_16x16x32_bf16 v[104:107], v[168:171], v[200:203], v[104:107]
	v_mfma_f32_16x16x32_bf16 v[92:95], v[160:163], v[208:211], v[92:95]
	v_mfma_f32_16x16x32_bf16 v[88:91], v[168:171], v[208:211], v[88:91]
	v_mfma_f32_16x16x32_bf16 v[76:79], v[160:163], v[216:219], v[76:79]
	v_mfma_f32_16x16x32_bf16 v[72:75], v[168:171], v[216:219], v[72:75]
	s_setprio 0
	s_setprio 1
	v_mfma_f32_16x16x32_bf16 v[116:119], v[172:175], v[188:191], v[116:119]
	v_mfma_f32_16x16x32_bf16 v[112:115], v[180:183], v[188:191], v[112:115]
	v_mfma_f32_16x16x32_bf16 v[100:103], v[172:175], v[196:199], v[100:103]
	v_mfma_f32_16x16x32_bf16 v[96:99], v[180:183], v[196:199], v[96:99]
	v_mfma_f32_16x16x32_bf16 v[84:87], v[172:175], v[204:207], v[84:87]
	v_mfma_f32_16x16x32_bf16 v[80:83], v[180:183], v[204:207], v[80:83]
	v_mfma_f32_16x16x32_bf16 v[68:71], v[172:175], v[212:215], v[68:71]
	v_mfma_f32_16x16x32_bf16 v[64:67], v[180:183], v[212:215], v[64:67]
	v_mfma_f32_16x16x32_bf16 v[116:119], v[176:179], v[192:195], v[116:119]
	v_mfma_f32_16x16x32_bf16 v[112:115], v[184:187], v[192:195], v[112:115]
	v_mfma_f32_16x16x32_bf16 v[100:103], v[176:179], v[200:203], v[100:103]
	v_mfma_f32_16x16x32_bf16 v[96:99], v[184:187], v[200:203], v[96:99]
	v_mfma_f32_16x16x32_bf16 v[84:87], v[176:179], v[208:211], v[84:87]
	v_mfma_f32_16x16x32_bf16 v[80:83], v[184:187], v[208:211], v[80:83]
	v_mfma_f32_16x16x32_bf16 v[68:71], v[176:179], v[216:219], v[68:71]
	v_mfma_f32_16x16x32_bf16 v[64:67], v[184:187], v[216:219], v[64:67]
	s_setprio 0
	s_barrier
	s_add_i32 s34, s61, s50
	v_lshl_add_u64 v[220:221], s[44:45], 0, v[134:135]
	s_mov_b32 m0, s34
	ds_read_b128 v[188:191], v159 offset:16384
	ds_read_b128 v[192:195], v159 offset:17408
	ds_read_b128 v[196:199], v159 offset:18432
	ds_read_b128 v[200:203], v159 offset:19456
	ds_read_b128 v[204:207], v159 offset:20480
	ds_read_b128 v[208:211], v159 offset:21504
	ds_read_b128 v[212:215], v159 offset:22528
	ds_read_b128 v[216:219], v159 offset:23552
	global_load_lds_dwordx4 v[220:221], off
	s_add_i32 m0, s34, 0x2000
	s_add_u32 s34, s44, 0x40000
	v_lshl_add_u64 v[222:223], s[44:45], 0, v[138:139]
	s_addc_u32 s35, s45, 0
	s_add_i32 s66, s62, s50
	global_load_lds_dwordx4 v[222:223], off
	v_lshl_add_u64 v[224:225], s[34:35], 0, v[134:135]
	s_mov_b32 m0, s66
	v_lshl_add_u64 v[226:227], s[46:47], 0, v[136:137]
	global_load_lds_dwordx4 v[224:225], off
	v_lshl_add_u64 v[224:225], s[34:35], 0, v[138:139]
	s_add_i32 m0, s66, 0x2000
	s_nop 0
	global_load_lds_dwordx4 v[224:225], off
	v_lshl_add_u64 v[224:225], s[46:47], 0, v[132:133]
	s_mov_b32 m0, s53
	s_nop 0
	global_load_lds_dwordx4 v[224:225], off
	s_mov_b32 m0, s54
	s_nop 0
	global_load_lds_dwordx4 v[226:227], off
	s_waitcnt vmcnt(8)
	s_waitcnt lgkmcnt(0)
	s_barrier
	s_setprio 1
	s_waitcnt lgkmcnt(0)
	v_mfma_f32_16x16x32_bf16 v[60:63], v[150:153], v[188:191], v[60:63]
	v_mfma_f32_16x16x32_bf16 v[56:59], v[164:167], v[188:191], v[56:59]
	v_mfma_f32_16x16x32_bf16 v[44:47], v[150:153], v[196:199], v[44:47]
	v_mfma_f32_16x16x32_bf16 v[40:43], v[164:167], v[196:199], v[40:43]
	v_mfma_f32_16x16x32_bf16 v[28:31], v[150:153], v[204:207], v[28:31]
	v_mfma_f32_16x16x32_bf16 v[24:27], v[164:167], v[204:207], v[24:27]
	v_mfma_f32_16x16x32_bf16 v[12:15], v[150:153], v[212:215], v[12:15]
	v_mfma_f32_16x16x32_bf16 v[8:11], v[164:167], v[212:215], v[8:11]
	v_mfma_f32_16x16x32_bf16 v[60:63], v[160:163], v[192:195], v[60:63]
	v_mfma_f32_16x16x32_bf16 v[56:59], v[168:171], v[192:195], v[56:59]
	v_mfma_f32_16x16x32_bf16 v[44:47], v[160:163], v[200:203], v[44:47]
	v_mfma_f32_16x16x32_bf16 v[40:43], v[168:171], v[200:203], v[40:43]
	v_mfma_f32_16x16x32_bf16 v[28:31], v[160:163], v[208:211], v[28:31]
	v_mfma_f32_16x16x32_bf16 v[24:27], v[168:171], v[208:211], v[24:27]
	v_mfma_f32_16x16x32_bf16 v[12:15], v[160:163], v[216:219], v[12:15]
	v_mfma_f32_16x16x32_bf16 v[8:11], v[168:171], v[216:219], v[8:11]
	s_setprio 0
	s_setprio 1
	v_mfma_f32_16x16x32_bf16 v[52:55], v[172:175], v[188:191], v[52:55]
	v_mfma_f32_16x16x32_bf16 v[48:51], v[180:183], v[188:191], v[48:51]
	v_mfma_f32_16x16x32_bf16 v[36:39], v[172:175], v[196:199], v[36:39]
	v_mfma_f32_16x16x32_bf16 v[32:35], v[180:183], v[196:199], v[32:35]
	v_mfma_f32_16x16x32_bf16 v[20:23], v[172:175], v[204:207], v[20:23]
	v_mfma_f32_16x16x32_bf16 v[16:19], v[180:183], v[204:207], v[16:19]
	v_mfma_f32_16x16x32_bf16 v[4:7], v[172:175], v[212:215], v[4:7]
	v_mfma_f32_16x16x32_bf16 v[0:3], v[180:183], v[212:215], v[0:3]
	v_mfma_f32_16x16x32_bf16 v[52:55], v[176:179], v[192:195], v[52:55]
	v_mfma_f32_16x16x32_bf16 v[48:51], v[184:187], v[192:195], v[48:51]
	v_mfma_f32_16x16x32_bf16 v[36:39], v[176:179], v[200:203], v[36:39]
	v_mfma_f32_16x16x32_bf16 v[32:35], v[184:187], v[200:203], v[32:35]
	v_mfma_f32_16x16x32_bf16 v[20:23], v[176:179], v[208:211], v[20:23]
	v_mfma_f32_16x16x32_bf16 v[16:19], v[184:187], v[208:211], v[16:19]
	v_mfma_f32_16x16x32_bf16 v[4:7], v[176:179], v[216:219], v[4:7]
	v_mfma_f32_16x16x32_bf16 v[0:3], v[184:187], v[216:219], v[0:3]
	s_setprio 0
	s_barrier
	s_add_i32 s66, 0, 0x18000
	v_add_u32_e32 v140, s66, v154
	s_add_i32 s67, 0, 0x1c000
	ds_read_b128 v[150:153], v140
	ds_read_b128 v[160:163], v140 offset:1024
	ds_read_b128 v[164:167], v140 offset:2048
	ds_read_b128 v[168:171], v140 offset:3072
	v_add_u32_e32 v140, s67, v154
	ds_read_b128 v[172:175], v140
	ds_read_b128 v[176:179], v140 offset:1024
	ds_read_b128 v[180:183], v140 offset:2048
	ds_read_b128 v[184:187], v140 offset:3072
	s_add_u32 s34, s46, 0x40000
	s_addc_u32 s35, s47, 0
	s_mov_b32 m0, s55
	v_lshl_add_u64 v[228:229], s[34:35], 0, v[132:133]
	ds_read_b128 v[188:191], v159 offset:32768
	ds_read_b128 v[192:195], v159 offset:33792
	ds_read_b128 v[196:199], v159 offset:34816
	ds_read_b128 v[200:203], v159 offset:35840
	ds_read_b128 v[204:207], v159 offset:36864
	ds_read_b128 v[208:211], v159 offset:37888
	ds_read_b128 v[212:215], v159 offset:38912
	ds_read_b128 v[216:219], v159 offset:39936
	global_load_lds_dwordx4 v[228:229], off
	v_lshl_add_u64 v[228:229], s[34:35], 0, v[136:137]
	s_mov_b32 m0, s56
	s_nop 0
	global_load_lds_dwordx4 v[228:229], off
	s_waitcnt vmcnt(8)
	s_waitcnt lgkmcnt(0)
	s_barrier
	s_setprio 1
	s_waitcnt lgkmcnt(0)
	v_mfma_f32_16x16x32_bf16 v[124:127], v[150:153], v[188:191], v[124:127]
	v_mfma_f32_16x16x32_bf16 v[120:123], v[164:167], v[188:191], v[120:123]
	v_mfma_f32_16x16x32_bf16 v[108:111], v[150:153], v[196:199], v[108:111]
	v_mfma_f32_16x16x32_bf16 v[104:107], v[164:167], v[196:199], v[104:107]
	v_mfma_f32_16x16x32_bf16 v[92:95], v[150:153], v[204:207], v[92:95]
	v_mfma_f32_16x16x32_bf16 v[88:91], v[164:167], v[204:207], v[88:91]
	v_mfma_f32_16x16x32_bf16 v[76:79], v[150:153], v[212:215], v[76:79]
	v_mfma_f32_16x16x32_bf16 v[72:75], v[164:167], v[212:215], v[72:75]
	v_mfma_f32_16x16x32_bf16 v[124:127], v[160:163], v[192:195], v[124:127]
	v_mfma_f32_16x16x32_bf16 v[120:123], v[168:171], v[192:195], v[120:123]
	v_mfma_f32_16x16x32_bf16 v[108:111], v[160:163], v[200:203], v[108:111]
	v_mfma_f32_16x16x32_bf16 v[104:107], v[168:171], v[200:203], v[104:107]
	v_mfma_f32_16x16x32_bf16 v[92:95], v[160:163], v[208:211], v[92:95]
	v_mfma_f32_16x16x32_bf16 v[88:91], v[168:171], v[208:211], v[88:91]
	v_mfma_f32_16x16x32_bf16 v[76:79], v[160:163], v[216:219], v[76:79]
	v_mfma_f32_16x16x32_bf16 v[72:75], v[168:171], v[216:219], v[72:75]
	s_setprio 0
	s_setprio 1
	v_mfma_f32_16x16x32_bf16 v[116:119], v[172:175], v[188:191], v[116:119]
	v_mfma_f32_16x16x32_bf16 v[112:115], v[180:183], v[188:191], v[112:115]
	v_mfma_f32_16x16x32_bf16 v[100:103], v[172:175], v[196:199], v[100:103]
	v_mfma_f32_16x16x32_bf16 v[96:99], v[180:183], v[196:199], v[96:99]
	v_mfma_f32_16x16x32_bf16 v[84:87], v[172:175], v[204:207], v[84:87]
	v_mfma_f32_16x16x32_bf16 v[80:83], v[180:183], v[204:207], v[80:83]
	v_mfma_f32_16x16x32_bf16 v[68:71], v[172:175], v[212:215], v[68:71]
	v_mfma_f32_16x16x32_bf16 v[64:67], v[180:183], v[212:215], v[64:67]
	v_mfma_f32_16x16x32_bf16 v[116:119], v[176:179], v[192:195], v[116:119]
	v_mfma_f32_16x16x32_bf16 v[112:115], v[184:187], v[192:195], v[112:115]
	v_mfma_f32_16x16x32_bf16 v[100:103], v[176:179], v[200:203], v[100:103]
	v_mfma_f32_16x16x32_bf16 v[96:99], v[184:187], v[200:203], v[96:99]
	v_mfma_f32_16x16x32_bf16 v[84:87], v[176:179], v[208:211], v[84:87]
	v_mfma_f32_16x16x32_bf16 v[80:83], v[184:187], v[208:211], v[80:83]
	v_mfma_f32_16x16x32_bf16 v[68:71], v[176:179], v[216:219], v[68:71]
	v_mfma_f32_16x16x32_bf16 v[64:67], v[184:187], v[216:219], v[64:67]
	s_setprio 0
	s_barrier
	s_add_i32 s34, s66, s50
	v_lshl_add_u64 v[220:221], v[220:221], 0, s[26:27]
	s_mov_b32 m0, s34
	ds_read_b128 v[188:191], v159 offset:49152
	ds_read_b128 v[192:195], v159 offset:50176
	ds_read_b128 v[196:199], v159 offset:51200
	ds_read_b128 v[200:203], v159 offset:52224
	ds_read_b128 v[204:207], v159 offset:53248
	ds_read_b128 v[208:211], v159 offset:54272
	ds_read_b128 v[212:215], v159 offset:55296
	ds_read_b128 v[216:219], v159 offset:56320
	global_load_lds_dwordx4 v[220:221], off
	s_add_i32 m0, s34, 0x2000
	s_add_u32 s34, s44, 0x40080
	v_lshl_add_u64 v[220:221], v[222:223], 0, s[26:27]
	s_addc_u32 s35, s45, 0
	s_add_i32 s44, s67, s50
	global_load_lds_dwordx4 v[220:221], off
	v_lshl_add_u64 v[220:221], s[34:35], 0, v[134:135]
	s_mov_b32 m0, s44
	s_nop 0
	global_load_lds_dwordx4 v[220:221], off
	v_lshl_add_u64 v[220:221], s[34:35], 0, v[138:139]
	s_add_i32 m0, s44, 0x2000
	s_nop 0
	global_load_lds_dwordx4 v[220:221], off
	v_lshl_add_u64 v[220:221], v[224:225], 0, s[26:27]
	s_mov_b32 m0, s58
	s_nop 0
	global_load_lds_dwordx4 v[220:221], off
	v_lshl_add_u64 v[220:221], v[226:227], 0, s[26:27]
	s_mov_b32 m0, s59
	s_nop 0
	global_load_lds_dwordx4 v[220:221], off
	s_waitcnt vmcnt(8)
	s_waitcnt lgkmcnt(0)
	s_barrier
	s_add_u32 s42, s42, 0x100
	s_addc_u32 s43, s43, 0
	s_add_u32 s31, s31, 0x100
	s_addc_u32 s37, s37, 0
	s_setprio 1
	s_waitcnt lgkmcnt(0)
	v_mfma_f32_16x16x32_bf16 v[60:63], v[150:153], v[188:191], v[60:63]
	v_mfma_f32_16x16x32_bf16 v[56:59], v[164:167], v[188:191], v[56:59]
	v_mfma_f32_16x16x32_bf16 v[44:47], v[150:153], v[196:199], v[44:47]
	v_mfma_f32_16x16x32_bf16 v[40:43], v[164:167], v[196:199], v[40:43]
	v_mfma_f32_16x16x32_bf16 v[28:31], v[150:153], v[204:207], v[28:31]
	v_mfma_f32_16x16x32_bf16 v[24:27], v[164:167], v[204:207], v[24:27]
	v_mfma_f32_16x16x32_bf16 v[12:15], v[150:153], v[212:215], v[12:15]
	v_mfma_f32_16x16x32_bf16 v[8:11], v[164:167], v[212:215], v[8:11]
	v_mfma_f32_16x16x32_bf16 v[60:63], v[160:163], v[192:195], v[60:63]
	v_mfma_f32_16x16x32_bf16 v[56:59], v[168:171], v[192:195], v[56:59]
	v_mfma_f32_16x16x32_bf16 v[44:47], v[160:163], v[200:203], v[44:47]
	v_mfma_f32_16x16x32_bf16 v[40:43], v[168:171], v[200:203], v[40:43]
	v_mfma_f32_16x16x32_bf16 v[28:31], v[160:163], v[208:211], v[28:31]
	v_mfma_f32_16x16x32_bf16 v[24:27], v[168:171], v[208:211], v[24:27]
	v_mfma_f32_16x16x32_bf16 v[12:15], v[160:163], v[216:219], v[12:15]
	v_mfma_f32_16x16x32_bf16 v[8:11], v[168:171], v[216:219], v[8:11]
	s_setprio 0
	s_setprio 1
	v_mfma_f32_16x16x32_bf16 v[52:55], v[172:175], v[188:191], v[52:55]
	v_mfma_f32_16x16x32_bf16 v[48:51], v[180:183], v[188:191], v[48:51]
	v_mfma_f32_16x16x32_bf16 v[36:39], v[172:175], v[196:199], v[36:39]
	v_mfma_f32_16x16x32_bf16 v[32:35], v[180:183], v[196:199], v[32:35]
	v_mfma_f32_16x16x32_bf16 v[20:23], v[172:175], v[204:207], v[20:23]
	v_mfma_f32_16x16x32_bf16 v[16:19], v[180:183], v[204:207], v[16:19]
	v_mfma_f32_16x16x32_bf16 v[4:7], v[172:175], v[212:215], v[4:7]
	v_mfma_f32_16x16x32_bf16 v[0:3], v[180:183], v[212:215], v[0:3]
	v_mfma_f32_16x16x32_bf16 v[52:55], v[176:179], v[192:195], v[52:55]
	v_mfma_f32_16x16x32_bf16 v[48:51], v[184:187], v[192:195], v[48:51]
	v_mfma_f32_16x16x32_bf16 v[36:39], v[176:179], v[200:203], v[36:39]
	v_mfma_f32_16x16x32_bf16 v[32:35], v[184:187], v[200:203], v[32:35]
	v_mfma_f32_16x16x32_bf16 v[20:23], v[176:179], v[208:211], v[20:23]
	v_mfma_f32_16x16x32_bf16 v[16:19], v[184:187], v[208:211], v[16:19]
	v_mfma_f32_16x16x32_bf16 v[4:7], v[176:179], v[216:219], v[4:7]
	v_mfma_f32_16x16x32_bf16 v[0:3], v[184:187], v[216:219], v[0:3]
	s_setprio 0
	s_add_i32 s65, s65, 2
	s_cmp_gt_u32 s65, 13
	s_cbranch_scc0 .LBB0_1826
	s_sub_i32 s100, s65, 2
	s_cmp_eq_u32 s100, s98
	s_cbranch_scc1 .Lmy_nobar_19
	s_barrier

.Lmy_nobar2_21:
	ds_read_b128 v[146:149], v153
	ds_read_b128 v[158:161], v153 offset:1024
	ds_read_b128 v[162:165], v153 offset:2048
	ds_read_b128 v[166:169], v153 offset:3072
	ds_read_b128 v[170:173], v154
	ds_read_b128 v[174:177], v154 offset:1024
	ds_read_b128 v[178:181], v154 offset:2048
	ds_read_b128 v[182:185], v154 offset:3072
	s_add_u32 s34, s38, 0xfffc0080
	s_addc_u32 s35, s39, -1
	s_cmp_eq_u32 s60, 12
	s_cselect_b32 s43, s12, s35
	s_cselect_b32 s42, s13, s34
	s_cselect_b32 s41, s25, s59
	s_cselect_b32 s40, s27, s37
	v_lshl_add_u64 v[218:219], s[38:39], 0, v[138:139]
	s_add_i32 m0, s46, 0xc000
	ds_read_b128 v[186:189], v155
	ds_read_b128 v[190:193], v155 offset:1024
	ds_read_b128 v[194:197], v155 offset:2048
	ds_read_b128 v[198:201], v155 offset:3072
	ds_read_b128 v[202:205], v155 offset:4096
	ds_read_b128 v[206:209], v155 offset:5120
	ds_read_b128 v[210:213], v155 offset:6144
	ds_read_b128 v[214:217], v155 offset:7168
	global_load_lds_dwordx4 v[218:219], off
	v_lshl_add_u64 v[218:219], s[38:39], 0, v[140:141]
	s_add_i32 m0, s46, 0xe000
	s_nop 0
	global_load_lds_dwordx4 v[218:219], off
	s_waitcnt vmcnt(8)
	s_waitcnt lgkmcnt(0)
	s_barrier
	s_setprio 1
	s_waitcnt lgkmcnt(0)
	v_mfma_f32_16x16x32_bf16 v[124:127], v[146:149], v[186:189], 0
	v_mfma_f32_16x16x32_bf16 v[120:123], v[162:165], v[186:189], 0
	v_mfma_f32_16x16x32_bf16 v[108:111], v[146:149], v[194:197], 0
	v_mfma_f32_16x16x32_bf16 v[104:107], v[162:165], v[194:197], 0
	v_mfma_f32_16x16x32_bf16 v[92:95], v[146:149], v[202:205], 0
	v_mfma_f32_16x16x32_bf16 v[88:91], v[162:165], v[202:205], 0
	v_mfma_f32_16x16x32_bf16 v[76:79], v[146:149], v[210:213], 0
	v_mfma_f32_16x16x32_bf16 v[72:75], v[162:165], v[210:213], 0
	v_mfma_f32_16x16x32_bf16 v[124:127], v[158:161], v[190:193], v[124:127]
	v_mfma_f32_16x16x32_bf16 v[120:123], v[166:169], v[190:193], v[120:123]
	v_mfma_f32_16x16x32_bf16 v[108:111], v[158:161], v[198:201], v[108:111]
	v_mfma_f32_16x16x32_bf16 v[104:107], v[166:169], v[198:201], v[104:107]
	v_mfma_f32_16x16x32_bf16 v[92:95], v[158:161], v[206:209], v[92:95]
	v_mfma_f32_16x16x32_bf16 v[88:91], v[166:169], v[206:209], v[88:91]
	v_mfma_f32_16x16x32_bf16 v[76:79], v[158:161], v[214:217], v[76:79]
	v_mfma_f32_16x16x32_bf16 v[72:75], v[166:169], v[214:217], v[72:75]
	s_setprio 0
	s_setprio 1
	v_mfma_f32_16x16x32_bf16 v[116:119], v[170:173], v[186:189], 0
	v_mfma_f32_16x16x32_bf16 v[112:115], v[178:181], v[186:189], 0
	v_mfma_f32_16x16x32_bf16 v[100:103], v[170:173], v[194:197], 0
	v_mfma_f32_16x16x32_bf16 v[96:99], v[178:181], v[194:197], 0
	v_mfma_f32_16x16x32_bf16 v[84:87], v[170:173], v[202:205], 0
	v_mfma_f32_16x16x32_bf16 v[80:83], v[178:181], v[202:205], 0
	v_mfma_f32_16x16x32_bf16 v[68:71], v[170:173], v[210:213], 0
	v_mfma_f32_16x16x32_bf16 v[64:67], v[178:181], v[210:213], 0
	v_mfma_f32_16x16x32_bf16 v[116:119], v[174:177], v[190:193], v[116:119]
	v_mfma_f32_16x16x32_bf16 v[112:115], v[182:185], v[190:193], v[112:115]
	v_mfma_f32_16x16x32_bf16 v[100:103], v[174:177], v[198:201], v[100:103]
	v_mfma_f32_16x16x32_bf16 v[96:99], v[182:185], v[198:201], v[96:99]
	v_mfma_f32_16x16x32_bf16 v[84:87], v[174:177], v[206:209], v[84:87]
	v_mfma_f32_16x16x32_bf16 v[80:83], v[182:185], v[206:209], v[80:83]
	v_mfma_f32_16x16x32_bf16 v[68:71], v[174:177], v[214:217], v[68:71]
	v_mfma_f32_16x16x32_bf16 v[64:67], v[182:185], v[214:217], v[64:67]
	s_setprio 0
	s_barrier
	s_add_i32 s34, s56, s45
	v_lshl_add_u64 v[218:219], s[40:41], 0, v[132:133]
	s_mov_b32 m0, s34
	ds_read_b128 v[186:189], v155 offset:16384
	ds_read_b128 v[190:193], v155 offset:17408
	ds_read_b128 v[194:197], v155 offset:18432
	ds_read_b128 v[198:201], v155 offset:19456
	ds_read_b128 v[202:205], v155 offset:20480
	ds_read_b128 v[206:209], v155 offset:21504
	ds_read_b128 v[210:213], v155 offset:22528
	ds_read_b128 v[214:217], v155 offset:23552
	global_load_lds_dwordx4 v[218:219], off
	s_add_i32 m0, s34, 0x2000
	s_add_u32 s34, s40, 0x40000
	v_lshl_add_u64 v[220:221], s[40:41], 0, v[136:137]
	s_addc_u32 s35, s41, 0
	s_add_i32 s61, s57, s45
	global_load_lds_dwordx4 v[220:221], off
	v_lshl_add_u64 v[222:223], s[34:35], 0, v[132:133]
	s_mov_b32 m0, s61
	v_lshl_add_u64 v[224:225], s[42:43], 0, v[134:135]
	global_load_lds_dwordx4 v[222:223], off
	v_lshl_add_u64 v[222:223], s[34:35], 0, v[136:137]
	s_add_i32 m0, s61, 0x2000
	s_nop 0
	global_load_lds_dwordx4 v[222:223], off
	v_lshl_add_u64 v[222:223], s[42:43], 0, v[130:131]
	s_mov_b32 m0, s46
	s_nop 0
	global_load_lds_dwordx4 v[222:223], off
	s_mov_b32 m0, s47
	s_nop 0
	global_load_lds_dwordx4 v[224:225], off
	s_waitcnt vmcnt(8)
	s_waitcnt lgkmcnt(0)
	s_barrier
	s_setprio 1
	s_waitcnt lgkmcnt(0)
	v_mfma_f32_16x16x32_bf16 v[60:63], v[146:149], v[186:189], 0
	v_mfma_f32_16x16x32_bf16 v[56:59], v[162:165], v[186:189], 0
	v_mfma_f32_16x16x32_bf16 v[44:47], v[146:149], v[194:197], 0
	v_mfma_f32_16x16x32_bf16 v[40:43], v[162:165], v[194:197], 0
	v_mfma_f32_16x16x32_bf16 v[28:31], v[146:149], v[202:205], 0
	v_mfma_f32_16x16x32_bf16 v[24:27], v[162:165], v[202:205], 0
	v_mfma_f32_16x16x32_bf16 v[12:15], v[146:149], v[210:213], 0
	v_mfma_f32_16x16x32_bf16 v[8:11], v[162:165], v[210:213], 0
	v_mfma_f32_16x16x32_bf16 v[60:63], v[158:161], v[190:193], v[60:63]
	v_mfma_f32_16x16x32_bf16 v[56:59], v[166:169], v[190:193], v[56:59]
	v_mfma_f32_16x16x32_bf16 v[44:47], v[158:161], v[198:201], v[44:47]
	v_mfma_f32_16x16x32_bf16 v[40:43], v[166:169], v[198:201], v[40:43]
	v_mfma_f32_16x16x32_bf16 v[28:31], v[158:161], v[206:209], v[28:31]
	v_mfma_f32_16x16x32_bf16 v[24:27], v[166:169], v[206:209], v[24:27]
	v_mfma_f32_16x16x32_bf16 v[12:15], v[158:161], v[214:217], v[12:15]
	v_mfma_f32_16x16x32_bf16 v[8:11], v[166:169], v[214:217], v[8:11]
	s_setprio 0
	s_setprio 1
	v_mfma_f32_16x16x32_bf16 v[52:55], v[170:173], v[186:189], 0
	v_mfma_f32_16x16x32_bf16 v[48:51], v[178:181], v[186:189], 0
	v_mfma_f32_16x16x32_bf16 v[36:39], v[170:173], v[194:197], 0
	v_mfma_f32_16x16x32_bf16 v[32:35], v[178:181], v[194:197], 0
	v_mfma_f32_16x16x32_bf16 v[20:23], v[170:173], v[202:205], 0
	v_mfma_f32_16x16x32_bf16 v[16:19], v[178:181], v[202:205], 0
	v_mfma_f32_16x16x32_bf16 v[4:7], v[170:173], v[210:213], 0
	v_mfma_f32_16x16x32_bf16 v[0:3], v[178:181], v[210:213], 0
	v_mfma_f32_16x16x32_bf16 v[52:55], v[174:177], v[190:193], v[52:55]
	v_mfma_f32_16x16x32_bf16 v[48:51], v[182:185], v[190:193], v[48:51]
	v_mfma_f32_16x16x32_bf16 v[36:39], v[174:177], v[198:201], v[36:39]
	v_mfma_f32_16x16x32_bf16 v[32:35], v[182:185], v[198:201], v[32:35]
	v_mfma_f32_16x16x32_bf16 v[20:23], v[174:177], v[206:209], v[20:23]
	v_mfma_f32_16x16x32_bf16 v[16:19], v[182:185], v[206:209], v[16:19]
	v_mfma_f32_16x16x32_bf16 v[4:7], v[174:177], v[214:217], v[4:7]
	v_mfma_f32_16x16x32_bf16 v[0:3], v[182:185], v[214:217], v[0:3]
	s_setprio 0
	s_barrier
	s_add_i32 s61, 0, 0x18000
	v_add_u32_e32 v157, s61, v151
	s_add_i32 s62, 0, 0x1c000
	ds_read_b128 v[146:149], v157
	ds_read_b128 v[158:161], v157 offset:1024
	ds_read_b128 v[162:165], v157 offset:2048
	ds_read_b128 v[166:169], v157 offset:3072
	v_add_u32_e32 v157, s62, v151
	ds_read_b128 v[170:173], v157
	ds_read_b128 v[174:177], v157 offset:1024
	ds_read_b128 v[178:181], v157 offset:2048
	ds_read_b128 v[182:185], v157 offset:3072
	s_add_u32 s34, s42, 0x40000
	s_addc_u32 s35, s43, 0
	s_mov_b32 m0, s48
	v_lshl_add_u64 v[226:227], s[34:35], 0, v[130:131]
	ds_read_b128 v[186:189], v155 offset:32768
	ds_read_b128 v[190:193], v155 offset:33792
	ds_read_b128 v[194:197], v155 offset:34816
	ds_read_b128 v[198:201], v155 offset:35840
	ds_read_b128 v[202:205], v155 offset:36864
	ds_read_b128 v[206:209], v155 offset:37888
	ds_read_b128 v[210:213], v155 offset:38912
	ds_read_b128 v[214:217], v155 offset:39936
	global_load_lds_dwordx4 v[226:227], off
	v_lshl_add_u64 v[226:227], s[34:35], 0, v[134:135]
	s_mov_b32 m0, s49
	s_nop 0
	global_load_lds_dwordx4 v[226:227], off
	s_waitcnt vmcnt(8)
	s_waitcnt lgkmcnt(0)
	s_barrier
	s_setprio 1
	s_waitcnt lgkmcnt(0)
	v_mfma_f32_16x16x32_bf16 v[124:127], v[146:149], v[186:189], v[124:127]
	v_mfma_f32_16x16x32_bf16 v[120:123], v[162:165], v[186:189], v[120:123]
	v_mfma_f32_16x16x32_bf16 v[108:111], v[146:149], v[194:197], v[108:111]
	v_mfma_f32_16x16x32_bf16 v[104:107], v[162:165], v[194:197], v[104:107]
	v_mfma_f32_16x16x32_bf16 v[92:95], v[146:149], v[202:205], v[92:95]
	v_mfma_f32_16x16x32_bf16 v[88:91], v[162:165], v[202:205], v[88:91]
	v_mfma_f32_16x16x32_bf16 v[76:79], v[146:149], v[210:213], v[76:79]
	v_mfma_f32_16x16x32_bf16 v[72:75], v[162:165], v[210:213], v[72:75]
	v_mfma_f32_16x16x32_bf16 v[124:127], v[158:161], v[190:193], v[124:127]
	v_mfma_f32_16x16x32_bf16 v[120:123], v[166:169], v[190:193], v[120:123]
	v_mfma_f32_16x16x32_bf16 v[108:111], v[158:161], v[198:201], v[108:111]
	v_mfma_f32_16x16x32_bf16 v[104:107], v[166:169], v[198:201], v[104:107]
	v_mfma_f32_16x16x32_bf16 v[92:95], v[158:161], v[206:209], v[92:95]
	v_mfma_f32_16x16x32_bf16 v[88:91], v[166:169], v[206:209], v[88:91]
	v_mfma_f32_16x16x32_bf16 v[76:79], v[158:161], v[214:217], v[76:79]
	v_mfma_f32_16x16x32_bf16 v[72:75], v[166:169], v[214:217], v[72:75]
	s_setprio 0
	s_setprio 1
	v_mfma_f32_16x16x32_bf16 v[116:119], v[170:173], v[186:189], v[116:119]
	v_mfma_f32_16x16x32_bf16 v[112:115], v[178:181], v[186:189], v[112:115]
	v_mfma_f32_16x16x32_bf16 v[100:103], v[170:173], v[194:197], v[100:103]
	v_mfma_f32_16x16x32_bf16 v[96:99], v[178:181], v[194:197], v[96:99]
	v_mfma_f32_16x16x32_bf16 v[84:87], v[170:173], v[202:205], v[84:87]
	v_mfma_f32_16x16x32_bf16 v[80:83], v[178:181], v[202:205], v[80:83]
	v_mfma_f32_16x16x32_bf16 v[68:71], v[170:173], v[210:213], v[68:71]
	v_mfma_f32_16x16x32_bf16 v[64:67], v[178:181], v[210:213], v[64:67]
	v_mfma_f32_16x16x32_bf16 v[116:119], v[174:177], v[190:193], v[116:119]
	v_mfma_f32_16x16x32_bf16 v[112:115], v[182:185], v[190:193], v[112:115]
	v_mfma_f32_16x16x32_bf16 v[100:103], v[174:177], v[198:201], v[100:103]
	v_mfma_f32_16x16x32_bf16 v[96:99], v[182:185], v[198:201], v[96:99]
	v_mfma_f32_16x16x32_bf16 v[84:87], v[174:177], v[206:209], v[84:87]
	v_mfma_f32_16x16x32_bf16 v[80:83], v[182:185], v[206:209], v[80:83]
	v_mfma_f32_16x16x32_bf16 v[68:71], v[174:177], v[214:217], v[68:71]
	v_mfma_f32_16x16x32_bf16 v[64:67], v[182:185], v[214:217], v[64:67]
	s_setprio 0
	s_barrier
	s_add_i32 s34, s61, s45
	v_lshl_add_u64 v[218:219], v[218:219], 0, s[10:11]
	s_mov_b32 m0, s34
	ds_read_b128 v[186:189], v155 offset:49152
	ds_read_b128 v[190:193], v155 offset:50176
	ds_read_b128 v[194:197], v155 offset:51200
	ds_read_b128 v[198:201], v155 offset:52224
	ds_read_b128 v[202:205], v155 offset:53248
	ds_read_b128 v[206:209], v155 offset:54272
	ds_read_b128 v[210:213], v155 offset:55296
	ds_read_b128 v[214:217], v155 offset:56320
	global_load_lds_dwordx4 v[218:219], off
	s_add_i32 m0, s34, 0x2000
	s_add_u32 s34, s40, 0x40080
	v_lshl_add_u64 v[218:219], v[220:221], 0, s[10:11]
	s_addc_u32 s35, s41, 0
	s_add_i32 s40, s62, s45
	global_load_lds_dwordx4 v[218:219], off
	v_lshl_add_u64 v[218:219], s[34:35], 0, v[132:133]
	s_mov_b32 m0, s40
	s_nop 0
	global_load_lds_dwordx4 v[218:219], off
	v_lshl_add_u64 v[218:219], s[34:35], 0, v[136:137]
	s_add_i32 m0, s40, 0x2000
	s_nop 0
	global_load_lds_dwordx4 v[218:219], off
	v_lshl_add_u64 v[218:219], v[222:223], 0, s[10:11]
	s_mov_b32 m0, s51
	s_nop 0
	global_load_lds_dwordx4 v[218:219], off
	v_lshl_add_u64 v[218:219], v[224:225], 0, s[10:11]
	s_mov_b32 m0, s52
	s_nop 0
	global_load_lds_dwordx4 v[218:219], off
	s_waitcnt vmcnt(8)
	s_waitcnt lgkmcnt(0)
	s_barrier
	s_add_u32 s38, s38, 0x100
	s_addc_u32 s39, s39, 0
	s_add_u32 s37, s37, 0x100
	s_addc_u32 s59, s59, 0
	s_setprio 1
	s_waitcnt lgkmcnt(0)
	v_mfma_f32_16x16x32_bf16 v[60:63], v[146:149], v[186:189], v[60:63]
	v_mfma_f32_16x16x32_bf16 v[56:59], v[162:165], v[186:189], v[56:59]
	v_mfma_f32_16x16x32_bf16 v[44:47], v[146:149], v[194:197], v[44:47]
	v_mfma_f32_16x16x32_bf16 v[40:43], v[162:165], v[194:197], v[40:43]
	v_mfma_f32_16x16x32_bf16 v[28:31], v[146:149], v[202:205], v[28:31]
	v_mfma_f32_16x16x32_bf16 v[24:27], v[162:165], v[202:205], v[24:27]
	v_mfma_f32_16x16x32_bf16 v[12:15], v[146:149], v[210:213], v[12:15]
	v_mfma_f32_16x16x32_bf16 v[8:11], v[162:165], v[210:213], v[8:11]
	v_mfma_f32_16x16x32_bf16 v[60:63], v[158:161], v[190:193], v[60:63]
	v_mfma_f32_16x16x32_bf16 v[56:59], v[166:169], v[190:193], v[56:59]
	v_mfma_f32_16x16x32_bf16 v[44:47], v[158:161], v[198:201], v[44:47]
	v_mfma_f32_16x16x32_bf16 v[40:43], v[166:169], v[198:201], v[40:43]
	v_mfma_f32_16x16x32_bf16 v[28:31], v[158:161], v[206:209], v[28:31]
	v_mfma_f32_16x16x32_bf16 v[24:27], v[166:169], v[206:209], v[24:27]
	v_mfma_f32_16x16x32_bf16 v[12:15], v[158:161], v[214:217], v[12:15]
	v_mfma_f32_16x16x32_bf16 v[8:11], v[166:169], v[214:217], v[8:11]
	s_setprio 0
	s_setprio 1
	v_mfma_f32_16x16x32_bf16 v[52:55], v[170:173], v[186:189], v[52:55]
	v_mfma_f32_16x16x32_bf16 v[48:51], v[178:181], v[186:189], v[48:51]
	v_mfma_f32_16x16x32_bf16 v[36:39], v[170:173], v[194:197], v[36:39]
	v_mfma_f32_16x16x32_bf16 v[32:35], v[178:181], v[194:197], v[32:35]
	v_mfma_f32_16x16x32_bf16 v[20:23], v[170:173], v[202:205], v[20:23]
	v_mfma_f32_16x16x32_bf16 v[16:19], v[178:181], v[202:205], v[16:19]
	v_mfma_f32_16x16x32_bf16 v[4:7], v[170:173], v[210:213], v[4:7]
	v_mfma_f32_16x16x32_bf16 v[0:3], v[178:181], v[210:213], v[0:3]
	v_mfma_f32_16x16x32_bf16 v[52:55], v[174:177], v[190:193], v[52:55]
	v_mfma_f32_16x16x32_bf16 v[48:51], v[182:185], v[190:193], v[48:51]
	v_mfma_f32_16x16x32_bf16 v[36:39], v[174:177], v[198:201], v[36:39]
	v_mfma_f32_16x16x32_bf16 v[32:35], v[182:185], v[198:201], v[32:35]
	v_mfma_f32_16x16x32_bf16 v[20:23], v[174:177], v[206:209], v[20:23]
	v_mfma_f32_16x16x32_bf16 v[16:19], v[182:185], v[206:209], v[16:19]
	v_mfma_f32_16x16x32_bf16 v[4:7], v[174:177], v[214:217], v[4:7]
	v_mfma_f32_16x16x32_bf16 v[0:3], v[182:185], v[214:217], v[0:3]
	s_setprio 0
	s_add_i32 s60, s60, 2
.LBB0_2001:
	s_barrier
	ds_read_b128 v[146:149], v153
	ds_read_b128 v[158:161], v153 offset:1024
	ds_read_b128 v[162:165], v153 offset:2048
	ds_read_b128 v[166:169], v153 offset:3072
	ds_read_b128 v[170:173], v154
	ds_read_b128 v[174:177], v154 offset:1024
	ds_read_b128 v[178:181], v154 offset:2048
	ds_read_b128 v[182:185], v154 offset:3072
	s_add_u32 s34, s38, 0xfffc0080
	s_addc_u32 s35, s39, -1
	s_cmp_eq_u32 s60, 12
	s_cselect_b32 s43, s12, s35
	s_cselect_b32 s42, s13, s34
	s_cselect_b32 s41, s25, s59
	s_cselect_b32 s40, s27, s37
	v_lshl_add_u64 v[218:219], s[38:39], 0, v[138:139]
	s_add_i32 m0, s46, 0xc000
	ds_read_b128 v[186:189], v155
	ds_read_b128 v[190:193], v155 offset:1024
	ds_read_b128 v[194:197], v155 offset:2048
	ds_read_b128 v[198:201], v155 offset:3072
	ds_read_b128 v[202:205], v155 offset:4096
	ds_read_b128 v[206:209], v155 offset:5120
	ds_read_b128 v[210:213], v155 offset:6144
	ds_read_b128 v[214:217], v155 offset:7168
	global_load_lds_dwordx4 v[218:219], off
	v_lshl_add_u64 v[218:219], s[38:39], 0, v[140:141]
	s_add_i32 m0, s46, 0xe000
	s_nop 0
	global_load_lds_dwordx4 v[218:219], off
	s_waitcnt vmcnt(8)
	s_waitcnt lgkmcnt(0)
	s_barrier
	s_setprio 1
	s_waitcnt lgkmcnt(0)
	v_mfma_f32_16x16x32_bf16 v[124:127], v[146:149], v[186:189], v[124:127]
	v_mfma_f32_16x16x32_bf16 v[120:123], v[162:165], v[186:189], v[120:123]
	v_mfma_f32_16x16x32_bf16 v[108:111], v[146:149], v[194:197], v[108:111]
	v_mfma_f32_16x16x32_bf16 v[104:107], v[162:165], v[194:197], v[104:107]
	v_mfma_f32_16x16x32_bf16 v[92:95], v[146:149], v[202:205], v[92:95]
	v_mfma_f32_16x16x32_bf16 v[88:91], v[162:165], v[202:205], v[88:91]
	v_mfma_f32_16x16x32_bf16 v[76:79], v[146:149], v[210:213], v[76:79]
	v_mfma_f32_16x16x32_bf16 v[72:75], v[162:165], v[210:213], v[72:75]
	v_mfma_f32_16x16x32_bf16 v[124:127], v[158:161], v[190:193], v[124:127]
	v_mfma_f32_16x16x32_bf16 v[120:123], v[166:169], v[190:193], v[120:123]
	v_mfma_f32_16x16x32_bf16 v[108:111], v[158:161], v[198:201], v[108:111]
	v_mfma_f32_16x16x32_bf16 v[104:107], v[166:169], v[198:201], v[104:107]
	v_mfma_f32_16x16x32_bf16 v[92:95], v[158:161], v[206:209], v[92:95]
	v_mfma_f32_16x16x32_bf16 v[88:91], v[166:169], v[206:209], v[88:91]
	v_mfma_f32_16x16x32_bf16 v[76:79], v[158:161], v[214:217], v[76:79]
	v_mfma_f32_16x16x32_bf16 v[72:75], v[166:169], v[214:217], v[72:75]
	s_setprio 0
	s_setprio 1
	v_mfma_f32_16x16x32_bf16 v[116:119], v[170:173], v[186:189], v[116:119]
	v_mfma_f32_16x16x32_bf16 v[112:115], v[178:181], v[186:189], v[112:115]
	v_mfma_f32_16x16x32_bf16 v[100:103], v[170:173], v[194:197], v[100:103]
	v_mfma_f32_16x16x32_bf16 v[96:99], v[178:181], v[194:197], v[96:99]
	v_mfma_f32_16x16x32_bf16 v[84:87], v[170:173], v[202:205], v[84:87]
	v_mfma_f32_16x16x32_bf16 v[80:83], v[178:181], v[202:205], v[80:83]
	v_mfma_f32_16x16x32_bf16 v[68:71], v[170:173], v[210:213], v[68:71]
	v_mfma_f32_16x16x32_bf16 v[64:67], v[178:181], v[210:213], v[64:67]
	v_mfma_f32_16x16x32_bf16 v[116:119], v[174:177], v[190:193], v[116:119]
	v_mfma_f32_16x16x32_bf16 v[112:115], v[182:185], v[190:193], v[112:115]
	v_mfma_f32_16x16x32_bf16 v[100:103], v[174:177], v[198:201], v[100:103]
	v_mfma_f32_16x16x32_bf16 v[96:99], v[182:185], v[198:201], v[96:99]
	v_mfma_f32_16x16x32_bf16 v[84:87], v[174:177], v[206:209], v[84:87]
	v_mfma_f32_16x16x32_bf16 v[80:83], v[182:185], v[206:209], v[80:83]
	v_mfma_f32_16x16x32_bf16 v[68:71], v[174:177], v[214:217], v[68:71]
	v_mfma_f32_16x16x32_bf16 v[64:67], v[182:185], v[214:217], v[64:67]
	s_setprio 0
	s_barrier
	s_add_i32 s34, s56, s45
	v_lshl_add_u64 v[218:219], s[40:41], 0, v[132:133]
	s_mov_b32 m0, s34
	ds_read_b128 v[186:189], v155 offset:16384
	ds_read_b128 v[190:193], v155 offset:17408
	ds_read_b128 v[194:197], v155 offset:18432
	ds_read_b128 v[198:201], v155 offset:19456
	ds_read_b128 v[202:205], v155 offset:20480
	ds_read_b128 v[206:209], v155 offset:21504
	ds_read_b128 v[210:213], v155 offset:22528
	ds_read_b128 v[214:217], v155 offset:23552
	global_load_lds_dwordx4 v[218:219], off
	s_add_i32 m0, s34, 0x2000
	s_add_u32 s34, s40, 0x40000
	v_lshl_add_u64 v[220:221], s[40:41], 0, v[136:137]
	s_addc_u32 s35, s41, 0
	s_add_i32 s61, s57, s45
	global_load_lds_dwordx4 v[220:221], off
	v_lshl_add_u64 v[222:223], s[34:35], 0, v[132:133]
	s_mov_b32 m0, s61
	v_lshl_add_u64 v[224:225], s[42:43], 0, v[134:135]
	global_load_lds_dwordx4 v[222:223], off
	v_lshl_add_u64 v[222:223], s[34:35], 0, v[136:137]
	s_add_i32 m0, s61, 0x2000
	s_nop 0
	global_load_lds_dwordx4 v[222:223], off
	v_lshl_add_u64 v[222:223], s[42:43], 0, v[130:131]
	s_mov_b32 m0, s46
	s_nop 0
	global_load_lds_dwordx4 v[222:223], off
	s_mov_b32 m0, s47
	s_nop 0
	global_load_lds_dwordx4 v[224:225], off
	s_waitcnt vmcnt(8)
	s_waitcnt lgkmcnt(0)
	s_barrier
	s_setprio 1
	s_waitcnt lgkmcnt(0)
	v_mfma_f32_16x16x32_bf16 v[60:63], v[146:149], v[186:189], v[60:63]
	v_mfma_f32_16x16x32_bf16 v[56:59], v[162:165], v[186:189], v[56:59]
	v_mfma_f32_16x16x32_bf16 v[44:47], v[146:149], v[194:197], v[44:47]
	v_mfma_f32_16x16x32_bf16 v[40:43], v[162:165], v[194:197], v[40:43]
	v_mfma_f32_16x16x32_bf16 v[28:31], v[146:149], v[202:205], v[28:31]
	v_mfma_f32_16x16x32_bf16 v[24:27], v[162:165], v[202:205], v[24:27]
	v_mfma_f32_16x16x32_bf16 v[12:15], v[146:149], v[210:213], v[12:15]
	v_mfma_f32_16x16x32_bf16 v[8:11], v[162:165], v[210:213], v[8:11]
	v_mfma_f32_16x16x32_bf16 v[60:63], v[158:161], v[190:193], v[60:63]
	v_mfma_f32_16x16x32_bf16 v[56:59], v[166:169], v[190:193], v[56:59]
	v_mfma_f32_16x16x32_bf16 v[44:47], v[158:161], v[198:201], v[44:47]
	v_mfma_f32_16x16x32_bf16 v[40:43], v[166:169], v[198:201], v[40:43]
	v_mfma_f32_16x16x32_bf16 v[28:31], v[158:161], v[206:209], v[28:31]
	v_mfma_f32_16x16x32_bf16 v[24:27], v[166:169], v[206:209], v[24:27]
	v_mfma_f32_16x16x32_bf16 v[12:15], v[158:161], v[214:217], v[12:15]
	v_mfma_f32_16x16x32_bf16 v[8:11], v[166:169], v[214:217], v[8:11]
	s_setprio 0
	s_setprio 1
	v_mfma_f32_16x16x32_bf16 v[52:55], v[170:173], v[186:189], v[52:55]
	v_mfma_f32_16x16x32_bf16 v[48:51], v[178:181], v[186:189], v[48:51]
	v_mfma_f32_16x16x32_bf16 v[36:39], v[170:173], v[194:197], v[36:39]
	v_mfma_f32_16x16x32_bf16 v[32:35], v[178:181], v[194:197], v[32:35]
	v_mfma_f32_16x16x32_bf16 v[20:23], v[170:173], v[202:205], v[20:23]
	v_mfma_f32_16x16x32_bf16 v[16:19], v[178:181], v[202:205], v[16:19]
	v_mfma_f32_16x16x32_bf16 v[4:7], v[170:173], v[210:213], v[4:7]
	v_mfma_f32_16x16x32_bf16 v[0:3], v[178:181], v[210:213], v[0:3]
	v_mfma_f32_16x16x32_bf16 v[52:55], v[174:177], v[190:193], v[52:55]
	v_mfma_f32_16x16x32_bf16 v[48:51], v[182:185], v[190:193], v[48:51]
	v_mfma_f32_16x16x32_bf16 v[36:39], v[174:177], v[198:201], v[36:39]
	v_mfma_f32_16x16x32_bf16 v[32:35], v[182:185], v[198:201], v[32:35]
	v_mfma_f32_16x16x32_bf16 v[20:23], v[174:177], v[206:209], v[20:23]
	v_mfma_f32_16x16x32_bf16 v[16:19], v[182:185], v[206:209], v[16:19]
	v_mfma_f32_16x16x32_bf16 v[4:7], v[174:177], v[214:217], v[4:7]
	v_mfma_f32_16x16x32_bf16 v[0:3], v[182:185], v[214:217], v[0:3]
	s_setprio 0
	s_barrier
	s_add_i32 s61, 0, 0x18000
	v_add_u32_e32 v157, s61, v151
	s_add_i32 s62, 0, 0x1c000
	ds_read_b128 v[146:149], v157
	ds_read_b128 v[158:161], v157 offset:1024
	ds_read_b128 v[162:165], v157 offset:2048
	ds_read_b128 v[166:169], v157 offset:3072
	v_add_u32_e32 v157, s62, v151
	ds_read_b128 v[170:173], v157
	ds_read_b128 v[174:177], v157 offset:1024
	ds_read_b128 v[178:181], v157 offset:2048
	ds_read_b128 v[182:185], v157 offset:3072
	s_add_u32 s34, s42, 0x40000
	s_addc_u32 s35, s43, 0
	s_mov_b32 m0, s48
	v_lshl_add_u64 v[226:227], s[34:35], 0, v[130:131]
	ds_read_b128 v[186:189], v155 offset:32768
	ds_read_b128 v[190:193], v155 offset:33792
	ds_read_b128 v[194:197], v155 offset:34816
	ds_read_b128 v[198:201], v155 offset:35840
	ds_read_b128 v[202:205], v155 offset:36864
	ds_read_b128 v[206:209], v155 offset:37888
	ds_read_b128 v[210:213], v155 offset:38912
	ds_read_b128 v[214:217], v155 offset:39936
	global_load_lds_dwordx4 v[226:227], off
	v_lshl_add_u64 v[226:227], s[34:35], 0, v[134:135]
	s_mov_b32 m0, s49
	s_nop 0
	global_load_lds_dwordx4 v[226:227], off
	s_waitcnt vmcnt(8)
	s_waitcnt lgkmcnt(0)
	s_barrier
	s_setprio 1
	s_waitcnt lgkmcnt(0)
	v_mfma_f32_16x16x32_bf16 v[124:127], v[146:149], v[186:189], v[124:127]
	v_mfma_f32_16x16x32_bf16 v[120:123], v[162:165], v[186:189], v[120:123]
	v_mfma_f32_16x16x32_bf16 v[108:111], v[146:149], v[194:197], v[108:111]
	v_mfma_f32_16x16x32_bf16 v[104:107], v[162:165], v[194:197], v[104:107]
	v_mfma_f32_16x16x32_bf16 v[92:95], v[146:149], v[202:205], v[92:95]
	v_mfma_f32_16x16x32_bf16 v[88:91], v[162:165], v[202:205], v[88:91]
	v_mfma_f32_16x16x32_bf16 v[76:79], v[146:149], v[210:213], v[76:79]
	v_mfma_f32_16x16x32_bf16 v[72:75], v[162:165], v[210:213], v[72:75]
	v_mfma_f32_16x16x32_bf16 v[124:127], v[158:161], v[190:193], v[124:127]
	v_mfma_f32_16x16x32_bf16 v[120:123], v[166:169], v[190:193], v[120:123]
	v_mfma_f32_16x16x32_bf16 v[108:111], v[158:161], v[198:201], v[108:111]
	v_mfma_f32_16x16x32_bf16 v[104:107], v[166:169], v[198:201], v[104:107]
	v_mfma_f32_16x16x32_bf16 v[92:95], v[158:161], v[206:209], v[92:95]
	v_mfma_f32_16x16x32_bf16 v[88:91], v[166:169], v[206:209], v[88:91]
	v_mfma_f32_16x16x32_bf16 v[76:79], v[158:161], v[214:217], v[76:79]
	v_mfma_f32_16x16x32_bf16 v[72:75], v[166:169], v[214:217], v[72:75]
	s_setprio 0
	s_setprio 1
	v_mfma_f32_16x16x32_bf16 v[116:119], v[170:173], v[186:189], v[116:119]
	v_mfma_f32_16x16x32_bf16 v[112:115], v[178:181], v[186:189], v[112:115]
	v_mfma_f32_16x16x32_bf16 v[100:103], v[170:173], v[194:197], v[100:103]
	v_mfma_f32_16x16x32_bf16 v[96:99], v[178:181], v[194:197], v[96:99]
	v_mfma_f32_16x16x32_bf16 v[84:87], v[170:173], v[202:205], v[84:87]
	v_mfma_f32_16x16x32_bf16 v[80:83], v[178:181], v[202:205], v[80:83]
	v_mfma_f32_16x16x32_bf16 v[68:71], v[170:173], v[210:213], v[68:71]
	v_mfma_f32_16x16x32_bf16 v[64:67], v[178:181], v[210:213], v[64:67]
	v_mfma_f32_16x16x32_bf16 v[116:119], v[174:177], v[190:193], v[116:119]
	v_mfma_f32_16x16x32_bf16 v[112:115], v[182:185], v[190:193], v[112:115]
	v_mfma_f32_16x16x32_bf16 v[100:103], v[174:177], v[198:201], v[100:103]
	v_mfma_f32_16x16x32_bf16 v[96:99], v[182:185], v[198:201], v[96:99]
	v_mfma_f32_16x16x32_bf16 v[84:87], v[174:177], v[206:209], v[84:87]
	v_mfma_f32_16x16x32_bf16 v[80:83], v[182:185], v[206:209], v[80:83]
	v_mfma_f32_16x16x32_bf16 v[68:71], v[174:177], v[214:217], v[68:71]
	v_mfma_f32_16x16x32_bf16 v[64:67], v[182:185], v[214:217], v[64:67]
	s_setprio 0
	s_barrier
	s_add_i32 s34, s61, s45
	v_lshl_add_u64 v[218:219], v[218:219], 0, s[10:11]
	s_mov_b32 m0, s34
	ds_read_b128 v[186:189], v155 offset:49152
	ds_read_b128 v[190:193], v155 offset:50176
	ds_read_b128 v[194:197], v155 offset:51200
	ds_read_b128 v[198:201], v155 offset:52224
	ds_read_b128 v[202:205], v155 offset:53248
	ds_read_b128 v[206:209], v155 offset:54272
	ds_read_b128 v[210:213], v155 offset:55296
	ds_read_b128 v[214:217], v155 offset:56320
	global_load_lds_dwordx4 v[218:219], off
	s_add_i32 m0, s34, 0x2000
	s_add_u32 s34, s40, 0x40080
	v_lshl_add_u64 v[218:219], v[220:221], 0, s[10:11]
	s_addc_u32 s35, s41, 0
	s_add_i32 s40, s62, s45
	global_load_lds_dwordx4 v[218:219], off
	v_lshl_add_u64 v[218:219], s[34:35], 0, v[132:133]
	s_mov_b32 m0, s40
	s_nop 0
	global_load_lds_dwordx4 v[218:219], off
	v_lshl_add_u64 v[218:219], s[34:35], 0, v[136:137]
	s_add_i32 m0, s40, 0x2000
	s_nop 0
	global_load_lds_dwordx4 v[218:219], off
	v_lshl_add_u64 v[218:219], v[222:223], 0, s[10:11]
	s_mov_b32 m0, s51
	s_nop 0
	global_load_lds_dwordx4 v[218:219], off
	v_lshl_add_u64 v[218:219], v[224:225], 0, s[10:11]
	s_mov_b32 m0, s52
	s_nop 0
	global_load_lds_dwordx4 v[218:219], off
	s_waitcnt vmcnt(8)
	s_waitcnt lgkmcnt(0)
	s_barrier
	s_add_u32 s38, s38, 0x100
	s_addc_u32 s39, s39, 0
	s_add_u32 s37, s37, 0x100
	s_addc_u32 s59, s59, 0
	s_setprio 1
	s_waitcnt lgkmcnt(0)
	v_mfma_f32_16x16x32_bf16 v[60:63], v[146:149], v[186:189], v[60:63]
	v_mfma_f32_16x16x32_bf16 v[56:59], v[162:165], v[186:189], v[56:59]
	v_mfma_f32_16x16x32_bf16 v[44:47], v[146:149], v[194:197], v[44:47]
	v_mfma_f32_16x16x32_bf16 v[40:43], v[162:165], v[194:197], v[40:43]
	v_mfma_f32_16x16x32_bf16 v[28:31], v[146:149], v[202:205], v[28:31]
	v_mfma_f32_16x16x32_bf16 v[24:27], v[162:165], v[202:205], v[24:27]
	v_mfma_f32_16x16x32_bf16 v[12:15], v[146:149], v[210:213], v[12:15]
	v_mfma_f32_16x16x32_bf16 v[8:11], v[162:165], v[210:213], v[8:11]
	v_mfma_f32_16x16x32_bf16 v[60:63], v[158:161], v[190:193], v[60:63]
	v_mfma_f32_16x16x32_bf16 v[56:59], v[166:169], v[190:193], v[56:59]
	v_mfma_f32_16x16x32_bf16 v[44:47], v[158:161], v[198:201], v[44:47]
	v_mfma_f32_16x16x32_bf16 v[40:43], v[166:169], v[198:201], v[40:43]
	v_mfma_f32_16x16x32_bf16 v[28:31], v[158:161], v[206:209], v[28:31]
	v_mfma_f32_16x16x32_bf16 v[24:27], v[166:169], v[206:209], v[24:27]
	v_mfma_f32_16x16x32_bf16 v[12:15], v[158:161], v[214:217], v[12:15]
	v_mfma_f32_16x16x32_bf16 v[8:11], v[166:169], v[214:217], v[8:11]
	s_setprio 0
	s_setprio 1
	v_mfma_f32_16x16x32_bf16 v[52:55], v[170:173], v[186:189], v[52:55]
	v_mfma_f32_16x16x32_bf16 v[48:51], v[178:181], v[186:189], v[48:51]
	v_mfma_f32_16x16x32_bf16 v[36:39], v[170:173], v[194:197], v[36:39]
	v_mfma_f32_16x16x32_bf16 v[32:35], v[178:181], v[194:197], v[32:35]
	v_mfma_f32_16x16x32_bf16 v[20:23], v[170:173], v[202:205], v[20:23]
	v_mfma_f32_16x16x32_bf16 v[16:19], v[178:181], v[202:205], v[16:19]
	v_mfma_f32_16x16x32_bf16 v[4:7], v[170:173], v[210:213], v[4:7]
	v_mfma_f32_16x16x32_bf16 v[0:3], v[178:181], v[210:213], v[0:3]
	v_mfma_f32_16x16x32_bf16 v[52:55], v[174:177], v[190:193], v[52:55]
	v_mfma_f32_16x16x32_bf16 v[48:51], v[182:185], v[190:193], v[48:51]
	v_mfma_f32_16x16x32_bf16 v[36:39], v[174:177], v[198:201], v[36:39]
	v_mfma_f32_16x16x32_bf16 v[32:35], v[182:185], v[198:201], v[32:35]
	v_mfma_f32_16x16x32_bf16 v[20:23], v[174:177], v[206:209], v[20:23]
	v_mfma_f32_16x16x32_bf16 v[16:19], v[182:185], v[206:209], v[16:19]
	v_mfma_f32_16x16x32_bf16 v[4:7], v[174:177], v[214:217], v[4:7]
	v_mfma_f32_16x16x32_bf16 v[0:3], v[182:185], v[214:217], v[0:3]
	s_setprio 0
	s_add_i32 s60, s60, 2
	s_cmp_gt_u32 s60, 13
	s_cbranch_scc0 .LBB0_2001
	s_sub_i32 s100, s60, 2
	s_cmp_eq_u32 s100, s98
	s_cbranch_scc1 .Lmy_nobar_21
	s_barrier

.Lmy_nobar2_22:
	ds_read_b128 v[146:149], v153
	ds_read_b128 v[156:159], v153 offset:1024
	ds_read_b128 v[160:163], v153 offset:2048
	ds_read_b128 v[164:167], v153 offset:3072
	ds_read_b128 v[168:171], v154
	ds_read_b128 v[172:175], v154 offset:1024
	ds_read_b128 v[176:179], v154 offset:2048
	ds_read_b128 v[180:183], v154 offset:3072
	s_add_u32 s28, s26, 0xfffc0080
	s_addc_u32 s29, s27, -1
	s_cmp_eq_u32 s56, 12
	s_cselect_b32 s31, s19, s29
	s_cselect_b32 s30, s52, s28
	s_cselect_b32 s29, s11, s55
	s_cselect_b32 s28, s53, s54
	v_lshl_add_u64 v[216:217], s[26:27], 0, v[138:139]
	s_add_i32 m0, s25, 0xc000
	ds_read_b128 v[184:187], v155
	ds_read_b128 v[188:191], v155 offset:1024
	ds_read_b128 v[192:195], v155 offset:2048
	ds_read_b128 v[196:199], v155 offset:3072
	ds_read_b128 v[200:203], v155 offset:4096
	ds_read_b128 v[204:207], v155 offset:5120
	ds_read_b128 v[208:211], v155 offset:6144
	ds_read_b128 v[212:215], v155 offset:7168
	global_load_lds_dwordx4 v[216:217], off
	v_lshl_add_u64 v[216:217], s[26:27], 0, v[140:141]
	s_add_i32 m0, s25, 0xe000
	s_nop 0
	global_load_lds_dwordx4 v[216:217], off
	s_waitcnt vmcnt(8)
	s_waitcnt lgkmcnt(0)
	s_barrier
	s_setprio 1
	s_waitcnt lgkmcnt(0)
	v_mfma_f32_16x16x32_bf16 v[124:127], v[146:149], v[184:187], 0
	v_mfma_f32_16x16x32_bf16 v[120:123], v[160:163], v[184:187], 0
	v_mfma_f32_16x16x32_bf16 v[108:111], v[146:149], v[192:195], 0
	v_mfma_f32_16x16x32_bf16 v[104:107], v[160:163], v[192:195], 0
	v_mfma_f32_16x16x32_bf16 v[92:95], v[146:149], v[200:203], 0
	v_mfma_f32_16x16x32_bf16 v[88:91], v[160:163], v[200:203], 0
	v_mfma_f32_16x16x32_bf16 v[76:79], v[146:149], v[208:211], 0
	v_mfma_f32_16x16x32_bf16 v[72:75], v[160:163], v[208:211], 0
	v_mfma_f32_16x16x32_bf16 v[124:127], v[156:159], v[188:191], v[124:127]
	v_mfma_f32_16x16x32_bf16 v[120:123], v[164:167], v[188:191], v[120:123]
	v_mfma_f32_16x16x32_bf16 v[108:111], v[156:159], v[196:199], v[108:111]
	v_mfma_f32_16x16x32_bf16 v[104:107], v[164:167], v[196:199], v[104:107]
	v_mfma_f32_16x16x32_bf16 v[92:95], v[156:159], v[204:207], v[92:95]
	v_mfma_f32_16x16x32_bf16 v[88:91], v[164:167], v[204:207], v[88:91]
	v_mfma_f32_16x16x32_bf16 v[76:79], v[156:159], v[212:215], v[76:79]
	v_mfma_f32_16x16x32_bf16 v[72:75], v[164:167], v[212:215], v[72:75]
	s_setprio 0
	s_setprio 1
	v_mfma_f32_16x16x32_bf16 v[116:119], v[168:171], v[184:187], 0
	v_mfma_f32_16x16x32_bf16 v[112:115], v[176:179], v[184:187], 0
	v_mfma_f32_16x16x32_bf16 v[100:103], v[168:171], v[192:195], 0
	v_mfma_f32_16x16x32_bf16 v[96:99], v[176:179], v[192:195], 0
	v_mfma_f32_16x16x32_bf16 v[84:87], v[168:171], v[200:203], 0
	v_mfma_f32_16x16x32_bf16 v[80:83], v[176:179], v[200:203], 0
	v_mfma_f32_16x16x32_bf16 v[68:71], v[168:171], v[208:211], 0
	v_mfma_f32_16x16x32_bf16 v[64:67], v[176:179], v[208:211], 0
	v_mfma_f32_16x16x32_bf16 v[116:119], v[172:175], v[188:191], v[116:119]
	v_mfma_f32_16x16x32_bf16 v[112:115], v[180:183], v[188:191], v[112:115]
	v_mfma_f32_16x16x32_bf16 v[100:103], v[172:175], v[196:199], v[100:103]
	v_mfma_f32_16x16x32_bf16 v[96:99], v[180:183], v[196:199], v[96:99]
	v_mfma_f32_16x16x32_bf16 v[84:87], v[172:175], v[204:207], v[84:87]
	v_mfma_f32_16x16x32_bf16 v[80:83], v[180:183], v[204:207], v[80:83]
	v_mfma_f32_16x16x32_bf16 v[68:71], v[172:175], v[212:215], v[68:71]
	v_mfma_f32_16x16x32_bf16 v[64:67], v[180:183], v[212:215], v[64:67]
	s_setprio 0
	s_barrier
	s_add_i32 s34, s47, s38
	v_lshl_add_u64 v[216:217], s[28:29], 0, v[134:135]
	s_mov_b32 m0, s34
	ds_read_b128 v[184:187], v155 offset:16384
	ds_read_b128 v[188:191], v155 offset:17408
	ds_read_b128 v[192:195], v155 offset:18432
	ds_read_b128 v[196:199], v155 offset:19456
	ds_read_b128 v[200:203], v155 offset:20480
	ds_read_b128 v[204:207], v155 offset:21504
	ds_read_b128 v[208:211], v155 offset:22528
	ds_read_b128 v[212:215], v155 offset:23552
	global_load_lds_dwordx4 v[216:217], off
	s_add_i32 m0, s34, 0x2000
	s_add_u32 s34, s28, 0x40000
	v_lshl_add_u64 v[218:219], s[28:29], 0, v[130:131]
	s_addc_u32 s35, s29, 0
	s_add_i32 s57, s48, s38
	global_load_lds_dwordx4 v[218:219], off
	v_lshl_add_u64 v[220:221], s[34:35], 0, v[134:135]
	s_mov_b32 m0, s57
	v_lshl_add_u64 v[222:223], s[30:31], 0, v[132:133]
	global_load_lds_dwordx4 v[220:221], off
	v_lshl_add_u64 v[220:221], s[34:35], 0, v[130:131]
	s_add_i32 m0, s57, 0x2000
	s_nop 0
	global_load_lds_dwordx4 v[220:221], off
	v_lshl_add_u64 v[220:221], s[30:31], 0, v[136:137]
	s_mov_b32 m0, s25
	s_nop 0
	global_load_lds_dwordx4 v[220:221], off
	s_mov_b32 m0, s42
	s_nop 0
	global_load_lds_dwordx4 v[222:223], off
	s_waitcnt vmcnt(8)
	s_waitcnt lgkmcnt(0)
	s_barrier
	s_setprio 1
	s_waitcnt lgkmcnt(0)
	v_mfma_f32_16x16x32_bf16 v[60:63], v[146:149], v[184:187], 0
	v_mfma_f32_16x16x32_bf16 v[56:59], v[160:163], v[184:187], 0
	v_mfma_f32_16x16x32_bf16 v[44:47], v[146:149], v[192:195], 0
	v_mfma_f32_16x16x32_bf16 v[40:43], v[160:163], v[192:195], 0
	v_mfma_f32_16x16x32_bf16 v[28:31], v[146:149], v[200:203], 0
	v_mfma_f32_16x16x32_bf16 v[24:27], v[160:163], v[200:203], 0
	v_mfma_f32_16x16x32_bf16 v[12:15], v[146:149], v[208:211], 0
	v_mfma_f32_16x16x32_bf16 v[8:11], v[160:163], v[208:211], 0
	v_mfma_f32_16x16x32_bf16 v[60:63], v[156:159], v[188:191], v[60:63]
	v_mfma_f32_16x16x32_bf16 v[56:59], v[164:167], v[188:191], v[56:59]
	v_mfma_f32_16x16x32_bf16 v[44:47], v[156:159], v[196:199], v[44:47]
	v_mfma_f32_16x16x32_bf16 v[40:43], v[164:167], v[196:199], v[40:43]
	v_mfma_f32_16x16x32_bf16 v[28:31], v[156:159], v[204:207], v[28:31]
	v_mfma_f32_16x16x32_bf16 v[24:27], v[164:167], v[204:207], v[24:27]
	v_mfma_f32_16x16x32_bf16 v[12:15], v[156:159], v[212:215], v[12:15]
	v_mfma_f32_16x16x32_bf16 v[8:11], v[164:167], v[212:215], v[8:11]
	s_setprio 0
	s_setprio 1
	v_mfma_f32_16x16x32_bf16 v[52:55], v[168:171], v[184:187], 0
	v_mfma_f32_16x16x32_bf16 v[48:51], v[176:179], v[184:187], 0
	v_mfma_f32_16x16x32_bf16 v[36:39], v[168:171], v[192:195], 0
	v_mfma_f32_16x16x32_bf16 v[32:35], v[176:179], v[192:195], 0
	v_mfma_f32_16x16x32_bf16 v[20:23], v[168:171], v[200:203], 0
	v_mfma_f32_16x16x32_bf16 v[16:19], v[176:179], v[200:203], 0
	v_mfma_f32_16x16x32_bf16 v[4:7], v[168:171], v[208:211], 0
	v_mfma_f32_16x16x32_bf16 v[0:3], v[176:179], v[208:211], 0
	v_mfma_f32_16x16x32_bf16 v[52:55], v[172:175], v[188:191], v[52:55]
	v_mfma_f32_16x16x32_bf16 v[48:51], v[180:183], v[188:191], v[48:51]
	v_mfma_f32_16x16x32_bf16 v[36:39], v[172:175], v[196:199], v[36:39]
	v_mfma_f32_16x16x32_bf16 v[32:35], v[180:183], v[196:199], v[32:35]
	v_mfma_f32_16x16x32_bf16 v[20:23], v[172:175], v[204:207], v[20:23]
	v_mfma_f32_16x16x32_bf16 v[16:19], v[180:183], v[204:207], v[16:19]
	v_mfma_f32_16x16x32_bf16 v[4:7], v[172:175], v[212:215], v[4:7]
	v_mfma_f32_16x16x32_bf16 v[0:3], v[180:183], v[212:215], v[0:3]
	s_setprio 0
	s_barrier
	s_add_i32 s34, 0, 0x18000
	s_add_i32 s35, 0, 0x1c000
	v_add_u32_e32 v164, s34, v150
	v_add_u32_e32 v180, s35, v150
	ds_read_b128 v[146:149], v164
	ds_read_b128 v[156:159], v164 offset:1024
	ds_read_b128 v[160:163], v164 offset:2048
	ds_read_b128 v[164:167], v164 offset:3072
	ds_read_b128 v[168:171], v180
	ds_read_b128 v[172:175], v180 offset:1024
	ds_read_b128 v[176:179], v180 offset:2048
	ds_read_b128 v[180:183], v180 offset:3072
	s_add_u32 s30, s30, 0x40000
	s_addc_u32 s31, s31, 0
	s_mov_b32 m0, s43
	v_lshl_add_u64 v[224:225], s[30:31], 0, v[136:137]
	ds_read_b128 v[184:187], v155 offset:32768
	ds_read_b128 v[188:191], v155 offset:33792
	ds_read_b128 v[192:195], v155 offset:34816
	ds_read_b128 v[196:199], v155 offset:35840
	ds_read_b128 v[200:203], v155 offset:36864
	ds_read_b128 v[204:207], v155 offset:37888
	ds_read_b128 v[208:211], v155 offset:38912
	ds_read_b128 v[212:215], v155 offset:39936
	global_load_lds_dwordx4 v[224:225], off
	v_lshl_add_u64 v[224:225], s[30:31], 0, v[132:133]
	s_mov_b32 m0, s44
	s_nop 0
	global_load_lds_dwordx4 v[224:225], off
	s_waitcnt vmcnt(8)
	s_waitcnt lgkmcnt(0)
	s_barrier
	s_setprio 1
	s_waitcnt lgkmcnt(0)
	v_mfma_f32_16x16x32_bf16 v[124:127], v[146:149], v[184:187], v[124:127]
	v_mfma_f32_16x16x32_bf16 v[120:123], v[160:163], v[184:187], v[120:123]
	v_mfma_f32_16x16x32_bf16 v[108:111], v[146:149], v[192:195], v[108:111]
	v_mfma_f32_16x16x32_bf16 v[104:107], v[160:163], v[192:195], v[104:107]
	v_mfma_f32_16x16x32_bf16 v[92:95], v[146:149], v[200:203], v[92:95]
	v_mfma_f32_16x16x32_bf16 v[88:91], v[160:163], v[200:203], v[88:91]
	v_mfma_f32_16x16x32_bf16 v[76:79], v[146:149], v[208:211], v[76:79]
	v_mfma_f32_16x16x32_bf16 v[72:75], v[160:163], v[208:211], v[72:75]
	v_mfma_f32_16x16x32_bf16 v[124:127], v[156:159], v[188:191], v[124:127]
	v_mfma_f32_16x16x32_bf16 v[120:123], v[164:167], v[188:191], v[120:123]
	v_mfma_f32_16x16x32_bf16 v[108:111], v[156:159], v[196:199], v[108:111]
	v_mfma_f32_16x16x32_bf16 v[104:107], v[164:167], v[196:199], v[104:107]
	v_mfma_f32_16x16x32_bf16 v[92:95], v[156:159], v[204:207], v[92:95]
	v_mfma_f32_16x16x32_bf16 v[88:91], v[164:167], v[204:207], v[88:91]
	v_mfma_f32_16x16x32_bf16 v[76:79], v[156:159], v[212:215], v[76:79]
	v_mfma_f32_16x16x32_bf16 v[72:75], v[164:167], v[212:215], v[72:75]
	s_setprio 0
	s_setprio 1
	v_mfma_f32_16x16x32_bf16 v[116:119], v[168:171], v[184:187], v[116:119]
	v_mfma_f32_16x16x32_bf16 v[112:115], v[176:179], v[184:187], v[112:115]
	v_mfma_f32_16x16x32_bf16 v[100:103], v[168:171], v[192:195], v[100:103]
	v_mfma_f32_16x16x32_bf16 v[96:99], v[176:179], v[192:195], v[96:99]
	v_mfma_f32_16x16x32_bf16 v[84:87], v[168:171], v[200:203], v[84:87]
	v_mfma_f32_16x16x32_bf16 v[80:83], v[176:179], v[200:203], v[80:83]
	v_mfma_f32_16x16x32_bf16 v[68:71], v[168:171], v[208:211], v[68:71]
	v_mfma_f32_16x16x32_bf16 v[64:67], v[176:179], v[208:211], v[64:67]
	v_mfma_f32_16x16x32_bf16 v[116:119], v[172:175], v[188:191], v[116:119]
	v_mfma_f32_16x16x32_bf16 v[112:115], v[180:183], v[188:191], v[112:115]
	v_mfma_f32_16x16x32_bf16 v[100:103], v[172:175], v[196:199], v[100:103]
	v_mfma_f32_16x16x32_bf16 v[96:99], v[180:183], v[196:199], v[96:99]
	v_mfma_f32_16x16x32_bf16 v[84:87], v[172:175], v[204:207], v[84:87]
	v_mfma_f32_16x16x32_bf16 v[80:83], v[180:183], v[204:207], v[80:83]
	v_mfma_f32_16x16x32_bf16 v[68:71], v[172:175], v[212:215], v[68:71]
	v_mfma_f32_16x16x32_bf16 v[64:67], v[180:183], v[212:215], v[64:67]
	s_setprio 0
	s_barrier
	s_add_i32 s30, s34, s38
	v_lshl_add_u64 v[216:217], v[216:217], 0, s[6:7]
	s_mov_b32 m0, s30
	ds_read_b128 v[184:187], v155 offset:49152
	ds_read_b128 v[188:191], v155 offset:50176
	ds_read_b128 v[192:195], v155 offset:51200
	ds_read_b128 v[196:199], v155 offset:52224
	ds_read_b128 v[200:203], v155 offset:53248
	ds_read_b128 v[204:207], v155 offset:54272
	ds_read_b128 v[208:211], v155 offset:55296
	ds_read_b128 v[212:215], v155 offset:56320
	global_load_lds_dwordx4 v[216:217], off
	s_add_i32 m0, s30, 0x2000
	s_add_u32 s28, s28, 0x40080
	v_lshl_add_u64 v[216:217], v[218:219], 0, s[6:7]
	s_addc_u32 s29, s29, 0
	s_add_i32 s30, s35, s38
	global_load_lds_dwordx4 v[216:217], off
	v_lshl_add_u64 v[216:217], s[28:29], 0, v[134:135]
	s_mov_b32 m0, s30
	s_nop 0
	global_load_lds_dwordx4 v[216:217], off
	v_lshl_add_u64 v[216:217], s[28:29], 0, v[130:131]
	s_add_i32 m0, s30, 0x2000
	s_nop 0
	global_load_lds_dwordx4 v[216:217], off
	v_lshl_add_u64 v[216:217], v[220:221], 0, s[6:7]
	s_mov_b32 m0, s45
	s_nop 0
	global_load_lds_dwordx4 v[216:217], off
	v_lshl_add_u64 v[216:217], v[222:223], 0, s[6:7]
	s_mov_b32 m0, s46
	s_nop 0
	global_load_lds_dwordx4 v[216:217], off
	s_waitcnt vmcnt(8)
	s_waitcnt lgkmcnt(0)
	s_barrier
	s_add_u32 s26, s26, 0x100
	s_addc_u32 s27, s27, 0
	s_add_u32 s54, s54, 0x100
	s_addc_u32 s55, s55, 0
	s_setprio 1
	s_waitcnt lgkmcnt(0)
	v_mfma_f32_16x16x32_bf16 v[60:63], v[146:149], v[184:187], v[60:63]
	v_mfma_f32_16x16x32_bf16 v[56:59], v[160:163], v[184:187], v[56:59]
	v_mfma_f32_16x16x32_bf16 v[44:47], v[146:149], v[192:195], v[44:47]
	v_mfma_f32_16x16x32_bf16 v[40:43], v[160:163], v[192:195], v[40:43]
	v_mfma_f32_16x16x32_bf16 v[28:31], v[146:149], v[200:203], v[28:31]
	v_mfma_f32_16x16x32_bf16 v[24:27], v[160:163], v[200:203], v[24:27]
	v_mfma_f32_16x16x32_bf16 v[12:15], v[146:149], v[208:211], v[12:15]
	v_mfma_f32_16x16x32_bf16 v[8:11], v[160:163], v[208:211], v[8:11]
	v_mfma_f32_16x16x32_bf16 v[60:63], v[156:159], v[188:191], v[60:63]
	v_mfma_f32_16x16x32_bf16 v[56:59], v[164:167], v[188:191], v[56:59]
	v_mfma_f32_16x16x32_bf16 v[44:47], v[156:159], v[196:199], v[44:47]
	v_mfma_f32_16x16x32_bf16 v[40:43], v[164:167], v[196:199], v[40:43]
	v_mfma_f32_16x16x32_bf16 v[28:31], v[156:159], v[204:207], v[28:31]
	v_mfma_f32_16x16x32_bf16 v[24:27], v[164:167], v[204:207], v[24:27]
	v_mfma_f32_16x16x32_bf16 v[12:15], v[156:159], v[212:215], v[12:15]
	v_mfma_f32_16x16x32_bf16 v[8:11], v[164:167], v[212:215], v[8:11]
	s_setprio 0
	s_setprio 1
	v_mfma_f32_16x16x32_bf16 v[52:55], v[168:171], v[184:187], v[52:55]
	v_mfma_f32_16x16x32_bf16 v[48:51], v[176:179], v[184:187], v[48:51]
	v_mfma_f32_16x16x32_bf16 v[36:39], v[168:171], v[192:195], v[36:39]
	v_mfma_f32_16x16x32_bf16 v[32:35], v[176:179], v[192:195], v[32:35]
	v_mfma_f32_16x16x32_bf16 v[20:23], v[168:171], v[200:203], v[20:23]
	v_mfma_f32_16x16x32_bf16 v[16:19], v[176:179], v[200:203], v[16:19]
	v_mfma_f32_16x16x32_bf16 v[4:7], v[168:171], v[208:211], v[4:7]
	v_mfma_f32_16x16x32_bf16 v[0:3], v[176:179], v[208:211], v[0:3]
	v_mfma_f32_16x16x32_bf16 v[52:55], v[172:175], v[188:191], v[52:55]
	v_mfma_f32_16x16x32_bf16 v[48:51], v[180:183], v[188:191], v[48:51]
	v_mfma_f32_16x16x32_bf16 v[36:39], v[172:175], v[196:199], v[36:39]
	v_mfma_f32_16x16x32_bf16 v[32:35], v[180:183], v[196:199], v[32:35]
	v_mfma_f32_16x16x32_bf16 v[20:23], v[172:175], v[204:207], v[20:23]
	v_mfma_f32_16x16x32_bf16 v[16:19], v[180:183], v[204:207], v[16:19]
	v_mfma_f32_16x16x32_bf16 v[4:7], v[172:175], v[212:215], v[4:7]
	v_mfma_f32_16x16x32_bf16 v[0:3], v[180:183], v[212:215], v[0:3]
	s_setprio 0
	s_add_i32 s56, s56, 2
.LBB0_2091:
	s_barrier
	ds_read_b128 v[146:149], v153
	ds_read_b128 v[156:159], v153 offset:1024
	ds_read_b128 v[160:163], v153 offset:2048
	ds_read_b128 v[164:167], v153 offset:3072
	ds_read_b128 v[168:171], v154
	ds_read_b128 v[172:175], v154 offset:1024
	ds_read_b128 v[176:179], v154 offset:2048
	ds_read_b128 v[180:183], v154 offset:3072
	s_add_u32 s28, s26, 0xfffc0080
	s_addc_u32 s29, s27, -1
	s_cmp_eq_u32 s56, 12
	s_cselect_b32 s31, s19, s29
	s_cselect_b32 s30, s52, s28
	s_cselect_b32 s29, s11, s55
	s_cselect_b32 s28, s53, s54
	v_lshl_add_u64 v[216:217], s[26:27], 0, v[138:139]
	s_add_i32 m0, s25, 0xc000
	ds_read_b128 v[184:187], v155
	ds_read_b128 v[188:191], v155 offset:1024
	ds_read_b128 v[192:195], v155 offset:2048
	ds_read_b128 v[196:199], v155 offset:3072
	ds_read_b128 v[200:203], v155 offset:4096
	ds_read_b128 v[204:207], v155 offset:5120
	ds_read_b128 v[208:211], v155 offset:6144
	ds_read_b128 v[212:215], v155 offset:7168
	global_load_lds_dwordx4 v[216:217], off
	v_lshl_add_u64 v[216:217], s[26:27], 0, v[140:141]
	s_add_i32 m0, s25, 0xe000
	s_nop 0
	global_load_lds_dwordx4 v[216:217], off
	s_waitcnt vmcnt(8)
	s_waitcnt lgkmcnt(0)
	s_barrier
	s_setprio 1
	s_waitcnt lgkmcnt(0)
	v_mfma_f32_16x16x32_bf16 v[124:127], v[146:149], v[184:187], v[124:127]
	v_mfma_f32_16x16x32_bf16 v[120:123], v[160:163], v[184:187], v[120:123]
	v_mfma_f32_16x16x32_bf16 v[108:111], v[146:149], v[192:195], v[108:111]
	v_mfma_f32_16x16x32_bf16 v[104:107], v[160:163], v[192:195], v[104:107]
	v_mfma_f32_16x16x32_bf16 v[92:95], v[146:149], v[200:203], v[92:95]
	v_mfma_f32_16x16x32_bf16 v[88:91], v[160:163], v[200:203], v[88:91]
	v_mfma_f32_16x16x32_bf16 v[76:79], v[146:149], v[208:211], v[76:79]
	v_mfma_f32_16x16x32_bf16 v[72:75], v[160:163], v[208:211], v[72:75]
	v_mfma_f32_16x16x32_bf16 v[124:127], v[156:159], v[188:191], v[124:127]
	v_mfma_f32_16x16x32_bf16 v[120:123], v[164:167], v[188:191], v[120:123]
	v_mfma_f32_16x16x32_bf16 v[108:111], v[156:159], v[196:199], v[108:111]
	v_mfma_f32_16x16x32_bf16 v[104:107], v[164:167], v[196:199], v[104:107]
	v_mfma_f32_16x16x32_bf16 v[92:95], v[156:159], v[204:207], v[92:95]
	v_mfma_f32_16x16x32_bf16 v[88:91], v[164:167], v[204:207], v[88:91]
	v_mfma_f32_16x16x32_bf16 v[76:79], v[156:159], v[212:215], v[76:79]
	v_mfma_f32_16x16x32_bf16 v[72:75], v[164:167], v[212:215], v[72:75]
	s_setprio 0
	s_setprio 1
	v_mfma_f32_16x16x32_bf16 v[116:119], v[168:171], v[184:187], v[116:119]
	v_mfma_f32_16x16x32_bf16 v[112:115], v[176:179], v[184:187], v[112:115]
	v_mfma_f32_16x16x32_bf16 v[100:103], v[168:171], v[192:195], v[100:103]
	v_mfma_f32_16x16x32_bf16 v[96:99], v[176:179], v[192:195], v[96:99]
	v_mfma_f32_16x16x32_bf16 v[84:87], v[168:171], v[200:203], v[84:87]
	v_mfma_f32_16x16x32_bf16 v[80:83], v[176:179], v[200:203], v[80:83]
	v_mfma_f32_16x16x32_bf16 v[68:71], v[168:171], v[208:211], v[68:71]
	v_mfma_f32_16x16x32_bf16 v[64:67], v[176:179], v[208:211], v[64:67]
	v_mfma_f32_16x16x32_bf16 v[116:119], v[172:175], v[188:191], v[116:119]
	v_mfma_f32_16x16x32_bf16 v[112:115], v[180:183], v[188:191], v[112:115]
	v_mfma_f32_16x16x32_bf16 v[100:103], v[172:175], v[196:199], v[100:103]
	v_mfma_f32_16x16x32_bf16 v[96:99], v[180:183], v[196:199], v[96:99]
	v_mfma_f32_16x16x32_bf16 v[84:87], v[172:175], v[204:207], v[84:87]
	v_mfma_f32_16x16x32_bf16 v[80:83], v[180:183], v[204:207], v[80:83]
	v_mfma_f32_16x16x32_bf16 v[68:71], v[172:175], v[212:215], v[68:71]
	v_mfma_f32_16x16x32_bf16 v[64:67], v[180:183], v[212:215], v[64:67]
	s_setprio 0
	s_barrier
	s_add_i32 s34, s47, s38
	v_lshl_add_u64 v[216:217], s[28:29], 0, v[134:135]
	s_mov_b32 m0, s34
	ds_read_b128 v[184:187], v155 offset:16384
	ds_read_b128 v[188:191], v155 offset:17408
	ds_read_b128 v[192:195], v155 offset:18432
	ds_read_b128 v[196:199], v155 offset:19456
	ds_read_b128 v[200:203], v155 offset:20480
	ds_read_b128 v[204:207], v155 offset:21504
	ds_read_b128 v[208:211], v155 offset:22528
	ds_read_b128 v[212:215], v155 offset:23552
	global_load_lds_dwordx4 v[216:217], off
	s_add_i32 m0, s34, 0x2000
	s_add_u32 s34, s28, 0x40000
	v_lshl_add_u64 v[218:219], s[28:29], 0, v[130:131]
	s_addc_u32 s35, s29, 0
	s_add_i32 s57, s48, s38
	global_load_lds_dwordx4 v[218:219], off
	v_lshl_add_u64 v[220:221], s[34:35], 0, v[134:135]
	s_mov_b32 m0, s57
	v_lshl_add_u64 v[222:223], s[30:31], 0, v[132:133]
	global_load_lds_dwordx4 v[220:221], off
	v_lshl_add_u64 v[220:221], s[34:35], 0, v[130:131]
	s_add_i32 m0, s57, 0x2000
	s_nop 0
	global_load_lds_dwordx4 v[220:221], off
	v_lshl_add_u64 v[220:221], s[30:31], 0, v[136:137]
	s_mov_b32 m0, s25
	s_nop 0
	global_load_lds_dwordx4 v[220:221], off
	s_mov_b32 m0, s42
	s_nop 0
	global_load_lds_dwordx4 v[222:223], off
	s_waitcnt vmcnt(8)
	s_waitcnt lgkmcnt(0)
	s_barrier
	s_setprio 1
	s_waitcnt lgkmcnt(0)
	v_mfma_f32_16x16x32_bf16 v[60:63], v[146:149], v[184:187], v[60:63]
	v_mfma_f32_16x16x32_bf16 v[56:59], v[160:163], v[184:187], v[56:59]
	v_mfma_f32_16x16x32_bf16 v[44:47], v[146:149], v[192:195], v[44:47]
	v_mfma_f32_16x16x32_bf16 v[40:43], v[160:163], v[192:195], v[40:43]
	v_mfma_f32_16x16x32_bf16 v[28:31], v[146:149], v[200:203], v[28:31]
	v_mfma_f32_16x16x32_bf16 v[24:27], v[160:163], v[200:203], v[24:27]
	v_mfma_f32_16x16x32_bf16 v[12:15], v[146:149], v[208:211], v[12:15]
	v_mfma_f32_16x16x32_bf16 v[8:11], v[160:163], v[208:211], v[8:11]
	v_mfma_f32_16x16x32_bf16 v[60:63], v[156:159], v[188:191], v[60:63]
	v_mfma_f32_16x16x32_bf16 v[56:59], v[164:167], v[188:191], v[56:59]
	v_mfma_f32_16x16x32_bf16 v[44:47], v[156:159], v[196:199], v[44:47]
	v_mfma_f32_16x16x32_bf16 v[40:43], v[164:167], v[196:199], v[40:43]
	v_mfma_f32_16x16x32_bf16 v[28:31], v[156:159], v[204:207], v[28:31]
	v_mfma_f32_16x16x32_bf16 v[24:27], v[164:167], v[204:207], v[24:27]
	v_mfma_f32_16x16x32_bf16 v[12:15], v[156:159], v[212:215], v[12:15]
	v_mfma_f32_16x16x32_bf16 v[8:11], v[164:167], v[212:215], v[8:11]
	s_setprio 0
	s_setprio 1
	v_mfma_f32_16x16x32_bf16 v[52:55], v[168:171], v[184:187], v[52:55]
	v_mfma_f32_16x16x32_bf16 v[48:51], v[176:179], v[184:187], v[48:51]
	v_mfma_f32_16x16x32_bf16 v[36:39], v[168:171], v[192:195], v[36:39]
	v_mfma_f32_16x16x32_bf16 v[32:35], v[176:179], v[192:195], v[32:35]
	v_mfma_f32_16x16x32_bf16 v[20:23], v[168:171], v[200:203], v[20:23]
	v_mfma_f32_16x16x32_bf16 v[16:19], v[176:179], v[200:203], v[16:19]
	v_mfma_f32_16x16x32_bf16 v[4:7], v[168:171], v[208:211], v[4:7]
	v_mfma_f32_16x16x32_bf16 v[0:3], v[176:179], v[208:211], v[0:3]
	v_mfma_f32_16x16x32_bf16 v[52:55], v[172:175], v[188:191], v[52:55]
	v_mfma_f32_16x16x32_bf16 v[48:51], v[180:183], v[188:191], v[48:51]
	v_mfma_f32_16x16x32_bf16 v[36:39], v[172:175], v[196:199], v[36:39]
	v_mfma_f32_16x16x32_bf16 v[32:35], v[180:183], v[196:199], v[32:35]
	v_mfma_f32_16x16x32_bf16 v[20:23], v[172:175], v[204:207], v[20:23]
	v_mfma_f32_16x16x32_bf16 v[16:19], v[180:183], v[204:207], v[16:19]
	v_mfma_f32_16x16x32_bf16 v[4:7], v[172:175], v[212:215], v[4:7]
	v_mfma_f32_16x16x32_bf16 v[0:3], v[180:183], v[212:215], v[0:3]
	s_setprio 0
	s_barrier
	s_add_i32 s34, 0, 0x18000
	s_add_i32 s35, 0, 0x1c000
	v_add_u32_e32 v164, s34, v150
	v_add_u32_e32 v180, s35, v150
	ds_read_b128 v[146:149], v164
	ds_read_b128 v[156:159], v164 offset:1024
	ds_read_b128 v[160:163], v164 offset:2048
	ds_read_b128 v[164:167], v164 offset:3072
	ds_read_b128 v[168:171], v180
	ds_read_b128 v[172:175], v180 offset:1024
	ds_read_b128 v[176:179], v180 offset:2048
	ds_read_b128 v[180:183], v180 offset:3072
	s_add_u32 s30, s30, 0x40000
	s_addc_u32 s31, s31, 0
	s_mov_b32 m0, s43
	v_lshl_add_u64 v[224:225], s[30:31], 0, v[136:137]
	ds_read_b128 v[184:187], v155 offset:32768
	ds_read_b128 v[188:191], v155 offset:33792
	ds_read_b128 v[192:195], v155 offset:34816
	ds_read_b128 v[196:199], v155 offset:35840
	ds_read_b128 v[200:203], v155 offset:36864
	ds_read_b128 v[204:207], v155 offset:37888
	ds_read_b128 v[208:211], v155 offset:38912
	ds_read_b128 v[212:215], v155 offset:39936
	global_load_lds_dwordx4 v[224:225], off
	v_lshl_add_u64 v[224:225], s[30:31], 0, v[132:133]
	s_mov_b32 m0, s44
	s_nop 0
	global_load_lds_dwordx4 v[224:225], off
	s_waitcnt vmcnt(8)
	s_waitcnt lgkmcnt(0)
	s_barrier
	s_setprio 1
	s_waitcnt lgkmcnt(0)
	v_mfma_f32_16x16x32_bf16 v[124:127], v[146:149], v[184:187], v[124:127]
	v_mfma_f32_16x16x32_bf16 v[120:123], v[160:163], v[184:187], v[120:123]
	v_mfma_f32_16x16x32_bf16 v[108:111], v[146:149], v[192:195], v[108:111]
	v_mfma_f32_16x16x32_bf16 v[104:107], v[160:163], v[192:195], v[104:107]
	v_mfma_f32_16x16x32_bf16 v[92:95], v[146:149], v[200:203], v[92:95]
	v_mfma_f32_16x16x32_bf16 v[88:91], v[160:163], v[200:203], v[88:91]
	v_mfma_f32_16x16x32_bf16 v[76:79], v[146:149], v[208:211], v[76:79]
	v_mfma_f32_16x16x32_bf16 v[72:75], v[160:163], v[208:211], v[72:75]
	v_mfma_f32_16x16x32_bf16 v[124:127], v[156:159], v[188:191], v[124:127]
	v_mfma_f32_16x16x32_bf16 v[120:123], v[164:167], v[188:191], v[120:123]
	v_mfma_f32_16x16x32_bf16 v[108:111], v[156:159], v[196:199], v[108:111]
	v_mfma_f32_16x16x32_bf16 v[104:107], v[164:167], v[196:199], v[104:107]
	v_mfma_f32_16x16x32_bf16 v[92:95], v[156:159], v[204:207], v[92:95]
	v_mfma_f32_16x16x32_bf16 v[88:91], v[164:167], v[204:207], v[88:91]
	v_mfma_f32_16x16x32_bf16 v[76:79], v[156:159], v[212:215], v[76:79]
	v_mfma_f32_16x16x32_bf16 v[72:75], v[164:167], v[212:215], v[72:75]
	s_setprio 0
	s_setprio 1
	v_mfma_f32_16x16x32_bf16 v[116:119], v[168:171], v[184:187], v[116:119]
	v_mfma_f32_16x16x32_bf16 v[112:115], v[176:179], v[184:187], v[112:115]
	v_mfma_f32_16x16x32_bf16 v[100:103], v[168:171], v[192:195], v[100:103]
	v_mfma_f32_16x16x32_bf16 v[96:99], v[176:179], v[192:195], v[96:99]
	v_mfma_f32_16x16x32_bf16 v[84:87], v[168:171], v[200:203], v[84:87]
	v_mfma_f32_16x16x32_bf16 v[80:83], v[176:179], v[200:203], v[80:83]
	v_mfma_f32_16x16x32_bf16 v[68:71], v[168:171], v[208:211], v[68:71]
	v_mfma_f32_16x16x32_bf16 v[64:67], v[176:179], v[208:211], v[64:67]
	v_mfma_f32_16x16x32_bf16 v[116:119], v[172:175], v[188:191], v[116:119]
	v_mfma_f32_16x16x32_bf16 v[112:115], v[180:183], v[188:191], v[112:115]
	v_mfma_f32_16x16x32_bf16 v[100:103], v[172:175], v[196:199], v[100:103]
	v_mfma_f32_16x16x32_bf16 v[96:99], v[180:183], v[196:199], v[96:99]
	v_mfma_f32_16x16x32_bf16 v[84:87], v[172:175], v[204:207], v[84:87]
	v_mfma_f32_16x16x32_bf16 v[80:83], v[180:183], v[204:207], v[80:83]
	v_mfma_f32_16x16x32_bf16 v[68:71], v[172:175], v[212:215], v[68:71]
	v_mfma_f32_16x16x32_bf16 v[64:67], v[180:183], v[212:215], v[64:67]
	s_setprio 0
	s_barrier
	s_add_i32 s30, s34, s38
	v_lshl_add_u64 v[216:217], v[216:217], 0, s[6:7]
	s_mov_b32 m0, s30
	ds_read_b128 v[184:187], v155 offset:49152
	ds_read_b128 v[188:191], v155 offset:50176
	ds_read_b128 v[192:195], v155 offset:51200
	ds_read_b128 v[196:199], v155 offset:52224
	ds_read_b128 v[200:203], v155 offset:53248
	ds_read_b128 v[204:207], v155 offset:54272
	ds_read_b128 v[208:211], v155 offset:55296
	ds_read_b128 v[212:215], v155 offset:56320
	global_load_lds_dwordx4 v[216:217], off
	s_add_i32 m0, s30, 0x2000
	s_add_u32 s28, s28, 0x40080
	v_lshl_add_u64 v[216:217], v[218:219], 0, s[6:7]
	s_addc_u32 s29, s29, 0
	s_add_i32 s30, s35, s38
	global_load_lds_dwordx4 v[216:217], off
	v_lshl_add_u64 v[216:217], s[28:29], 0, v[134:135]
	s_mov_b32 m0, s30
	s_nop 0
	global_load_lds_dwordx4 v[216:217], off
	v_lshl_add_u64 v[216:217], s[28:29], 0, v[130:131]
	s_add_i32 m0, s30, 0x2000
	s_nop 0
	global_load_lds_dwordx4 v[216:217], off
	v_lshl_add_u64 v[216:217], v[220:221], 0, s[6:7]
	s_mov_b32 m0, s45
	s_nop 0
	global_load_lds_dwordx4 v[216:217], off
	v_lshl_add_u64 v[216:217], v[222:223], 0, s[6:7]
	s_mov_b32 m0, s46
	s_nop 0
	global_load_lds_dwordx4 v[216:217], off
	s_waitcnt vmcnt(8)
	s_waitcnt lgkmcnt(0)
	s_barrier
	s_add_u32 s26, s26, 0x100
	s_addc_u32 s27, s27, 0
	s_add_u32 s54, s54, 0x100
	s_addc_u32 s55, s55, 0
	s_setprio 1
	s_waitcnt lgkmcnt(0)
	v_mfma_f32_16x16x32_bf16 v[60:63], v[146:149], v[184:187], v[60:63]
	v_mfma_f32_16x16x32_bf16 v[56:59], v[160:163], v[184:187], v[56:59]
	v_mfma_f32_16x16x32_bf16 v[44:47], v[146:149], v[192:195], v[44:47]
	v_mfma_f32_16x16x32_bf16 v[40:43], v[160:163], v[192:195], v[40:43]
	v_mfma_f32_16x16x32_bf16 v[28:31], v[146:149], v[200:203], v[28:31]
	v_mfma_f32_16x16x32_bf16 v[24:27], v[160:163], v[200:203], v[24:27]
	v_mfma_f32_16x16x32_bf16 v[12:15], v[146:149], v[208:211], v[12:15]
	v_mfma_f32_16x16x32_bf16 v[8:11], v[160:163], v[208:211], v[8:11]
	v_mfma_f32_16x16x32_bf16 v[60:63], v[156:159], v[188:191], v[60:63]
	v_mfma_f32_16x16x32_bf16 v[56:59], v[164:167], v[188:191], v[56:59]
	v_mfma_f32_16x16x32_bf16 v[44:47], v[156:159], v[196:199], v[44:47]
	v_mfma_f32_16x16x32_bf16 v[40:43], v[164:167], v[196:199], v[40:43]
	v_mfma_f32_16x16x32_bf16 v[28:31], v[156:159], v[204:207], v[28:31]
	v_mfma_f32_16x16x32_bf16 v[24:27], v[164:167], v[204:207], v[24:27]
	v_mfma_f32_16x16x32_bf16 v[12:15], v[156:159], v[212:215], v[12:15]
	v_mfma_f32_16x16x32_bf16 v[8:11], v[164:167], v[212:215], v[8:11]
	s_setprio 0
	s_setprio 1
	v_mfma_f32_16x16x32_bf16 v[52:55], v[168:171], v[184:187], v[52:55]
	v_mfma_f32_16x16x32_bf16 v[48:51], v[176:179], v[184:187], v[48:51]
	v_mfma_f32_16x16x32_bf16 v[36:39], v[168:171], v[192:195], v[36:39]
	v_mfma_f32_16x16x32_bf16 v[32:35], v[176:179], v[192:195], v[32:35]
	v_mfma_f32_16x16x32_bf16 v[20:23], v[168:171], v[200:203], v[20:23]
	v_mfma_f32_16x16x32_bf16 v[16:19], v[176:179], v[200:203], v[16:19]
	v_mfma_f32_16x16x32_bf16 v[4:7], v[168:171], v[208:211], v[4:7]
	v_mfma_f32_16x16x32_bf16 v[0:3], v[176:179], v[208:211], v[0:3]
	v_mfma_f32_16x16x32_bf16 v[52:55], v[172:175], v[188:191], v[52:55]
	v_mfma_f32_16x16x32_bf16 v[48:51], v[180:183], v[188:191], v[48:51]
	v_mfma_f32_16x16x32_bf16 v[36:39], v[172:175], v[196:199], v[36:39]
	v_mfma_f32_16x16x32_bf16 v[32:35], v[180:183], v[196:199], v[32:35]
	v_mfma_f32_16x16x32_bf16 v[20:23], v[172:175], v[204:207], v[20:23]
	v_mfma_f32_16x16x32_bf16 v[16:19], v[180:183], v[204:207], v[16:19]
	v_mfma_f32_16x16x32_bf16 v[4:7], v[172:175], v[212:215], v[4:7]
	v_mfma_f32_16x16x32_bf16 v[0:3], v[180:183], v[212:215], v[0:3]
	s_setprio 0
	s_add_i32 s56, s56, 2
	s_cmp_gt_u32 s56, 13
	s_cbranch_scc0 .LBB0_2091
	s_sub_i32 s100, s56, 2
	s_cmp_eq_u32 s100, s98
	s_cbranch_scc1 .Lmy_nobar_22
	s_barrier

.Lmy_nobar2_23:
	ds_read_b128 v[144:147], v153
	ds_read_b128 v[156:159], v153 offset:1024
	ds_read_b128 v[160:163], v153 offset:2048
	ds_read_b128 v[164:167], v153 offset:3072
	ds_read_b128 v[168:171], v154
	ds_read_b128 v[172:175], v154 offset:1024
	ds_read_b128 v[176:179], v154 offset:2048
	ds_read_b128 v[180:183], v154 offset:3072
	s_add_u32 s30, s28, 0xfff50080
	s_addc_u32 s31, s29, -1
	s_cmp_eq_u32 s56, 40
	s_cselect_b32 s37, s1, s31
	s_cselect_b32 s36, s0, s30
	s_cselect_b32 s31, s27, s55
	s_cselect_b32 s30, s26, s54
	v_lshl_add_u64 v[148:149], s[28:29], 0, v[128:129]
	s_add_i32 m0, s41, 0xc000
	ds_read_b128 v[184:187], v155
	ds_read_b128 v[188:191], v155 offset:1024
	ds_read_b128 v[192:195], v155 offset:2048
	ds_read_b128 v[196:199], v155 offset:3072
	ds_read_b128 v[200:203], v155 offset:4096
	ds_read_b128 v[204:207], v155 offset:5120
	ds_read_b128 v[208:211], v155 offset:6144
	ds_read_b128 v[212:215], v155 offset:7168
	global_load_lds_dwordx4 v[148:149], off
	v_lshl_add_u64 v[148:149], s[28:29], 0, v[138:139]
	s_add_i32 m0, s41, 0xe000
	s_nop 0
	global_load_lds_dwordx4 v[148:149], off
	s_waitcnt vmcnt(8)
	s_waitcnt lgkmcnt(0)
	s_barrier
	s_setprio 1
	s_waitcnt lgkmcnt(0)
	v_mfma_f32_16x16x32_bf16 v[124:127], v[144:147], v[184:187], 0
	v_mfma_f32_16x16x32_bf16 v[120:123], v[160:163], v[184:187], 0
	v_mfma_f32_16x16x32_bf16 v[108:111], v[144:147], v[192:195], 0
	v_mfma_f32_16x16x32_bf16 v[104:107], v[160:163], v[192:195], 0
	v_mfma_f32_16x16x32_bf16 v[92:95], v[144:147], v[200:203], 0
	v_mfma_f32_16x16x32_bf16 v[88:91], v[160:163], v[200:203], 0
	v_mfma_f32_16x16x32_bf16 v[76:79], v[144:147], v[208:211], 0
	v_mfma_f32_16x16x32_bf16 v[72:75], v[160:163], v[208:211], 0
	v_mfma_f32_16x16x32_bf16 v[124:127], v[156:159], v[188:191], v[124:127]
	v_mfma_f32_16x16x32_bf16 v[120:123], v[164:167], v[188:191], v[120:123]
	v_mfma_f32_16x16x32_bf16 v[108:111], v[156:159], v[196:199], v[108:111]
	v_mfma_f32_16x16x32_bf16 v[104:107], v[164:167], v[196:199], v[104:107]
	v_mfma_f32_16x16x32_bf16 v[92:95], v[156:159], v[204:207], v[92:95]
	v_mfma_f32_16x16x32_bf16 v[88:91], v[164:167], v[204:207], v[88:91]
	v_mfma_f32_16x16x32_bf16 v[76:79], v[156:159], v[212:215], v[76:79]
	v_mfma_f32_16x16x32_bf16 v[72:75], v[164:167], v[212:215], v[72:75]
	s_setprio 0
	s_setprio 1
	v_mfma_f32_16x16x32_bf16 v[116:119], v[168:171], v[184:187], 0
	v_mfma_f32_16x16x32_bf16 v[112:115], v[176:179], v[184:187], 0
	v_mfma_f32_16x16x32_bf16 v[100:103], v[168:171], v[192:195], 0
	v_mfma_f32_16x16x32_bf16 v[96:99], v[176:179], v[192:195], 0
	v_mfma_f32_16x16x32_bf16 v[84:87], v[168:171], v[200:203], 0
	v_mfma_f32_16x16x32_bf16 v[80:83], v[176:179], v[200:203], 0
	v_mfma_f32_16x16x32_bf16 v[68:71], v[168:171], v[208:211], 0
	v_mfma_f32_16x16x32_bf16 v[64:67], v[176:179], v[208:211], 0
	v_mfma_f32_16x16x32_bf16 v[116:119], v[172:175], v[188:191], v[116:119]
	v_mfma_f32_16x16x32_bf16 v[112:115], v[180:183], v[188:191], v[112:115]
	v_mfma_f32_16x16x32_bf16 v[100:103], v[172:175], v[196:199], v[100:103]
	v_mfma_f32_16x16x32_bf16 v[96:99], v[180:183], v[196:199], v[96:99]
	v_mfma_f32_16x16x32_bf16 v[84:87], v[172:175], v[204:207], v[84:87]
	v_mfma_f32_16x16x32_bf16 v[80:83], v[180:183], v[204:207], v[80:83]
	v_mfma_f32_16x16x32_bf16 v[68:71], v[172:175], v[212:215], v[68:71]
	v_mfma_f32_16x16x32_bf16 v[64:67], v[180:183], v[212:215], v[64:67]
	s_setprio 0
	s_barrier
	s_add_i32 s34, s50, s40
	v_lshl_add_u64 v[148:149], s[30:31], 0, v[132:133]
	s_mov_b32 m0, s34
	ds_read_b128 v[184:187], v155 offset:16384
	ds_read_b128 v[188:191], v155 offset:17408
	ds_read_b128 v[192:195], v155 offset:18432
	ds_read_b128 v[196:199], v155 offset:19456
	ds_read_b128 v[200:203], v155 offset:20480
	ds_read_b128 v[204:207], v155 offset:21504
	ds_read_b128 v[208:211], v155 offset:22528
	ds_read_b128 v[212:215], v155 offset:23552
	global_load_lds_dwordx4 v[148:149], off
	s_add_i32 m0, s34, 0x2000
	s_add_u32 s34, s30, 0xb0000
	v_lshl_add_u64 v[216:217], s[30:31], 0, v[136:137]
	s_addc_u32 s35, s31, 0
	s_add_i32 s57, s51, s40
	global_load_lds_dwordx4 v[216:217], off
	v_lshl_add_u64 v[218:219], s[34:35], 0, v[132:133]
	s_mov_b32 m0, s57
	v_lshl_add_u64 v[220:221], s[36:37], 0, v[134:135]
	global_load_lds_dwordx4 v[218:219], off
	v_lshl_add_u64 v[218:219], s[34:35], 0, v[136:137]
	s_add_i32 m0, s57, 0x2000
	s_nop 0
	global_load_lds_dwordx4 v[218:219], off
	v_lshl_add_u64 v[218:219], s[36:37], 0, v[130:131]
	s_mov_b32 m0, s41
	s_nop 0
	global_load_lds_dwordx4 v[218:219], off
	s_mov_b32 m0, s42
	s_nop 0
	global_load_lds_dwordx4 v[220:221], off
	s_waitcnt vmcnt(8)
	s_waitcnt lgkmcnt(0)
	s_barrier
	s_setprio 1
	s_waitcnt lgkmcnt(0)
	v_mfma_f32_16x16x32_bf16 v[60:63], v[144:147], v[184:187], 0
	v_mfma_f32_16x16x32_bf16 v[56:59], v[160:163], v[184:187], 0
	v_mfma_f32_16x16x32_bf16 v[44:47], v[144:147], v[192:195], 0
	v_mfma_f32_16x16x32_bf16 v[40:43], v[160:163], v[192:195], 0
	v_mfma_f32_16x16x32_bf16 v[28:31], v[144:147], v[200:203], 0
	v_mfma_f32_16x16x32_bf16 v[24:27], v[160:163], v[200:203], 0
	v_mfma_f32_16x16x32_bf16 v[12:15], v[144:147], v[208:211], 0
	v_mfma_f32_16x16x32_bf16 v[8:11], v[160:163], v[208:211], 0
	v_mfma_f32_16x16x32_bf16 v[60:63], v[156:159], v[188:191], v[60:63]
	v_mfma_f32_16x16x32_bf16 v[56:59], v[164:167], v[188:191], v[56:59]
	v_mfma_f32_16x16x32_bf16 v[44:47], v[156:159], v[196:199], v[44:47]
	v_mfma_f32_16x16x32_bf16 v[40:43], v[164:167], v[196:199], v[40:43]
	v_mfma_f32_16x16x32_bf16 v[28:31], v[156:159], v[204:207], v[28:31]
	v_mfma_f32_16x16x32_bf16 v[24:27], v[164:167], v[204:207], v[24:27]
	v_mfma_f32_16x16x32_bf16 v[12:15], v[156:159], v[212:215], v[12:15]
	v_mfma_f32_16x16x32_bf16 v[8:11], v[164:167], v[212:215], v[8:11]
	s_setprio 0
	s_setprio 1
	v_mfma_f32_16x16x32_bf16 v[52:55], v[168:171], v[184:187], 0
	v_mfma_f32_16x16x32_bf16 v[48:51], v[176:179], v[184:187], 0
	v_mfma_f32_16x16x32_bf16 v[36:39], v[168:171], v[192:195], 0
	v_mfma_f32_16x16x32_bf16 v[32:35], v[176:179], v[192:195], 0
	v_mfma_f32_16x16x32_bf16 v[20:23], v[168:171], v[200:203], 0
	v_mfma_f32_16x16x32_bf16 v[16:19], v[176:179], v[200:203], 0
	v_mfma_f32_16x16x32_bf16 v[4:7], v[168:171], v[208:211], 0
	v_mfma_f32_16x16x32_bf16 v[0:3], v[176:179], v[208:211], 0
	v_mfma_f32_16x16x32_bf16 v[52:55], v[172:175], v[188:191], v[52:55]
	v_mfma_f32_16x16x32_bf16 v[48:51], v[180:183], v[188:191], v[48:51]
	v_mfma_f32_16x16x32_bf16 v[36:39], v[172:175], v[196:199], v[36:39]
	v_mfma_f32_16x16x32_bf16 v[32:35], v[180:183], v[196:199], v[32:35]
	v_mfma_f32_16x16x32_bf16 v[20:23], v[172:175], v[204:207], v[20:23]
	v_mfma_f32_16x16x32_bf16 v[16:19], v[180:183], v[204:207], v[16:19]
	v_mfma_f32_16x16x32_bf16 v[4:7], v[172:175], v[212:215], v[4:7]
	v_mfma_f32_16x16x32_bf16 v[0:3], v[180:183], v[212:215], v[0:3]
	s_setprio 0
	s_barrier
	s_add_i32 s57, 0, 0x18000
	s_add_i32 s58, 0, 0x1c000
	v_add_u32_e32 v164, s57, v151
	v_add_u32_e32 v180, s58, v151
	ds_read_b128 v[144:147], v164
	ds_read_b128 v[156:159], v164 offset:1024
	ds_read_b128 v[160:163], v164 offset:2048
	ds_read_b128 v[164:167], v164 offset:3072
	ds_read_b128 v[168:171], v180
	ds_read_b128 v[172:175], v180 offset:1024
	ds_read_b128 v[176:179], v180 offset:2048
	ds_read_b128 v[180:183], v180 offset:3072
	s_add_u32 s34, s36, 0xb0000
	s_addc_u32 s35, s37, 0
	s_mov_b32 m0, s43
	v_lshl_add_u64 v[222:223], s[34:35], 0, v[130:131]
	ds_read_b128 v[184:187], v155 offset:32768
	ds_read_b128 v[188:191], v155 offset:33792
	ds_read_b128 v[192:195], v155 offset:34816
	ds_read_b128 v[196:199], v155 offset:35840
	ds_read_b128 v[200:203], v155 offset:36864
	ds_read_b128 v[204:207], v155 offset:37888
	ds_read_b128 v[208:211], v155 offset:38912
	ds_read_b128 v[212:215], v155 offset:39936
	global_load_lds_dwordx4 v[222:223], off
	v_lshl_add_u64 v[222:223], s[34:35], 0, v[134:135]
	s_mov_b32 m0, s44
	s_nop 0
	global_load_lds_dwordx4 v[222:223], off
	s_waitcnt vmcnt(8)
	s_waitcnt lgkmcnt(0)
	s_barrier
	s_setprio 1
	s_waitcnt lgkmcnt(0)
	v_mfma_f32_16x16x32_bf16 v[124:127], v[144:147], v[184:187], v[124:127]
	v_mfma_f32_16x16x32_bf16 v[120:123], v[160:163], v[184:187], v[120:123]
	v_mfma_f32_16x16x32_bf16 v[108:111], v[144:147], v[192:195], v[108:111]
	v_mfma_f32_16x16x32_bf16 v[104:107], v[160:163], v[192:195], v[104:107]
	v_mfma_f32_16x16x32_bf16 v[92:95], v[144:147], v[200:203], v[92:95]
	v_mfma_f32_16x16x32_bf16 v[88:91], v[160:163], v[200:203], v[88:91]
	v_mfma_f32_16x16x32_bf16 v[76:79], v[144:147], v[208:211], v[76:79]
	v_mfma_f32_16x16x32_bf16 v[72:75], v[160:163], v[208:211], v[72:75]
	v_mfma_f32_16x16x32_bf16 v[124:127], v[156:159], v[188:191], v[124:127]
	v_mfma_f32_16x16x32_bf16 v[120:123], v[164:167], v[188:191], v[120:123]
	v_mfma_f32_16x16x32_bf16 v[108:111], v[156:159], v[196:199], v[108:111]
	v_mfma_f32_16x16x32_bf16 v[104:107], v[164:167], v[196:199], v[104:107]
	v_mfma_f32_16x16x32_bf16 v[92:95], v[156:159], v[204:207], v[92:95]
	v_mfma_f32_16x16x32_bf16 v[88:91], v[164:167], v[204:207], v[88:91]
	v_mfma_f32_16x16x32_bf16 v[76:79], v[156:159], v[212:215], v[76:79]
	v_mfma_f32_16x16x32_bf16 v[72:75], v[164:167], v[212:215], v[72:75]
	s_setprio 0
	s_setprio 1
	v_mfma_f32_16x16x32_bf16 v[116:119], v[168:171], v[184:187], v[116:119]
	v_mfma_f32_16x16x32_bf16 v[112:115], v[176:179], v[184:187], v[112:115]
	v_mfma_f32_16x16x32_bf16 v[100:103], v[168:171], v[192:195], v[100:103]
	v_mfma_f32_16x16x32_bf16 v[96:99], v[176:179], v[192:195], v[96:99]
	v_mfma_f32_16x16x32_bf16 v[84:87], v[168:171], v[200:203], v[84:87]
	v_mfma_f32_16x16x32_bf16 v[80:83], v[176:179], v[200:203], v[80:83]
	v_mfma_f32_16x16x32_bf16 v[68:71], v[168:171], v[208:211], v[68:71]
	v_mfma_f32_16x16x32_bf16 v[64:67], v[176:179], v[208:211], v[64:67]
	v_mfma_f32_16x16x32_bf16 v[116:119], v[172:175], v[188:191], v[116:119]
	v_mfma_f32_16x16x32_bf16 v[112:115], v[180:183], v[188:191], v[112:115]
	v_mfma_f32_16x16x32_bf16 v[100:103], v[172:175], v[196:199], v[100:103]
	v_mfma_f32_16x16x32_bf16 v[96:99], v[180:183], v[196:199], v[96:99]
	v_mfma_f32_16x16x32_bf16 v[84:87], v[172:175], v[204:207], v[84:87]
	v_mfma_f32_16x16x32_bf16 v[80:83], v[180:183], v[204:207], v[80:83]
	v_mfma_f32_16x16x32_bf16 v[68:71], v[172:175], v[212:215], v[68:71]
	v_mfma_f32_16x16x32_bf16 v[64:67], v[180:183], v[212:215], v[64:67]
	s_setprio 0
	s_barrier
	s_add_i32 s34, s57, s40
	v_lshl_add_u64 v[148:149], v[148:149], 0, s[8:9]
	s_mov_b32 m0, s34
	ds_read_b128 v[184:187], v155 offset:49152
	ds_read_b128 v[188:191], v155 offset:50176
	ds_read_b128 v[192:195], v155 offset:51200
	ds_read_b128 v[196:199], v155 offset:52224
	ds_read_b128 v[200:203], v155 offset:53248
	ds_read_b128 v[204:207], v155 offset:54272
	ds_read_b128 v[208:211], v155 offset:55296
	ds_read_b128 v[212:215], v155 offset:56320
	global_load_lds_dwordx4 v[148:149], off
	s_add_i32 m0, s34, 0x2000
	s_add_u32 s30, s30, 0xb0080
	v_lshl_add_u64 v[148:149], v[216:217], 0, s[8:9]
	s_addc_u32 s31, s31, 0
	s_add_i32 s34, s58, s40
	global_load_lds_dwordx4 v[148:149], off
	v_lshl_add_u64 v[148:149], s[30:31], 0, v[132:133]
	s_mov_b32 m0, s34
	s_nop 0
	global_load_lds_dwordx4 v[148:149], off
	v_lshl_add_u64 v[148:149], s[30:31], 0, v[136:137]
	s_add_i32 m0, s34, 0x2000
	s_nop 0
	global_load_lds_dwordx4 v[148:149], off
	v_lshl_add_u64 v[148:149], v[218:219], 0, s[8:9]
	s_mov_b32 m0, s46
	s_nop 0
	global_load_lds_dwordx4 v[148:149], off
	v_lshl_add_u64 v[148:149], v[220:221], 0, s[8:9]
	s_mov_b32 m0, s47
	s_nop 0
	global_load_lds_dwordx4 v[148:149], off
	s_waitcnt vmcnt(8)
	s_waitcnt lgkmcnt(0)
	s_barrier
	s_add_u32 s28, s28, 0x100
	s_addc_u32 s29, s29, 0
	s_add_u32 s54, s54, 0x100
	s_addc_u32 s55, s55, 0
	s_setprio 1
	s_waitcnt lgkmcnt(0)
	v_mfma_f32_16x16x32_bf16 v[60:63], v[144:147], v[184:187], v[60:63]
	v_mfma_f32_16x16x32_bf16 v[56:59], v[160:163], v[184:187], v[56:59]
	v_mfma_f32_16x16x32_bf16 v[44:47], v[144:147], v[192:195], v[44:47]
	v_mfma_f32_16x16x32_bf16 v[40:43], v[160:163], v[192:195], v[40:43]
	v_mfma_f32_16x16x32_bf16 v[28:31], v[144:147], v[200:203], v[28:31]
	v_mfma_f32_16x16x32_bf16 v[24:27], v[160:163], v[200:203], v[24:27]
	v_mfma_f32_16x16x32_bf16 v[12:15], v[144:147], v[208:211], v[12:15]
	v_mfma_f32_16x16x32_bf16 v[8:11], v[160:163], v[208:211], v[8:11]
	v_mfma_f32_16x16x32_bf16 v[60:63], v[156:159], v[188:191], v[60:63]
	v_mfma_f32_16x16x32_bf16 v[56:59], v[164:167], v[188:191], v[56:59]
	v_mfma_f32_16x16x32_bf16 v[44:47], v[156:159], v[196:199], v[44:47]
	v_mfma_f32_16x16x32_bf16 v[40:43], v[164:167], v[196:199], v[40:43]
	v_mfma_f32_16x16x32_bf16 v[28:31], v[156:159], v[204:207], v[28:31]
	v_mfma_f32_16x16x32_bf16 v[24:27], v[164:167], v[204:207], v[24:27]
	v_mfma_f32_16x16x32_bf16 v[12:15], v[156:159], v[212:215], v[12:15]
	v_mfma_f32_16x16x32_bf16 v[8:11], v[164:167], v[212:215], v[8:11]
	s_setprio 0
	s_setprio 1
	v_mfma_f32_16x16x32_bf16 v[52:55], v[168:171], v[184:187], v[52:55]
	v_mfma_f32_16x16x32_bf16 v[48:51], v[176:179], v[184:187], v[48:51]
	v_mfma_f32_16x16x32_bf16 v[36:39], v[168:171], v[192:195], v[36:39]
	v_mfma_f32_16x16x32_bf16 v[32:35], v[176:179], v[192:195], v[32:35]
	v_mfma_f32_16x16x32_bf16 v[20:23], v[168:171], v[200:203], v[20:23]
	v_mfma_f32_16x16x32_bf16 v[16:19], v[176:179], v[200:203], v[16:19]
	v_mfma_f32_16x16x32_bf16 v[4:7], v[168:171], v[208:211], v[4:7]
	v_mfma_f32_16x16x32_bf16 v[0:3], v[176:179], v[208:211], v[0:3]
	v_mfma_f32_16x16x32_bf16 v[52:55], v[172:175], v[188:191], v[52:55]
	v_mfma_f32_16x16x32_bf16 v[48:51], v[180:183], v[188:191], v[48:51]
	v_mfma_f32_16x16x32_bf16 v[36:39], v[172:175], v[196:199], v[36:39]
	v_mfma_f32_16x16x32_bf16 v[32:35], v[180:183], v[196:199], v[32:35]
	v_mfma_f32_16x16x32_bf16 v[20:23], v[172:175], v[204:207], v[20:23]
	v_mfma_f32_16x16x32_bf16 v[16:19], v[180:183], v[204:207], v[16:19]
	v_mfma_f32_16x16x32_bf16 v[4:7], v[172:175], v[212:215], v[4:7]
	v_mfma_f32_16x16x32_bf16 v[0:3], v[180:183], v[212:215], v[0:3]
	s_setprio 0
	s_add_i32 s56, s56, 2
.LBB0_2174:
	s_barrier
	ds_read_b128 v[144:147], v153
	ds_read_b128 v[156:159], v153 offset:1024
	ds_read_b128 v[160:163], v153 offset:2048
	ds_read_b128 v[164:167], v153 offset:3072
	ds_read_b128 v[168:171], v154
	ds_read_b128 v[172:175], v154 offset:1024
	ds_read_b128 v[176:179], v154 offset:2048
	ds_read_b128 v[180:183], v154 offset:3072
	s_add_u32 s30, s28, 0xfff50080
	s_addc_u32 s31, s29, -1
	s_cmp_eq_u32 s56, 40
	s_cselect_b32 s37, s1, s31
	s_cselect_b32 s36, s0, s30
	s_cselect_b32 s31, s27, s55
	s_cselect_b32 s30, s26, s54
	v_lshl_add_u64 v[148:149], s[28:29], 0, v[128:129]
	s_add_i32 m0, s41, 0xc000
	ds_read_b128 v[184:187], v155
	ds_read_b128 v[188:191], v155 offset:1024
	ds_read_b128 v[192:195], v155 offset:2048
	ds_read_b128 v[196:199], v155 offset:3072
	ds_read_b128 v[200:203], v155 offset:4096
	ds_read_b128 v[204:207], v155 offset:5120
	ds_read_b128 v[208:211], v155 offset:6144
	ds_read_b128 v[212:215], v155 offset:7168
	global_load_lds_dwordx4 v[148:149], off
	v_lshl_add_u64 v[148:149], s[28:29], 0, v[138:139]
	s_add_i32 m0, s41, 0xe000
	s_nop 0
	global_load_lds_dwordx4 v[148:149], off
	s_waitcnt vmcnt(8)
	s_waitcnt lgkmcnt(0)
	s_barrier
	s_setprio 1
	s_waitcnt lgkmcnt(0)
	v_mfma_f32_16x16x32_bf16 v[124:127], v[144:147], v[184:187], v[124:127]
	v_mfma_f32_16x16x32_bf16 v[120:123], v[160:163], v[184:187], v[120:123]
	v_mfma_f32_16x16x32_bf16 v[108:111], v[144:147], v[192:195], v[108:111]
	v_mfma_f32_16x16x32_bf16 v[104:107], v[160:163], v[192:195], v[104:107]
	v_mfma_f32_16x16x32_bf16 v[92:95], v[144:147], v[200:203], v[92:95]
	v_mfma_f32_16x16x32_bf16 v[88:91], v[160:163], v[200:203], v[88:91]
	v_mfma_f32_16x16x32_bf16 v[76:79], v[144:147], v[208:211], v[76:79]
	v_mfma_f32_16x16x32_bf16 v[72:75], v[160:163], v[208:211], v[72:75]
	v_mfma_f32_16x16x32_bf16 v[124:127], v[156:159], v[188:191], v[124:127]
	v_mfma_f32_16x16x32_bf16 v[120:123], v[164:167], v[188:191], v[120:123]
	v_mfma_f32_16x16x32_bf16 v[108:111], v[156:159], v[196:199], v[108:111]
	v_mfma_f32_16x16x32_bf16 v[104:107], v[164:167], v[196:199], v[104:107]
	v_mfma_f32_16x16x32_bf16 v[92:95], v[156:159], v[204:207], v[92:95]
	v_mfma_f32_16x16x32_bf16 v[88:91], v[164:167], v[204:207], v[88:91]
	v_mfma_f32_16x16x32_bf16 v[76:79], v[156:159], v[212:215], v[76:79]
	v_mfma_f32_16x16x32_bf16 v[72:75], v[164:167], v[212:215], v[72:75]
	s_setprio 0
	s_setprio 1
	v_mfma_f32_16x16x32_bf16 v[116:119], v[168:171], v[184:187], v[116:119]
	v_mfma_f32_16x16x32_bf16 v[112:115], v[176:179], v[184:187], v[112:115]
	v_mfma_f32_16x16x32_bf16 v[100:103], v[168:171], v[192:195], v[100:103]
	v_mfma_f32_16x16x32_bf16 v[96:99], v[176:179], v[192:195], v[96:99]
	v_mfma_f32_16x16x32_bf16 v[84:87], v[168:171], v[200:203], v[84:87]
	v_mfma_f32_16x16x32_bf16 v[80:83], v[176:179], v[200:203], v[80:83]
	v_mfma_f32_16x16x32_bf16 v[68:71], v[168:171], v[208:211], v[68:71]
	v_mfma_f32_16x16x32_bf16 v[64:67], v[176:179], v[208:211], v[64:67]
	v_mfma_f32_16x16x32_bf16 v[116:119], v[172:175], v[188:191], v[116:119]
	v_mfma_f32_16x16x32_bf16 v[112:115], v[180:183], v[188:191], v[112:115]
	v_mfma_f32_16x16x32_bf16 v[100:103], v[172:175], v[196:199], v[100:103]
	v_mfma_f32_16x16x32_bf16 v[96:99], v[180:183], v[196:199], v[96:99]
	v_mfma_f32_16x16x32_bf16 v[84:87], v[172:175], v[204:207], v[84:87]
	v_mfma_f32_16x16x32_bf16 v[80:83], v[180:183], v[204:207], v[80:83]
	v_mfma_f32_16x16x32_bf16 v[68:71], v[172:175], v[212:215], v[68:71]
	v_mfma_f32_16x16x32_bf16 v[64:67], v[180:183], v[212:215], v[64:67]
	s_setprio 0
	s_barrier
	s_add_i32 s34, s50, s40
	v_lshl_add_u64 v[148:149], s[30:31], 0, v[132:133]
	s_mov_b32 m0, s34
	ds_read_b128 v[184:187], v155 offset:16384
	ds_read_b128 v[188:191], v155 offset:17408
	ds_read_b128 v[192:195], v155 offset:18432
	ds_read_b128 v[196:199], v155 offset:19456
	ds_read_b128 v[200:203], v155 offset:20480
	ds_read_b128 v[204:207], v155 offset:21504
	ds_read_b128 v[208:211], v155 offset:22528
	ds_read_b128 v[212:215], v155 offset:23552
	global_load_lds_dwordx4 v[148:149], off
	s_add_i32 m0, s34, 0x2000
	s_add_u32 s34, s30, 0xb0000
	v_lshl_add_u64 v[216:217], s[30:31], 0, v[136:137]
	s_addc_u32 s35, s31, 0
	s_add_i32 s57, s51, s40
	global_load_lds_dwordx4 v[216:217], off
	v_lshl_add_u64 v[218:219], s[34:35], 0, v[132:133]
	s_mov_b32 m0, s57
	v_lshl_add_u64 v[220:221], s[36:37], 0, v[134:135]
	global_load_lds_dwordx4 v[218:219], off
	v_lshl_add_u64 v[218:219], s[34:35], 0, v[136:137]
	s_add_i32 m0, s57, 0x2000
	s_nop 0
	global_load_lds_dwordx4 v[218:219], off
	v_lshl_add_u64 v[218:219], s[36:37], 0, v[130:131]
	s_mov_b32 m0, s41
	s_nop 0
	global_load_lds_dwordx4 v[218:219], off
	s_mov_b32 m0, s42
	s_nop 0
	global_load_lds_dwordx4 v[220:221], off
	s_waitcnt vmcnt(8)
	s_waitcnt lgkmcnt(0)
	s_barrier
	s_setprio 1
	s_waitcnt lgkmcnt(0)
	v_mfma_f32_16x16x32_bf16 v[60:63], v[144:147], v[184:187], v[60:63]
	v_mfma_f32_16x16x32_bf16 v[56:59], v[160:163], v[184:187], v[56:59]
	v_mfma_f32_16x16x32_bf16 v[44:47], v[144:147], v[192:195], v[44:47]
	v_mfma_f32_16x16x32_bf16 v[40:43], v[160:163], v[192:195], v[40:43]
	v_mfma_f32_16x16x32_bf16 v[28:31], v[144:147], v[200:203], v[28:31]
	v_mfma_f32_16x16x32_bf16 v[24:27], v[160:163], v[200:203], v[24:27]
	v_mfma_f32_16x16x32_bf16 v[12:15], v[144:147], v[208:211], v[12:15]
	v_mfma_f32_16x16x32_bf16 v[8:11], v[160:163], v[208:211], v[8:11]
	v_mfma_f32_16x16x32_bf16 v[60:63], v[156:159], v[188:191], v[60:63]
	v_mfma_f32_16x16x32_bf16 v[56:59], v[164:167], v[188:191], v[56:59]
	v_mfma_f32_16x16x32_bf16 v[44:47], v[156:159], v[196:199], v[44:47]
	v_mfma_f32_16x16x32_bf16 v[40:43], v[164:167], v[196:199], v[40:43]
	v_mfma_f32_16x16x32_bf16 v[28:31], v[156:159], v[204:207], v[28:31]
	v_mfma_f32_16x16x32_bf16 v[24:27], v[164:167], v[204:207], v[24:27]
	v_mfma_f32_16x16x32_bf16 v[12:15], v[156:159], v[212:215], v[12:15]
	v_mfma_f32_16x16x32_bf16 v[8:11], v[164:167], v[212:215], v[8:11]
	s_setprio 0
	s_setprio 1
	v_mfma_f32_16x16x32_bf16 v[52:55], v[168:171], v[184:187], v[52:55]
	v_mfma_f32_16x16x32_bf16 v[48:51], v[176:179], v[184:187], v[48:51]
	v_mfma_f32_16x16x32_bf16 v[36:39], v[168:171], v[192:195], v[36:39]
	v_mfma_f32_16x16x32_bf16 v[32:35], v[176:179], v[192:195], v[32:35]
	v_mfma_f32_16x16x32_bf16 v[20:23], v[168:171], v[200:203], v[20:23]
	v_mfma_f32_16x16x32_bf16 v[16:19], v[176:179], v[200:203], v[16:19]
	v_mfma_f32_16x16x32_bf16 v[4:7], v[168:171], v[208:211], v[4:7]
	v_mfma_f32_16x16x32_bf16 v[0:3], v[176:179], v[208:211], v[0:3]
	v_mfma_f32_16x16x32_bf16 v[52:55], v[172:175], v[188:191], v[52:55]
	v_mfma_f32_16x16x32_bf16 v[48:51], v[180:183], v[188:191], v[48:51]
	v_mfma_f32_16x16x32_bf16 v[36:39], v[172:175], v[196:199], v[36:39]
	v_mfma_f32_16x16x32_bf16 v[32:35], v[180:183], v[196:199], v[32:35]
	v_mfma_f32_16x16x32_bf16 v[20:23], v[172:175], v[204:207], v[20:23]
	v_mfma_f32_16x16x32_bf16 v[16:19], v[180:183], v[204:207], v[16:19]
	v_mfma_f32_16x16x32_bf16 v[4:7], v[172:175], v[212:215], v[4:7]
	v_mfma_f32_16x16x32_bf16 v[0:3], v[180:183], v[212:215], v[0:3]
	s_setprio 0
	s_barrier
	s_add_i32 s57, 0, 0x18000
	s_add_i32 s58, 0, 0x1c000
	v_add_u32_e32 v164, s57, v151
	v_add_u32_e32 v180, s58, v151
	ds_read_b128 v[144:147], v164
	ds_read_b128 v[156:159], v164 offset:1024
	ds_read_b128 v[160:163], v164 offset:2048
	ds_read_b128 v[164:167], v164 offset:3072
	ds_read_b128 v[168:171], v180
	ds_read_b128 v[172:175], v180 offset:1024
	ds_read_b128 v[176:179], v180 offset:2048
	ds_read_b128 v[180:183], v180 offset:3072
	s_add_u32 s34, s36, 0xb0000
	s_addc_u32 s35, s37, 0
	s_mov_b32 m0, s43
	v_lshl_add_u64 v[222:223], s[34:35], 0, v[130:131]
	ds_read_b128 v[184:187], v155 offset:32768
	ds_read_b128 v[188:191], v155 offset:33792
	ds_read_b128 v[192:195], v155 offset:34816
	ds_read_b128 v[196:199], v155 offset:35840
	ds_read_b128 v[200:203], v155 offset:36864
	ds_read_b128 v[204:207], v155 offset:37888
	ds_read_b128 v[208:211], v155 offset:38912
	ds_read_b128 v[212:215], v155 offset:39936
	global_load_lds_dwordx4 v[222:223], off
	v_lshl_add_u64 v[222:223], s[34:35], 0, v[134:135]
	s_mov_b32 m0, s44
	s_nop 0
	global_load_lds_dwordx4 v[222:223], off
	s_waitcnt vmcnt(8)
	s_waitcnt lgkmcnt(0)
	s_barrier
	s_setprio 1
	s_waitcnt lgkmcnt(0)
	v_mfma_f32_16x16x32_bf16 v[124:127], v[144:147], v[184:187], v[124:127]
	v_mfma_f32_16x16x32_bf16 v[120:123], v[160:163], v[184:187], v[120:123]
	v_mfma_f32_16x16x32_bf16 v[108:111], v[144:147], v[192:195], v[108:111]
	v_mfma_f32_16x16x32_bf16 v[104:107], v[160:163], v[192:195], v[104:107]
	v_mfma_f32_16x16x32_bf16 v[92:95], v[144:147], v[200:203], v[92:95]
	v_mfma_f32_16x16x32_bf16 v[88:91], v[160:163], v[200:203], v[88:91]
	v_mfma_f32_16x16x32_bf16 v[76:79], v[144:147], v[208:211], v[76:79]
	v_mfma_f32_16x16x32_bf16 v[72:75], v[160:163], v[208:211], v[72:75]
	v_mfma_f32_16x16x32_bf16 v[124:127], v[156:159], v[188:191], v[124:127]
	v_mfma_f32_16x16x32_bf16 v[120:123], v[164:167], v[188:191], v[120:123]
	v_mfma_f32_16x16x32_bf16 v[108:111], v[156:159], v[196:199], v[108:111]
	v_mfma_f32_16x16x32_bf16 v[104:107], v[164:167], v[196:199], v[104:107]
	v_mfma_f32_16x16x32_bf16 v[92:95], v[156:159], v[204:207], v[92:95]
	v_mfma_f32_16x16x32_bf16 v[88:91], v[164:167], v[204:207], v[88:91]
	v_mfma_f32_16x16x32_bf16 v[76:79], v[156:159], v[212:215], v[76:79]
	v_mfma_f32_16x16x32_bf16 v[72:75], v[164:167], v[212:215], v[72:75]
	s_setprio 0
	s_setprio 1
	v_mfma_f32_16x16x32_bf16 v[116:119], v[168:171], v[184:187], v[116:119]
	v_mfma_f32_16x16x32_bf16 v[112:115], v[176:179], v[184:187], v[112:115]
	v_mfma_f32_16x16x32_bf16 v[100:103], v[168:171], v[192:195], v[100:103]
	v_mfma_f32_16x16x32_bf16 v[96:99], v[176:179], v[192:195], v[96:99]
	v_mfma_f32_16x16x32_bf16 v[84:87], v[168:171], v[200:203], v[84:87]
	v_mfma_f32_16x16x32_bf16 v[80:83], v[176:179], v[200:203], v[80:83]
	v_mfma_f32_16x16x32_bf16 v[68:71], v[168:171], v[208:211], v[68:71]
	v_mfma_f32_16x16x32_bf16 v[64:67], v[176:179], v[208:211], v[64:67]
	v_mfma_f32_16x16x32_bf16 v[116:119], v[172:175], v[188:191], v[116:119]
	v_mfma_f32_16x16x32_bf16 v[112:115], v[180:183], v[188:191], v[112:115]
	v_mfma_f32_16x16x32_bf16 v[100:103], v[172:175], v[196:199], v[100:103]
	v_mfma_f32_16x16x32_bf16 v[96:99], v[180:183], v[196:199], v[96:99]
	v_mfma_f32_16x16x32_bf16 v[84:87], v[172:175], v[204:207], v[84:87]
	v_mfma_f32_16x16x32_bf16 v[80:83], v[180:183], v[204:207], v[80:83]
	v_mfma_f32_16x16x32_bf16 v[68:71], v[172:175], v[212:215], v[68:71]
	v_mfma_f32_16x16x32_bf16 v[64:67], v[180:183], v[212:215], v[64:67]
	s_setprio 0
	s_barrier
	s_add_i32 s34, s57, s40
	v_lshl_add_u64 v[148:149], v[148:149], 0, s[8:9]
	s_mov_b32 m0, s34
	ds_read_b128 v[184:187], v155 offset:49152
	ds_read_b128 v[188:191], v155 offset:50176
	ds_read_b128 v[192:195], v155 offset:51200
	ds_read_b128 v[196:199], v155 offset:52224
	ds_read_b128 v[200:203], v155 offset:53248
	ds_read_b128 v[204:207], v155 offset:54272
	ds_read_b128 v[208:211], v155 offset:55296
	ds_read_b128 v[212:215], v155 offset:56320
	global_load_lds_dwordx4 v[148:149], off
	s_add_i32 m0, s34, 0x2000
	s_add_u32 s30, s30, 0xb0080
	v_lshl_add_u64 v[148:149], v[216:217], 0, s[8:9]
	s_addc_u32 s31, s31, 0
	s_add_i32 s34, s58, s40
	global_load_lds_dwordx4 v[148:149], off
	v_lshl_add_u64 v[148:149], s[30:31], 0, v[132:133]
	s_mov_b32 m0, s34
	s_nop 0
	global_load_lds_dwordx4 v[148:149], off
	v_lshl_add_u64 v[148:149], s[30:31], 0, v[136:137]
	s_add_i32 m0, s34, 0x2000
	s_nop 0
	global_load_lds_dwordx4 v[148:149], off
	v_lshl_add_u64 v[148:149], v[218:219], 0, s[8:9]
	s_mov_b32 m0, s46
	s_nop 0
	global_load_lds_dwordx4 v[148:149], off
	v_lshl_add_u64 v[148:149], v[220:221], 0, s[8:9]
	s_mov_b32 m0, s47
	s_nop 0
	global_load_lds_dwordx4 v[148:149], off
	s_waitcnt vmcnt(8)
	s_waitcnt lgkmcnt(0)
	s_barrier
	s_add_u32 s28, s28, 0x100
	s_addc_u32 s29, s29, 0
	s_add_u32 s54, s54, 0x100
	s_addc_u32 s55, s55, 0
	s_setprio 1
	s_waitcnt lgkmcnt(0)
	v_mfma_f32_16x16x32_bf16 v[60:63], v[144:147], v[184:187], v[60:63]
	v_mfma_f32_16x16x32_bf16 v[56:59], v[160:163], v[184:187], v[56:59]
	v_mfma_f32_16x16x32_bf16 v[44:47], v[144:147], v[192:195], v[44:47]
	v_mfma_f32_16x16x32_bf16 v[40:43], v[160:163], v[192:195], v[40:43]
	v_mfma_f32_16x16x32_bf16 v[28:31], v[144:147], v[200:203], v[28:31]
	v_mfma_f32_16x16x32_bf16 v[24:27], v[160:163], v[200:203], v[24:27]
	v_mfma_f32_16x16x32_bf16 v[12:15], v[144:147], v[208:211], v[12:15]
	v_mfma_f32_16x16x32_bf16 v[8:11], v[160:163], v[208:211], v[8:11]
	v_mfma_f32_16x16x32_bf16 v[60:63], v[156:159], v[188:191], v[60:63]
	v_mfma_f32_16x16x32_bf16 v[56:59], v[164:167], v[188:191], v[56:59]
	v_mfma_f32_16x16x32_bf16 v[44:47], v[156:159], v[196:199], v[44:47]
	v_mfma_f32_16x16x32_bf16 v[40:43], v[164:167], v[196:199], v[40:43]
	v_mfma_f32_16x16x32_bf16 v[28:31], v[156:159], v[204:207], v[28:31]
	v_mfma_f32_16x16x32_bf16 v[24:27], v[164:167], v[204:207], v[24:27]
	v_mfma_f32_16x16x32_bf16 v[12:15], v[156:159], v[212:215], v[12:15]
	v_mfma_f32_16x16x32_bf16 v[8:11], v[164:167], v[212:215], v[8:11]
	s_setprio 0
	s_setprio 1
	v_mfma_f32_16x16x32_bf16 v[52:55], v[168:171], v[184:187], v[52:55]
	v_mfma_f32_16x16x32_bf16 v[48:51], v[176:179], v[184:187], v[48:51]
	v_mfma_f32_16x16x32_bf16 v[36:39], v[168:171], v[192:195], v[36:39]
	v_mfma_f32_16x16x32_bf16 v[32:35], v[176:179], v[192:195], v[32:35]
	v_mfma_f32_16x16x32_bf16 v[20:23], v[168:171], v[200:203], v[20:23]
	v_mfma_f32_16x16x32_bf16 v[16:19], v[176:179], v[200:203], v[16:19]
	v_mfma_f32_16x16x32_bf16 v[4:7], v[168:171], v[208:211], v[4:7]
	v_mfma_f32_16x16x32_bf16 v[0:3], v[176:179], v[208:211], v[0:3]
	v_mfma_f32_16x16x32_bf16 v[52:55], v[172:175], v[188:191], v[52:55]
	v_mfma_f32_16x16x32_bf16 v[48:51], v[180:183], v[188:191], v[48:51]
	v_mfma_f32_16x16x32_bf16 v[36:39], v[172:175], v[196:199], v[36:39]
	v_mfma_f32_16x16x32_bf16 v[32:35], v[180:183], v[196:199], v[32:35]
	v_mfma_f32_16x16x32_bf16 v[20:23], v[172:175], v[204:207], v[20:23]
	v_mfma_f32_16x16x32_bf16 v[16:19], v[180:183], v[204:207], v[16:19]
	v_mfma_f32_16x16x32_bf16 v[4:7], v[172:175], v[212:215], v[4:7]
	v_mfma_f32_16x16x32_bf16 v[0:3], v[180:183], v[212:215], v[0:3]
	s_setprio 0
	s_add_i32 s56, s56, 2
	s_cmp_gt_u32 s56, 41
	s_cbranch_scc0 .LBB0_2174
	s_sub_i32 s100, s56, 2
	s_cmp_eq_u32 s100, s98
	s_cbranch_scc1 .Lmy_nobar_23
	s_barrier
.Lmy_nobar_23:
	s_and_b64 vcc, exec, s[10:11]
	s_cbranch_vccz .LBB0_2177
	s_nop 0
